# GEMM K-loops: no setprio, no duplicate lgkmcnt wait, post-MFMA SALU/VALU tails moved past the closing barrier
# speedup vs baseline: 1.0171x; 1.0025x over previous
; #define PG8_STAGE(bufoff, gbase, voff) do { _Pragma("unroll") for (int _i = 0; _i < 2; ++_i) \
;         __builtin_amdgcn_global_load_lds((const unsigned*)((const char*)(gbase) + (voff)[_i]), (PG8_LAS unsigned*)(lds + (bufoff) + ldsw + _i * 8192), 16, 0, 0); } while (0)
; #define PG8_LDA(dst, b, h) do { _Pragma("unroll") for (int m = 0; m < 4; ++m) _Pragma("unroll") for (int k = 0; k < 2; ++k) dst[m][k] = *(const PG8_LAS bf16x8*)(lds + PG8_SA(b, h) + aoff + m * 2048 + k * 1024); } while (0)
; #define PG8_LDB(dst, b, h) do { _Pragma("unroll") for (int n = 0; n < 2; ++n) _Pragma("unroll") for (int k = 0; k < 2; ++k) dst[n][k] = *(const PG8_LAS bf16x8*)(lds + PG8_SB(b, h) + boff + n * 2048 + k * 1024); } while (0)
; #define PG8_MMA(ai, bj, At, Bt) do { __builtin_amdgcn_s_setprio(1); _Pragma("unroll") for (int m = 0; m < 4; ++m) _Pragma("unroll") for (int n = 0; n < 2; ++n) _Pragma("unroll") for (int k = 0; k < 2; ++k) \
;         acc[ai][bj][m][n] = __builtin_amdgcn_mfma_f32_16x16x32_bf16(Bt[n][k], At[m][k], acc[ai][bj][m][n], 0, 0, 0); __builtin_amdgcn_s_setprio(0); } while (0)
; #define PG8_WAIT_V(n) asm volatile("s_waitcnt vmcnt(" #n ")" ::: "memory")
; #define PG8_WAIT_L(n) asm volatile("s_waitcnt lgkmcnt(" #n ")" ::: "memory")
; #define PG8_BAR __builtin_amdgcn_s_barrier()
; #define PG8_SCHED __builtin_amdgcn_sched_barrier(0)
; template <class Epi, class Sched>
; __device__ __forceinline__ void gemm_phase(PG8_LAS unsigned char* lds, const Gemm g, const Sched& S, const Epi& E) {
;     ...
;             PG8_LDB(B0, 0, 0); PG8_SCHED; PG8_LDA(At, 0, 0); PG8_STAGE(PG8_SA(1, 1), a1 + hstep, voffA);
;             PG8_WAIT_L(8); PG8_BAR; PG8_WAIT_L(0); PG8_MMA(0, 0, At, B0); PG8_BAR; PG8_SCHED;
;             PG8_LDB(B1, 0, 1); PG8_STAGE(PG8_SB(0, 0), b2, voffB);
;             PG8_BAR; PG8_WAIT_L(0); PG8_MMA(0, 1, At, B1); PG8_BAR;
;             PG8_LDA(At, 0, 1); PG8_STAGE(PG8_SA(0, 0), a2, voffA);
;             PG8_BAR; PG8_WAIT_L(0); PG8_MMA(1, 0, At, B0); PG8_BAR; PG8_SCHED;
;             PG8_STAGE(PG8_SB(0, 1), b2 + hstep, voffB);
;             PG8_WAIT_V(6); PG8_BAR; PG8_MMA(1, 1, At, B1); PG8_BAR;
.LBB0_195:
	ds_read_b128 v[144:147], v151
	ds_read_b128 v[156:159], v151 offset:1024
	ds_read_b128 v[160:163], v151 offset:2048
	ds_read_b128 v[166:169], v151 offset:3072
	s_add_u32 s30, s28, 0xfffc0080
	s_addc_u32 s31, s29, -1
	s_cmp_eq_u32 s58, 12
	s_cselect_b32 s35, s17, s31
	s_cselect_b32 s34, s54, s30
	s_cselect_b32 s31, s15, s57
	s_cselect_b32 s30, s55, s56
	v_lshl_add_u64 v[174:175], s[28:29], 0, v[136:137]
	s_add_i32 m0, s27, 0xc000
	ds_read_b128 v[170:173], v153
	ds_read_b128 v[182:185], v153 offset:1024
	ds_read_b128 v[190:193], v153 offset:2048
	ds_read_b128 v[194:197], v153 offset:3072
	ds_read_b128 v[198:201], v153 offset:4096
	ds_read_b128 v[202:205], v153 offset:5120
	ds_read_b128 v[206:209], v153 offset:6144
	ds_read_b128 v[210:213], v153 offset:7168
	global_load_lds_dwordx4 v[174:175], off
	v_lshl_add_u64 v[174:175], s[28:29], 0, v[138:139]
	s_add_i32 m0, s27, 0xe000
	s_nop 0
	global_load_lds_dwordx4 v[174:175], off
	s_waitcnt lgkmcnt(8)
	s_barrier
	s_waitcnt lgkmcnt(0)
	v_mfma_f32_16x16x32_bf16 v[124:127], v[144:147], v[170:173], v[124:127]
	v_mfma_f32_16x16x32_bf16 v[120:123], v[160:163], v[170:173], v[120:123]
	v_mfma_f32_16x16x32_bf16 v[108:111], v[144:147], v[190:193], v[108:111]
	v_mfma_f32_16x16x32_bf16 v[104:107], v[160:163], v[190:193], v[104:107]
	v_mfma_f32_16x16x32_bf16 v[92:95], v[144:147], v[198:201], v[92:95]
	v_mfma_f32_16x16x32_bf16 v[88:91], v[160:163], v[198:201], v[88:91]
	v_mfma_f32_16x16x32_bf16 v[76:79], v[144:147], v[206:209], v[76:79]
	v_mfma_f32_16x16x32_bf16 v[72:75], v[160:163], v[206:209], v[72:75]
	v_mfma_f32_16x16x32_bf16 v[124:127], v[156:159], v[182:185], v[124:127]
	v_mfma_f32_16x16x32_bf16 v[120:123], v[166:169], v[182:185], v[120:123]
	v_mfma_f32_16x16x32_bf16 v[108:111], v[156:159], v[194:197], v[108:111]
	v_mfma_f32_16x16x32_bf16 v[104:107], v[166:169], v[194:197], v[104:107]
	v_mfma_f32_16x16x32_bf16 v[92:95], v[156:159], v[202:205], v[92:95]
	v_mfma_f32_16x16x32_bf16 v[88:91], v[166:169], v[202:205], v[88:91]
	v_mfma_f32_16x16x32_bf16 v[76:79], v[156:159], v[210:213], v[76:79]
	v_mfma_f32_16x16x32_bf16 v[72:75], v[166:169], v[210:213], v[72:75]
	s_barrier
	s_add_i32 s59, s50, s40
	v_lshl_add_u64 v[174:175], s[30:31], 0, v[132:133]
	s_mov_b32 m0, s59
	ds_read_b128 v[214:217], v154
	ds_read_b128 v[218:221], v154 offset:1024
	ds_read_b128 v[222:225], v154 offset:2048
	ds_read_b128 v[226:229], v154 offset:3072
	global_load_lds_dwordx4 v[174:175], off
	v_lshl_add_u64 v[178:179], s[30:31], 0, v[128:129]
	s_add_i32 m0, s59, 0x2000
	s_nop 0
	global_load_lds_dwordx4 v[178:179], off
	s_barrier
	s_waitcnt lgkmcnt(0)
	v_mfma_f32_16x16x32_bf16 v[116:119], v[214:217], v[170:173], v[116:119]
	v_mfma_f32_16x16x32_bf16 v[112:115], v[222:225], v[170:173], v[112:115]
	v_mfma_f32_16x16x32_bf16 v[100:103], v[214:217], v[190:193], v[100:103]
	v_mfma_f32_16x16x32_bf16 v[96:99], v[222:225], v[190:193], v[96:99]
	v_mfma_f32_16x16x32_bf16 v[84:87], v[214:217], v[198:201], v[84:87]
	v_mfma_f32_16x16x32_bf16 v[80:83], v[222:225], v[198:201], v[80:83]
	v_mfma_f32_16x16x32_bf16 v[68:71], v[214:217], v[206:209], v[68:71]
	v_mfma_f32_16x16x32_bf16 v[64:67], v[222:225], v[206:209], v[64:67]
	v_mfma_f32_16x16x32_bf16 v[116:119], v[218:221], v[182:185], v[116:119]
	v_mfma_f32_16x16x32_bf16 v[112:115], v[226:229], v[182:185], v[112:115]
	v_mfma_f32_16x16x32_bf16 v[100:103], v[218:221], v[194:197], v[100:103]
	v_mfma_f32_16x16x32_bf16 v[96:99], v[226:229], v[194:197], v[96:99]
	v_mfma_f32_16x16x32_bf16 v[84:87], v[218:221], v[202:205], v[84:87]
	v_mfma_f32_16x16x32_bf16 v[80:83], v[226:229], v[202:205], v[80:83]
	v_mfma_f32_16x16x32_bf16 v[68:71], v[218:221], v[210:213], v[68:71]
	v_mfma_f32_16x16x32_bf16 v[64:67], v[226:229], v[210:213], v[64:67]
	s_barrier
	s_mov_b32 m0, s27
	v_lshl_add_u64 v[186:187], s[34:35], 0, v[134:135]
	ds_read_b128 v[170:173], v153 offset:16384
	ds_read_b128 v[182:185], v153 offset:17408
	ds_read_b128 v[190:193], v153 offset:18432
	ds_read_b128 v[194:197], v153 offset:19456
	ds_read_b128 v[198:201], v153 offset:20480
	ds_read_b128 v[202:205], v153 offset:21504
	ds_read_b128 v[206:209], v153 offset:22528
	ds_read_b128 v[210:213], v153 offset:23552
	global_load_lds_dwordx4 v[186:187], off
	v_lshl_add_u64 v[230:231], s[34:35], 0, v[130:131]
	s_mov_b32 m0, s43
	s_nop 0
	global_load_lds_dwordx4 v[230:231], off
	s_barrier
	s_waitcnt lgkmcnt(0)
	v_mfma_f32_16x16x32_bf16 v[60:63], v[144:147], v[170:173], v[60:63]
	v_mfma_f32_16x16x32_bf16 v[56:59], v[160:163], v[170:173], v[56:59]
	v_mfma_f32_16x16x32_bf16 v[44:47], v[144:147], v[190:193], v[44:47]
	v_mfma_f32_16x16x32_bf16 v[40:43], v[160:163], v[190:193], v[40:43]
	v_mfma_f32_16x16x32_bf16 v[28:31], v[144:147], v[198:201], v[28:31]
	v_mfma_f32_16x16x32_bf16 v[24:27], v[160:163], v[198:201], v[24:27]
	v_mfma_f32_16x16x32_bf16 v[12:15], v[144:147], v[206:209], v[12:15]
	v_mfma_f32_16x16x32_bf16 v[8:11], v[160:163], v[206:209], v[8:11]
	v_mfma_f32_16x16x32_bf16 v[60:63], v[156:159], v[182:185], v[60:63]
	v_mfma_f32_16x16x32_bf16 v[56:59], v[166:169], v[182:185], v[56:59]
	v_mfma_f32_16x16x32_bf16 v[44:47], v[156:159], v[194:197], v[44:47]
	v_mfma_f32_16x16x32_bf16 v[40:43], v[166:169], v[194:197], v[40:43]
	v_mfma_f32_16x16x32_bf16 v[28:31], v[156:159], v[202:205], v[28:31]
	v_mfma_f32_16x16x32_bf16 v[24:27], v[166:169], v[202:205], v[24:27]
	v_mfma_f32_16x16x32_bf16 v[12:15], v[156:159], v[210:213], v[12:15]
	v_mfma_f32_16x16x32_bf16 v[8:11], v[166:169], v[210:213], v[8:11]
	s_barrier
; #define PG8_STAGE(bufoff, gbase, voff) do { _Pragma("unroll") for (int _i = 0; _i < 2; ++_i) \
;         __builtin_amdgcn_global_load_lds((const unsigned*)((const char*)(gbase) + (voff)[_i]), (PG8_LAS unsigned*)(lds + (bufoff) + ldsw + _i * 8192), 16, 0, 0); } while (0)
; #define PG8_LDA(dst, b, h) do { _Pragma("unroll") for (int m = 0; m < 4; ++m) _Pragma("unroll") for (int k = 0; k < 2; ++k) dst[m][k] = *(const PG8_LAS bf16x8*)(lds + PG8_SA(b, h) + aoff + m * 2048 + k * 1024); } while (0)
; #define PG8_LDB(dst, b, h) do { _Pragma("unroll") for (int n = 0; n < 2; ++n) _Pragma("unroll") for (int k = 0; k < 2; ++k) dst[n][k] = *(const PG8_LAS bf16x8*)(lds + PG8_SB(b, h) + boff + n * 2048 + k * 1024); } while (0)
; #define PG8_MMA(ai, bj, At, Bt) do { __builtin_amdgcn_s_setprio(1); _Pragma("unroll") for (int m = 0; m < 4; ++m) _Pragma("unroll") for (int n = 0; n < 2; ++n) _Pragma("unroll") for (int k = 0; k < 2; ++k) \
;         acc[ai][bj][m][n] = __builtin_amdgcn_mfma_f32_16x16x32_bf16(Bt[n][k], At[m][k], acc[ai][bj][m][n], 0, 0, 0); __builtin_amdgcn_s_setprio(0); } while (0)
; #define PG8_WAIT_V(n) asm volatile("s_waitcnt vmcnt(" #n ")" ::: "memory")
; #define PG8_WAIT_L(n) asm volatile("s_waitcnt lgkmcnt(" #n ")" ::: "memory")
; #define PG8_BAR __builtin_amdgcn_s_barrier()
; #define PG8_SCHED __builtin_amdgcn_sched_barrier(0)
; template <class Epi, class Sched>
; __device__ __forceinline__ void gemm_phase(PG8_LAS unsigned char* lds, const Gemm g, const Sched& S, const Epi& E) {
;     ...
;             PG8_STAGE(PG8_SB(0, 1), b2 + hstep, voffB);
;             PG8_WAIT_V(6); PG8_BAR; PG8_MMA(1, 1, At, B1); PG8_BAR;
;             PG8_LDB(B0, 1, 0); PG8_SCHED; PG8_LDA(At, 1, 0); PG8_STAGE(PG8_SA(0, 1), a2 + hstep, voffA);
;             PG8_WAIT_L(8); PG8_BAR; PG8_WAIT_L(0); PG8_MMA(0, 0, At, B0); PG8_BAR; PG8_SCHED;
;             PG8_LDB(B1, 1, 1); PG8_STAGE(PG8_SB(1, 0), b3, voffB);
;             PG8_BAR; PG8_WAIT_L(0); PG8_MMA(0, 1, At, B1); PG8_BAR;
;             PG8_LDA(At, 1, 1); PG8_STAGE(PG8_SA(1, 0), a3, voffA);
	s_add_u32 s60, s30, 0x40000
	s_addc_u32 s61, s31, 0
	s_add_i32 s59, s51, s40
	v_lshl_add_u64 v[144:145], s[60:61], 0, v[132:133]
	s_mov_b32 m0, s59
	s_nop 0
	global_load_lds_dwordx4 v[144:145], off
	v_lshl_add_u64 v[144:145], s[60:61], 0, v[128:129]
	s_add_i32 m0, s59, 0x2000
	s_nop 0
	global_load_lds_dwordx4 v[144:145], off
	s_waitcnt vmcnt(6)
	s_barrier
	v_mfma_f32_16x16x32_bf16 v[52:55], v[214:217], v[170:173], v[52:55]
	v_mfma_f32_16x16x32_bf16 v[48:51], v[222:225], v[170:173], v[48:51]
	v_mfma_f32_16x16x32_bf16 v[36:39], v[214:217], v[190:193], v[36:39]
	v_mfma_f32_16x16x32_bf16 v[32:35], v[222:225], v[190:193], v[32:35]
	v_mfma_f32_16x16x32_bf16 v[20:23], v[214:217], v[198:201], v[20:23]
	v_mfma_f32_16x16x32_bf16 v[16:19], v[222:225], v[198:201], v[16:19]
	v_mfma_f32_16x16x32_bf16 v[4:7], v[214:217], v[206:209], v[4:7]
	v_mfma_f32_16x16x32_bf16 v[0:3], v[222:225], v[206:209], v[0:3]
	v_mfma_f32_16x16x32_bf16 v[52:55], v[218:221], v[182:185], v[52:55]
	v_mfma_f32_16x16x32_bf16 v[48:51], v[226:229], v[182:185], v[48:51]
	v_mfma_f32_16x16x32_bf16 v[36:39], v[218:221], v[194:197], v[36:39]
	v_mfma_f32_16x16x32_bf16 v[32:35], v[226:229], v[194:197], v[32:35]
	v_mfma_f32_16x16x32_bf16 v[20:23], v[218:221], v[202:205], v[20:23]
	v_mfma_f32_16x16x32_bf16 v[16:19], v[226:229], v[202:205], v[16:19]
	v_mfma_f32_16x16x32_bf16 v[4:7], v[218:221], v[210:213], v[4:7]
	v_mfma_f32_16x16x32_bf16 v[0:3], v[226:229], v[210:213], v[0:3]
	s_barrier
	s_add_i32 s59, 0, 0x18000
	v_add_u32_e32 v155, s59, v149
	ds_read_b128 v[144:147], v155
	ds_read_b128 v[156:159], v155 offset:1024
	ds_read_b128 v[160:163], v155 offset:2048
	ds_read_b128 v[166:169], v155 offset:3072
	s_add_u32 s34, s34, 0x40000
	s_addc_u32 s35, s35, 0
	s_mov_b32 m0, s44
	v_lshl_add_u64 v[214:215], s[34:35], 0, v[134:135]
	ds_read_b128 v[170:173], v153 offset:32768
	ds_read_b128 v[182:185], v153 offset:33792
	ds_read_b128 v[190:193], v153 offset:34816
	ds_read_b128 v[194:197], v153 offset:35840
	ds_read_b128 v[198:201], v153 offset:36864
	ds_read_b128 v[202:205], v153 offset:37888
	ds_read_b128 v[206:209], v153 offset:38912
	ds_read_b128 v[210:213], v153 offset:39936
	global_load_lds_dwordx4 v[214:215], off
	v_lshl_add_u64 v[214:215], s[34:35], 0, v[130:131]
	s_mov_b32 m0, s45
	s_nop 0
	global_load_lds_dwordx4 v[214:215], off
	s_waitcnt lgkmcnt(8)
	s_barrier
	s_waitcnt lgkmcnt(0)
	v_mfma_f32_16x16x32_bf16 v[124:127], v[144:147], v[170:173], v[124:127]
	v_mfma_f32_16x16x32_bf16 v[120:123], v[160:163], v[170:173], v[120:123]
	v_mfma_f32_16x16x32_bf16 v[108:111], v[144:147], v[190:193], v[108:111]
	v_mfma_f32_16x16x32_bf16 v[104:107], v[160:163], v[190:193], v[104:107]
	v_mfma_f32_16x16x32_bf16 v[92:95], v[144:147], v[198:201], v[92:95]
	v_mfma_f32_16x16x32_bf16 v[88:91], v[160:163], v[198:201], v[88:91]
	v_mfma_f32_16x16x32_bf16 v[76:79], v[144:147], v[206:209], v[76:79]
	v_mfma_f32_16x16x32_bf16 v[72:75], v[160:163], v[206:209], v[72:75]
	v_mfma_f32_16x16x32_bf16 v[124:127], v[156:159], v[182:185], v[124:127]
	v_mfma_f32_16x16x32_bf16 v[120:123], v[166:169], v[182:185], v[120:123]
	v_mfma_f32_16x16x32_bf16 v[108:111], v[156:159], v[194:197], v[108:111]
	v_mfma_f32_16x16x32_bf16 v[104:107], v[166:169], v[194:197], v[104:107]
	v_mfma_f32_16x16x32_bf16 v[92:95], v[156:159], v[202:205], v[92:95]
	v_mfma_f32_16x16x32_bf16 v[88:91], v[166:169], v[202:205], v[88:91]
	v_mfma_f32_16x16x32_bf16 v[76:79], v[156:159], v[210:213], v[76:79]
	v_mfma_f32_16x16x32_bf16 v[72:75], v[166:169], v[210:213], v[72:75]
	s_barrier
	s_add_i32 s34, 0, 0x1c000
	s_add_i32 s35, s59, s40
	v_add_u32_e32 v155, s34, v149
	v_lshl_add_u64 v[174:175], v[174:175], 0, s[10:11]
	s_mov_b32 m0, s35
	ds_read_b128 v[214:217], v155
	ds_read_b128 v[218:221], v155 offset:1024
	ds_read_b128 v[222:225], v155 offset:2048
	ds_read_b128 v[226:229], v155 offset:3072
	global_load_lds_dwordx4 v[174:175], off
	v_lshl_add_u64 v[174:175], v[178:179], 0, s[10:11]
	s_add_i32 m0, s35, 0x2000
	s_nop 0
	global_load_lds_dwordx4 v[174:175], off
	s_barrier
	s_waitcnt lgkmcnt(0)
	v_mfma_f32_16x16x32_bf16 v[116:119], v[214:217], v[170:173], v[116:119]
	v_mfma_f32_16x16x32_bf16 v[112:115], v[222:225], v[170:173], v[112:115]
	v_mfma_f32_16x16x32_bf16 v[100:103], v[214:217], v[190:193], v[100:103]
	v_mfma_f32_16x16x32_bf16 v[96:99], v[222:225], v[190:193], v[96:99]
	v_mfma_f32_16x16x32_bf16 v[84:87], v[214:217], v[198:201], v[84:87]
	v_mfma_f32_16x16x32_bf16 v[80:83], v[222:225], v[198:201], v[80:83]
	v_mfma_f32_16x16x32_bf16 v[68:71], v[214:217], v[206:209], v[68:71]
	v_mfma_f32_16x16x32_bf16 v[64:67], v[222:225], v[206:209], v[64:67]
	v_mfma_f32_16x16x32_bf16 v[116:119], v[218:221], v[182:185], v[116:119]
	v_mfma_f32_16x16x32_bf16 v[112:115], v[226:229], v[182:185], v[112:115]
	v_mfma_f32_16x16x32_bf16 v[100:103], v[218:221], v[194:197], v[100:103]
	v_mfma_f32_16x16x32_bf16 v[96:99], v[226:229], v[194:197], v[96:99]
	v_mfma_f32_16x16x32_bf16 v[84:87], v[218:221], v[202:205], v[84:87]
	v_mfma_f32_16x16x32_bf16 v[80:83], v[226:229], v[202:205], v[80:83]
	v_mfma_f32_16x16x32_bf16 v[68:71], v[218:221], v[210:213], v[68:71]
	v_mfma_f32_16x16x32_bf16 v[64:67], v[226:229], v[210:213], v[64:67]
	s_barrier
	s_mov_b32 m0, s47
	v_lshl_add_u64 v[174:175], v[186:187], 0, s[10:11]
	ds_read_b128 v[170:173], v153 offset:49152
	ds_read_b128 v[182:185], v153 offset:50176
	ds_read_b128 v[190:193], v153 offset:51200
	ds_read_b128 v[194:197], v153 offset:52224
	ds_read_b128 v[198:201], v153 offset:53248
	ds_read_b128 v[202:205], v153 offset:54272
	ds_read_b128 v[206:209], v153 offset:55296
	ds_read_b128 v[210:213], v153 offset:56320
	global_load_lds_dwordx4 v[174:175], off
	v_lshl_add_u64 v[174:175], v[230:231], 0, s[10:11]
	s_mov_b32 m0, s48
	s_nop 0
	global_load_lds_dwordx4 v[174:175], off
	s_barrier
; __device__ __forceinline__ unsigned cvt_pk_bf16(float lo, float hi) { unsigned r; asm volatile("v_cvt_pk_bf16_f32 %0, %1, %2" : "=v"(r) : "v"(lo), "v"(hi)); return r; }
; #define PG8_STAGE(bufoff, gbase, voff) do { _Pragma("unroll") for (int _i = 0; _i < 2; ++_i) \
;         __builtin_amdgcn_global_load_lds((const unsigned*)((const char*)(gbase) + (voff)[_i]), (PG8_LAS unsigned*)(lds + (bufoff) + ldsw + _i * 8192), 16, 0, 0); } while (0)
; #define PG8_LDA(dst, b, h) do { _Pragma("unroll") for (int m = 0; m < 4; ++m) _Pragma("unroll") for (int k = 0; k < 2; ++k) dst[m][k] = *(const PG8_LAS bf16x8*)(lds + PG8_SA(b, h) + aoff + m * 2048 + k * 1024); } while (0)
; #define PG8_MMA(ai, bj, At, Bt) do { __builtin_amdgcn_s_setprio(1); _Pragma("unroll") for (int m = 0; m < 4; ++m) _Pragma("unroll") for (int n = 0; n < 2; ++n) _Pragma("unroll") for (int k = 0; k < 2; ++k) \
;         acc[ai][bj][m][n] = __builtin_amdgcn_mfma_f32_16x16x32_bf16(Bt[n][k], At[m][k], acc[ai][bj][m][n], 0, 0, 0); __builtin_amdgcn_s_setprio(0); } while (0)
; #define PG8_BAR __builtin_amdgcn_s_barrier()
;     __device__ __forceinline__ void operator()(const f32x4 (&acc)[2][2][4][2], const Unit& u, int wr, int wc, int fr, int fq) const {
;         const int row0 = u.pm * BM + wr * 64 + fr, col0 = u.pn * HALF + wc * 32 + 8 * fq;
; #pragma unroll
;         for (int ai = 0; ai < 2; ++ai)
; #pragma unroll
;             for (int m = 0; m < 4; ++m) { bf16_t* rowp = O + (size_t)(row0 + ai * HALF + m * 16) * ldc + col0;
;                 f32x4 v0, v1;
; #pragma unroll
;                 for (int j = 0; j < 1; ++j) { v0 = acc[ai][0][m][0] * sigmoid4(acc[ai][0][m][0]) * acc[ai][1][m][0]; v1 = acc[ai][0][m][1] * sigmoid4(acc[ai][0][m][1]) * acc[ai][1][m][1]; }
;                 u32x4 w; w.x = cvt_pk_bf16(v0[0], v0[1]); w.y = cvt_pk_bf16(v0[2], v0[3]); w.z = cvt_pk_bf16(v1[0], v1[1]); w.w = cvt_pk_bf16(v1[2], v1[3]);
;                 *(u32x4*)rowp = w; }
; template <class Epi, class Sched>
; __device__ __forceinline__ void gemm_phase(PG8_LAS unsigned char* lds, const Gemm g, const Sched& S, const Epi& E) {
;     ...
;             PG8_LDA(At, 1, 1); PG8_STAGE(PG8_SA(1, 0), a3, voffA);
;             PG8_BAR; PG8_WAIT_L(0); PG8_MMA(1, 0, At, B0); PG8_BAR; PG8_SCHED;
;             PG8_STAGE(PG8_SB(1, 1), b3 + hstep, voffB);
;             PG8_WAIT_V(6); PG8_BAR; PG8_MMA(1, 1, At, B1); PG8_BAR;
	s_waitcnt lgkmcnt(0)
	v_mfma_f32_16x16x32_bf16 v[60:63], v[144:147], v[170:173], v[60:63]
	v_mfma_f32_16x16x32_bf16 v[56:59], v[160:163], v[170:173], v[56:59]
	v_mfma_f32_16x16x32_bf16 v[44:47], v[144:147], v[190:193], v[44:47]
	v_mfma_f32_16x16x32_bf16 v[40:43], v[160:163], v[190:193], v[40:43]
	v_mfma_f32_16x16x32_bf16 v[28:31], v[144:147], v[198:201], v[28:31]
	v_mfma_f32_16x16x32_bf16 v[24:27], v[160:163], v[198:201], v[24:27]
	v_mfma_f32_16x16x32_bf16 v[12:15], v[144:147], v[206:209], v[12:15]
	v_mfma_f32_16x16x32_bf16 v[8:11], v[160:163], v[206:209], v[8:11]
	v_mfma_f32_16x16x32_bf16 v[60:63], v[156:159], v[182:185], v[60:63]
	v_mfma_f32_16x16x32_bf16 v[56:59], v[166:169], v[182:185], v[56:59]
	v_mfma_f32_16x16x32_bf16 v[44:47], v[156:159], v[194:197], v[44:47]
	v_mfma_f32_16x16x32_bf16 v[40:43], v[166:169], v[194:197], v[40:43]
	v_mfma_f32_16x16x32_bf16 v[28:31], v[156:159], v[202:205], v[28:31]
	v_mfma_f32_16x16x32_bf16 v[24:27], v[166:169], v[202:205], v[24:27]
	v_mfma_f32_16x16x32_bf16 v[12:15], v[156:159], v[210:213], v[12:15]
	v_mfma_f32_16x16x32_bf16 v[8:11], v[166:169], v[210:213], v[8:11]
	s_barrier
	s_add_u32 s30, s30, 0x40080
	s_addc_u32 s31, s31, 0
	s_add_i32 s34, s34, s40
	v_lshl_add_u64 v[144:145], s[30:31], 0, v[132:133]
	s_mov_b32 m0, s34
	s_nop 0
	global_load_lds_dwordx4 v[144:145], off
	v_lshl_add_u64 v[144:145], s[30:31], 0, v[128:129]
	s_add_i32 m0, s34, 0x2000
	s_nop 0
	global_load_lds_dwordx4 v[144:145], off
	s_waitcnt vmcnt(6)
	s_barrier
	v_mfma_f32_16x16x32_bf16 v[52:55], v[214:217], v[170:173], v[52:55]
	v_mfma_f32_16x16x32_bf16 v[48:51], v[222:225], v[170:173], v[48:51]
	v_mfma_f32_16x16x32_bf16 v[36:39], v[214:217], v[190:193], v[36:39]
	v_mfma_f32_16x16x32_bf16 v[32:35], v[222:225], v[190:193], v[32:35]
	v_mfma_f32_16x16x32_bf16 v[20:23], v[214:217], v[198:201], v[20:23]
	v_mfma_f32_16x16x32_bf16 v[16:19], v[222:225], v[198:201], v[16:19]
	v_mfma_f32_16x16x32_bf16 v[4:7], v[214:217], v[206:209], v[4:7]
	v_mfma_f32_16x16x32_bf16 v[0:3], v[222:225], v[206:209], v[0:3]
	v_mfma_f32_16x16x32_bf16 v[52:55], v[218:221], v[182:185], v[52:55]
	v_mfma_f32_16x16x32_bf16 v[48:51], v[226:229], v[182:185], v[48:51]
	v_mfma_f32_16x16x32_bf16 v[36:39], v[218:221], v[194:197], v[36:39]
	v_mfma_f32_16x16x32_bf16 v[32:35], v[226:229], v[194:197], v[32:35]
	v_mfma_f32_16x16x32_bf16 v[20:23], v[218:221], v[202:205], v[20:23]
	v_mfma_f32_16x16x32_bf16 v[16:19], v[226:229], v[202:205], v[16:19]
	v_mfma_f32_16x16x32_bf16 v[4:7], v[218:221], v[210:213], v[4:7]
	v_mfma_f32_16x16x32_bf16 v[0:3], v[226:229], v[210:213], v[0:3]
	s_barrier
	s_add_i32 s58, s58, 2
	s_add_u32 s28, s28, 0x100
	s_addc_u32 s29, s29, 0
	s_add_u32 s56, s56, 0x100
	s_addc_u32 s57, s57, 0
	s_cmp_gt_u32 s58, 13
	s_cbranch_scc0 .LBB0_195
	v_max_f32_e32 v144, v124, v124
	v_max_f32_e32 v144, 0xc1a00000, v144
	v_mul_f32_e32 v144, 0xbfb8aa3b, v144
	v_exp_f32_e32 v157, v144
	v_max_f32_e32 v144, v125, v125
	v_max_f32_e32 v144, 0xc1a00000, v144
	v_mul_f32_e32 v144, 0xbfb8aa3b, v144
	v_exp_f32_e32 v156, v144
	v_max_f32_e32 v144, v126, v126
	v_max_f32_e32 v144, 0xc1a00000, v144
	v_mul_f32_e32 v144, 0xbfb8aa3b, v144
	v_exp_f32_e32 v159, v144
	v_max_f32_e32 v144, v127, v127
	v_max_f32_e32 v144, 0xc1a00000, v144
	v_mul_f32_e32 v144, 0xbfb8aa3b, v144
	v_exp_f32_e32 v158, v144
	v_pk_add_f32 v[156:157], v[156:157], 1.0 op_sel_hi:[1,0]
	v_lshl_or_b32 v146, s53, 7, v150
	v_mov_b32_e32 v160, v157
	v_pk_add_f32 v[158:159], v[158:159], 1.0 op_sel_hi:[1,0]
	v_mov_b32_e32 v162, v156
	v_mov_b32_e32 v161, v159
	v_mov_b32_e32 v163, v158
	v_pk_mul_f32 v[160:161], v[160:161], v[162:163]
	v_lshl_add_u32 v155, s26, 8, v148
	v_mul_f32_e32 v162, v160, v161
	v_rcp_f32_e32 v166, v162
	v_ashrrev_i32_e32 v147, 31, v146
	v_mov_b64_e32 v[144:145], s[4:5]
	v_mad_i64_i32 v[162:163], s[28:29], v155, s52, v[144:145]
	v_mul_f32_e32 v160, v160, v166
	v_mul_f32_e32 v164, v161, v166
	v_pk_mul_f32 v[158:159], v[158:159], v[160:161] op_sel_hi:[1,0]
	v_max_f32_e32 v160, v120, v120
	v_max_f32_e32 v166, v122, v122
	v_max_f32_e32 v160, 0xc1a00000, v160
	v_max_f32_e32 v166, 0xc1a00000, v166
	v_mul_f32_e32 v160, 0xbfb8aa3b, v160
	v_mul_f32_e32 v166, 0xbfb8aa3b, v166
	v_exp_f32_e32 v161, v160
	v_max_f32_e32 v160, v121, v121
	v_exp_f32_e32 v167, v166
	v_max_f32_e32 v166, v123, v123
	v_max_f32_e32 v160, 0xc1a00000, v160
	v_max_f32_e32 v166, 0xc1a00000, v166
	v_mul_f32_e32 v160, 0xbfb8aa3b, v160
	v_mul_f32_e32 v166, 0xbfb8aa3b, v166
	v_exp_f32_e32 v160, v160
	v_exp_f32_e32 v166, v166
	v_pk_mul_f32 v[156:157], v[156:157], v[164:165] op_sel_hi:[1,0]
	v_pk_mul_f32 v[126:127], v[126:127], v[158:159]
	v_pk_mul_f32 v[124:125], v[124:125], v[156:157]
	v_pk_add_f32 v[156:157], v[160:161], 1.0 op_sel_hi:[1,0]
	v_pk_add_f32 v[160:161], v[166:167], 1.0 op_sel_hi:[1,0]
	v_mov_b32_e32 v166, v157
	v_mov_b32_e32 v167, v161
	v_mov_b32_e32 v168, v156
	v_mov_b32_e32 v169, v160
	v_pk_mul_f32 v[166:167], v[166:167], v[168:169]
	v_pk_mul_f32 v[118:119], v[126:127], v[118:119]
	v_mul_f32_e32 v164, v166, v167
	v_rcp_f32_e32 v164, v164
	v_pk_mul_f32 v[116:117], v[124:125], v[116:117]
	v_lshlrev_b64 v[146:147], 1, v[146:147]
	v_lshl_add_u64 v[162:163], v[162:163], 0, v[146:147]
	v_mul_f32_e32 v124, v167, v164
	v_mul_f32_e32 v126, v166, v164
	v_pk_mul_f32 v[126:127], v[160:161], v[126:127] op_sel_hi:[1,0]
	v_pk_mul_f32 v[124:125], v[156:157], v[124:125] op_sel_hi:[1,0]
	v_pk_mul_f32 v[122:123], v[122:123], v[126:127]
	v_pk_mul_f32 v[120:121], v[120:121], v[124:125]
	v_pk_mul_f32 v[122:123], v[122:123], v[114:115]
	v_pk_mul_f32 v[114:115], v[120:121], v[112:113]
	v_cvt_pk_bf16_f32 v112, v116, v117
	v_cvt_pk_bf16_f32 v113, v118, v119
; __device__ __forceinline__ unsigned cvt_pk_bf16(float lo, float hi) { unsigned r; asm volatile("v_cvt_pk_bf16_f32 %0, %1, %2" : "=v"(r) : "v"(lo), "v"(hi)); return r; }
; __device__ __forceinline__ f32x4 sigmoid4(f32x4 x) {
;     f32x4 d;
; #pragma unroll
;     for (int j = 0; j < 4; ++j) d[j] = 1.0f + __expf(-fmaxf(x[j], -20.0f));
;     const float p01 = d[0] * d[1], p23 = d[2] * d[3], r = __builtin_amdgcn_rcpf(p01 * p23), r01 = r * p23, r23 = r * p01;
;     return (f32x4){r01 * d[1], r01 * d[0], r23 * d[3], r23 * d[2]};
; }
;     __device__ __forceinline__ void operator()(const f32x4 (&acc)[2][2][4][2], const Unit& u, int wr, int wc, int fr, int fq) const {
;     ...
;         for (int ai = 0; ai < 2; ++ai)
; #pragma unroll
;             for (int m = 0; m < 4; ++m) { bf16_t* rowp = O + (size_t)(row0 + ai * HALF + m * 16) * ldc + col0;
;                 f32x4 v0, v1;
; #pragma unroll
;                 for (int j = 0; j < 1; ++j) { v0 = acc[ai][0][m][0] * sigmoid4(acc[ai][0][m][0]) * acc[ai][1][m][0]; v1 = acc[ai][0][m][1] * sigmoid4(acc[ai][0][m][1]) * acc[ai][1][m][1]; }
;                 u32x4 w; w.x = cvt_pk_bf16(v0[0], v0[1]); w.y = cvt_pk_bf16(v0[2], v0[3]); w.z = cvt_pk_bf16(v1[0], v1[1]); w.w = cvt_pk_bf16(v1[2], v1[3]);
;                 *(u32x4*)rowp = w; }
	v_max_f32_e32 v116, v108, v108
	v_max_f32_e32 v118, v110, v110
	v_max_f32_e32 v116, 0xc1a00000, v116
	v_max_f32_e32 v118, 0xc1a00000, v118
	v_mul_f32_e32 v116, 0xbfb8aa3b, v116
	v_mul_f32_e32 v118, 0xbfb8aa3b, v118
	v_exp_f32_e32 v117, v116
	v_max_f32_e32 v116, v109, v109
	v_exp_f32_e32 v119, v118
	v_max_f32_e32 v118, v111, v111
	v_max_f32_e32 v116, 0xc1a00000, v116
	v_max_f32_e32 v118, 0xc1a00000, v118
	v_mul_f32_e32 v116, 0xbfb8aa3b, v116
	v_mul_f32_e32 v118, 0xbfb8aa3b, v118
	v_exp_f32_e32 v116, v116
	v_exp_f32_e32 v118, v118
	v_cvt_pk_bf16_f32 v114, v114, v115
	v_cvt_pk_bf16_f32 v115, v122, v123
	global_store_dwordx4 v[162:163], v[112:115], off
	v_or_b32_e32 v120, 16, v155
	s_and_b64 vcc, exec, s[2:3]
	v_pk_add_f32 v[112:113], v[116:117], 1.0 op_sel_hi:[1,0]
	v_pk_add_f32 v[114:115], v[118:119], 1.0 op_sel_hi:[1,0]
	v_mov_b32_e32 v116, v113
	v_mov_b32_e32 v117, v115
	v_mov_b32_e32 v118, v112
	v_mov_b32_e32 v119, v114
	v_pk_mul_f32 v[116:117], v[116:117], v[118:119]
	s_mov_b32 s53, s14
	v_mul_f32_e32 v118, v116, v117
	v_rcp_f32_e32 v121, v118
	v_mad_i64_i32 v[118:119], s[28:29], v120, s52, v[144:145]
	v_lshl_add_u64 v[118:119], v[118:119], 0, v[146:147]
	v_mul_f32_e32 v116, v116, v121
	v_mul_f32_e32 v120, v117, v121
	v_pk_mul_f32 v[114:115], v[114:115], v[116:117] op_sel_hi:[1,0]
	v_max_f32_e32 v116, v104, v104
	v_max_f32_e32 v121, v106, v106
	v_max_f32_e32 v116, 0xc1a00000, v116
	v_max_f32_e32 v121, 0xc1a00000, v121
	v_mul_f32_e32 v116, 0xbfb8aa3b, v116
	v_mul_f32_e32 v121, 0xbfb8aa3b, v121
	v_exp_f32_e32 v117, v116
	v_max_f32_e32 v116, v105, v105
	v_exp_f32_e32 v123, v121
	v_max_f32_e32 v121, v107, v107
	v_max_f32_e32 v116, 0xc1a00000, v116
	v_max_f32_e32 v121, 0xc1a00000, v121
	v_mul_f32_e32 v116, 0xbfb8aa3b, v116
	v_mul_f32_e32 v121, 0xbfb8aa3b, v121
	v_exp_f32_e32 v116, v116
	v_exp_f32_e32 v122, v121
	v_pk_mul_f32 v[112:113], v[112:113], v[120:121] op_sel_hi:[1,0]
	v_pk_mul_f32 v[110:111], v[110:111], v[114:115]
	v_pk_mul_f32 v[108:109], v[108:109], v[112:113]
	v_pk_add_f32 v[112:113], v[116:117], 1.0 op_sel_hi:[1,0]
	v_pk_add_f32 v[116:117], v[122:123], 1.0 op_sel_hi:[1,0]
	v_mov_b32_e32 v120, v113
	v_mov_b32_e32 v121, v117
	v_mov_b32_e32 v122, v112
	v_mov_b32_e32 v123, v116
	v_pk_mul_f32 v[120:121], v[120:121], v[122:123]
	v_pk_mul_f32 v[102:103], v[110:111], v[102:103]
	v_mul_f32_e32 v122, v120, v121
	v_rcp_f32_e32 v122, v122
	v_pk_mul_f32 v[100:101], v[108:109], v[100:101]
	s_mov_b32 s26, s16
	s_mov_b64 s[30:31], s[24:25]
	v_mul_f32_e32 v108, v121, v122
	v_mul_f32_e32 v110, v120, v122
	v_pk_mul_f32 v[110:111], v[116:117], v[110:111] op_sel_hi:[1,0]
	v_pk_mul_f32 v[108:109], v[112:113], v[108:109] op_sel_hi:[1,0]
	v_pk_mul_f32 v[106:107], v[106:107], v[110:111]
	v_pk_mul_f32 v[104:105], v[104:105], v[108:109]
	v_pk_mul_f32 v[106:107], v[106:107], v[98:99]
	v_pk_mul_f32 v[98:99], v[104:105], v[96:97]
	v_cvt_pk_bf16_f32 v96, v100, v101
	v_cvt_pk_bf16_f32 v97, v102, v103
	v_max_f32_e32 v100, v92, v92
	v_max_f32_e32 v102, v94, v94
	v_max_f32_e32 v100, 0xc1a00000, v100
	v_max_f32_e32 v102, 0xc1a00000, v102
	v_mul_f32_e32 v100, 0xbfb8aa3b, v100
	v_mul_f32_e32 v102, 0xbfb8aa3b, v102
	v_exp_f32_e32 v101, v100
	v_max_f32_e32 v100, v93, v93
	v_exp_f32_e32 v103, v102
	v_max_f32_e32 v102, v95, v95
	v_max_f32_e32 v100, 0xc1a00000, v100
	v_max_f32_e32 v102, 0xc1a00000, v102
	v_mul_f32_e32 v100, 0xbfb8aa3b, v100
	v_mul_f32_e32 v102, 0xbfb8aa3b, v102
	v_exp_f32_e32 v100, v100
	v_exp_f32_e32 v102, v102
	v_cvt_pk_bf16_f32 v98, v98, v99
	v_cvt_pk_bf16_f32 v99, v106, v107
	global_store_dwordx4 v[118:119], v[96:99], off
	v_or_b32_e32 v104, 32, v155
	s_nop 0
	v_pk_add_f32 v[96:97], v[100:101], 1.0 op_sel_hi:[1,0]
	v_pk_add_f32 v[98:99], v[102:103], 1.0 op_sel_hi:[1,0]
	v_mov_b32_e32 v100, v97
	v_mov_b32_e32 v101, v99
	v_mov_b32_e32 v102, v96
	v_mov_b32_e32 v103, v98
	v_pk_mul_f32 v[100:101], v[100:101], v[102:103]
	s_nop 0
	v_mul_f32_e32 v102, v100, v101
	v_rcp_f32_e32 v105, v102
	v_mad_i64_i32 v[102:103], s[28:29], v104, s52, v[144:145]
	v_lshl_add_u64 v[102:103], v[102:103], 0, v[146:147]
	v_mul_f32_e32 v100, v100, v105
	v_mul_f32_e32 v104, v101, v105
	v_pk_mul_f32 v[98:99], v[98:99], v[100:101] op_sel_hi:[1,0]
	v_max_f32_e32 v100, v88, v88
	v_max_f32_e32 v105, v90, v90
	v_max_f32_e32 v100, 0xc1a00000, v100
	v_max_f32_e32 v105, 0xc1a00000, v105
	v_mul_f32_e32 v100, 0xbfb8aa3b, v100
	v_mul_f32_e32 v105, 0xbfb8aa3b, v105
	v_exp_f32_e32 v101, v100
	v_max_f32_e32 v100, v89, v89
	v_exp_f32_e32 v107, v105
	v_max_f32_e32 v105, v91, v91
	v_max_f32_e32 v100, 0xc1a00000, v100
	v_max_f32_e32 v105, 0xc1a00000, v105
	v_mul_f32_e32 v100, 0xbfb8aa3b, v100
	v_mul_f32_e32 v105, 0xbfb8aa3b, v105
	v_exp_f32_e32 v100, v100
	v_exp_f32_e32 v106, v105
	v_pk_mul_f32 v[96:97], v[96:97], v[104:105] op_sel_hi:[1,0]
	v_pk_mul_f32 v[94:95], v[94:95], v[98:99]
	v_pk_mul_f32 v[92:93], v[92:93], v[96:97]
	v_pk_add_f32 v[96:97], v[100:101], 1.0 op_sel_hi:[1,0]
	v_pk_add_f32 v[100:101], v[106:107], 1.0 op_sel_hi:[1,0]
	v_mov_b32_e32 v104, v97
	v_mov_b32_e32 v105, v101
	v_mov_b32_e32 v106, v96
	v_mov_b32_e32 v107, v100
	v_pk_mul_f32 v[104:105], v[104:105], v[106:107]
	v_pk_mul_f32 v[86:87], v[94:95], v[86:87]
	v_mul_f32_e32 v106, v104, v105
	v_rcp_f32_e32 v106, v106
	v_pk_mul_f32 v[84:85], v[92:93], v[84:85]
	v_mul_f32_e32 v92, v105, v106
	v_mul_f32_e32 v94, v104, v106
	v_pk_mul_f32 v[94:95], v[100:101], v[94:95] op_sel_hi:[1,0]
	v_pk_mul_f32 v[92:93], v[96:97], v[92:93] op_sel_hi:[1,0]
	v_pk_mul_f32 v[90:91], v[90:91], v[94:95]
	v_pk_mul_f32 v[88:89], v[88:89], v[92:93]
	v_pk_mul_f32 v[90:91], v[90:91], v[82:83]
	v_pk_mul_f32 v[82:83], v[88:89], v[80:81]
	v_cvt_pk_bf16_f32 v80, v84, v85
; __device__ __forceinline__ unsigned cvt_pk_bf16(float lo, float hi) { unsigned r; asm volatile("v_cvt_pk_bf16_f32 %0, %1, %2" : "=v"(r) : "v"(lo), "v"(hi)); return r; }
; __device__ __forceinline__ f32x4 sigmoid4(f32x4 x) {
;     f32x4 d;
; #pragma unroll
;     for (int j = 0; j < 4; ++j) d[j] = 1.0f + __expf(-fmaxf(x[j], -20.0f));
;     const float p01 = d[0] * d[1], p23 = d[2] * d[3], r = __builtin_amdgcn_rcpf(p01 * p23), r01 = r * p23, r23 = r * p01;
;     return (f32x4){r01 * d[1], r01 * d[0], r23 * d[3], r23 * d[2]};
; }
;     __device__ __forceinline__ void operator()(const f32x4 (&acc)[2][2][4][2], const Unit& u, int wr, int wc, int fr, int fq) const {
;     ...
;         for (int ai = 0; ai < 2; ++ai)
; #pragma unroll
;             for (int m = 0; m < 4; ++m) { bf16_t* rowp = O + (size_t)(row0 + ai * HALF + m * 16) * ldc + col0;
;                 f32x4 v0, v1;
; #pragma unroll
;                 for (int j = 0; j < 1; ++j) { v0 = acc[ai][0][m][0] * sigmoid4(acc[ai][0][m][0]) * acc[ai][1][m][0]; v1 = acc[ai][0][m][1] * sigmoid4(acc[ai][0][m][1]) * acc[ai][1][m][1]; }
;                 u32x4 w; w.x = cvt_pk_bf16(v0[0], v0[1]); w.y = cvt_pk_bf16(v0[2], v0[3]); w.z = cvt_pk_bf16(v1[0], v1[1]); w.w = cvt_pk_bf16(v1[2], v1[3]);
;                 *(u32x4*)rowp = w; }
	v_cvt_pk_bf16_f32 v81, v86, v87
	v_max_f32_e32 v84, v76, v76
	v_max_f32_e32 v86, v78, v78
	v_max_f32_e32 v84, 0xc1a00000, v84
	v_max_f32_e32 v86, 0xc1a00000, v86
	v_mul_f32_e32 v84, 0xbfb8aa3b, v84
	v_mul_f32_e32 v86, 0xbfb8aa3b, v86
	v_exp_f32_e32 v85, v84
	v_max_f32_e32 v84, v77, v77
	v_exp_f32_e32 v87, v86
	v_max_f32_e32 v86, v79, v79
	v_max_f32_e32 v84, 0xc1a00000, v84
	v_max_f32_e32 v86, 0xc1a00000, v86
	v_mul_f32_e32 v84, 0xbfb8aa3b, v84
	v_mul_f32_e32 v86, 0xbfb8aa3b, v86
	v_exp_f32_e32 v84, v84
	v_exp_f32_e32 v86, v86
	v_cvt_pk_bf16_f32 v82, v82, v83
	v_cvt_pk_bf16_f32 v83, v90, v91
	global_store_dwordx4 v[102:103], v[80:83], off
	v_or_b32_e32 v88, 48, v155
	s_nop 0
	v_pk_add_f32 v[80:81], v[84:85], 1.0 op_sel_hi:[1,0]
	v_pk_add_f32 v[82:83], v[86:87], 1.0 op_sel_hi:[1,0]
	v_mov_b32_e32 v84, v81
	v_mov_b32_e32 v85, v83
	v_mov_b32_e32 v86, v80
	v_mov_b32_e32 v87, v82
	v_pk_mul_f32 v[84:85], v[84:85], v[86:87]
	s_nop 0
	v_mul_f32_e32 v86, v84, v85
	v_rcp_f32_e32 v89, v86
	v_mad_i64_i32 v[86:87], s[28:29], v88, s52, v[144:145]
	v_lshl_add_u64 v[86:87], v[86:87], 0, v[146:147]
	v_mul_f32_e32 v84, v84, v89
	v_mul_f32_e32 v88, v85, v89
	v_pk_mul_f32 v[82:83], v[82:83], v[84:85] op_sel_hi:[1,0]
	v_max_f32_e32 v84, v72, v72
	v_max_f32_e32 v89, v74, v74
	v_max_f32_e32 v84, 0xc1a00000, v84
	v_max_f32_e32 v89, 0xc1a00000, v89
	v_mul_f32_e32 v84, 0xbfb8aa3b, v84
	v_mul_f32_e32 v89, 0xbfb8aa3b, v89
	v_exp_f32_e32 v85, v84
	v_max_f32_e32 v84, v73, v73
	v_exp_f32_e32 v91, v89
	v_max_f32_e32 v89, v75, v75
	v_max_f32_e32 v84, 0xc1a00000, v84
	v_max_f32_e32 v89, 0xc1a00000, v89
	v_mul_f32_e32 v84, 0xbfb8aa3b, v84
	v_mul_f32_e32 v89, 0xbfb8aa3b, v89
	v_exp_f32_e32 v84, v84
	v_exp_f32_e32 v90, v89
	v_pk_mul_f32 v[80:81], v[80:81], v[88:89] op_sel_hi:[1,0]
	v_pk_mul_f32 v[78:79], v[78:79], v[82:83]
	v_pk_mul_f32 v[76:77], v[76:77], v[80:81]
	v_pk_add_f32 v[80:81], v[84:85], 1.0 op_sel_hi:[1,0]
	v_pk_add_f32 v[84:85], v[90:91], 1.0 op_sel_hi:[1,0]
	v_mov_b32_e32 v88, v81
	v_mov_b32_e32 v89, v85
	v_mov_b32_e32 v90, v80
	v_mov_b32_e32 v91, v84
	v_pk_mul_f32 v[88:89], v[88:89], v[90:91]
	v_pk_mul_f32 v[70:71], v[78:79], v[70:71]
	v_mul_f32_e32 v90, v88, v89
	v_rcp_f32_e32 v90, v90
	v_pk_mul_f32 v[68:69], v[76:77], v[68:69]
	v_mul_f32_e32 v76, v89, v90
	v_mul_f32_e32 v78, v88, v90
	v_pk_mul_f32 v[78:79], v[84:85], v[78:79] op_sel_hi:[1,0]
	v_pk_mul_f32 v[76:77], v[80:81], v[76:77] op_sel_hi:[1,0]
	v_pk_mul_f32 v[74:75], v[74:75], v[78:79]
	v_pk_mul_f32 v[72:73], v[72:73], v[76:77]
	v_pk_mul_f32 v[74:75], v[74:75], v[66:67]
	v_pk_mul_f32 v[66:67], v[72:73], v[64:65]
	v_cvt_pk_bf16_f32 v64, v68, v69
	v_cvt_pk_bf16_f32 v65, v70, v71
	v_max_f32_e32 v68, v60, v60
	v_max_f32_e32 v70, v62, v62
	v_max_f32_e32 v68, 0xc1a00000, v68
	v_max_f32_e32 v70, 0xc1a00000, v70
	v_mul_f32_e32 v68, 0xbfb8aa3b, v68
	v_mul_f32_e32 v70, 0xbfb8aa3b, v70
	v_exp_f32_e32 v69, v68
	v_max_f32_e32 v68, v61, v61
	v_exp_f32_e32 v71, v70
	v_max_f32_e32 v70, v63, v63
	v_max_f32_e32 v68, 0xc1a00000, v68
	v_max_f32_e32 v70, 0xc1a00000, v70
	v_mul_f32_e32 v68, 0xbfb8aa3b, v68
	v_mul_f32_e32 v70, 0xbfb8aa3b, v70
	v_exp_f32_e32 v68, v68
	v_exp_f32_e32 v70, v70
	v_cvt_pk_bf16_f32 v66, v66, v67
	v_cvt_pk_bf16_f32 v67, v74, v75
	global_store_dwordx4 v[86:87], v[64:67], off
	v_add_u32_e32 v72, 0x80, v155
	s_nop 0
	v_pk_add_f32 v[64:65], v[68:69], 1.0 op_sel_hi:[1,0]
	v_pk_add_f32 v[66:67], v[70:71], 1.0 op_sel_hi:[1,0]
	v_mov_b32_e32 v68, v65
	v_mov_b32_e32 v69, v67
	v_mov_b32_e32 v70, v64
	v_mov_b32_e32 v71, v66
	v_pk_mul_f32 v[68:69], v[68:69], v[70:71]
	s_nop 0
	v_mul_f32_e32 v70, v68, v69
	v_rcp_f32_e32 v73, v70
	v_mad_i64_i32 v[70:71], s[28:29], v72, s52, v[144:145]
	v_lshl_add_u64 v[70:71], v[70:71], 0, v[146:147]
	v_mul_f32_e32 v68, v68, v73
	v_mul_f32_e32 v72, v69, v73
	v_pk_mul_f32 v[66:67], v[66:67], v[68:69] op_sel_hi:[1,0]
	v_max_f32_e32 v68, v56, v56
	v_max_f32_e32 v73, v58, v58
	v_max_f32_e32 v68, 0xc1a00000, v68
	v_max_f32_e32 v73, 0xc1a00000, v73
	v_mul_f32_e32 v68, 0xbfb8aa3b, v68
	v_mul_f32_e32 v73, 0xbfb8aa3b, v73
	v_exp_f32_e32 v69, v68
	v_max_f32_e32 v68, v57, v57
	v_exp_f32_e32 v75, v73
	v_max_f32_e32 v73, v59, v59
	v_max_f32_e32 v68, 0xc1a00000, v68
	v_max_f32_e32 v73, 0xc1a00000, v73
	v_mul_f32_e32 v68, 0xbfb8aa3b, v68
	v_mul_f32_e32 v73, 0xbfb8aa3b, v73
	v_exp_f32_e32 v68, v68
	v_exp_f32_e32 v74, v73
	v_pk_mul_f32 v[64:65], v[64:65], v[72:73] op_sel_hi:[1,0]
	v_pk_mul_f32 v[62:63], v[62:63], v[66:67]
	v_pk_mul_f32 v[60:61], v[60:61], v[64:65]
	v_pk_add_f32 v[64:65], v[68:69], 1.0 op_sel_hi:[1,0]
	v_pk_add_f32 v[68:69], v[74:75], 1.0 op_sel_hi:[1,0]
	v_mov_b32_e32 v72, v65
	v_mov_b32_e32 v73, v69
	v_mov_b32_e32 v74, v64
	v_mov_b32_e32 v75, v68
	v_pk_mul_f32 v[72:73], v[72:73], v[74:75]
	v_pk_mul_f32 v[54:55], v[62:63], v[54:55]
	v_mul_f32_e32 v74, v72, v73
	v_rcp_f32_e32 v74, v74
	v_pk_mul_f32 v[52:53], v[60:61], v[52:53]
	v_mul_f32_e32 v60, v73, v74
	v_mul_f32_e32 v62, v72, v74
	v_pk_mul_f32 v[62:63], v[68:69], v[62:63] op_sel_hi:[1,0]
	v_pk_mul_f32 v[60:61], v[64:65], v[60:61] op_sel_hi:[1,0]
	v_pk_mul_f32 v[58:59], v[58:59], v[62:63]
	v_pk_mul_f32 v[56:57], v[56:57], v[60:61]
	v_pk_mul_f32 v[58:59], v[58:59], v[50:51]
	v_pk_mul_f32 v[50:51], v[56:57], v[48:49]
	v_cvt_pk_bf16_f32 v48, v52, v53
	v_cvt_pk_bf16_f32 v49, v54, v55
	v_max_f32_e32 v52, v44, v44
	v_max_f32_e32 v54, v46, v46
	v_max_f32_e32 v52, 0xc1a00000, v52
	v_max_f32_e32 v54, 0xc1a00000, v54
	v_mul_f32_e32 v52, 0xbfb8aa3b, v52
	v_mul_f32_e32 v54, 0xbfb8aa3b, v54
	v_exp_f32_e32 v53, v52
	v_max_f32_e32 v52, v45, v45
	v_exp_f32_e32 v55, v54
	v_max_f32_e32 v54, v47, v47
	v_max_f32_e32 v52, 0xc1a00000, v52
; __device__ __forceinline__ unsigned cvt_pk_bf16(float lo, float hi) { unsigned r; asm volatile("v_cvt_pk_bf16_f32 %0, %1, %2" : "=v"(r) : "v"(lo), "v"(hi)); return r; }
; __device__ __forceinline__ f32x4 sigmoid4(f32x4 x) {
;     f32x4 d;
; #pragma unroll
;     for (int j = 0; j < 4; ++j) d[j] = 1.0f + __expf(-fmaxf(x[j], -20.0f));
;     const float p01 = d[0] * d[1], p23 = d[2] * d[3], r = __builtin_amdgcn_rcpf(p01 * p23), r01 = r * p23, r23 = r * p01;
;     return (f32x4){r01 * d[1], r01 * d[0], r23 * d[3], r23 * d[2]};
; }
;     __device__ __forceinline__ void operator()(const f32x4 (&acc)[2][2][4][2], const Unit& u, int wr, int wc, int fr, int fq) const {
;     ...
;         for (int ai = 0; ai < 2; ++ai)
; #pragma unroll
;             for (int m = 0; m < 4; ++m) { bf16_t* rowp = O + (size_t)(row0 + ai * HALF + m * 16) * ldc + col0;
;                 f32x4 v0, v1;
; #pragma unroll
;                 for (int j = 0; j < 1; ++j) { v0 = acc[ai][0][m][0] * sigmoid4(acc[ai][0][m][0]) * acc[ai][1][m][0]; v1 = acc[ai][0][m][1] * sigmoid4(acc[ai][0][m][1]) * acc[ai][1][m][1]; }
;                 u32x4 w; w.x = cvt_pk_bf16(v0[0], v0[1]); w.y = cvt_pk_bf16(v0[2], v0[3]); w.z = cvt_pk_bf16(v1[0], v1[1]); w.w = cvt_pk_bf16(v1[2], v1[3]);
;                 *(u32x4*)rowp = w; }
	v_max_f32_e32 v54, 0xc1a00000, v54
	v_mul_f32_e32 v52, 0xbfb8aa3b, v52
	v_mul_f32_e32 v54, 0xbfb8aa3b, v54
	v_exp_f32_e32 v52, v52
	v_exp_f32_e32 v54, v54
	v_cvt_pk_bf16_f32 v50, v50, v51
	v_cvt_pk_bf16_f32 v51, v58, v59
	global_store_dwordx4 v[70:71], v[48:51], off
	v_add_u32_e32 v56, 0x90, v155
	s_nop 0
	v_pk_add_f32 v[48:49], v[52:53], 1.0 op_sel_hi:[1,0]
	v_pk_add_f32 v[50:51], v[54:55], 1.0 op_sel_hi:[1,0]
	v_mov_b32_e32 v52, v49
	v_mov_b32_e32 v53, v51
	v_mov_b32_e32 v54, v48
	v_mov_b32_e32 v55, v50
	v_pk_mul_f32 v[52:53], v[52:53], v[54:55]
	s_nop 0
	v_mul_f32_e32 v54, v52, v53
	v_rcp_f32_e32 v57, v54
	v_mad_i64_i32 v[54:55], s[28:29], v56, s52, v[144:145]
	v_lshl_add_u64 v[54:55], v[54:55], 0, v[146:147]
	v_mul_f32_e32 v52, v52, v57
	v_mul_f32_e32 v56, v53, v57
	v_pk_mul_f32 v[50:51], v[50:51], v[52:53] op_sel_hi:[1,0]
	v_max_f32_e32 v52, v40, v40
	v_max_f32_e32 v57, v42, v42
	v_max_f32_e32 v52, 0xc1a00000, v52
	v_max_f32_e32 v57, 0xc1a00000, v57
	v_mul_f32_e32 v52, 0xbfb8aa3b, v52
	v_mul_f32_e32 v57, 0xbfb8aa3b, v57
	v_exp_f32_e32 v53, v52
	v_max_f32_e32 v52, v41, v41
	v_exp_f32_e32 v59, v57
	v_max_f32_e32 v57, v43, v43
	v_max_f32_e32 v52, 0xc1a00000, v52
	v_max_f32_e32 v57, 0xc1a00000, v57
	v_mul_f32_e32 v52, 0xbfb8aa3b, v52
	v_mul_f32_e32 v57, 0xbfb8aa3b, v57
	v_exp_f32_e32 v52, v52
	v_exp_f32_e32 v58, v57
	v_pk_mul_f32 v[48:49], v[48:49], v[56:57] op_sel_hi:[1,0]
	v_pk_mul_f32 v[46:47], v[46:47], v[50:51]
	v_pk_mul_f32 v[44:45], v[44:45], v[48:49]
	v_pk_add_f32 v[48:49], v[52:53], 1.0 op_sel_hi:[1,0]
	v_pk_add_f32 v[52:53], v[58:59], 1.0 op_sel_hi:[1,0]
	v_mov_b32_e32 v56, v49
	v_mov_b32_e32 v57, v53
	v_mov_b32_e32 v58, v48
	v_mov_b32_e32 v59, v52
	v_pk_mul_f32 v[56:57], v[56:57], v[58:59]
	v_pk_mul_f32 v[38:39], v[46:47], v[38:39]
	v_mul_f32_e32 v58, v56, v57
	v_rcp_f32_e32 v58, v58
	v_pk_mul_f32 v[36:37], v[44:45], v[36:37]
	v_mul_f32_e32 v44, v57, v58
	v_mul_f32_e32 v46, v56, v58
	v_pk_mul_f32 v[46:47], v[52:53], v[46:47] op_sel_hi:[1,0]
	v_pk_mul_f32 v[44:45], v[48:49], v[44:45] op_sel_hi:[1,0]
	v_pk_mul_f32 v[42:43], v[42:43], v[46:47]
	v_pk_mul_f32 v[40:41], v[40:41], v[44:45]
	v_pk_mul_f32 v[42:43], v[42:43], v[34:35]
	v_pk_mul_f32 v[34:35], v[40:41], v[32:33]
	v_cvt_pk_bf16_f32 v32, v36, v37
	v_cvt_pk_bf16_f32 v33, v38, v39
	v_max_f32_e32 v36, v28, v28
	v_max_f32_e32 v38, v30, v30
	v_max_f32_e32 v36, 0xc1a00000, v36
	v_max_f32_e32 v38, 0xc1a00000, v38
	v_mul_f32_e32 v36, 0xbfb8aa3b, v36
	v_mul_f32_e32 v38, 0xbfb8aa3b, v38
	v_exp_f32_e32 v37, v36
	v_max_f32_e32 v36, v29, v29
	v_exp_f32_e32 v39, v38
	v_max_f32_e32 v38, v31, v31
	v_max_f32_e32 v36, 0xc1a00000, v36
	v_max_f32_e32 v38, 0xc1a00000, v38
	v_mul_f32_e32 v36, 0xbfb8aa3b, v36
	v_mul_f32_e32 v38, 0xbfb8aa3b, v38
	v_exp_f32_e32 v36, v36
	v_exp_f32_e32 v38, v38
	v_cvt_pk_bf16_f32 v34, v34, v35
	v_cvt_pk_bf16_f32 v35, v42, v43
	global_store_dwordx4 v[54:55], v[32:35], off
	v_add_u32_e32 v40, 0xa0, v155
	s_nop 0
	v_pk_add_f32 v[32:33], v[36:37], 1.0 op_sel_hi:[1,0]
	v_pk_add_f32 v[34:35], v[38:39], 1.0 op_sel_hi:[1,0]
	v_mov_b32_e32 v36, v33
	v_mov_b32_e32 v37, v35
	v_mov_b32_e32 v38, v32
	v_mov_b32_e32 v39, v34
	v_pk_mul_f32 v[36:37], v[36:37], v[38:39]
	s_nop 0
	v_mul_f32_e32 v38, v36, v37
	v_rcp_f32_e32 v41, v38
	v_mad_i64_i32 v[38:39], s[28:29], v40, s52, v[144:145]
	v_lshl_add_u64 v[38:39], v[38:39], 0, v[146:147]
	v_mul_f32_e32 v36, v36, v41
	v_mul_f32_e32 v40, v37, v41
	v_pk_mul_f32 v[34:35], v[34:35], v[36:37] op_sel_hi:[1,0]
	v_max_f32_e32 v36, v24, v24
	v_max_f32_e32 v41, v26, v26
	v_max_f32_e32 v36, 0xc1a00000, v36
	v_max_f32_e32 v41, 0xc1a00000, v41
	v_mul_f32_e32 v36, 0xbfb8aa3b, v36
	v_mul_f32_e32 v41, 0xbfb8aa3b, v41
	v_exp_f32_e32 v37, v36
	v_max_f32_e32 v36, v25, v25
	v_exp_f32_e32 v43, v41
	v_max_f32_e32 v41, v27, v27
	v_max_f32_e32 v36, 0xc1a00000, v36
	v_max_f32_e32 v41, 0xc1a00000, v41
	v_mul_f32_e32 v36, 0xbfb8aa3b, v36
; __device__ __forceinline__ unsigned cvt_pk_bf16(float lo, float hi) { unsigned r; asm volatile("v_cvt_pk_bf16_f32 %0, %1, %2" : "=v"(r) : "v"(lo), "v"(hi)); return r; }
; __device__ __forceinline__ f32x4 sigmoid4(f32x4 x) {
;     f32x4 d;
; #pragma unroll
;     for (int j = 0; j < 4; ++j) d[j] = 1.0f + __expf(-fmaxf(x[j], -20.0f));
;     const float p01 = d[0] * d[1], p23 = d[2] * d[3], r = __builtin_amdgcn_rcpf(p01 * p23), r01 = r * p23, r23 = r * p01;
;     return (f32x4){r01 * d[1], r01 * d[0], r23 * d[3], r23 * d[2]};
; }
;     __device__ __forceinline__ void operator()(const f32x4 (&acc)[2][2][4][2], const Unit& u, int wr, int wc, int fr, int fq) const {
;     ...
;         for (int ai = 0; ai < 2; ++ai)
; #pragma unroll
;             for (int m = 0; m < 4; ++m) { bf16_t* rowp = O + (size_t)(row0 + ai * HALF + m * 16) * ldc + col0;
;                 f32x4 v0, v1;
; #pragma unroll
;                 for (int j = 0; j < 1; ++j) { v0 = acc[ai][0][m][0] * sigmoid4(acc[ai][0][m][0]) * acc[ai][1][m][0]; v1 = acc[ai][0][m][1] * sigmoid4(acc[ai][0][m][1]) * acc[ai][1][m][1]; }
;                 u32x4 w; w.x = cvt_pk_bf16(v0[0], v0[1]); w.y = cvt_pk_bf16(v0[2], v0[3]); w.z = cvt_pk_bf16(v1[0], v1[1]); w.w = cvt_pk_bf16(v1[2], v1[3]);
;                 *(u32x4*)rowp = w; }
	v_mul_f32_e32 v41, 0xbfb8aa3b, v41
	v_exp_f32_e32 v36, v36
	v_exp_f32_e32 v42, v41
	v_pk_mul_f32 v[32:33], v[32:33], v[40:41] op_sel_hi:[1,0]
	v_pk_mul_f32 v[30:31], v[30:31], v[34:35]
	v_pk_mul_f32 v[28:29], v[28:29], v[32:33]
	v_pk_add_f32 v[32:33], v[36:37], 1.0 op_sel_hi:[1,0]
	v_pk_add_f32 v[36:37], v[42:43], 1.0 op_sel_hi:[1,0]
	v_mov_b32_e32 v40, v33
	v_mov_b32_e32 v41, v37
	v_mov_b32_e32 v42, v32
	v_mov_b32_e32 v43, v36
	v_pk_mul_f32 v[40:41], v[40:41], v[42:43]
	v_pk_mul_f32 v[22:23], v[30:31], v[22:23]
	v_mul_f32_e32 v42, v40, v41
	v_rcp_f32_e32 v42, v42
	v_pk_mul_f32 v[20:21], v[28:29], v[20:21]
	v_mul_f32_e32 v28, v41, v42
	v_mul_f32_e32 v30, v40, v42
	v_pk_mul_f32 v[30:31], v[36:37], v[30:31] op_sel_hi:[1,0]
	v_pk_mul_f32 v[28:29], v[32:33], v[28:29] op_sel_hi:[1,0]
	v_pk_mul_f32 v[26:27], v[26:27], v[30:31]
	v_pk_mul_f32 v[24:25], v[24:25], v[28:29]
	v_pk_mul_f32 v[26:27], v[26:27], v[18:19]
	v_pk_mul_f32 v[18:19], v[24:25], v[16:17]
	v_cvt_pk_bf16_f32 v16, v20, v21
	v_cvt_pk_bf16_f32 v17, v22, v23
	v_max_f32_e32 v20, v12, v12
	v_max_f32_e32 v22, v14, v14
	v_max_f32_e32 v20, 0xc1a00000, v20
	v_max_f32_e32 v22, 0xc1a00000, v22
	v_mul_f32_e32 v20, 0xbfb8aa3b, v20
	v_mul_f32_e32 v22, 0xbfb8aa3b, v22
	v_exp_f32_e32 v21, v20
	v_max_f32_e32 v20, v13, v13
	v_exp_f32_e32 v23, v22
	v_max_f32_e32 v22, v15, v15
	v_max_f32_e32 v20, 0xc1a00000, v20
	v_max_f32_e32 v22, 0xc1a00000, v22
	v_mul_f32_e32 v20, 0xbfb8aa3b, v20
	v_mul_f32_e32 v22, 0xbfb8aa3b, v22
	v_exp_f32_e32 v20, v20
	v_exp_f32_e32 v22, v22
	v_cvt_pk_bf16_f32 v18, v18, v19
	v_cvt_pk_bf16_f32 v19, v26, v27
	global_store_dwordx4 v[38:39], v[16:19], off
	v_add_u32_e32 v24, 0xb0, v155
	s_nop 0
	v_pk_add_f32 v[16:17], v[20:21], 1.0 op_sel_hi:[1,0]
	v_pk_add_f32 v[18:19], v[22:23], 1.0 op_sel_hi:[1,0]
	v_mov_b32_e32 v20, v17
	v_mov_b32_e32 v21, v19
	v_mov_b32_e32 v22, v16
	v_mov_b32_e32 v23, v18
	v_pk_mul_f32 v[20:21], v[20:21], v[22:23]
	s_nop 0
	v_mul_f32_e32 v22, v20, v21
	v_rcp_f32_e32 v25, v22
	v_mad_i64_i32 v[22:23], s[28:29], v24, s52, v[144:145]
	v_lshl_add_u64 v[22:23], v[22:23], 0, v[146:147]
	v_mul_f32_e32 v20, v20, v25
	v_mul_f32_e32 v24, v21, v25
	v_pk_mul_f32 v[18:19], v[18:19], v[20:21] op_sel_hi:[1,0]
	v_max_f32_e32 v20, v8, v8
	v_max_f32_e32 v25, v10, v10
	v_max_f32_e32 v20, 0xc1a00000, v20
	v_max_f32_e32 v25, 0xc1a00000, v25
	v_mul_f32_e32 v20, 0xbfb8aa3b, v20
	v_mul_f32_e32 v25, 0xbfb8aa3b, v25
	v_exp_f32_e32 v21, v20
	v_max_f32_e32 v20, v9, v9
	v_exp_f32_e32 v27, v25
	v_max_f32_e32 v25, v11, v11
	v_max_f32_e32 v20, 0xc1a00000, v20
	v_max_f32_e32 v25, 0xc1a00000, v25
	v_mul_f32_e32 v20, 0xbfb8aa3b, v20
	v_mul_f32_e32 v25, 0xbfb8aa3b, v25
	v_exp_f32_e32 v20, v20
	v_exp_f32_e32 v26, v25
	v_pk_mul_f32 v[16:17], v[16:17], v[24:25] op_sel_hi:[1,0]
	v_pk_mul_f32 v[14:15], v[14:15], v[18:19]
	v_pk_mul_f32 v[12:13], v[12:13], v[16:17]
	v_pk_add_f32 v[16:17], v[20:21], 1.0 op_sel_hi:[1,0]
	v_pk_add_f32 v[20:21], v[26:27], 1.0 op_sel_hi:[1,0]
	v_mov_b32_e32 v24, v17
	v_mov_b32_e32 v25, v21
	v_mov_b32_e32 v26, v16
	v_mov_b32_e32 v27, v20
	v_pk_mul_f32 v[24:25], v[24:25], v[26:27]
	v_pk_mul_f32 v[6:7], v[14:15], v[6:7]
	v_mul_f32_e32 v26, v24, v25
	v_rcp_f32_e32 v26, v26
	v_pk_mul_f32 v[4:5], v[12:13], v[4:5]
	s_mov_b64 s[28:29], s[18:19]
	v_mul_f32_e32 v12, v25, v26
	v_mul_f32_e32 v14, v24, v26
	v_pk_mul_f32 v[14:15], v[20:21], v[14:15] op_sel_hi:[1,0]
	v_pk_mul_f32 v[12:13], v[16:17], v[12:13] op_sel_hi:[1,0]
	v_pk_mul_f32 v[10:11], v[10:11], v[14:15]
	v_pk_mul_f32 v[8:9], v[8:9], v[12:13]
	v_pk_mul_f32 v[10:11], v[10:11], v[2:3]
	v_pk_mul_f32 v[2:3], v[8:9], v[0:1]
	v_cvt_pk_bf16_f32 v0, v4, v5
	v_cvt_pk_bf16_f32 v1, v6, v7
	s_nop 0
	v_cvt_pk_bf16_f32 v2, v2, v3
	v_cvt_pk_bf16_f32 v3, v10, v11
	global_store_dwordx4 v[22:23], v[0:3], off
	s_cbranch_vccz .LBB0_192
	s_waitcnt vmcnt(0)
	s_cmpk_gt_u32 s37, 0xff
	s_cbranch_scc1 .LBB0_199
	s_barrier

; #define PG8_STAGE(bufoff, gbase, voff) do { _Pragma("unroll") for (int _i = 0; _i < 2; ++_i) \
;         __builtin_amdgcn_global_load_lds((const unsigned*)((const char*)(gbase) + (voff)[_i]), (PG8_LAS unsigned*)(lds + (bufoff) + ldsw + _i * 8192), 16, 0, 0); } while (0)
; #define PG8_LDA(dst, b, h) do { _Pragma("unroll") for (int m = 0; m < 4; ++m) _Pragma("unroll") for (int k = 0; k < 2; ++k) dst[m][k] = *(const PG8_LAS bf16x8*)(lds + PG8_SA(b, h) + aoff + m * 2048 + k * 1024); } while (0)
; #define PG8_LDB(dst, b, h) do { _Pragma("unroll") for (int n = 0; n < 2; ++n) _Pragma("unroll") for (int k = 0; k < 2; ++k) dst[n][k] = *(const PG8_LAS bf16x8*)(lds + PG8_SB(b, h) + boff + n * 2048 + k * 1024); } while (0)
; #define PG8_MMA(ai, bj, At, Bt) do { __builtin_amdgcn_s_setprio(1); _Pragma("unroll") for (int m = 0; m < 4; ++m) _Pragma("unroll") for (int n = 0; n < 2; ++n) _Pragma("unroll") for (int k = 0; k < 2; ++k) \
;         acc[ai][bj][m][n] = __builtin_amdgcn_mfma_f32_16x16x32_bf16(Bt[n][k], At[m][k], acc[ai][bj][m][n], 0, 0, 0); __builtin_amdgcn_s_setprio(0); } while (0)
; #define PG8_WAIT_V(n) asm volatile("s_waitcnt vmcnt(" #n ")" ::: "memory")
; #define PG8_WAIT_L(n) asm volatile("s_waitcnt lgkmcnt(" #n ")" ::: "memory")
; #define PG8_BAR __builtin_amdgcn_s_barrier()
; #define PG8_SCHED __builtin_amdgcn_sched_barrier(0)
; template <class Epi, class Sched>
; __device__ __forceinline__ void gemm_phase(PG8_LAS unsigned char* lds, const Gemm g, const Sched& S, const Epi& E) {
;     ...
;             PG8_LDB(B0, 0, 0); PG8_SCHED; PG8_LDA(At, 0, 0); PG8_STAGE(PG8_SA(1, 1), a1 + hstep, voffA);
;             PG8_WAIT_L(8); PG8_BAR; PG8_WAIT_L(0); PG8_MMA(0, 0, At, B0); PG8_BAR; PG8_SCHED;
;             PG8_LDB(B1, 0, 1); PG8_STAGE(PG8_SB(0, 0), b2, voffB);
;             PG8_BAR; PG8_WAIT_L(0); PG8_MMA(0, 1, At, B1); PG8_BAR;
;             PG8_LDA(At, 0, 1); PG8_STAGE(PG8_SA(0, 0), a2, voffA);
;             PG8_BAR; PG8_WAIT_L(0); PG8_MMA(1, 0, At, B0); PG8_BAR; PG8_SCHED;
;             PG8_STAGE(PG8_SB(0, 1), b2 + hstep, voffB);
;             PG8_WAIT_V(6); PG8_BAR; PG8_MMA(1, 1, At, B1); PG8_BAR;
.LBB0_286:
	ds_read_b128 v[154:157], v149
	ds_read_b128 v[158:161], v149 offset:1024
	ds_read_b128 v[166:169], v149 offset:2048
	ds_read_b128 v[170:173], v149 offset:3072
	s_add_u32 s24, s22, 0x100
	s_addc_u32 s25, s23, 0
	s_cmp_eq_u32 s57, 40
	s_cselect_b32 s29, s1, s25
	s_cselect_b32 s28, s0, s24
	s_cselect_b32 s27, s5, s56
	s_cselect_b32 s26, s4, s55
	v_lshl_add_u64 v[144:145], s[22:23], 0, v[136:137]
	s_add_i32 m0, s38, 0xc000
	ds_read_b128 v[182:185], v150
	ds_read_b128 v[190:193], v150 offset:1024
	ds_read_b128 v[194:197], v150 offset:2048
	ds_read_b128 v[198:201], v150 offset:3072
	ds_read_b128 v[202:205], v150 offset:4096
	ds_read_b128 v[206:209], v150 offset:5120
	ds_read_b128 v[210:213], v150 offset:6144
	ds_read_b128 v[214:217], v150 offset:7168
	global_load_lds_dwordx4 v[144:145], off
	v_lshl_add_u64 v[144:145], s[22:23], 0, v[138:139]
	s_add_i32 m0, s38, 0xe000
	s_nop 0
	global_load_lds_dwordx4 v[144:145], off
	s_waitcnt lgkmcnt(8)
	s_barrier
	s_waitcnt lgkmcnt(0)
	v_mfma_f32_16x16x32_bf16 v[124:127], v[154:157], v[182:185], v[124:127]
	v_mfma_f32_16x16x32_bf16 v[120:123], v[166:169], v[182:185], v[120:123]
	v_mfma_f32_16x16x32_bf16 v[108:111], v[154:157], v[194:197], v[108:111]
	v_mfma_f32_16x16x32_bf16 v[104:107], v[166:169], v[194:197], v[104:107]
	v_mfma_f32_16x16x32_bf16 v[92:95], v[154:157], v[202:205], v[92:95]
	v_mfma_f32_16x16x32_bf16 v[88:91], v[166:169], v[202:205], v[88:91]
	v_mfma_f32_16x16x32_bf16 v[76:79], v[154:157], v[210:213], v[76:79]
	v_mfma_f32_16x16x32_bf16 v[72:75], v[166:169], v[210:213], v[72:75]
	v_mfma_f32_16x16x32_bf16 v[124:127], v[158:161], v[190:193], v[124:127]
	v_mfma_f32_16x16x32_bf16 v[120:123], v[170:173], v[190:193], v[120:123]
	v_mfma_f32_16x16x32_bf16 v[108:111], v[158:161], v[198:201], v[108:111]
	v_mfma_f32_16x16x32_bf16 v[104:107], v[170:173], v[198:201], v[104:107]
	v_mfma_f32_16x16x32_bf16 v[92:95], v[158:161], v[206:209], v[92:95]
	v_mfma_f32_16x16x32_bf16 v[88:91], v[170:173], v[206:209], v[88:91]
	v_mfma_f32_16x16x32_bf16 v[76:79], v[158:161], v[214:217], v[76:79]
	v_mfma_f32_16x16x32_bf16 v[72:75], v[170:173], v[214:217], v[72:75]
	s_barrier
	s_add_i32 s22, s46, s37
	v_lshl_add_u64 v[144:145], s[26:27], 0, v[130:131]
	s_mov_b32 m0, s22
	ds_read_b128 v[218:221], v151
	ds_read_b128 v[222:225], v151 offset:1024
	ds_read_b128 v[226:229], v151 offset:2048
	ds_read_b128 v[230:233], v151 offset:3072
	global_load_lds_dwordx4 v[144:145], off
	v_lshl_add_u64 v[162:163], s[26:27], 0, v[134:135]
	s_add_i32 m0, s22, 0x2000
	s_nop 0
	global_load_lds_dwordx4 v[162:163], off
	s_barrier
	s_waitcnt lgkmcnt(0)
	v_mfma_f32_16x16x32_bf16 v[116:119], v[218:221], v[182:185], v[116:119]
	v_mfma_f32_16x16x32_bf16 v[112:115], v[226:229], v[182:185], v[112:115]
	v_mfma_f32_16x16x32_bf16 v[100:103], v[218:221], v[194:197], v[100:103]
	v_mfma_f32_16x16x32_bf16 v[96:99], v[226:229], v[194:197], v[96:99]
	v_mfma_f32_16x16x32_bf16 v[84:87], v[218:221], v[202:205], v[84:87]
	v_mfma_f32_16x16x32_bf16 v[80:83], v[226:229], v[202:205], v[80:83]
	v_mfma_f32_16x16x32_bf16 v[68:71], v[218:221], v[210:213], v[68:71]
	v_mfma_f32_16x16x32_bf16 v[64:67], v[226:229], v[210:213], v[64:67]
	v_mfma_f32_16x16x32_bf16 v[116:119], v[222:225], v[190:193], v[116:119]
	v_mfma_f32_16x16x32_bf16 v[112:115], v[230:233], v[190:193], v[112:115]
	v_mfma_f32_16x16x32_bf16 v[100:103], v[222:225], v[198:201], v[100:103]
	v_mfma_f32_16x16x32_bf16 v[96:99], v[230:233], v[198:201], v[96:99]
	v_mfma_f32_16x16x32_bf16 v[84:87], v[222:225], v[206:209], v[84:87]
	v_mfma_f32_16x16x32_bf16 v[80:83], v[230:233], v[206:209], v[80:83]
	v_mfma_f32_16x16x32_bf16 v[68:71], v[222:225], v[214:217], v[68:71]
	v_mfma_f32_16x16x32_bf16 v[64:67], v[230:233], v[214:217], v[64:67]
	s_barrier
	s_mov_b32 m0, s38
	v_lshl_add_u64 v[174:175], s[28:29], 0, v[128:129]
	ds_read_b128 v[182:185], v150 offset:16384
	ds_read_b128 v[190:193], v150 offset:17408
	ds_read_b128 v[194:197], v150 offset:18432
	ds_read_b128 v[198:201], v150 offset:19456
	ds_read_b128 v[202:205], v150 offset:20480
	ds_read_b128 v[206:209], v150 offset:21504
	ds_read_b128 v[210:213], v150 offset:22528
	ds_read_b128 v[214:217], v150 offset:23552
	global_load_lds_dwordx4 v[174:175], off
	v_lshl_add_u64 v[178:179], s[28:29], 0, v[132:133]
	s_mov_b32 m0, s39
	s_nop 0
	global_load_lds_dwordx4 v[178:179], off
	s_barrier
	s_waitcnt lgkmcnt(0)
	v_mfma_f32_16x16x32_bf16 v[60:63], v[154:157], v[182:185], v[60:63]
	v_mfma_f32_16x16x32_bf16 v[56:59], v[166:169], v[182:185], v[56:59]
	v_mfma_f32_16x16x32_bf16 v[48:51], v[154:157], v[194:197], v[48:51]
	v_mfma_f32_16x16x32_bf16 v[40:43], v[166:169], v[194:197], v[40:43]
	v_mfma_f32_16x16x32_bf16 v[32:35], v[154:157], v[202:205], v[32:35]
	v_mfma_f32_16x16x32_bf16 v[24:27], v[166:169], v[202:205], v[24:27]
	v_mfma_f32_16x16x32_bf16 v[16:19], v[154:157], v[210:213], v[16:19]
	v_mfma_f32_16x16x32_bf16 v[8:11], v[166:169], v[210:213], v[8:11]
	v_mfma_f32_16x16x32_bf16 v[60:63], v[158:161], v[190:193], v[60:63]
	v_mfma_f32_16x16x32_bf16 v[56:59], v[170:173], v[190:193], v[56:59]
	v_mfma_f32_16x16x32_bf16 v[48:51], v[158:161], v[198:201], v[48:51]
	v_mfma_f32_16x16x32_bf16 v[40:43], v[170:173], v[198:201], v[40:43]
	v_mfma_f32_16x16x32_bf16 v[32:35], v[158:161], v[206:209], v[32:35]
	v_mfma_f32_16x16x32_bf16 v[24:27], v[170:173], v[206:209], v[24:27]
	v_mfma_f32_16x16x32_bf16 v[16:19], v[158:161], v[214:217], v[16:19]
	v_mfma_f32_16x16x32_bf16 v[8:11], v[170:173], v[214:217], v[8:11]
	s_barrier
; #define PG8_STAGE(bufoff, gbase, voff) do { _Pragma("unroll") for (int _i = 0; _i < 2; ++_i) \
;         __builtin_amdgcn_global_load_lds((const unsigned*)((const char*)(gbase) + (voff)[_i]), (PG8_LAS unsigned*)(lds + (bufoff) + ldsw + _i * 8192), 16, 0, 0); } while (0)
; #define PG8_LDA(dst, b, h) do { _Pragma("unroll") for (int m = 0; m < 4; ++m) _Pragma("unroll") for (int k = 0; k < 2; ++k) dst[m][k] = *(const PG8_LAS bf16x8*)(lds + PG8_SA(b, h) + aoff + m * 2048 + k * 1024); } while (0)
; #define PG8_LDB(dst, b, h) do { _Pragma("unroll") for (int n = 0; n < 2; ++n) _Pragma("unroll") for (int k = 0; k < 2; ++k) dst[n][k] = *(const PG8_LAS bf16x8*)(lds + PG8_SB(b, h) + boff + n * 2048 + k * 1024); } while (0)
; #define PG8_MMA(ai, bj, At, Bt) do { __builtin_amdgcn_s_setprio(1); _Pragma("unroll") for (int m = 0; m < 4; ++m) _Pragma("unroll") for (int n = 0; n < 2; ++n) _Pragma("unroll") for (int k = 0; k < 2; ++k) \
;         acc[ai][bj][m][n] = __builtin_amdgcn_mfma_f32_16x16x32_bf16(Bt[n][k], At[m][k], acc[ai][bj][m][n], 0, 0, 0); __builtin_amdgcn_s_setprio(0); } while (0)
; #define PG8_WAIT_V(n) asm volatile("s_waitcnt vmcnt(" #n ")" ::: "memory")
; #define PG8_WAIT_L(n) asm volatile("s_waitcnt lgkmcnt(" #n ")" ::: "memory")
; #define PG8_BAR __builtin_amdgcn_s_barrier()
; #define PG8_SCHED __builtin_amdgcn_sched_barrier(0)
; template <class Epi, class Sched>
; __device__ __forceinline__ void gemm_phase(PG8_LAS unsigned char* lds, const Gemm g, const Sched& S, const Epi& E) {
;     ...
;             PG8_STAGE(PG8_SB(0, 1), b2 + hstep, voffB);
;             PG8_WAIT_V(6); PG8_BAR; PG8_MMA(1, 1, At, B1); PG8_BAR;
;             PG8_LDB(B0, 1, 0); PG8_SCHED; PG8_LDA(At, 1, 0); PG8_STAGE(PG8_SA(0, 1), a2 + hstep, voffA);
;             PG8_WAIT_L(8); PG8_BAR; PG8_WAIT_L(0); PG8_MMA(0, 0, At, B0); PG8_BAR; PG8_SCHED;
;             PG8_LDB(B1, 1, 1); PG8_STAGE(PG8_SB(1, 0), b3, voffB);
;             PG8_BAR; PG8_WAIT_L(0); PG8_MMA(0, 1, At, B1); PG8_BAR;
;             PG8_LDA(At, 1, 1); PG8_STAGE(PG8_SA(1, 0), a3, voffA);
	s_add_u32 s22, s26, 0xb0000
	s_addc_u32 s23, s27, 0
	s_add_i32 s58, s47, s37
	v_lshl_add_u64 v[154:155], s[22:23], 0, v[130:131]
	s_mov_b32 m0, s58
	s_nop 0
	global_load_lds_dwordx4 v[154:155], off
	v_lshl_add_u64 v[154:155], s[22:23], 0, v[134:135]
	s_add_i32 m0, s58, 0x2000
	s_nop 0
	global_load_lds_dwordx4 v[154:155], off
	s_waitcnt vmcnt(6)
	s_barrier
	v_mfma_f32_16x16x32_bf16 v[52:55], v[218:221], v[182:185], v[52:55]
	v_mfma_f32_16x16x32_bf16 v[44:47], v[226:229], v[182:185], v[44:47]
	v_mfma_f32_16x16x32_bf16 v[36:39], v[218:221], v[194:197], v[36:39]
	v_mfma_f32_16x16x32_bf16 v[28:31], v[226:229], v[194:197], v[28:31]
	v_mfma_f32_16x16x32_bf16 v[20:23], v[218:221], v[202:205], v[20:23]
	v_mfma_f32_16x16x32_bf16 v[12:15], v[226:229], v[202:205], v[12:15]
	v_mfma_f32_16x16x32_bf16 v[4:7], v[218:221], v[210:213], v[4:7]
	v_mfma_f32_16x16x32_bf16 v[0:3], v[226:229], v[210:213], v[0:3]
	v_mfma_f32_16x16x32_bf16 v[52:55], v[222:225], v[190:193], v[52:55]
	v_mfma_f32_16x16x32_bf16 v[44:47], v[230:233], v[190:193], v[44:47]
	v_mfma_f32_16x16x32_bf16 v[36:39], v[222:225], v[198:201], v[36:39]
	v_mfma_f32_16x16x32_bf16 v[28:31], v[230:233], v[198:201], v[28:31]
	v_mfma_f32_16x16x32_bf16 v[20:23], v[222:225], v[206:209], v[20:23]
	v_mfma_f32_16x16x32_bf16 v[12:15], v[230:233], v[206:209], v[12:15]
	v_mfma_f32_16x16x32_bf16 v[4:7], v[222:225], v[214:217], v[4:7]
	v_mfma_f32_16x16x32_bf16 v[0:3], v[230:233], v[214:217], v[0:3]
	s_barrier
	s_add_i32 s58, 0, 0x18000
	v_add_u32_e32 v153, s58, v147
	ds_read_b128 v[154:157], v153
	ds_read_b128 v[158:161], v153 offset:1024
	ds_read_b128 v[166:169], v153 offset:2048
	ds_read_b128 v[170:173], v153 offset:3072
	s_add_u32 s22, s28, 0xb0000
	s_addc_u32 s23, s29, 0
	s_mov_b32 m0, s40
	v_lshl_add_u64 v[186:187], s[22:23], 0, v[128:129]
	ds_read_b128 v[182:185], v150 offset:32768
	ds_read_b128 v[190:193], v150 offset:33792
	ds_read_b128 v[194:197], v150 offset:34816
	ds_read_b128 v[198:201], v150 offset:35840
	ds_read_b128 v[202:205], v150 offset:36864
	ds_read_b128 v[206:209], v150 offset:37888
	ds_read_b128 v[210:213], v150 offset:38912
	ds_read_b128 v[214:217], v150 offset:39936
	global_load_lds_dwordx4 v[186:187], off
	v_lshl_add_u64 v[186:187], s[22:23], 0, v[132:133]
	s_mov_b32 m0, s41
	s_nop 0
	global_load_lds_dwordx4 v[186:187], off
	s_waitcnt lgkmcnt(8)
	s_barrier
	s_waitcnt lgkmcnt(0)
	v_mfma_f32_16x16x32_bf16 v[124:127], v[154:157], v[182:185], v[124:127]
	v_mfma_f32_16x16x32_bf16 v[120:123], v[166:169], v[182:185], v[120:123]
	v_mfma_f32_16x16x32_bf16 v[108:111], v[154:157], v[194:197], v[108:111]
	v_mfma_f32_16x16x32_bf16 v[104:107], v[166:169], v[194:197], v[104:107]
	v_mfma_f32_16x16x32_bf16 v[92:95], v[154:157], v[202:205], v[92:95]
	v_mfma_f32_16x16x32_bf16 v[88:91], v[166:169], v[202:205], v[88:91]
	v_mfma_f32_16x16x32_bf16 v[76:79], v[154:157], v[210:213], v[76:79]
	v_mfma_f32_16x16x32_bf16 v[72:75], v[166:169], v[210:213], v[72:75]
	v_mfma_f32_16x16x32_bf16 v[124:127], v[158:161], v[190:193], v[124:127]
	v_mfma_f32_16x16x32_bf16 v[120:123], v[170:173], v[190:193], v[120:123]
	v_mfma_f32_16x16x32_bf16 v[108:111], v[158:161], v[198:201], v[108:111]
	v_mfma_f32_16x16x32_bf16 v[104:107], v[170:173], v[198:201], v[104:107]
	v_mfma_f32_16x16x32_bf16 v[92:95], v[158:161], v[206:209], v[92:95]
	v_mfma_f32_16x16x32_bf16 v[88:91], v[170:173], v[206:209], v[88:91]
	v_mfma_f32_16x16x32_bf16 v[76:79], v[158:161], v[214:217], v[76:79]
	v_mfma_f32_16x16x32_bf16 v[72:75], v[170:173], v[214:217], v[72:75]
	s_barrier
	s_add_i32 s28, 0, 0x1c000
	s_add_i32 s22, s58, s37
	v_add_u32_e32 v153, s28, v147
	v_lshl_add_u64 v[144:145], v[144:145], 0, s[14:15]
	s_mov_b32 m0, s22
	ds_read_b128 v[218:221], v153
	ds_read_b128 v[222:225], v153 offset:1024
	ds_read_b128 v[226:229], v153 offset:2048
	ds_read_b128 v[230:233], v153 offset:3072
	global_load_lds_dwordx4 v[144:145], off
	v_lshl_add_u64 v[144:145], v[162:163], 0, s[14:15]
	s_add_i32 m0, s22, 0x2000
	s_nop 0
	global_load_lds_dwordx4 v[144:145], off
	s_barrier
	s_waitcnt lgkmcnt(0)
	v_mfma_f32_16x16x32_bf16 v[116:119], v[218:221], v[182:185], v[116:119]
	v_mfma_f32_16x16x32_bf16 v[112:115], v[226:229], v[182:185], v[112:115]
	v_mfma_f32_16x16x32_bf16 v[100:103], v[218:221], v[194:197], v[100:103]
	v_mfma_f32_16x16x32_bf16 v[96:99], v[226:229], v[194:197], v[96:99]
	v_mfma_f32_16x16x32_bf16 v[84:87], v[218:221], v[202:205], v[84:87]
	v_mfma_f32_16x16x32_bf16 v[80:83], v[226:229], v[202:205], v[80:83]
	v_mfma_f32_16x16x32_bf16 v[68:71], v[218:221], v[210:213], v[68:71]
	v_mfma_f32_16x16x32_bf16 v[64:67], v[226:229], v[210:213], v[64:67]
	v_mfma_f32_16x16x32_bf16 v[116:119], v[222:225], v[190:193], v[116:119]
	v_mfma_f32_16x16x32_bf16 v[112:115], v[230:233], v[190:193], v[112:115]
	v_mfma_f32_16x16x32_bf16 v[100:103], v[222:225], v[198:201], v[100:103]
	v_mfma_f32_16x16x32_bf16 v[96:99], v[230:233], v[198:201], v[96:99]
	v_mfma_f32_16x16x32_bf16 v[84:87], v[222:225], v[206:209], v[84:87]
	v_mfma_f32_16x16x32_bf16 v[80:83], v[230:233], v[206:209], v[80:83]
	v_mfma_f32_16x16x32_bf16 v[68:71], v[222:225], v[214:217], v[68:71]
	v_mfma_f32_16x16x32_bf16 v[64:67], v[230:233], v[214:217], v[64:67]
	s_barrier
	s_mov_b32 m0, s43
	v_lshl_add_u64 v[144:145], v[174:175], 0, s[14:15]
	ds_read_b128 v[182:185], v150 offset:49152
	ds_read_b128 v[190:193], v150 offset:50176
	ds_read_b128 v[194:197], v150 offset:51200
	ds_read_b128 v[198:201], v150 offset:52224
	ds_read_b128 v[202:205], v150 offset:53248
	ds_read_b128 v[206:209], v150 offset:54272
	ds_read_b128 v[210:213], v150 offset:55296
	ds_read_b128 v[214:217], v150 offset:56320
	global_load_lds_dwordx4 v[144:145], off
	v_lshl_add_u64 v[144:145], v[178:179], 0, s[14:15]
	s_mov_b32 m0, s44
	s_nop 0
	global_load_lds_dwordx4 v[144:145], off
	s_barrier
; __device__ __forceinline__ unsigned cvt_pk_bf16(float lo, float hi) { unsigned r; asm volatile("v_cvt_pk_bf16_f32 %0, %1, %2" : "=v"(r) : "v"(lo), "v"(hi)); return r; }
; __device__ __forceinline__ float flogsig16(float x) { return (fminf(x, 0.f) - __logf(1.0f + __expf(-fabsf(x)))) * 0.0625f; }
; #define PG8_WAIT_V(n) asm volatile("s_waitcnt vmcnt(" #n ")" ::: "memory")
; #define PG8_WAIT_L(n) asm volatile("s_waitcnt lgkmcnt(" #n ")" ::: "memory")
;     __device__ __forceinline__ void operator()(const f32x4 (&acc)[2][2][4][2], const Unit& u, int wr, int wc, int fr, int fq) const {
;     ...
;         const int row0 = u.pm * BM + wr * 64 + fr, col0 = u.pn * BM + wc * 32 + 8 * fq, bcol0 = wc * 32 + 8 * fq;
;         f32x4 bv[2][2];
; #pragma unroll
;         for (int bj = 0; bj < 2; ++bj)
; #pragma unroll
;             for (int n = 0; n < 2; ++n) bv[bj][n] = bias ? *(const f32x4*)(bias + bcol0 + bj * HALF + 4 * n) : (f32x4){0.f, 0.f, 0.f, 0.f};
; #pragma unroll
;         for (int ai = 0; ai < 2; ++ai)
; #pragma unroll
;             for (int m = 0; m < 4; ++m) { bf16_t* rowp = O + (size_t)(row0 + ai * HALF + m * 16) * ldc + col0;
; #pragma unroll
;                 for (int bj = 0; bj < 2; ++bj) { f32x4 v0 = acc[ai][bj][m][0] + bv[bj][0], v1 = acc[ai][bj][m][1] + bv[bj][1];
;                     if (act == 1) {
; #pragma unroll
;                         for (int j = 0; j < 1; ++j) { v0 = v0 * sigmoid4(v0); v1 = v1 * sigmoid4(v1); } }
;                     else if (act == 2) {
; #pragma unroll
;                         for (int j = 0; j < 1; ++j) { v0 = sigmoid4(v0); v1 = sigmoid4(v1); } }
;                     else if (act == 3) {
; #pragma unroll
;                         for (int j = 0; j < 4; ++j) { v0[j] = flogsig16(v0[j]); v1[j] = flogsig16(v1[j]); } }
;                     u32x4 w; w.x = cvt_pk_bf16(v0[0], v0[1]); w.y = cvt_pk_bf16(v0[2], v0[3]); w.z = cvt_pk_bf16(v1[0], v1[1]); w.w = cvt_pk_bf16(v1[2], v1[3]);
;                     *(u32x4*)(rowp + bj * HALF) = w; } }
; template <class Epi, class Sched>
; __device__ __forceinline__ void gemm_phase(PG8_LAS unsigned char* lds, const Gemm g, const Sched& S, const Epi& E) {
;     ...
;             PG8_BAR; PG8_WAIT_L(0); PG8_MMA(1, 0, At, B0); PG8_BAR; PG8_SCHED;
;             PG8_STAGE(PG8_SB(1, 1), b3 + hstep, voffB);
;             PG8_WAIT_V(6); PG8_BAR; PG8_MMA(1, 1, At, B1); PG8_BAR;
	s_waitcnt lgkmcnt(0)
	v_mfma_f32_16x16x32_bf16 v[60:63], v[154:157], v[182:185], v[60:63]
	v_mfma_f32_16x16x32_bf16 v[56:59], v[166:169], v[182:185], v[56:59]
	v_mfma_f32_16x16x32_bf16 v[48:51], v[154:157], v[194:197], v[48:51]
	v_mfma_f32_16x16x32_bf16 v[40:43], v[166:169], v[194:197], v[40:43]
	v_mfma_f32_16x16x32_bf16 v[32:35], v[154:157], v[202:205], v[32:35]
	v_mfma_f32_16x16x32_bf16 v[24:27], v[166:169], v[202:205], v[24:27]
	v_mfma_f32_16x16x32_bf16 v[16:19], v[154:157], v[210:213], v[16:19]
	v_mfma_f32_16x16x32_bf16 v[8:11], v[166:169], v[210:213], v[8:11]
	v_mfma_f32_16x16x32_bf16 v[60:63], v[158:161], v[190:193], v[60:63]
	v_mfma_f32_16x16x32_bf16 v[56:59], v[170:173], v[190:193], v[56:59]
	v_mfma_f32_16x16x32_bf16 v[48:51], v[158:161], v[198:201], v[48:51]
	v_mfma_f32_16x16x32_bf16 v[40:43], v[170:173], v[198:201], v[40:43]
	v_mfma_f32_16x16x32_bf16 v[32:35], v[158:161], v[206:209], v[32:35]
	v_mfma_f32_16x16x32_bf16 v[24:27], v[170:173], v[206:209], v[24:27]
	v_mfma_f32_16x16x32_bf16 v[16:19], v[158:161], v[214:217], v[16:19]
	v_mfma_f32_16x16x32_bf16 v[8:11], v[170:173], v[214:217], v[8:11]
	s_barrier
	s_add_u32 s22, s26, 0xb0080
	s_addc_u32 s23, s27, 0
	s_add_i32 s26, s28, s37
	v_lshl_add_u64 v[144:145], s[22:23], 0, v[130:131]
	s_mov_b32 m0, s26
	s_nop 0
	global_load_lds_dwordx4 v[144:145], off
	v_lshl_add_u64 v[144:145], s[22:23], 0, v[134:135]
	s_add_i32 m0, s26, 0x2000
	s_nop 0
	global_load_lds_dwordx4 v[144:145], off
	s_waitcnt vmcnt(6)
	s_barrier
	v_mfma_f32_16x16x32_bf16 v[52:55], v[218:221], v[182:185], v[52:55]
	v_mfma_f32_16x16x32_bf16 v[44:47], v[226:229], v[182:185], v[44:47]
	v_mfma_f32_16x16x32_bf16 v[36:39], v[218:221], v[194:197], v[36:39]
	v_mfma_f32_16x16x32_bf16 v[28:31], v[226:229], v[194:197], v[28:31]
	v_mfma_f32_16x16x32_bf16 v[20:23], v[218:221], v[202:205], v[20:23]
	v_mfma_f32_16x16x32_bf16 v[12:15], v[226:229], v[202:205], v[12:15]
	v_mfma_f32_16x16x32_bf16 v[4:7], v[218:221], v[210:213], v[4:7]
	v_mfma_f32_16x16x32_bf16 v[0:3], v[226:229], v[210:213], v[0:3]
	v_mfma_f32_16x16x32_bf16 v[52:55], v[222:225], v[190:193], v[52:55]
	v_mfma_f32_16x16x32_bf16 v[44:47], v[230:233], v[190:193], v[44:47]
	v_mfma_f32_16x16x32_bf16 v[36:39], v[222:225], v[198:201], v[36:39]
	v_mfma_f32_16x16x32_bf16 v[28:31], v[230:233], v[198:201], v[28:31]
	v_mfma_f32_16x16x32_bf16 v[20:23], v[222:225], v[206:209], v[20:23]
	v_mfma_f32_16x16x32_bf16 v[12:15], v[230:233], v[206:209], v[12:15]
	v_mfma_f32_16x16x32_bf16 v[4:7], v[222:225], v[214:217], v[4:7]
	v_mfma_f32_16x16x32_bf16 v[0:3], v[230:233], v[214:217], v[0:3]
	s_add_i32 s57, s57, 2
	s_add_u32 s55, s55, 0x100
	s_addc_u32 s56, s56, 0
	s_cmp_gt_u32 s57, 41
	s_mov_b64 s[22:23], s[24:25]
	s_barrier
	s_cbranch_scc0 .LBB0_286
	v_lshl_add_u32 v154, s53, 8, v146
	v_lshl_or_b32 v144, s54, 8, v148
	v_ashrrev_i32_e32 v155, 31, v154
	v_ashrrev_i32_e32 v145, 31, v144
	v_lshlrev_b64 v[156:157], 11, v[154:155]
	v_lshl_add_u64 v[156:157], s[10:11], 0, v[156:157]
	v_lshlrev_b64 v[158:159], 1, v[144:145]
	v_lshl_add_u64 v[144:145], v[156:157], 0, v[158:159]
	v_pk_add_f32 v[126:127], v[126:127], 0 op_sel_hi:[1,0]
	v_pk_add_f32 v[124:125], v[124:125], 0 op_sel_hi:[1,0]
	v_pk_add_f32 v[156:157], v[122:123], 0 op_sel_hi:[1,0]
	v_pk_add_f32 v[122:123], v[120:121], 0 op_sel_hi:[1,0]
	v_cvt_pk_bf16_f32 v120, v124, v125
	v_cvt_pk_bf16_f32 v121, v126, v127
	v_pk_add_f32 v[116:117], v[116:117], 0 op_sel_hi:[1,0]
	v_cvt_pk_bf16_f32 v122, v122, v123
	v_cvt_pk_bf16_f32 v123, v156, v157
	global_store_dwordx4 v[144:145], v[120:123], off
	v_pk_add_f32 v[118:119], v[118:119], 0 op_sel_hi:[1,0]
	v_pk_add_f32 v[110:111], v[110:111], 0 op_sel_hi:[1,0]
	v_pk_add_f32 v[120:121], v[114:115], 0 op_sel_hi:[1,0]
	v_pk_add_f32 v[114:115], v[112:113], 0 op_sel_hi:[1,0]
	v_cvt_pk_bf16_f32 v112, v116, v117
	v_cvt_pk_bf16_f32 v113, v118, v119
	v_pk_add_f32 v[108:109], v[108:109], 0 op_sel_hi:[1,0]
	v_cvt_pk_bf16_f32 v114, v114, v115
	v_cvt_pk_bf16_f32 v115, v120, v121
	global_store_dwordx4 v[144:145], v[112:115], off offset:256
	v_pk_add_f32 v[100:101], v[100:101], 0 op_sel_hi:[1,0]
	v_pk_add_f32 v[102:103], v[102:103], 0 op_sel_hi:[1,0]
	v_or_b32_e32 v112, 16, v154
	v_ashrrev_i32_e32 v113, 31, v112
	v_lshlrev_b64 v[112:113], 11, v[112:113]
	v_lshl_add_u64 v[112:113], s[10:11], 0, v[112:113]
	v_lshl_add_u64 v[112:113], v[112:113], 0, v[158:159]
	v_pk_add_f32 v[114:115], v[106:107], 0 op_sel_hi:[1,0]
	v_pk_add_f32 v[106:107], v[104:105], 0 op_sel_hi:[1,0]
	v_cvt_pk_bf16_f32 v104, v108, v109
	v_cvt_pk_bf16_f32 v105, v110, v111
	v_pk_add_f32 v[94:95], v[94:95], 0 op_sel_hi:[1,0]
	v_cvt_pk_bf16_f32 v106, v106, v107
	v_cvt_pk_bf16_f32 v107, v114, v115
	global_store_dwordx4 v[112:113], v[104:107], off
	v_pk_add_f32 v[92:93], v[92:93], 0 op_sel_hi:[1,0]
	v_pk_add_f32 v[84:85], v[84:85], 0 op_sel_hi:[1,0]
	v_pk_add_f32 v[104:105], v[98:99], 0 op_sel_hi:[1,0]
	v_pk_add_f32 v[98:99], v[96:97], 0 op_sel_hi:[1,0]
	v_cvt_pk_bf16_f32 v96, v100, v101
	v_cvt_pk_bf16_f32 v97, v102, v103
	v_pk_add_f32 v[86:87], v[86:87], 0 op_sel_hi:[1,0]
	v_cvt_pk_bf16_f32 v98, v98, v99
	v_cvt_pk_bf16_f32 v99, v104, v105
	global_store_dwordx4 v[112:113], v[96:99], off offset:256
	v_pk_add_f32 v[78:79], v[78:79], 0 op_sel_hi:[1,0]
	v_pk_add_f32 v[76:77], v[76:77], 0 op_sel_hi:[1,0]
	v_or_b32_e32 v96, 32, v154
	v_ashrrev_i32_e32 v97, 31, v96
	v_lshlrev_b64 v[96:97], 11, v[96:97]
	v_lshl_add_u64 v[96:97], s[10:11], 0, v[96:97]
	v_lshl_add_u64 v[96:97], v[96:97], 0, v[158:159]
; __device__ __forceinline__ unsigned cvt_pk_bf16(float lo, float hi) { unsigned r; asm volatile("v_cvt_pk_bf16_f32 %0, %1, %2" : "=v"(r) : "v"(lo), "v"(hi)); return r; }
; __device__ __forceinline__ float flogsig16(float x) { return (fminf(x, 0.f) - __logf(1.0f + __expf(-fabsf(x)))) * 0.0625f; }
;     __device__ __forceinline__ void operator()(const f32x4 (&acc)[2][2][4][2], const Unit& u, int wr, int wc, int fr, int fq) const {
;     ...
;             for (int m = 0; m < 4; ++m) { bf16_t* rowp = O + (size_t)(row0 + ai * HALF + m * 16) * ldc + col0;
; #pragma unroll
;                 for (int bj = 0; bj < 2; ++bj) { f32x4 v0 = acc[ai][bj][m][0] + bv[bj][0], v1 = acc[ai][bj][m][1] + bv[bj][1];
;                     if (act == 1) {
; #pragma unroll
;                         for (int j = 0; j < 1; ++j) { v0 = v0 * sigmoid4(v0); v1 = v1 * sigmoid4(v1); } }
;                     else if (act == 2) {
; #pragma unroll
;                         for (int j = 0; j < 1; ++j) { v0 = sigmoid4(v0); v1 = sigmoid4(v1); } }
;                     else if (act == 3) {
; #pragma unroll
;                         for (int j = 0; j < 4; ++j) { v0[j] = flogsig16(v0[j]); v1[j] = flogsig16(v1[j]); } }
;                     u32x4 w; w.x = cvt_pk_bf16(v0[0], v0[1]); w.y = cvt_pk_bf16(v0[2], v0[3]); w.z = cvt_pk_bf16(v1[0], v1[1]); w.w = cvt_pk_bf16(v1[2], v1[3]);
;                     *(u32x4*)(rowp + bj * HALF) = w; } }
	v_pk_add_f32 v[98:99], v[90:91], 0 op_sel_hi:[1,0]
	v_pk_add_f32 v[90:91], v[88:89], 0 op_sel_hi:[1,0]
	v_cvt_pk_bf16_f32 v88, v92, v93
	v_cvt_pk_bf16_f32 v89, v94, v95
	v_pk_add_f32 v[70:71], v[70:71], 0 op_sel_hi:[1,0]
	v_cvt_pk_bf16_f32 v90, v90, v91
	v_cvt_pk_bf16_f32 v91, v98, v99
	global_store_dwordx4 v[96:97], v[88:91], off
	v_pk_add_f32 v[68:69], v[68:69], 0 op_sel_hi:[1,0]
	s_mov_b64 s[22:23], 0x40000
	v_pk_add_f32 v[88:89], v[82:83], 0 op_sel_hi:[1,0]
	v_pk_add_f32 v[82:83], v[80:81], 0 op_sel_hi:[1,0]
	v_cvt_pk_bf16_f32 v80, v84, v85
	v_cvt_pk_bf16_f32 v81, v86, v87
	v_pk_add_f32 v[60:61], v[60:61], 0 op_sel_hi:[1,0]
	v_cvt_pk_bf16_f32 v82, v82, v83
	v_cvt_pk_bf16_f32 v83, v88, v89
	global_store_dwordx4 v[96:97], v[80:83], off offset:256
	v_pk_add_f32 v[62:63], v[62:63], 0 op_sel_hi:[1,0]
	v_pk_add_f32 v[54:55], v[54:55], 0 op_sel_hi:[1,0]
	v_or_b32_e32 v80, 48, v154
	v_ashrrev_i32_e32 v81, 31, v80
	v_lshlrev_b64 v[80:81], 11, v[80:81]
	v_lshl_add_u64 v[80:81], s[10:11], 0, v[80:81]
	v_lshl_add_u64 v[80:81], v[80:81], 0, v[158:159]
	v_pk_add_f32 v[82:83], v[74:75], 0 op_sel_hi:[1,0]
	v_pk_add_f32 v[74:75], v[72:73], 0 op_sel_hi:[1,0]
	v_cvt_pk_bf16_f32 v72, v76, v77
	v_cvt_pk_bf16_f32 v73, v78, v79
	v_pk_add_f32 v[52:53], v[52:53], 0 op_sel_hi:[1,0]
	v_cvt_pk_bf16_f32 v74, v74, v75
	v_cvt_pk_bf16_f32 v75, v82, v83
	global_store_dwordx4 v[80:81], v[72:75], off
	v_pk_add_f32 v[48:49], v[48:49], 0 op_sel_hi:[1,0]
	v_pk_add_f32 v[38:39], v[38:39], 0 op_sel_hi:[1,0]
	v_pk_add_f32 v[72:73], v[66:67], 0 op_sel_hi:[1,0]
	v_pk_add_f32 v[66:67], v[64:65], 0 op_sel_hi:[1,0]
	v_cvt_pk_bf16_f32 v64, v68, v69
	v_cvt_pk_bf16_f32 v65, v70, v71
	v_pk_add_f32 v[36:37], v[36:37], 0 op_sel_hi:[1,0]
	v_cvt_pk_bf16_f32 v66, v66, v67
	v_cvt_pk_bf16_f32 v67, v72, v73
	global_store_dwordx4 v[80:81], v[64:67], off offset:256
	v_pk_add_f32 v[32:33], v[32:33], 0 op_sel_hi:[1,0]
	v_pk_add_f32 v[22:23], v[22:23], 0 op_sel_hi:[1,0]
	v_lshl_add_u64 v[64:65], v[144:145], 0, s[22:23]
	s_mov_b32 s22, 0x40000
	v_pk_add_f32 v[66:67], v[58:59], 0 op_sel_hi:[1,0]
	v_pk_add_f32 v[58:59], v[56:57], 0 op_sel_hi:[1,0]
	v_cvt_pk_bf16_f32 v56, v60, v61
	v_add_co_u32_e32 v60, vcc, s22, v144
	v_cvt_pk_bf16_f32 v57, v62, v63
	v_cvt_pk_bf16_f32 v58, v58, v59
	v_cvt_pk_bf16_f32 v59, v66, v67
	s_mov_b64 s[22:23], 0x48000
	s_nop 0
	v_addc_co_u32_e32 v61, vcc, 0, v145, vcc
	global_store_dwordx4 v[60:61], v[56:59], off
	v_pk_add_f32 v[20:21], v[20:21], 0 op_sel_hi:[1,0]
	v_pk_add_f32 v[16:17], v[16:17], 0 op_sel_hi:[1,0]
	v_pk_add_f32 v[56:57], v[46:47], 0 op_sel_hi:[1,0]
	v_pk_add_f32 v[46:47], v[44:45], 0 op_sel_hi:[1,0]
	v_cvt_pk_bf16_f32 v44, v52, v53
	v_cvt_pk_bf16_f32 v45, v54, v55
	s_mov_b32 s54, s51
	v_cvt_pk_bf16_f32 v46, v46, v47
	v_cvt_pk_bf16_f32 v47, v56, v57
	global_store_dwordx4 v[64:65], v[44:47], off offset:256
	s_mov_b32 s53, s52
	s_mov_b64 s[24:25], s[4:5]
	v_pk_add_f32 v[46:47], v[50:51], 0 op_sel_hi:[1,0]
	v_pk_add_f32 v[50:51], v[42:43], 0 op_sel_hi:[1,0]
	v_pk_add_f32 v[42:43], v[40:41], 0 op_sel_hi:[1,0]
	v_cvt_pk_bf16_f32 v40, v48, v49
	v_cvt_pk_bf16_f32 v41, v46, v47
	v_add_co_u32_e32 v46, vcc, s48, v144
	v_cvt_pk_bf16_f32 v42, v42, v43
	v_cvt_pk_bf16_f32 v43, v50, v51
	v_lshl_add_u64 v[44:45], v[144:145], 0, s[22:23]
	s_nop 0
	v_addc_co_u32_e32 v47, vcc, 0, v145, vcc
	global_store_dwordx4 v[46:47], v[40:43], off
	s_mov_b64 s[22:23], s[0:1]
	v_pk_add_f32 v[6:7], v[6:7], 0 op_sel_hi:[1,0]
	v_pk_add_f32 v[40:41], v[30:31], 0 op_sel_hi:[1,0]
	v_pk_add_f32 v[30:31], v[28:29], 0 op_sel_hi:[1,0]
	v_cvt_pk_bf16_f32 v28, v36, v37
	v_cvt_pk_bf16_f32 v29, v38, v39
	v_pk_add_f32 v[4:5], v[4:5], 0 op_sel_hi:[1,0]
	v_cvt_pk_bf16_f32 v30, v30, v31
	v_cvt_pk_bf16_f32 v31, v40, v41
	global_store_dwordx4 v[44:45], v[28:31], off offset:256
	s_nop 1
	v_pk_add_f32 v[30:31], v[34:35], 0 op_sel_hi:[1,0]
	v_pk_add_f32 v[34:35], v[26:27], 0 op_sel_hi:[1,0]
	v_pk_add_f32 v[26:27], v[24:25], 0 op_sel_hi:[1,0]
	v_cvt_pk_bf16_f32 v24, v32, v33
	v_cvt_pk_bf16_f32 v25, v30, v31
	v_add_co_u32_e32 v30, vcc, s49, v144
	v_cvt_pk_bf16_f32 v26, v26, v27
	v_cvt_pk_bf16_f32 v27, v34, v35
	v_lshl_add_u64 v[28:29], v[144:145], 0, s[16:17]
	s_nop 0
	v_addc_co_u32_e32 v31, vcc, 0, v145, vcc
	global_store_dwordx4 v[30:31], v[24:27], off
	s_nop 1
	v_pk_add_f32 v[24:25], v[14:15], 0 op_sel_hi:[1,0]
	v_pk_add_f32 v[14:15], v[12:13], 0 op_sel_hi:[1,0]
	v_cvt_pk_bf16_f32 v12, v20, v21
	v_cvt_pk_bf16_f32 v13, v22, v23
	s_nop 0
	v_cvt_pk_bf16_f32 v14, v14, v15
	v_cvt_pk_bf16_f32 v15, v24, v25
	global_store_dwordx4 v[28:29], v[12:15], off offset:256
	s_nop 1
	v_pk_add_f32 v[14:15], v[18:19], 0 op_sel_hi:[1,0]
	v_pk_add_f32 v[18:19], v[10:11], 0 op_sel_hi:[1,0]
	v_pk_add_f32 v[10:11], v[8:9], 0 op_sel_hi:[1,0]
	v_cvt_pk_bf16_f32 v8, v16, v17
	v_cvt_pk_bf16_f32 v9, v14, v15
	v_add_co_u32_e32 v14, vcc, s50, v144
	v_lshl_add_u64 v[12:13], v[144:145], 0, s[18:19]
	s_nop 0
	v_addc_co_u32_e32 v15, vcc, 0, v145, vcc
	v_cvt_pk_bf16_f32 v10, v10, v11
	v_cvt_pk_bf16_f32 v11, v18, v19
	global_store_dwordx4 v[14:15], v[8:11], off
	s_and_b64 vcc, exec, s[2:3]
	s_nop 0
	v_pk_add_f32 v[8:9], v[2:3], 0 op_sel_hi:[1,0]
	v_pk_add_f32 v[2:3], v[0:1], 0 op_sel_hi:[1,0]
	v_cvt_pk_bf16_f32 v0, v4, v5
	v_cvt_pk_bf16_f32 v1, v6, v7
	s_nop 0
	v_cvt_pk_bf16_f32 v2, v2, v3
	v_cvt_pk_bf16_f32 v3, v8, v9
	global_store_dwordx4 v[12:13], v[0:3], off offset:256
	s_cbranch_vccz .LBB0_275
	s_waitcnt vmcnt(0)
	s_cmpk_gt_u32 s31, 0xff
	s_cbranch_scc1 .LBB0_290
	s_barrier

; #define PG8_STAGE(bufoff, gbase, voff) do { _Pragma("unroll") for (int _i = 0; _i < 2; ++_i) \
;         __builtin_amdgcn_global_load_lds((const unsigned*)((const char*)(gbase) + (voff)[_i]), (PG8_LAS unsigned*)(lds + (bufoff) + ldsw + _i * 8192), 16, 0, 0); } while (0)
; #define PG8_LDA(dst, b, h) do { _Pragma("unroll") for (int m = 0; m < 4; ++m) _Pragma("unroll") for (int k = 0; k < 2; ++k) dst[m][k] = *(const PG8_LAS bf16x8*)(lds + PG8_SA(b, h) + aoff + m * 2048 + k * 1024); } while (0)
; #define PG8_LDB(dst, b, h) do { _Pragma("unroll") for (int n = 0; n < 2; ++n) _Pragma("unroll") for (int k = 0; k < 2; ++k) dst[n][k] = *(const PG8_LAS bf16x8*)(lds + PG8_SB(b, h) + boff + n * 2048 + k * 1024); } while (0)
; #define PG8_MMA(ai, bj, At, Bt) do { __builtin_amdgcn_s_setprio(1); _Pragma("unroll") for (int m = 0; m < 4; ++m) _Pragma("unroll") for (int n = 0; n < 2; ++n) _Pragma("unroll") for (int k = 0; k < 2; ++k) \
;         acc[ai][bj][m][n] = __builtin_amdgcn_mfma_f32_16x16x32_bf16(Bt[n][k], At[m][k], acc[ai][bj][m][n], 0, 0, 0); __builtin_amdgcn_s_setprio(0); } while (0)
; #define PG8_WAIT_V(n) asm volatile("s_waitcnt vmcnt(" #n ")" ::: "memory")
; #define PG8_WAIT_L(n) asm volatile("s_waitcnt lgkmcnt(" #n ")" ::: "memory")
; #define PG8_BAR __builtin_amdgcn_s_barrier()
; #define PG8_SCHED __builtin_amdgcn_sched_barrier(0)
; template <class Epi, class Sched>
; __device__ __forceinline__ void gemm_phase(PG8_LAS unsigned char* lds, const Gemm g, const Sched& S, const Epi& E) {
;     ...
;             PG8_LDB(B0, 0, 0); PG8_SCHED; PG8_LDA(At, 0, 0); PG8_STAGE(PG8_SA(1, 1), a1 + hstep, voffA);
;             PG8_WAIT_L(8); PG8_BAR; PG8_WAIT_L(0); PG8_MMA(0, 0, At, B0); PG8_BAR; PG8_SCHED;
;             PG8_LDB(B1, 0, 1); PG8_STAGE(PG8_SB(0, 0), b2, voffB);
;             PG8_BAR; PG8_WAIT_L(0); PG8_MMA(0, 1, At, B1); PG8_BAR;
;             PG8_LDA(At, 0, 1); PG8_STAGE(PG8_SA(0, 0), a2, voffA);
;             PG8_BAR; PG8_WAIT_L(0); PG8_MMA(1, 0, At, B0); PG8_BAR; PG8_SCHED;
;             PG8_STAGE(PG8_SB(0, 1), b2 + hstep, voffB);
;             PG8_WAIT_V(6); PG8_BAR; PG8_MMA(1, 1, At, B1); PG8_BAR;
;             PG8_LDB(B0, 1, 0); PG8_SCHED; PG8_LDA(At, 1, 0); PG8_STAGE(PG8_SA(0, 1), a2 + hstep, voffA);
.LBB0_416:
	ds_read_b128 v[24:27], v186
	ds_read_b128 v[28:31], v186 offset:1024
	ds_read_b128 v[40:43], v186 offset:2048
	ds_read_b128 v[44:47], v186 offset:3072
	s_add_u32 s4, s0, 0xfffc0080
	s_addc_u32 s5, s1, -1
	s_cmp_eq_u32 s53, 12
	s_cselect_b32 s29, s7, s5
	s_cselect_b32 s28, s10, s4
	s_cselect_b32 s5, s19, s52
	s_cselect_b32 s4, s21, s51
	v_lshl_add_u64 v[174:175], s[0:1], 0, v[166:167]
	s_add_i32 m0, s27, 0xc000
	ds_read_b128 v[144:147], v187
	ds_read_b128 v[148:151], v187 offset:1024
	ds_read_b128 v[182:185], v187 offset:2048
	ds_read_b128 v[192:195], v187 offset:3072
	ds_read_b128 v[196:199], v187 offset:4096
	ds_read_b128 v[200:203], v187 offset:5120
	ds_read_b128 v[204:207], v187 offset:6144
	ds_read_b128 v[208:211], v187 offset:7168
	global_load_lds_dwordx4 v[174:175], off
	v_lshl_add_u64 v[174:175], s[0:1], 0, v[168:169]
	s_add_i32 m0, s27, 0xe000
	s_nop 0
	global_load_lds_dwordx4 v[174:175], off
	s_waitcnt lgkmcnt(8)
	s_barrier
	s_waitcnt lgkmcnt(0)
	v_mfma_f32_16x16x32_bf16 v[140:143], v[24:27], v[144:147], v[140:143]
	v_mfma_f32_16x16x32_bf16 v[136:139], v[40:43], v[144:147], v[136:139]
	v_mfma_f32_16x16x32_bf16 v[124:127], v[24:27], v[182:185], v[124:127]
	v_mfma_f32_16x16x32_bf16 v[120:123], v[40:43], v[182:185], v[120:123]
	v_mfma_f32_16x16x32_bf16 v[108:111], v[24:27], v[196:199], v[108:111]
	v_mfma_f32_16x16x32_bf16 v[104:107], v[40:43], v[196:199], v[104:107]
	v_mfma_f32_16x16x32_bf16 v[92:95], v[24:27], v[204:207], v[92:95]
	v_mfma_f32_16x16x32_bf16 v[88:91], v[40:43], v[204:207], v[88:91]
	v_mfma_f32_16x16x32_bf16 v[140:143], v[28:31], v[148:151], v[140:143]
	v_mfma_f32_16x16x32_bf16 v[136:139], v[44:47], v[148:151], v[136:139]
	v_mfma_f32_16x16x32_bf16 v[124:127], v[28:31], v[192:195], v[124:127]
	v_mfma_f32_16x16x32_bf16 v[120:123], v[44:47], v[192:195], v[120:123]
	v_mfma_f32_16x16x32_bf16 v[108:111], v[28:31], v[200:203], v[108:111]
	v_mfma_f32_16x16x32_bf16 v[104:107], v[44:47], v[200:203], v[104:107]
	v_mfma_f32_16x16x32_bf16 v[92:95], v[28:31], v[208:211], v[92:95]
	v_mfma_f32_16x16x32_bf16 v[88:91], v[44:47], v[208:211], v[88:91]
	s_barrier
	s_add_i32 s54, s43, s35
	v_lshl_add_u64 v[174:175], s[4:5], 0, v[156:157]
	s_mov_b32 m0, s54
	ds_read_b128 v[212:215], v189
	ds_read_b128 v[216:219], v189 offset:1024
	ds_read_b128 v[220:223], v189 offset:2048
	ds_read_b128 v[224:227], v189 offset:3072
	global_load_lds_dwordx4 v[174:175], off
	v_lshl_add_u64 v[228:229], s[4:5], 0, v[160:161]
	s_add_i32 m0, s54, 0x2000
	s_nop 0
	global_load_lds_dwordx4 v[228:229], off
	s_barrier
	s_waitcnt lgkmcnt(0)
	v_mfma_f32_16x16x32_bf16 v[132:135], v[212:215], v[144:147], v[132:135]
	v_mfma_f32_16x16x32_bf16 v[128:131], v[220:223], v[144:147], v[128:131]
	v_mfma_f32_16x16x32_bf16 v[116:119], v[212:215], v[182:185], v[116:119]
	v_mfma_f32_16x16x32_bf16 v[112:115], v[220:223], v[182:185], v[112:115]
	v_mfma_f32_16x16x32_bf16 v[100:103], v[212:215], v[196:199], v[100:103]
	v_mfma_f32_16x16x32_bf16 v[96:99], v[220:223], v[196:199], v[96:99]
	v_mfma_f32_16x16x32_bf16 v[84:87], v[212:215], v[204:207], v[84:87]
	v_mfma_f32_16x16x32_bf16 v[80:83], v[220:223], v[204:207], v[80:83]
	v_mfma_f32_16x16x32_bf16 v[132:135], v[216:219], v[148:151], v[132:135]
	v_mfma_f32_16x16x32_bf16 v[128:131], v[224:227], v[148:151], v[128:131]
	v_mfma_f32_16x16x32_bf16 v[116:119], v[216:219], v[192:195], v[116:119]
	v_mfma_f32_16x16x32_bf16 v[112:115], v[224:227], v[192:195], v[112:115]
	v_mfma_f32_16x16x32_bf16 v[100:103], v[216:219], v[200:203], v[100:103]
	v_mfma_f32_16x16x32_bf16 v[96:99], v[224:227], v[200:203], v[96:99]
	v_mfma_f32_16x16x32_bf16 v[84:87], v[216:219], v[208:211], v[84:87]
	v_mfma_f32_16x16x32_bf16 v[80:83], v[224:227], v[208:211], v[80:83]
	s_barrier
	s_mov_b32 m0, s27
	v_lshl_add_u64 v[230:231], s[28:29], 0, v[154:155]
	ds_read_b128 v[144:147], v187 offset:16384
	ds_read_b128 v[148:151], v187 offset:17408
	ds_read_b128 v[182:185], v187 offset:18432
	ds_read_b128 v[192:195], v187 offset:19456
	ds_read_b128 v[196:199], v187 offset:20480
	ds_read_b128 v[200:203], v187 offset:21504
	ds_read_b128 v[204:207], v187 offset:22528
	ds_read_b128 v[208:211], v187 offset:23552
	global_load_lds_dwordx4 v[230:231], off
	v_lshl_add_u64 v[232:233], s[28:29], 0, v[158:159]
	s_mov_b32 m0, s36
	s_nop 0
	global_load_lds_dwordx4 v[232:233], off
	s_barrier
	s_waitcnt lgkmcnt(0)
	v_mfma_f32_16x16x32_bf16 v[76:79], v[24:27], v[144:147], v[76:79]
	v_mfma_f32_16x16x32_bf16 v[72:75], v[40:43], v[144:147], v[72:75]
	v_mfma_f32_16x16x32_bf16 v[60:63], v[24:27], v[182:185], v[60:63]
	v_mfma_f32_16x16x32_bf16 v[56:59], v[40:43], v[182:185], v[56:59]
	v_mfma_f32_16x16x32_bf16 v[36:39], v[24:27], v[196:199], v[36:39]
	v_mfma_f32_16x16x32_bf16 v[32:35], v[40:43], v[196:199], v[32:35]
	v_mfma_f32_16x16x32_bf16 v[12:15], v[24:27], v[204:207], v[12:15]
	v_mfma_f32_16x16x32_bf16 v[8:11], v[40:43], v[204:207], v[8:11]
	v_mfma_f32_16x16x32_bf16 v[76:79], v[28:31], v[148:151], v[76:79]
	v_mfma_f32_16x16x32_bf16 v[72:75], v[44:47], v[148:151], v[72:75]
	v_mfma_f32_16x16x32_bf16 v[60:63], v[28:31], v[192:195], v[60:63]
	v_mfma_f32_16x16x32_bf16 v[56:59], v[44:47], v[192:195], v[56:59]
	v_mfma_f32_16x16x32_bf16 v[36:39], v[28:31], v[200:203], v[36:39]
	v_mfma_f32_16x16x32_bf16 v[32:35], v[44:47], v[200:203], v[32:35]
	v_mfma_f32_16x16x32_bf16 v[12:15], v[28:31], v[208:211], v[12:15]
	v_mfma_f32_16x16x32_bf16 v[8:11], v[44:47], v[208:211], v[8:11]
	s_barrier
	s_add_u32 s54, s4, 0x40000
	s_addc_u32 s55, s5, 0
	s_add_i32 s56, s44, s35
	v_lshl_add_u64 v[24:25], s[54:55], 0, v[156:157]
	s_mov_b32 m0, s56
	s_nop 0
	global_load_lds_dwordx4 v[24:25], off
	v_lshl_add_u64 v[24:25], s[54:55], 0, v[160:161]
	s_add_i32 m0, s56, 0x2000
	s_nop 0
	global_load_lds_dwordx4 v[24:25], off
	s_waitcnt vmcnt(6)
	s_barrier
; #define PG8_STAGE(bufoff, gbase, voff) do { _Pragma("unroll") for (int _i = 0; _i < 2; ++_i) \
;         __builtin_amdgcn_global_load_lds((const unsigned*)((const char*)(gbase) + (voff)[_i]), (PG8_LAS unsigned*)(lds + (bufoff) + ldsw + _i * 8192), 16, 0, 0); } while (0)
; #define PG8_LDA(dst, b, h) do { _Pragma("unroll") for (int m = 0; m < 4; ++m) _Pragma("unroll") for (int k = 0; k < 2; ++k) dst[m][k] = *(const PG8_LAS bf16x8*)(lds + PG8_SA(b, h) + aoff + m * 2048 + k * 1024); } while (0)
; #define PG8_LDB(dst, b, h) do { _Pragma("unroll") for (int n = 0; n < 2; ++n) _Pragma("unroll") for (int k = 0; k < 2; ++k) dst[n][k] = *(const PG8_LAS bf16x8*)(lds + PG8_SB(b, h) + boff + n * 2048 + k * 1024); } while (0)
; #define PG8_MMA(ai, bj, At, Bt) do { __builtin_amdgcn_s_setprio(1); _Pragma("unroll") for (int m = 0; m < 4; ++m) _Pragma("unroll") for (int n = 0; n < 2; ++n) _Pragma("unroll") for (int k = 0; k < 2; ++k) \
;         acc[ai][bj][m][n] = __builtin_amdgcn_mfma_f32_16x16x32_bf16(Bt[n][k], At[m][k], acc[ai][bj][m][n], 0, 0, 0); __builtin_amdgcn_s_setprio(0); } while (0)
; #define PG8_WAIT_V(n) asm volatile("s_waitcnt vmcnt(" #n ")" ::: "memory")
; #define PG8_WAIT_L(n) asm volatile("s_waitcnt lgkmcnt(" #n ")" ::: "memory")
; #define PG8_BAR __builtin_amdgcn_s_barrier()
; #define PG8_SCHED __builtin_amdgcn_sched_barrier(0)
; template <class Epi, class Sched>
; __device__ __forceinline__ void gemm_phase(PG8_LAS unsigned char* lds, const Gemm g, const Sched& S, const Epi& E) {
;     ...
;             PG8_WAIT_V(6); PG8_BAR; PG8_MMA(1, 1, At, B1); PG8_BAR;
;             PG8_LDB(B0, 1, 0); PG8_SCHED; PG8_LDA(At, 1, 0); PG8_STAGE(PG8_SA(0, 1), a2 + hstep, voffA);
;             PG8_WAIT_L(8); PG8_BAR; PG8_WAIT_L(0); PG8_MMA(0, 0, At, B0); PG8_BAR; PG8_SCHED;
;             PG8_LDB(B1, 1, 1); PG8_STAGE(PG8_SB(1, 0), b3, voffB);
;             PG8_BAR; PG8_WAIT_L(0); PG8_MMA(0, 1, At, B1); PG8_BAR;
	v_mfma_f32_16x16x32_bf16 v[20:23], v[212:215], v[196:199], v[20:23]
	v_mfma_f32_16x16x32_bf16 v[16:19], v[220:223], v[196:199], v[16:19]
	v_mfma_f32_16x16x32_bf16 v[4:7], v[212:215], v[204:207], v[4:7]
	v_mfma_f32_16x16x32_bf16 v[0:3], v[220:223], v[204:207], v[0:3]
	v_mfma_f32_16x16x32_bf16 v[24:27], v[212:215], v[144:147], v[68:71]
	v_mfma_f32_16x16x32_bf16 v[28:31], v[220:223], v[144:147], v[64:67]
	v_mfma_f32_16x16x32_bf16 v[40:43], v[212:215], v[182:185], v[52:55]
	v_mfma_f32_16x16x32_bf16 v[44:47], v[220:223], v[182:185], v[48:51]
	v_mfma_f32_16x16x32_bf16 v[20:23], v[216:219], v[200:203], v[20:23]
	v_mfma_f32_16x16x32_bf16 v[16:19], v[224:227], v[200:203], v[16:19]
	v_mfma_f32_16x16x32_bf16 v[4:7], v[216:219], v[208:211], v[4:7]
	v_mfma_f32_16x16x32_bf16 v[0:3], v[224:227], v[208:211], v[0:3]
	v_mfma_f32_16x16x32_bf16 v[24:27], v[216:219], v[148:151], v[24:27]
	v_mfma_f32_16x16x32_bf16 v[28:31], v[224:227], v[148:151], v[28:31]
	v_mfma_f32_16x16x32_bf16 v[40:43], v[216:219], v[192:195], v[40:43]
	v_mfma_f32_16x16x32_bf16 v[44:47], v[224:227], v[192:195], v[44:47]
	s_barrier
	s_add_i32 s54, 0, 0x18000
	v_add_u32_e32 v68, s54, v179
	ds_read_b128 v[48:51], v68
	ds_read_b128 v[52:55], v68 offset:1024
	ds_read_b128 v[64:67], v68 offset:2048
	ds_read_b128 v[68:71], v68 offset:3072
	s_add_u32 s28, s28, 0x40000
	s_addc_u32 s29, s29, 0
	s_mov_b32 m0, s37
	v_lshl_add_u64 v[212:213], s[28:29], 0, v[154:155]
	ds_read_b128 v[144:147], v187 offset:32768
	ds_read_b128 v[148:151], v187 offset:33792
	ds_read_b128 v[182:185], v187 offset:34816
	ds_read_b128 v[192:195], v187 offset:35840
	ds_read_b128 v[196:199], v187 offset:36864
	ds_read_b128 v[200:203], v187 offset:37888
	ds_read_b128 v[204:207], v187 offset:38912
	ds_read_b128 v[208:211], v187 offset:39936
	global_load_lds_dwordx4 v[212:213], off
	v_lshl_add_u64 v[212:213], s[28:29], 0, v[158:159]
	s_mov_b32 m0, s38
	s_nop 0
	global_load_lds_dwordx4 v[212:213], off
	s_waitcnt lgkmcnt(8)
	s_barrier
	s_waitcnt lgkmcnt(0)
	v_mfma_f32_16x16x32_bf16 v[140:143], v[48:51], v[144:147], v[140:143]
	v_mfma_f32_16x16x32_bf16 v[136:139], v[64:67], v[144:147], v[136:139]
	v_mfma_f32_16x16x32_bf16 v[124:127], v[48:51], v[182:185], v[124:127]
	v_mfma_f32_16x16x32_bf16 v[120:123], v[64:67], v[182:185], v[120:123]
	v_mfma_f32_16x16x32_bf16 v[108:111], v[48:51], v[196:199], v[108:111]
	v_mfma_f32_16x16x32_bf16 v[104:107], v[64:67], v[196:199], v[104:107]
	v_mfma_f32_16x16x32_bf16 v[92:95], v[48:51], v[204:207], v[92:95]
	v_mfma_f32_16x16x32_bf16 v[88:91], v[64:67], v[204:207], v[88:91]
	v_mfma_f32_16x16x32_bf16 v[140:143], v[52:55], v[148:151], v[140:143]
	v_mfma_f32_16x16x32_bf16 v[136:139], v[68:71], v[148:151], v[136:139]
	v_mfma_f32_16x16x32_bf16 v[124:127], v[52:55], v[192:195], v[124:127]
	v_mfma_f32_16x16x32_bf16 v[120:123], v[68:71], v[192:195], v[120:123]
	v_mfma_f32_16x16x32_bf16 v[108:111], v[52:55], v[200:203], v[108:111]
	v_mfma_f32_16x16x32_bf16 v[104:107], v[68:71], v[200:203], v[104:107]
	v_mfma_f32_16x16x32_bf16 v[92:95], v[52:55], v[208:211], v[92:95]
	v_mfma_f32_16x16x32_bf16 v[88:91], v[68:71], v[208:211], v[88:91]
	s_barrier
	s_add_i32 s28, 0, 0x1c000
	s_add_i32 s29, s54, s35
	v_add_u32_e32 v162, s28, v179
	v_lshl_add_u64 v[174:175], v[174:175], 0, s[14:15]
	s_mov_b32 m0, s29
	ds_read_b128 v[212:215], v162
	ds_read_b128 v[216:219], v162 offset:1024
	ds_read_b128 v[220:223], v162 offset:2048
	ds_read_b128 v[224:227], v162 offset:3072
	global_load_lds_dwordx4 v[174:175], off
	v_lshl_add_u64 v[174:175], v[228:229], 0, s[14:15]
	s_add_i32 m0, s29, 0x2000
	s_nop 0
	global_load_lds_dwordx4 v[174:175], off
	s_barrier
	s_waitcnt lgkmcnt(0)
	v_mfma_f32_16x16x32_bf16 v[132:135], v[212:215], v[144:147], v[132:135]
	v_mfma_f32_16x16x32_bf16 v[128:131], v[220:223], v[144:147], v[128:131]
	v_mfma_f32_16x16x32_bf16 v[116:119], v[212:215], v[182:185], v[116:119]
	v_mfma_f32_16x16x32_bf16 v[112:115], v[220:223], v[182:185], v[112:115]
	v_mfma_f32_16x16x32_bf16 v[100:103], v[212:215], v[196:199], v[100:103]
	v_mfma_f32_16x16x32_bf16 v[96:99], v[220:223], v[196:199], v[96:99]
	v_mfma_f32_16x16x32_bf16 v[84:87], v[212:215], v[204:207], v[84:87]
	v_mfma_f32_16x16x32_bf16 v[80:83], v[220:223], v[204:207], v[80:83]
	v_mfma_f32_16x16x32_bf16 v[132:135], v[216:219], v[148:151], v[132:135]
	v_mfma_f32_16x16x32_bf16 v[128:131], v[224:227], v[148:151], v[128:131]
	v_mfma_f32_16x16x32_bf16 v[116:119], v[216:219], v[192:195], v[116:119]
	v_mfma_f32_16x16x32_bf16 v[112:115], v[224:227], v[192:195], v[112:115]
	v_mfma_f32_16x16x32_bf16 v[100:103], v[216:219], v[200:203], v[100:103]
	v_mfma_f32_16x16x32_bf16 v[96:99], v[224:227], v[200:203], v[96:99]
	v_mfma_f32_16x16x32_bf16 v[84:87], v[216:219], v[208:211], v[84:87]
	v_mfma_f32_16x16x32_bf16 v[80:83], v[224:227], v[208:211], v[80:83]
	s_barrier
; #define PG8_STAGE(bufoff, gbase, voff) do { _Pragma("unroll") for (int _i = 0; _i < 2; ++_i) \
;         __builtin_amdgcn_global_load_lds((const unsigned*)((const char*)(gbase) + (voff)[_i]), (PG8_LAS unsigned*)(lds + (bufoff) + ldsw + _i * 8192), 16, 0, 0); } while (0)
; #define PG8_LDA(dst, b, h) do { _Pragma("unroll") for (int m = 0; m < 4; ++m) _Pragma("unroll") for (int k = 0; k < 2; ++k) dst[m][k] = *(const PG8_LAS bf16x8*)(lds + PG8_SA(b, h) + aoff + m * 2048 + k * 1024); } while (0)
; #define PG8_MMA(ai, bj, At, Bt) do { __builtin_amdgcn_s_setprio(1); _Pragma("unroll") for (int m = 0; m < 4; ++m) _Pragma("unroll") for (int n = 0; n < 2; ++n) _Pragma("unroll") for (int k = 0; k < 2; ++k) \
;         acc[ai][bj][m][n] = __builtin_amdgcn_mfma_f32_16x16x32_bf16(Bt[n][k], At[m][k], acc[ai][bj][m][n], 0, 0, 0); __builtin_amdgcn_s_setprio(0); } while (0)
; #define PG8_WAIT_V(n) asm volatile("s_waitcnt vmcnt(" #n ")" ::: "memory")
; #define PG8_WAIT_L(n) asm volatile("s_waitcnt lgkmcnt(" #n ")" ::: "memory")
; #define PG8_BAR __builtin_amdgcn_s_barrier()
; #define PG8_SCHED __builtin_amdgcn_sched_barrier(0)
;     __device__ __forceinline__ void operator()(const f32x4 (&acc)[2][2][4][2], const Unit& u, int wr, int wc, int fr, int fq) const {
;         int act = 0; const float* bias = nullptr;
;         if (mode == 1) { if (u.pn >= 8 && u.pn < 12) act = 1; else if (u.pn >= 12) { act = 3; bias = (u.pn >= 14) ? bias_b + (u.pn - 14) * 256 : bias_f + (u.pn - 12) * 256; } }
;         else if (mode == 2) { if (u.pn >= 6) act = 2; }
;         const int row0 = u.pm * BM + wr * 64 + fr, col0 = u.pn * BM + wc * 32 + 8 * fq, bcol0 = wc * 32 + 8 * fq;
;         f32x4 bv[2][2];
; #pragma unroll
;         for (int bj = 0; bj < 2; ++bj)
; #pragma unroll
;             for (int n = 0; n < 2; ++n) bv[bj][n] = bias ? *(const f32x4*)(bias + bcol0 + bj * HALF + 4 * n) : (f32x4){0.f, 0.f, 0.f, 0.f};
; template <class Epi, class Sched>
; __device__ __forceinline__ void gemm_phase(PG8_LAS unsigned char* lds, const Gemm g, const Sched& S, const Epi& E) {
;     ...
;             PG8_LDA(At, 1, 1); PG8_STAGE(PG8_SA(1, 0), a3, voffA);
;             PG8_BAR; PG8_WAIT_L(0); PG8_MMA(1, 0, At, B0); PG8_BAR; PG8_SCHED;
;             PG8_STAGE(PG8_SB(1, 1), b3 + hstep, voffB);
;             PG8_WAIT_V(6); PG8_BAR; PG8_MMA(1, 1, At, B1); PG8_BAR;
	s_mov_b32 m0, s39
	v_lshl_add_u64 v[174:175], v[230:231], 0, s[14:15]
	ds_read_b128 v[144:147], v187 offset:49152
	ds_read_b128 v[148:151], v187 offset:50176
	ds_read_b128 v[182:185], v187 offset:51200
	ds_read_b128 v[192:195], v187 offset:52224
	ds_read_b128 v[196:199], v187 offset:53248
	ds_read_b128 v[200:203], v187 offset:54272
	ds_read_b128 v[204:207], v187 offset:55296
	ds_read_b128 v[208:211], v187 offset:56320
	global_load_lds_dwordx4 v[174:175], off
	v_lshl_add_u64 v[174:175], v[232:233], 0, s[14:15]
	s_mov_b32 m0, s40
	s_nop 0
	global_load_lds_dwordx4 v[174:175], off
	s_barrier
	s_waitcnt lgkmcnt(0)
	v_mfma_f32_16x16x32_bf16 v[76:79], v[48:51], v[144:147], v[76:79]
	v_mfma_f32_16x16x32_bf16 v[72:75], v[64:67], v[144:147], v[72:75]
	v_mfma_f32_16x16x32_bf16 v[60:63], v[48:51], v[182:185], v[60:63]
	v_mfma_f32_16x16x32_bf16 v[56:59], v[64:67], v[182:185], v[56:59]
	v_mfma_f32_16x16x32_bf16 v[36:39], v[48:51], v[196:199], v[36:39]
	v_mfma_f32_16x16x32_bf16 v[32:35], v[64:67], v[196:199], v[32:35]
	v_mfma_f32_16x16x32_bf16 v[12:15], v[48:51], v[204:207], v[12:15]
	v_mfma_f32_16x16x32_bf16 v[8:11], v[64:67], v[204:207], v[8:11]
	v_mfma_f32_16x16x32_bf16 v[76:79], v[52:55], v[148:151], v[76:79]
	v_mfma_f32_16x16x32_bf16 v[72:75], v[68:71], v[148:151], v[72:75]
	v_mfma_f32_16x16x32_bf16 v[60:63], v[52:55], v[192:195], v[60:63]
	v_mfma_f32_16x16x32_bf16 v[56:59], v[68:71], v[192:195], v[56:59]
	v_mfma_f32_16x16x32_bf16 v[36:39], v[52:55], v[200:203], v[36:39]
	v_mfma_f32_16x16x32_bf16 v[32:35], v[68:71], v[200:203], v[32:35]
	v_mfma_f32_16x16x32_bf16 v[12:15], v[52:55], v[208:211], v[12:15]
	v_mfma_f32_16x16x32_bf16 v[8:11], v[68:71], v[208:211], v[8:11]
	s_barrier
	s_add_u32 s4, s4, 0x40080
	s_addc_u32 s5, s5, 0
	s_add_i32 s28, s28, s35
	v_lshl_add_u64 v[48:49], s[4:5], 0, v[156:157]
	s_mov_b32 m0, s28
	s_nop 0
	global_load_lds_dwordx4 v[48:49], off
	v_lshl_add_u64 v[48:49], s[4:5], 0, v[160:161]
	s_add_i32 m0, s28, 0x2000
	s_nop 0
	global_load_lds_dwordx4 v[48:49], off
	s_waitcnt vmcnt(6)
	s_barrier
	v_mfma_f32_16x16x32_bf16 v[24:27], v[212:215], v[144:147], v[24:27]
	v_mfma_f32_16x16x32_bf16 v[68:71], v[216:219], v[148:151], v[24:27]
	v_mfma_f32_16x16x32_bf16 v[24:27], v[220:223], v[144:147], v[28:31]
	v_mfma_f32_16x16x32_bf16 v[64:67], v[224:227], v[148:151], v[24:27]
	v_mfma_f32_16x16x32_bf16 v[24:27], v[212:215], v[182:185], v[40:43]
	v_mfma_f32_16x16x32_bf16 v[52:55], v[216:219], v[192:195], v[24:27]
	v_mfma_f32_16x16x32_bf16 v[24:27], v[220:223], v[182:185], v[44:47]
	v_mfma_f32_16x16x32_bf16 v[20:23], v[212:215], v[196:199], v[20:23]
	v_mfma_f32_16x16x32_bf16 v[16:19], v[220:223], v[196:199], v[16:19]
	v_mfma_f32_16x16x32_bf16 v[4:7], v[212:215], v[204:207], v[4:7]
	v_mfma_f32_16x16x32_bf16 v[0:3], v[220:223], v[204:207], v[0:3]
	v_mfma_f32_16x16x32_bf16 v[48:51], v[224:227], v[192:195], v[24:27]
	v_mfma_f32_16x16x32_bf16 v[20:23], v[216:219], v[200:203], v[20:23]
	v_mfma_f32_16x16x32_bf16 v[16:19], v[224:227], v[200:203], v[16:19]
	v_mfma_f32_16x16x32_bf16 v[4:7], v[216:219], v[208:211], v[4:7]
	v_mfma_f32_16x16x32_bf16 v[0:3], v[224:227], v[208:211], v[0:3]
	s_barrier
	s_add_i32 s53, s53, 2
	s_add_u32 s0, s0, 0x100
	s_addc_u32 s1, s1, 0
	s_add_u32 s51, s51, 0x100
	s_addc_u32 s52, s52, 0
	s_cmp_gt_u32 s53, 13
	s_cbranch_scc0 .LBB0_416
	s_cmp_gt_i32 s26, 11
	s_cselect_b64 s[4:5], -1, 0
	s_cmp_lt_i32 s26, 12
	s_mov_b64 s[0:1], 0
	s_cbranch_scc1 .LBB0_422
	s_lshl_b32 s10, s26, 8
	s_cmp_lt_u32 s26, 14
	s_mov_b64 s[28:29], -1
	s_cbranch_scc0 .LBB0_420
	s_lshl_b64 s[0:1], s[10:11], 2
	v_readlane_b32 s52, v245, 0
	v_readlane_b32 s53, v245, 1
	s_add_u32 s0, s52, s0
	s_addc_u32 s1, s53, s1
	s_add_u32 s0, s0, 0xffffd000
	v_readlane_b32 s54, v245, 2
	v_readlane_b32 s55, v245, 3
	v_readlane_b32 s56, v245, 4
	v_readlane_b32 s57, v245, 5
	v_readlane_b32 s58, v245, 6
	v_readlane_b32 s59, v245, 7
	v_readlane_b32 s60, v245, 8
	v_readlane_b32 s61, v245, 9
	v_readlane_b32 s62, v245, 10
	v_readlane_b32 s63, v245, 11
	v_readlane_b32 s64, v245, 12
	v_readlane_b32 s65, v245, 13
	v_readlane_b32 s66, v245, 14
	v_readlane_b32 s67, v245, 15
	s_addc_u32 s1, s1, -1
	s_mov_b64 s[28:29], 0

; #define PG8_STAGE(bufoff, gbase, voff) do { _Pragma("unroll") for (int _i = 0; _i < 2; ++_i) \
;         __builtin_amdgcn_global_load_lds((const unsigned*)((const char*)(gbase) + (voff)[_i]), (PG8_LAS unsigned*)(lds + (bufoff) + ldsw + _i * 8192), 16, 0, 0); } while (0)
; #define PG8_LDA(dst, b, h) do { _Pragma("unroll") for (int m = 0; m < 4; ++m) _Pragma("unroll") for (int k = 0; k < 2; ++k) dst[m][k] = *(const PG8_LAS bf16x8*)(lds + PG8_SA(b, h) + aoff + m * 2048 + k * 1024); } while (0)
; #define PG8_LDB(dst, b, h) do { _Pragma("unroll") for (int n = 0; n < 2; ++n) _Pragma("unroll") for (int k = 0; k < 2; ++k) dst[n][k] = *(const PG8_LAS bf16x8*)(lds + PG8_SB(b, h) + boff + n * 2048 + k * 1024); } while (0)
; #define PG8_MMA(ai, bj, At, Bt) do { __builtin_amdgcn_s_setprio(1); _Pragma("unroll") for (int m = 0; m < 4; ++m) _Pragma("unroll") for (int n = 0; n < 2; ++n) _Pragma("unroll") for (int k = 0; k < 2; ++k) \
;         acc[ai][bj][m][n] = __builtin_amdgcn_mfma_f32_16x16x32_bf16(Bt[n][k], At[m][k], acc[ai][bj][m][n], 0, 0, 0); __builtin_amdgcn_s_setprio(0); } while (0)
; #define PG8_WAIT_V(n) asm volatile("s_waitcnt vmcnt(" #n ")" ::: "memory")
; #define PG8_WAIT_L(n) asm volatile("s_waitcnt lgkmcnt(" #n ")" ::: "memory")
; #define PG8_BAR __builtin_amdgcn_s_barrier()
; #define PG8_SCHED __builtin_amdgcn_sched_barrier(0)
; template <class Epi, class Sched>
; __device__ __forceinline__ void gemm_phase(PG8_LAS unsigned char* lds, const Gemm g, const Sched& S, const Epi& E) {
;     ...
;             PG8_LDB(B0, 0, 0); PG8_SCHED; PG8_LDA(At, 0, 0); PG8_STAGE(PG8_SA(1, 1), a1 + hstep, voffA);
;             PG8_WAIT_L(8); PG8_BAR; PG8_WAIT_L(0); PG8_MMA(0, 0, At, B0); PG8_BAR; PG8_SCHED;
;             PG8_LDB(B1, 0, 1); PG8_STAGE(PG8_SB(0, 0), b2, voffB);
;             PG8_BAR; PG8_WAIT_L(0); PG8_MMA(0, 1, At, B1); PG8_BAR;
;             PG8_LDA(At, 0, 1); PG8_STAGE(PG8_SA(0, 0), a2, voffA);
;             PG8_BAR; PG8_WAIT_L(0); PG8_MMA(1, 0, At, B0); PG8_BAR; PG8_SCHED;
;             PG8_STAGE(PG8_SB(0, 1), b2 + hstep, voffB);
;             PG8_WAIT_V(6); PG8_BAR; PG8_MMA(1, 1, At, B1); PG8_BAR;
.LBB0_724:
	ds_read_b128 v[144:147], v151
	ds_read_b128 v[156:159], v151 offset:1024
	ds_read_b128 v[160:163], v151 offset:2048
	ds_read_b128 v[166:169], v151 offset:3072
	s_add_u32 s20, s18, 0xfffc0080
	s_addc_u32 s21, s19, -1
	s_cmp_eq_u32 s48, 12
	s_cselect_b32 s23, s5, s21
	s_cselect_b32 s22, s11, s20
	s_cselect_b32 s21, s9, s47
	s_cselect_b32 s20, s45, s46
	v_lshl_add_u64 v[174:175], s[18:19], 0, v[136:137]
	s_add_i32 m0, s17, 0xc000
	ds_read_b128 v[170:173], v153
	ds_read_b128 v[182:185], v153 offset:1024
	ds_read_b128 v[190:193], v153 offset:2048
	ds_read_b128 v[194:197], v153 offset:3072
	ds_read_b128 v[198:201], v153 offset:4096
	ds_read_b128 v[202:205], v153 offset:5120
	ds_read_b128 v[206:209], v153 offset:6144
	ds_read_b128 v[210:213], v153 offset:7168
	global_load_lds_dwordx4 v[174:175], off
	v_lshl_add_u64 v[174:175], s[18:19], 0, v[138:139]
	s_add_i32 m0, s17, 0xe000
	s_nop 0
	global_load_lds_dwordx4 v[174:175], off
	s_waitcnt lgkmcnt(8)
	s_barrier
	s_waitcnt lgkmcnt(0)
	v_mfma_f32_16x16x32_bf16 v[124:127], v[144:147], v[170:173], v[124:127]
	v_mfma_f32_16x16x32_bf16 v[120:123], v[160:163], v[170:173], v[120:123]
	v_mfma_f32_16x16x32_bf16 v[108:111], v[144:147], v[190:193], v[108:111]
	v_mfma_f32_16x16x32_bf16 v[104:107], v[160:163], v[190:193], v[104:107]
	v_mfma_f32_16x16x32_bf16 v[92:95], v[144:147], v[198:201], v[92:95]
	v_mfma_f32_16x16x32_bf16 v[88:91], v[160:163], v[198:201], v[88:91]
	v_mfma_f32_16x16x32_bf16 v[76:79], v[144:147], v[206:209], v[76:79]
	v_mfma_f32_16x16x32_bf16 v[72:75], v[160:163], v[206:209], v[72:75]
	v_mfma_f32_16x16x32_bf16 v[124:127], v[156:159], v[182:185], v[124:127]
	v_mfma_f32_16x16x32_bf16 v[120:123], v[166:169], v[182:185], v[120:123]
	v_mfma_f32_16x16x32_bf16 v[108:111], v[156:159], v[194:197], v[108:111]
	v_mfma_f32_16x16x32_bf16 v[104:107], v[166:169], v[194:197], v[104:107]
	v_mfma_f32_16x16x32_bf16 v[92:95], v[156:159], v[202:205], v[92:95]
	v_mfma_f32_16x16x32_bf16 v[88:91], v[166:169], v[202:205], v[88:91]
	v_mfma_f32_16x16x32_bf16 v[76:79], v[156:159], v[210:213], v[76:79]
	v_mfma_f32_16x16x32_bf16 v[72:75], v[166:169], v[210:213], v[72:75]
	s_barrier
	s_add_i32 s49, s42, s30
	v_lshl_add_u64 v[174:175], s[20:21], 0, v[130:131]
	s_mov_b32 m0, s49
	ds_read_b128 v[214:217], v154
	ds_read_b128 v[218:221], v154 offset:1024
	ds_read_b128 v[222:225], v154 offset:2048
	ds_read_b128 v[226:229], v154 offset:3072
	global_load_lds_dwordx4 v[174:175], off
	v_lshl_add_u64 v[186:187], s[20:21], 0, v[134:135]
	s_add_i32 m0, s49, 0x2000
	s_nop 0
	global_load_lds_dwordx4 v[186:187], off
	s_barrier
	s_waitcnt lgkmcnt(0)
	v_mfma_f32_16x16x32_bf16 v[116:119], v[214:217], v[170:173], v[116:119]
	v_mfma_f32_16x16x32_bf16 v[112:115], v[222:225], v[170:173], v[112:115]
	v_mfma_f32_16x16x32_bf16 v[100:103], v[214:217], v[190:193], v[100:103]
	v_mfma_f32_16x16x32_bf16 v[96:99], v[222:225], v[190:193], v[96:99]
	v_mfma_f32_16x16x32_bf16 v[84:87], v[214:217], v[198:201], v[84:87]
	v_mfma_f32_16x16x32_bf16 v[80:83], v[222:225], v[198:201], v[80:83]
	v_mfma_f32_16x16x32_bf16 v[68:71], v[214:217], v[206:209], v[68:71]
	v_mfma_f32_16x16x32_bf16 v[64:67], v[222:225], v[206:209], v[64:67]
	v_mfma_f32_16x16x32_bf16 v[116:119], v[218:221], v[182:185], v[116:119]
	v_mfma_f32_16x16x32_bf16 v[112:115], v[226:229], v[182:185], v[112:115]
	v_mfma_f32_16x16x32_bf16 v[100:103], v[218:221], v[194:197], v[100:103]
	v_mfma_f32_16x16x32_bf16 v[96:99], v[226:229], v[194:197], v[96:99]
	v_mfma_f32_16x16x32_bf16 v[84:87], v[218:221], v[202:205], v[84:87]
	v_mfma_f32_16x16x32_bf16 v[80:83], v[226:229], v[202:205], v[80:83]
	v_mfma_f32_16x16x32_bf16 v[68:71], v[218:221], v[210:213], v[68:71]
	v_mfma_f32_16x16x32_bf16 v[64:67], v[226:229], v[210:213], v[64:67]
	s_barrier
	s_mov_b32 m0, s17
	v_lshl_add_u64 v[230:231], s[22:23], 0, v[128:129]
	ds_read_b128 v[170:173], v153 offset:16384
	ds_read_b128 v[182:185], v153 offset:17408
	ds_read_b128 v[190:193], v153 offset:18432
	ds_read_b128 v[194:197], v153 offset:19456
	ds_read_b128 v[198:201], v153 offset:20480
	ds_read_b128 v[202:205], v153 offset:21504
	ds_read_b128 v[206:209], v153 offset:22528
	ds_read_b128 v[210:213], v153 offset:23552
	global_load_lds_dwordx4 v[230:231], off
	v_lshl_add_u64 v[232:233], s[22:23], 0, v[132:133]
	s_mov_b32 m0, s31
	s_nop 0
	global_load_lds_dwordx4 v[232:233], off
	s_barrier
	s_waitcnt lgkmcnt(0)
	v_mfma_f32_16x16x32_bf16 v[60:63], v[144:147], v[170:173], v[60:63]
	v_mfma_f32_16x16x32_bf16 v[56:59], v[160:163], v[170:173], v[56:59]
	v_mfma_f32_16x16x32_bf16 v[44:47], v[144:147], v[190:193], v[44:47]
	v_mfma_f32_16x16x32_bf16 v[40:43], v[160:163], v[190:193], v[40:43]
	v_mfma_f32_16x16x32_bf16 v[28:31], v[144:147], v[198:201], v[28:31]
	v_mfma_f32_16x16x32_bf16 v[24:27], v[160:163], v[198:201], v[24:27]
	v_mfma_f32_16x16x32_bf16 v[12:15], v[144:147], v[206:209], v[12:15]
	v_mfma_f32_16x16x32_bf16 v[8:11], v[160:163], v[206:209], v[8:11]
	v_mfma_f32_16x16x32_bf16 v[60:63], v[156:159], v[182:185], v[60:63]
	v_mfma_f32_16x16x32_bf16 v[56:59], v[166:169], v[182:185], v[56:59]
	v_mfma_f32_16x16x32_bf16 v[44:47], v[156:159], v[194:197], v[44:47]
	v_mfma_f32_16x16x32_bf16 v[40:43], v[166:169], v[194:197], v[40:43]
	v_mfma_f32_16x16x32_bf16 v[28:31], v[156:159], v[202:205], v[28:31]
	v_mfma_f32_16x16x32_bf16 v[24:27], v[166:169], v[202:205], v[24:27]
	v_mfma_f32_16x16x32_bf16 v[12:15], v[156:159], v[210:213], v[12:15]
	v_mfma_f32_16x16x32_bf16 v[8:11], v[166:169], v[210:213], v[8:11]
	s_barrier
; #define PG8_STAGE(bufoff, gbase, voff) do { _Pragma("unroll") for (int _i = 0; _i < 2; ++_i) \
;         __builtin_amdgcn_global_load_lds((const unsigned*)((const char*)(gbase) + (voff)[_i]), (PG8_LAS unsigned*)(lds + (bufoff) + ldsw + _i * 8192), 16, 0, 0); } while (0)
; #define PG8_LDA(dst, b, h) do { _Pragma("unroll") for (int m = 0; m < 4; ++m) _Pragma("unroll") for (int k = 0; k < 2; ++k) dst[m][k] = *(const PG8_LAS bf16x8*)(lds + PG8_SA(b, h) + aoff + m * 2048 + k * 1024); } while (0)
; #define PG8_LDB(dst, b, h) do { _Pragma("unroll") for (int n = 0; n < 2; ++n) _Pragma("unroll") for (int k = 0; k < 2; ++k) dst[n][k] = *(const PG8_LAS bf16x8*)(lds + PG8_SB(b, h) + boff + n * 2048 + k * 1024); } while (0)
; #define PG8_MMA(ai, bj, At, Bt) do { __builtin_amdgcn_s_setprio(1); _Pragma("unroll") for (int m = 0; m < 4; ++m) _Pragma("unroll") for (int n = 0; n < 2; ++n) _Pragma("unroll") for (int k = 0; k < 2; ++k) \
;         acc[ai][bj][m][n] = __builtin_amdgcn_mfma_f32_16x16x32_bf16(Bt[n][k], At[m][k], acc[ai][bj][m][n], 0, 0, 0); __builtin_amdgcn_s_setprio(0); } while (0)
; #define PG8_WAIT_V(n) asm volatile("s_waitcnt vmcnt(" #n ")" ::: "memory")
; #define PG8_WAIT_L(n) asm volatile("s_waitcnt lgkmcnt(" #n ")" ::: "memory")
; #define PG8_BAR __builtin_amdgcn_s_barrier()
; #define PG8_SCHED __builtin_amdgcn_sched_barrier(0)
; template <class Epi, class Sched>
; __device__ __forceinline__ void gemm_phase(PG8_LAS unsigned char* lds, const Gemm g, const Sched& S, const Epi& E) {
;     ...
;             PG8_WAIT_V(6); PG8_BAR; PG8_MMA(1, 1, At, B1); PG8_BAR;
;             PG8_LDB(B0, 1, 0); PG8_SCHED; PG8_LDA(At, 1, 0); PG8_STAGE(PG8_SA(0, 1), a2 + hstep, voffA);
;             PG8_WAIT_L(8); PG8_BAR; PG8_WAIT_L(0); PG8_MMA(0, 0, At, B0); PG8_BAR; PG8_SCHED;
;             PG8_LDB(B1, 1, 1); PG8_STAGE(PG8_SB(1, 0), b3, voffB);
;             PG8_BAR; PG8_WAIT_L(0); PG8_MMA(0, 1, At, B1); PG8_BAR;
;             PG8_LDA(At, 1, 1); PG8_STAGE(PG8_SA(1, 0), a3, voffA);
;             PG8_BAR; PG8_WAIT_L(0); PG8_MMA(1, 0, At, B0); PG8_BAR; PG8_SCHED;
;             PG8_STAGE(PG8_SB(1, 1), b3 + hstep, voffB);
	s_add_u32 s50, s20, 0x40000
	s_addc_u32 s51, s21, 0
	s_add_i32 s49, s43, s30
	v_lshl_add_u64 v[144:145], s[50:51], 0, v[130:131]
	s_mov_b32 m0, s49
	s_nop 0
	global_load_lds_dwordx4 v[144:145], off
	v_lshl_add_u64 v[144:145], s[50:51], 0, v[134:135]
	s_add_i32 m0, s49, 0x2000
	s_nop 0
	global_load_lds_dwordx4 v[144:145], off
	s_waitcnt vmcnt(6)
	s_barrier
	v_mfma_f32_16x16x32_bf16 v[52:55], v[214:217], v[170:173], v[52:55]
	v_mfma_f32_16x16x32_bf16 v[48:51], v[222:225], v[170:173], v[48:51]
	v_mfma_f32_16x16x32_bf16 v[36:39], v[214:217], v[190:193], v[36:39]
	v_mfma_f32_16x16x32_bf16 v[32:35], v[222:225], v[190:193], v[32:35]
	v_mfma_f32_16x16x32_bf16 v[20:23], v[214:217], v[198:201], v[20:23]
	v_mfma_f32_16x16x32_bf16 v[16:19], v[222:225], v[198:201], v[16:19]
	v_mfma_f32_16x16x32_bf16 v[4:7], v[214:217], v[206:209], v[4:7]
	v_mfma_f32_16x16x32_bf16 v[0:3], v[222:225], v[206:209], v[0:3]
	v_mfma_f32_16x16x32_bf16 v[52:55], v[218:221], v[182:185], v[52:55]
	v_mfma_f32_16x16x32_bf16 v[48:51], v[226:229], v[182:185], v[48:51]
	v_mfma_f32_16x16x32_bf16 v[36:39], v[218:221], v[194:197], v[36:39]
	v_mfma_f32_16x16x32_bf16 v[32:35], v[226:229], v[194:197], v[32:35]
	v_mfma_f32_16x16x32_bf16 v[20:23], v[218:221], v[202:205], v[20:23]
	v_mfma_f32_16x16x32_bf16 v[16:19], v[226:229], v[202:205], v[16:19]
	v_mfma_f32_16x16x32_bf16 v[4:7], v[218:221], v[210:213], v[4:7]
	v_mfma_f32_16x16x32_bf16 v[0:3], v[226:229], v[210:213], v[0:3]
	s_barrier
	s_add_i32 s49, 0, 0x18000
	v_add_u32_e32 v155, s49, v149
	ds_read_b128 v[144:147], v155
	ds_read_b128 v[156:159], v155 offset:1024
	ds_read_b128 v[160:163], v155 offset:2048
	ds_read_b128 v[166:169], v155 offset:3072
	s_add_u32 s22, s22, 0x40000
	s_addc_u32 s23, s23, 0
	s_mov_b32 m0, s34
	v_lshl_add_u64 v[214:215], s[22:23], 0, v[128:129]
	ds_read_b128 v[170:173], v153 offset:32768
	ds_read_b128 v[182:185], v153 offset:33792
	ds_read_b128 v[190:193], v153 offset:34816
	ds_read_b128 v[194:197], v153 offset:35840
	ds_read_b128 v[198:201], v153 offset:36864
	ds_read_b128 v[202:205], v153 offset:37888
	ds_read_b128 v[206:209], v153 offset:38912
	ds_read_b128 v[210:213], v153 offset:39936
	global_load_lds_dwordx4 v[214:215], off
	v_lshl_add_u64 v[214:215], s[22:23], 0, v[132:133]
	s_mov_b32 m0, s35
	s_nop 0
	global_load_lds_dwordx4 v[214:215], off
	s_waitcnt lgkmcnt(8)
	s_barrier
	s_waitcnt lgkmcnt(0)
	v_mfma_f32_16x16x32_bf16 v[124:127], v[144:147], v[170:173], v[124:127]
	v_mfma_f32_16x16x32_bf16 v[120:123], v[160:163], v[170:173], v[120:123]
	v_mfma_f32_16x16x32_bf16 v[108:111], v[144:147], v[190:193], v[108:111]
	v_mfma_f32_16x16x32_bf16 v[104:107], v[160:163], v[190:193], v[104:107]
	v_mfma_f32_16x16x32_bf16 v[92:95], v[144:147], v[198:201], v[92:95]
	v_mfma_f32_16x16x32_bf16 v[88:91], v[160:163], v[198:201], v[88:91]
	v_mfma_f32_16x16x32_bf16 v[76:79], v[144:147], v[206:209], v[76:79]
	v_mfma_f32_16x16x32_bf16 v[72:75], v[160:163], v[206:209], v[72:75]
	v_mfma_f32_16x16x32_bf16 v[124:127], v[156:159], v[182:185], v[124:127]
	v_mfma_f32_16x16x32_bf16 v[120:123], v[166:169], v[182:185], v[120:123]
	v_mfma_f32_16x16x32_bf16 v[108:111], v[156:159], v[194:197], v[108:111]
	v_mfma_f32_16x16x32_bf16 v[104:107], v[166:169], v[194:197], v[104:107]
	v_mfma_f32_16x16x32_bf16 v[92:95], v[156:159], v[202:205], v[92:95]
	v_mfma_f32_16x16x32_bf16 v[88:91], v[166:169], v[202:205], v[88:91]
	v_mfma_f32_16x16x32_bf16 v[76:79], v[156:159], v[210:213], v[76:79]
	v_mfma_f32_16x16x32_bf16 v[72:75], v[166:169], v[210:213], v[72:75]
	s_barrier
	s_add_i32 s22, 0, 0x1c000
	s_add_i32 s23, s49, s30
	v_add_u32_e32 v155, s22, v149
	v_lshl_add_u64 v[174:175], v[174:175], 0, s[6:7]
	s_mov_b32 m0, s23
	ds_read_b128 v[214:217], v155
	ds_read_b128 v[218:221], v155 offset:1024
	ds_read_b128 v[222:225], v155 offset:2048
	ds_read_b128 v[226:229], v155 offset:3072
	global_load_lds_dwordx4 v[174:175], off
	v_lshl_add_u64 v[174:175], v[186:187], 0, s[6:7]
	s_add_i32 m0, s23, 0x2000
	s_nop 0
	global_load_lds_dwordx4 v[174:175], off
	s_barrier
	s_waitcnt lgkmcnt(0)
	v_mfma_f32_16x16x32_bf16 v[116:119], v[214:217], v[170:173], v[116:119]
	v_mfma_f32_16x16x32_bf16 v[112:115], v[222:225], v[170:173], v[112:115]
	v_mfma_f32_16x16x32_bf16 v[100:103], v[214:217], v[190:193], v[100:103]
	v_mfma_f32_16x16x32_bf16 v[96:99], v[222:225], v[190:193], v[96:99]
	v_mfma_f32_16x16x32_bf16 v[84:87], v[214:217], v[198:201], v[84:87]
	v_mfma_f32_16x16x32_bf16 v[80:83], v[222:225], v[198:201], v[80:83]
	v_mfma_f32_16x16x32_bf16 v[68:71], v[214:217], v[206:209], v[68:71]
	v_mfma_f32_16x16x32_bf16 v[64:67], v[222:225], v[206:209], v[64:67]
	v_mfma_f32_16x16x32_bf16 v[116:119], v[218:221], v[182:185], v[116:119]
	v_mfma_f32_16x16x32_bf16 v[112:115], v[226:229], v[182:185], v[112:115]
	v_mfma_f32_16x16x32_bf16 v[100:103], v[218:221], v[194:197], v[100:103]
	v_mfma_f32_16x16x32_bf16 v[96:99], v[226:229], v[194:197], v[96:99]
	v_mfma_f32_16x16x32_bf16 v[84:87], v[218:221], v[202:205], v[84:87]
	v_mfma_f32_16x16x32_bf16 v[80:83], v[226:229], v[202:205], v[80:83]
	v_mfma_f32_16x16x32_bf16 v[68:71], v[218:221], v[210:213], v[68:71]
	v_mfma_f32_16x16x32_bf16 v[64:67], v[226:229], v[210:213], v[64:67]
	s_barrier
	s_mov_b32 m0, s37
	v_lshl_add_u64 v[174:175], v[230:231], 0, s[6:7]
	ds_read_b128 v[170:173], v153 offset:49152
	ds_read_b128 v[182:185], v153 offset:50176
	ds_read_b128 v[190:193], v153 offset:51200
	ds_read_b128 v[194:197], v153 offset:52224
	ds_read_b128 v[198:201], v153 offset:53248
	ds_read_b128 v[202:205], v153 offset:54272
	ds_read_b128 v[206:209], v153 offset:55296
	ds_read_b128 v[210:213], v153 offset:56320
	global_load_lds_dwordx4 v[174:175], off
	v_lshl_add_u64 v[174:175], v[232:233], 0, s[6:7]
	s_mov_b32 m0, s38
	s_nop 0
	global_load_lds_dwordx4 v[174:175], off
	s_barrier
; #define PG8_WAIT_V(n) asm volatile("s_waitcnt vmcnt(" #n ")" ::: "memory")
; __device__ __forceinline__ f32x4 sigmoid4(f32x4 x) {
;     f32x4 d;
; #pragma unroll
;     for (int j = 0; j < 4; ++j) d[j] = 1.0f + __expf(-fmaxf(x[j], -20.0f));
;     const float p01 = d[0] * d[1], p23 = d[2] * d[3], r = __builtin_amdgcn_rcpf(p01 * p23), r01 = r * p23, r23 = r * p01;
;     return (f32x4){r01 * d[1], r01 * d[0], r23 * d[3], r23 * d[2]};
; }
; __device__ __forceinline__ float flogsig16(float x) { return (fminf(x, 0.f) - __logf(1.0f + __expf(-fabsf(x)))) * 0.0625f; }
; __device__ __forceinline__ float bf_lo(unsigned u) { return __uint_as_float(u << 16); }
; __device__ __forceinline__ float bf_hi(unsigned u) { return __uint_as_float(u & 0xffff0000u); }
;     __device__ __forceinline__ void operator()(const f32x4 (&acc)[2][2][4][2], const Unit& u, int wr, int wc, int fr, int fq) const {
;         int act = 0; const float* bias = nullptr;
;         if (mode == 1) { if (u.pn >= 8 && u.pn < 12) act = 1; else if (u.pn >= 12) { act = 3; bias = (u.pn >= 14) ? bias_b + (u.pn - 14) * 256 : bias_f + (u.pn - 12) * 256; } }
;         else if (mode == 2) { if (u.pn >= 6) act = 2; }
;         const int row0 = u.pm * BM + wr * 64 + fr, col0 = u.pn * BM + wc * 32 + 8 * fq, bcol0 = wc * 32 + 8 * fq;
;         f32x4 bv[2][2];
; #pragma unroll
;         for (int bj = 0; bj < 2; ++bj)
; #pragma unroll
;             for (int n = 0; n < 2; ++n) bv[bj][n] = bias ? *(const f32x4*)(bias + bcol0 + bj * HALF + 4 * n) : (f32x4){0.f, 0.f, 0.f, 0.f};
; #pragma unroll
;         for (int ai = 0; ai < 2; ++ai)
; #pragma unroll
;             for (int m = 0; m < 4; ++m) { bf16_t* rowp = O + (size_t)(row0 + ai * HALF + m * 16) * ldc + col0;
; #pragma unroll
;                 for (int bj = 0; bj < 2; ++bj) { f32x4 v0 = acc[ai][bj][m][0] + bv[bj][0], v1 = acc[ai][bj][m][1] + bv[bj][1];
;                     if (act == 1) {
; #pragma unroll
; template <class Epi, class Sched>
; __device__ __forceinline__ void gemm_phase(PG8_LAS unsigned char* lds, const Gemm g, const Sched& S, const Epi& E) {
;     ...
;             PG8_BAR; PG8_WAIT_L(0); PG8_MMA(1, 0, At, B0); PG8_BAR; PG8_SCHED;
;             PG8_STAGE(PG8_SB(1, 1), b3 + hstep, voffB);
;             PG8_WAIT_V(6); PG8_BAR; PG8_MMA(1, 1, At, B1); PG8_BAR;
;         }
;         if constexpr (!Epi::AFTER_DRAIN) { E(acc, cur, wr, wc, fr, fq); S.done(cur); }
	s_waitcnt lgkmcnt(0)
	v_mfma_f32_16x16x32_bf16 v[60:63], v[144:147], v[170:173], v[60:63]
	v_mfma_f32_16x16x32_bf16 v[56:59], v[160:163], v[170:173], v[56:59]
	v_mfma_f32_16x16x32_bf16 v[44:47], v[144:147], v[190:193], v[44:47]
	v_mfma_f32_16x16x32_bf16 v[40:43], v[160:163], v[190:193], v[40:43]
	v_mfma_f32_16x16x32_bf16 v[28:31], v[144:147], v[198:201], v[28:31]
	v_mfma_f32_16x16x32_bf16 v[24:27], v[160:163], v[198:201], v[24:27]
	v_mfma_f32_16x16x32_bf16 v[12:15], v[144:147], v[206:209], v[12:15]
	v_mfma_f32_16x16x32_bf16 v[8:11], v[160:163], v[206:209], v[8:11]
	v_mfma_f32_16x16x32_bf16 v[60:63], v[156:159], v[182:185], v[60:63]
	v_mfma_f32_16x16x32_bf16 v[56:59], v[166:169], v[182:185], v[56:59]
	v_mfma_f32_16x16x32_bf16 v[44:47], v[156:159], v[194:197], v[44:47]
	v_mfma_f32_16x16x32_bf16 v[40:43], v[166:169], v[194:197], v[40:43]
	v_mfma_f32_16x16x32_bf16 v[28:31], v[156:159], v[202:205], v[28:31]
	v_mfma_f32_16x16x32_bf16 v[24:27], v[166:169], v[202:205], v[24:27]
	v_mfma_f32_16x16x32_bf16 v[12:15], v[156:159], v[210:213], v[12:15]
	v_mfma_f32_16x16x32_bf16 v[8:11], v[166:169], v[210:213], v[8:11]
	s_barrier
	s_add_u32 s20, s20, 0x40080
	s_addc_u32 s21, s21, 0
	s_add_i32 s22, s22, s30
	v_lshl_add_u64 v[144:145], s[20:21], 0, v[130:131]
	s_mov_b32 m0, s22
	s_nop 0
	global_load_lds_dwordx4 v[144:145], off
	v_lshl_add_u64 v[144:145], s[20:21], 0, v[134:135]
	s_add_i32 m0, s22, 0x2000
	s_nop 0
	global_load_lds_dwordx4 v[144:145], off
	s_waitcnt vmcnt(6)
	s_barrier
	v_mfma_f32_16x16x32_bf16 v[52:55], v[214:217], v[170:173], v[52:55]
	v_mfma_f32_16x16x32_bf16 v[48:51], v[222:225], v[170:173], v[48:51]
	v_mfma_f32_16x16x32_bf16 v[36:39], v[214:217], v[190:193], v[36:39]
	v_mfma_f32_16x16x32_bf16 v[32:35], v[222:225], v[190:193], v[32:35]
	v_mfma_f32_16x16x32_bf16 v[20:23], v[214:217], v[198:201], v[20:23]
	v_mfma_f32_16x16x32_bf16 v[16:19], v[222:225], v[198:201], v[16:19]
	v_mfma_f32_16x16x32_bf16 v[4:7], v[214:217], v[206:209], v[4:7]
	v_mfma_f32_16x16x32_bf16 v[0:3], v[222:225], v[206:209], v[0:3]
	v_mfma_f32_16x16x32_bf16 v[52:55], v[218:221], v[182:185], v[52:55]
	v_mfma_f32_16x16x32_bf16 v[48:51], v[226:229], v[182:185], v[48:51]
	v_mfma_f32_16x16x32_bf16 v[36:39], v[218:221], v[194:197], v[36:39]
	v_mfma_f32_16x16x32_bf16 v[32:35], v[226:229], v[194:197], v[32:35]
	v_mfma_f32_16x16x32_bf16 v[20:23], v[218:221], v[202:205], v[20:23]
	v_mfma_f32_16x16x32_bf16 v[16:19], v[226:229], v[202:205], v[16:19]
	v_mfma_f32_16x16x32_bf16 v[4:7], v[218:221], v[210:213], v[4:7]
	v_mfma_f32_16x16x32_bf16 v[0:3], v[226:229], v[210:213], v[0:3]
	s_barrier
	s_add_i32 s48, s48, 2
	s_add_u32 s18, s18, 0x100
	s_addc_u32 s19, s19, 0
	s_add_u32 s46, s46, 0x100
	s_addc_u32 s47, s47, 0
	s_cmp_gt_u32 s48, 13
	s_cbranch_scc0 .LBB0_724
	s_cmp_gt_i32 s4, 5
	s_cselect_b64 s[18:19], -1, 0
	s_cmp_lt_i32 s4, 6
	v_pk_add_f32 v[144:145], v[126:127], 0 op_sel_hi:[1,0]
	v_pk_add_f32 v[146:147], v[124:125], 0 op_sel_hi:[1,0]
	v_pk_add_f32 v[124:125], v[122:123], 0 op_sel_hi:[1,0]
	v_pk_add_f32 v[126:127], v[120:121], 0 op_sel_hi:[1,0]
	s_cbranch_scc1 .LBB0_727
	v_max_f32_e32 v122, v144, v144
	v_max_f32_e32 v122, 0xc1a00000, v122
	v_mul_f32_e32 v122, 0xbfb8aa3b, v122
	v_max_f32_e32 v120, v146, v146
	v_max_f32_e32 v121, v147, v147
	v_exp_f32_e32 v123, v122
	v_max_f32_e32 v122, v145, v145
	v_max_f32_e32 v120, 0xc1a00000, v120
	v_max_f32_e32 v121, 0xc1a00000, v121
	v_max_f32_e32 v122, 0xc1a00000, v122
	v_mul_f32_e32 v120, 0xbfb8aa3b, v120
	v_mul_f32_e32 v121, 0xbfb8aa3b, v121
	v_mul_f32_e32 v122, 0xbfb8aa3b, v122
	v_exp_f32_e32 v120, v120
	v_exp_f32_e32 v121, v121
	v_exp_f32_e32 v122, v122
	v_max_f32_e32 v124, v124, v124
	v_max_f32_e32 v124, 0xc1a00000, v124
	v_pk_add_f32 v[120:121], v[120:121], 1.0 op_sel_hi:[1,0]
	v_pk_add_f32 v[122:123], v[122:123], 1.0 op_sel_hi:[1,0]
	v_mov_b32_e32 v144, v120
	v_mov_b32_e32 v145, v123
	v_pk_mov_b32 v[146:147], v[120:121], v[122:123] op_sel:[1,0]
	v_mul_f32_e32 v124, 0xbfb8aa3b, v124
	v_pk_mul_f32 v[144:145], v[144:145], v[146:147]
	v_max_f32_e32 v126, v126, v126
	v_max_f32_e32 v127, v127, v127
	v_exp_f32_e32 v147, v124
	v_max_f32_e32 v124, v125, v125
	v_max_f32_e32 v126, 0xc1a00000, v126
	v_max_f32_e32 v127, 0xc1a00000, v127
	v_max_f32_e32 v124, 0xc1a00000, v124
	v_mul_f32_e32 v146, v144, v145
	v_mul_f32_e32 v126, 0xbfb8aa3b, v126
	v_mul_f32_e32 v127, 0xbfb8aa3b, v127
	v_mul_f32_e32 v124, 0xbfb8aa3b, v124
	v_rcp_f32_e32 v155, v146
	v_exp_f32_e32 v126, v126
	v_exp_f32_e32 v127, v127
	v_exp_f32_e32 v146, v124
	v_mul_f32_e32 v124, v145, v155
	v_mul_f32_e32 v144, v144, v155
	v_pk_add_f32 v[126:127], v[126:127], 1.0 op_sel_hi:[1,0]
	v_pk_add_f32 v[156:157], v[146:147], 1.0 op_sel_hi:[1,0]
	v_mov_b32_e32 v146, v126
	v_mov_b32_e32 v147, v157
	v_pk_mov_b32 v[158:159], v[126:127], v[156:157] op_sel:[1,0]
	v_pk_mul_f32 v[144:145], v[122:123], v[144:145] op_sel_hi:[1,0]
	v_pk_mul_f32 v[158:159], v[146:147], v[158:159]
	s_nop 0
	v_mul_f32_e32 v125, v158, v159
	v_rcp_f32_e32 v125, v125
	s_nop 0
	v_pk_mul_f32 v[146:147], v[120:121], v[124:125] op_sel:[1,0] op_sel_hi:[0,0]
	v_mul_f32_e32 v120, v159, v125
	v_mul_f32_e32 v122, v158, v125
	v_pk_mul_f32 v[124:125], v[156:157], v[122:123] op_sel_hi:[1,0]
	v_pk_mul_f32 v[126:127], v[126:127], v[120:121] op_sel:[1,0] op_sel_hi:[0,0]

; #define PG8_STAGE(bufoff, gbase, voff) do { _Pragma("unroll") for (int _i = 0; _i < 2; ++_i) \
;         __builtin_amdgcn_global_load_lds((const unsigned*)((const char*)(gbase) + (voff)[_i]), (PG8_LAS unsigned*)(lds + (bufoff) + ldsw + _i * 8192), 16, 0, 0); } while (0)
; #define PG8_LDA(dst, b, h) do { _Pragma("unroll") for (int m = 0; m < 4; ++m) _Pragma("unroll") for (int k = 0; k < 2; ++k) dst[m][k] = *(const PG8_LAS bf16x8*)(lds + PG8_SA(b, h) + aoff + m * 2048 + k * 1024); } while (0)
; #define PG8_LDB(dst, b, h) do { _Pragma("unroll") for (int n = 0; n < 2; ++n) _Pragma("unroll") for (int k = 0; k < 2; ++k) dst[n][k] = *(const PG8_LAS bf16x8*)(lds + PG8_SB(b, h) + boff + n * 2048 + k * 1024); } while (0)
; #define PG8_MMA(ai, bj, At, Bt) do { __builtin_amdgcn_s_setprio(1); _Pragma("unroll") for (int m = 0; m < 4; ++m) _Pragma("unroll") for (int n = 0; n < 2; ++n) _Pragma("unroll") for (int k = 0; k < 2; ++k) \
;         acc[ai][bj][m][n] = __builtin_amdgcn_mfma_f32_16x16x32_bf16(Bt[n][k], At[m][k], acc[ai][bj][m][n], 0, 0, 0); __builtin_amdgcn_s_setprio(0); } while (0)
; #define PG8_WAIT_V(n) asm volatile("s_waitcnt vmcnt(" #n ")" ::: "memory")
; #define PG8_WAIT_L(n) asm volatile("s_waitcnt lgkmcnt(" #n ")" ::: "memory")
; #define PG8_BAR __builtin_amdgcn_s_barrier()
; #define PG8_SCHED __builtin_amdgcn_sched_barrier(0)
; template <class Epi, class Sched>
; __device__ __forceinline__ void gemm_phase(PG8_LAS unsigned char* lds, const Gemm g, const Sched& S, const Epi& E) {
;     ...
;             PG8_LDB(B0, 0, 0); PG8_SCHED; PG8_LDA(At, 0, 0); PG8_STAGE(PG8_SA(1, 1), a1 + hstep, voffA);
;             PG8_WAIT_L(8); PG8_BAR; PG8_WAIT_L(0); PG8_MMA(0, 0, At, B0); PG8_BAR; PG8_SCHED;
;             PG8_LDB(B1, 0, 1); PG8_STAGE(PG8_SB(0, 0), b2, voffB);
;             PG8_BAR; PG8_WAIT_L(0); PG8_MMA(0, 1, At, B1); PG8_BAR;
;             PG8_LDA(At, 0, 1); PG8_STAGE(PG8_SA(0, 0), a2, voffA);
;             PG8_BAR; PG8_WAIT_L(0); PG8_MMA(1, 0, At, B0); PG8_BAR; PG8_SCHED;
;             PG8_STAGE(PG8_SB(0, 1), b2 + hstep, voffB);
;             PG8_WAIT_V(6); PG8_BAR; PG8_MMA(1, 1, At, B1); PG8_BAR;
.LBB0_991:
	ds_read_b128 v[144:147], v153
	ds_read_b128 v[156:159], v153 offset:1024
	ds_read_b128 v[160:163], v153 offset:2048
	ds_read_b128 v[164:167], v153 offset:3072
	s_add_u32 s20, s18, 0xfffc0080
	s_addc_u32 s21, s19, -1
	s_cmp_eq_u32 s47, 12
	s_cselect_b32 s23, s11, s21
	s_cselect_b32 s22, s43, s20
	s_cselect_b32 s21, s9, s46
	s_cselect_b32 s20, s44, s45
	v_lshl_add_u64 v[148:149], s[18:19], 0, v[136:137]
	s_add_i32 m0, s17, 0xc000
	ds_read_b128 v[168:171], v154
	ds_read_b128 v[172:175], v154 offset:1024
	ds_read_b128 v[182:185], v154 offset:2048
	ds_read_b128 v[190:193], v154 offset:3072
	ds_read_b128 v[194:197], v154 offset:4096
	ds_read_b128 v[198:201], v154 offset:5120
	ds_read_b128 v[202:205], v154 offset:6144
	ds_read_b128 v[206:209], v154 offset:7168
	global_load_lds_dwordx4 v[148:149], off
	v_lshl_add_u64 v[148:149], s[18:19], 0, v[138:139]
	s_add_i32 m0, s17, 0xe000
	s_nop 0
	global_load_lds_dwordx4 v[148:149], off
	s_waitcnt lgkmcnt(8)
	s_barrier
	s_waitcnt lgkmcnt(0)
	v_mfma_f32_16x16x32_bf16 v[124:127], v[144:147], v[168:171], v[124:127]
	v_mfma_f32_16x16x32_bf16 v[120:123], v[160:163], v[168:171], v[120:123]
	v_mfma_f32_16x16x32_bf16 v[112:115], v[144:147], v[182:185], v[112:115]
	v_mfma_f32_16x16x32_bf16 v[104:107], v[160:163], v[182:185], v[104:107]
	v_mfma_f32_16x16x32_bf16 v[96:99], v[144:147], v[194:197], v[96:99]
	v_mfma_f32_16x16x32_bf16 v[88:91], v[160:163], v[194:197], v[88:91]
	v_mfma_f32_16x16x32_bf16 v[80:83], v[144:147], v[202:205], v[80:83]
	v_mfma_f32_16x16x32_bf16 v[72:75], v[160:163], v[202:205], v[72:75]
	v_mfma_f32_16x16x32_bf16 v[124:127], v[156:159], v[172:175], v[124:127]
	v_mfma_f32_16x16x32_bf16 v[120:123], v[164:167], v[172:175], v[120:123]
	v_mfma_f32_16x16x32_bf16 v[112:115], v[156:159], v[190:193], v[112:115]
	v_mfma_f32_16x16x32_bf16 v[104:107], v[164:167], v[190:193], v[104:107]
	v_mfma_f32_16x16x32_bf16 v[96:99], v[156:159], v[198:201], v[96:99]
	v_mfma_f32_16x16x32_bf16 v[88:91], v[164:167], v[198:201], v[88:91]
	v_mfma_f32_16x16x32_bf16 v[80:83], v[156:159], v[206:209], v[80:83]
	v_mfma_f32_16x16x32_bf16 v[72:75], v[164:167], v[206:209], v[72:75]
	s_barrier
	s_add_i32 s48, s39, s29
	v_lshl_add_u64 v[148:149], s[20:21], 0, v[130:131]
	s_mov_b32 m0, s48
	ds_read_b128 v[210:213], v155
	ds_read_b128 v[214:217], v155 offset:1024
	ds_read_b128 v[218:221], v155 offset:2048
	ds_read_b128 v[222:225], v155 offset:3072
	global_load_lds_dwordx4 v[148:149], off
	v_lshl_add_u64 v[186:187], s[20:21], 0, v[134:135]
	s_add_i32 m0, s48, 0x2000
	s_nop 0
	global_load_lds_dwordx4 v[186:187], off
	s_barrier
	s_waitcnt lgkmcnt(0)
	v_mfma_f32_16x16x32_bf16 v[116:119], v[210:213], v[168:171], v[116:119]
	v_mfma_f32_16x16x32_bf16 v[108:111], v[218:221], v[168:171], v[108:111]
	v_mfma_f32_16x16x32_bf16 v[100:103], v[210:213], v[182:185], v[100:103]
	v_mfma_f32_16x16x32_bf16 v[92:95], v[218:221], v[182:185], v[92:95]
	v_mfma_f32_16x16x32_bf16 v[84:87], v[210:213], v[194:197], v[84:87]
	v_mfma_f32_16x16x32_bf16 v[76:79], v[218:221], v[194:197], v[76:79]
	v_mfma_f32_16x16x32_bf16 v[68:71], v[210:213], v[202:205], v[68:71]
	v_mfma_f32_16x16x32_bf16 v[64:67], v[218:221], v[202:205], v[64:67]
	v_mfma_f32_16x16x32_bf16 v[116:119], v[214:217], v[172:175], v[116:119]
	v_mfma_f32_16x16x32_bf16 v[108:111], v[222:225], v[172:175], v[108:111]
	v_mfma_f32_16x16x32_bf16 v[100:103], v[214:217], v[190:193], v[100:103]
	v_mfma_f32_16x16x32_bf16 v[92:95], v[222:225], v[190:193], v[92:95]
	v_mfma_f32_16x16x32_bf16 v[84:87], v[214:217], v[198:201], v[84:87]
	v_mfma_f32_16x16x32_bf16 v[76:79], v[222:225], v[198:201], v[76:79]
	v_mfma_f32_16x16x32_bf16 v[68:71], v[214:217], v[206:209], v[68:71]
	v_mfma_f32_16x16x32_bf16 v[64:67], v[222:225], v[206:209], v[64:67]
	s_barrier
	s_mov_b32 m0, s17
	v_lshl_add_u64 v[226:227], s[22:23], 0, v[128:129]
	ds_read_b128 v[168:171], v154 offset:16384
	ds_read_b128 v[172:175], v154 offset:17408
	ds_read_b128 v[182:185], v154 offset:18432
	ds_read_b128 v[190:193], v154 offset:19456
	ds_read_b128 v[194:197], v154 offset:20480
	ds_read_b128 v[198:201], v154 offset:21504
	ds_read_b128 v[202:205], v154 offset:22528
	ds_read_b128 v[206:209], v154 offset:23552
	global_load_lds_dwordx4 v[226:227], off
	v_lshl_add_u64 v[228:229], s[22:23], 0, v[132:133]
	s_mov_b32 m0, s30
	s_nop 0
	global_load_lds_dwordx4 v[228:229], off
	s_barrier
	s_waitcnt lgkmcnt(0)
	v_mfma_f32_16x16x32_bf16 v[60:63], v[144:147], v[168:171], v[60:63]
	v_mfma_f32_16x16x32_bf16 v[56:59], v[160:163], v[168:171], v[56:59]
	v_mfma_f32_16x16x32_bf16 v[48:51], v[144:147], v[182:185], v[48:51]
	v_mfma_f32_16x16x32_bf16 v[40:43], v[160:163], v[182:185], v[40:43]
	v_mfma_f32_16x16x32_bf16 v[32:35], v[144:147], v[194:197], v[32:35]
	v_mfma_f32_16x16x32_bf16 v[24:27], v[160:163], v[194:197], v[24:27]
	v_mfma_f32_16x16x32_bf16 v[16:19], v[144:147], v[202:205], v[16:19]
	v_mfma_f32_16x16x32_bf16 v[8:11], v[160:163], v[202:205], v[8:11]
	v_mfma_f32_16x16x32_bf16 v[60:63], v[156:159], v[172:175], v[60:63]
	v_mfma_f32_16x16x32_bf16 v[56:59], v[164:167], v[172:175], v[56:59]
	v_mfma_f32_16x16x32_bf16 v[48:51], v[156:159], v[190:193], v[48:51]
	v_mfma_f32_16x16x32_bf16 v[40:43], v[164:167], v[190:193], v[40:43]
	v_mfma_f32_16x16x32_bf16 v[32:35], v[156:159], v[198:201], v[32:35]
	v_mfma_f32_16x16x32_bf16 v[24:27], v[164:167], v[198:201], v[24:27]
	v_mfma_f32_16x16x32_bf16 v[16:19], v[156:159], v[206:209], v[16:19]
	v_mfma_f32_16x16x32_bf16 v[8:11], v[164:167], v[206:209], v[8:11]
	s_barrier
; #define PG8_STAGE(bufoff, gbase, voff) do { _Pragma("unroll") for (int _i = 0; _i < 2; ++_i) \
;         __builtin_amdgcn_global_load_lds((const unsigned*)((const char*)(gbase) + (voff)[_i]), (PG8_LAS unsigned*)(lds + (bufoff) + ldsw + _i * 8192), 16, 0, 0); } while (0)
; #define PG8_LDA(dst, b, h) do { _Pragma("unroll") for (int m = 0; m < 4; ++m) _Pragma("unroll") for (int k = 0; k < 2; ++k) dst[m][k] = *(const PG8_LAS bf16x8*)(lds + PG8_SA(b, h) + aoff + m * 2048 + k * 1024); } while (0)
; #define PG8_LDB(dst, b, h) do { _Pragma("unroll") for (int n = 0; n < 2; ++n) _Pragma("unroll") for (int k = 0; k < 2; ++k) dst[n][k] = *(const PG8_LAS bf16x8*)(lds + PG8_SB(b, h) + boff + n * 2048 + k * 1024); } while (0)
; #define PG8_MMA(ai, bj, At, Bt) do { __builtin_amdgcn_s_setprio(1); _Pragma("unroll") for (int m = 0; m < 4; ++m) _Pragma("unroll") for (int n = 0; n < 2; ++n) _Pragma("unroll") for (int k = 0; k < 2; ++k) \
;         acc[ai][bj][m][n] = __builtin_amdgcn_mfma_f32_16x16x32_bf16(Bt[n][k], At[m][k], acc[ai][bj][m][n], 0, 0, 0); __builtin_amdgcn_s_setprio(0); } while (0)
; #define PG8_WAIT_V(n) asm volatile("s_waitcnt vmcnt(" #n ")" ::: "memory")
; #define PG8_WAIT_L(n) asm volatile("s_waitcnt lgkmcnt(" #n ")" ::: "memory")
; #define PG8_BAR __builtin_amdgcn_s_barrier()
; #define PG8_SCHED __builtin_amdgcn_sched_barrier(0)
; template <class Epi, class Sched>
; __device__ __forceinline__ void gemm_phase(PG8_LAS unsigned char* lds, const Gemm g, const Sched& S, const Epi& E) {
;     ...
;             PG8_WAIT_V(6); PG8_BAR; PG8_MMA(1, 1, At, B1); PG8_BAR;
;             PG8_LDB(B0, 1, 0); PG8_SCHED; PG8_LDA(At, 1, 0); PG8_STAGE(PG8_SA(0, 1), a2 + hstep, voffA);
;             PG8_WAIT_L(8); PG8_BAR; PG8_WAIT_L(0); PG8_MMA(0, 0, At, B0); PG8_BAR; PG8_SCHED;
;             PG8_LDB(B1, 1, 1); PG8_STAGE(PG8_SB(1, 0), b3, voffB);
;             PG8_BAR; PG8_WAIT_L(0); PG8_MMA(0, 1, At, B1); PG8_BAR;
;             PG8_LDA(At, 1, 1); PG8_STAGE(PG8_SA(1, 0), a3, voffA);
;             PG8_BAR; PG8_WAIT_L(0); PG8_MMA(1, 0, At, B0); PG8_BAR; PG8_SCHED;
;             PG8_STAGE(PG8_SB(1, 1), b3 + hstep, voffB);
	s_add_u32 s48, s20, 0x40000
	s_addc_u32 s49, s21, 0
	s_add_i32 s50, s40, s29
	v_lshl_add_u64 v[144:145], s[48:49], 0, v[130:131]
	s_mov_b32 m0, s50
	s_nop 0
	global_load_lds_dwordx4 v[144:145], off
	v_lshl_add_u64 v[144:145], s[48:49], 0, v[134:135]
	s_add_i32 m0, s50, 0x2000
	s_nop 0
	global_load_lds_dwordx4 v[144:145], off
	s_waitcnt vmcnt(6)
	s_barrier
	v_mfma_f32_16x16x32_bf16 v[52:55], v[210:213], v[168:171], v[52:55]
	v_mfma_f32_16x16x32_bf16 v[44:47], v[218:221], v[168:171], v[44:47]
	v_mfma_f32_16x16x32_bf16 v[36:39], v[210:213], v[182:185], v[36:39]
	v_mfma_f32_16x16x32_bf16 v[28:31], v[218:221], v[182:185], v[28:31]
	v_mfma_f32_16x16x32_bf16 v[20:23], v[210:213], v[194:197], v[20:23]
	v_mfma_f32_16x16x32_bf16 v[12:15], v[218:221], v[194:197], v[12:15]
	v_mfma_f32_16x16x32_bf16 v[4:7], v[210:213], v[202:205], v[4:7]
	v_mfma_f32_16x16x32_bf16 v[0:3], v[218:221], v[202:205], v[0:3]
	v_mfma_f32_16x16x32_bf16 v[52:55], v[214:217], v[172:175], v[52:55]
	v_mfma_f32_16x16x32_bf16 v[44:47], v[222:225], v[172:175], v[44:47]
	v_mfma_f32_16x16x32_bf16 v[36:39], v[214:217], v[190:193], v[36:39]
	v_mfma_f32_16x16x32_bf16 v[28:31], v[222:225], v[190:193], v[28:31]
	v_mfma_f32_16x16x32_bf16 v[20:23], v[214:217], v[198:201], v[20:23]
	v_mfma_f32_16x16x32_bf16 v[12:15], v[222:225], v[198:201], v[12:15]
	v_mfma_f32_16x16x32_bf16 v[4:7], v[214:217], v[206:209], v[4:7]
	v_mfma_f32_16x16x32_bf16 v[0:3], v[222:225], v[206:209], v[0:3]
	s_barrier
	s_add_i32 s48, 0, 0x18000
	v_add_u32_e32 v164, s48, v151
	ds_read_b128 v[144:147], v164
	ds_read_b128 v[156:159], v164 offset:1024
	ds_read_b128 v[160:163], v164 offset:2048
	ds_read_b128 v[164:167], v164 offset:3072
	s_add_u32 s22, s22, 0x40000
	s_addc_u32 s23, s23, 0
	s_mov_b32 m0, s31
	v_lshl_add_u64 v[210:211], s[22:23], 0, v[128:129]
	ds_read_b128 v[168:171], v154 offset:32768
	ds_read_b128 v[172:175], v154 offset:33792
	ds_read_b128 v[182:185], v154 offset:34816
	ds_read_b128 v[190:193], v154 offset:35840
	ds_read_b128 v[194:197], v154 offset:36864
	ds_read_b128 v[198:201], v154 offset:37888
	ds_read_b128 v[202:205], v154 offset:38912
	ds_read_b128 v[206:209], v154 offset:39936
	global_load_lds_dwordx4 v[210:211], off
	v_lshl_add_u64 v[210:211], s[22:23], 0, v[132:133]
	s_mov_b32 m0, s34
	s_nop 0
	global_load_lds_dwordx4 v[210:211], off
	s_waitcnt lgkmcnt(8)
	s_barrier
	s_waitcnt lgkmcnt(0)
	v_mfma_f32_16x16x32_bf16 v[124:127], v[144:147], v[168:171], v[124:127]
	v_mfma_f32_16x16x32_bf16 v[120:123], v[160:163], v[168:171], v[120:123]
	v_mfma_f32_16x16x32_bf16 v[112:115], v[144:147], v[182:185], v[112:115]
	v_mfma_f32_16x16x32_bf16 v[104:107], v[160:163], v[182:185], v[104:107]
	v_mfma_f32_16x16x32_bf16 v[96:99], v[144:147], v[194:197], v[96:99]
	v_mfma_f32_16x16x32_bf16 v[88:91], v[160:163], v[194:197], v[88:91]
	v_mfma_f32_16x16x32_bf16 v[80:83], v[144:147], v[202:205], v[80:83]
	v_mfma_f32_16x16x32_bf16 v[72:75], v[160:163], v[202:205], v[72:75]
	v_mfma_f32_16x16x32_bf16 v[124:127], v[156:159], v[172:175], v[124:127]
	v_mfma_f32_16x16x32_bf16 v[120:123], v[164:167], v[172:175], v[120:123]
	v_mfma_f32_16x16x32_bf16 v[112:115], v[156:159], v[190:193], v[112:115]
	v_mfma_f32_16x16x32_bf16 v[104:107], v[164:167], v[190:193], v[104:107]
	v_mfma_f32_16x16x32_bf16 v[96:99], v[156:159], v[198:201], v[96:99]
	v_mfma_f32_16x16x32_bf16 v[88:91], v[164:167], v[198:201], v[88:91]
	v_mfma_f32_16x16x32_bf16 v[80:83], v[156:159], v[206:209], v[80:83]
	v_mfma_f32_16x16x32_bf16 v[72:75], v[164:167], v[206:209], v[72:75]
	s_barrier
	s_add_i32 s22, 0, 0x1c000
	s_add_i32 s23, s48, s29
	v_add_u32_e32 v179, s22, v151
	v_lshl_add_u64 v[148:149], v[148:149], 0, s[6:7]
	s_mov_b32 m0, s23
	ds_read_b128 v[210:213], v179
	ds_read_b128 v[214:217], v179 offset:1024
	ds_read_b128 v[218:221], v179 offset:2048
	ds_read_b128 v[222:225], v179 offset:3072
	global_load_lds_dwordx4 v[148:149], off
	v_lshl_add_u64 v[148:149], v[186:187], 0, s[6:7]
	s_add_i32 m0, s23, 0x2000
	s_nop 0
	global_load_lds_dwordx4 v[148:149], off
	s_barrier
	s_waitcnt lgkmcnt(0)
	v_mfma_f32_16x16x32_bf16 v[116:119], v[210:213], v[168:171], v[116:119]
	v_mfma_f32_16x16x32_bf16 v[108:111], v[218:221], v[168:171], v[108:111]
	v_mfma_f32_16x16x32_bf16 v[100:103], v[210:213], v[182:185], v[100:103]
	v_mfma_f32_16x16x32_bf16 v[92:95], v[218:221], v[182:185], v[92:95]
	v_mfma_f32_16x16x32_bf16 v[84:87], v[210:213], v[194:197], v[84:87]
	v_mfma_f32_16x16x32_bf16 v[76:79], v[218:221], v[194:197], v[76:79]
	v_mfma_f32_16x16x32_bf16 v[68:71], v[210:213], v[202:205], v[68:71]
	v_mfma_f32_16x16x32_bf16 v[64:67], v[218:221], v[202:205], v[64:67]
	v_mfma_f32_16x16x32_bf16 v[116:119], v[214:217], v[172:175], v[116:119]
	v_mfma_f32_16x16x32_bf16 v[108:111], v[222:225], v[172:175], v[108:111]
	v_mfma_f32_16x16x32_bf16 v[100:103], v[214:217], v[190:193], v[100:103]
	v_mfma_f32_16x16x32_bf16 v[92:95], v[222:225], v[190:193], v[92:95]
	v_mfma_f32_16x16x32_bf16 v[84:87], v[214:217], v[198:201], v[84:87]
	v_mfma_f32_16x16x32_bf16 v[76:79], v[222:225], v[198:201], v[76:79]
	v_mfma_f32_16x16x32_bf16 v[68:71], v[214:217], v[206:209], v[68:71]
	v_mfma_f32_16x16x32_bf16 v[64:67], v[222:225], v[206:209], v[64:67]
	s_barrier
	s_mov_b32 m0, s36
	v_lshl_add_u64 v[148:149], v[226:227], 0, s[6:7]
	ds_read_b128 v[168:171], v154 offset:49152
	ds_read_b128 v[172:175], v154 offset:50176
	ds_read_b128 v[182:185], v154 offset:51200
	ds_read_b128 v[190:193], v154 offset:52224
	ds_read_b128 v[194:197], v154 offset:53248
	ds_read_b128 v[198:201], v154 offset:54272
	ds_read_b128 v[202:205], v154 offset:55296
	ds_read_b128 v[206:209], v154 offset:56320
	global_load_lds_dwordx4 v[148:149], off
	v_lshl_add_u64 v[148:149], v[228:229], 0, s[6:7]
	s_mov_b32 m0, s37
	s_nop 0
	global_load_lds_dwordx4 v[148:149], off
	s_barrier
; __device__ __forceinline__ unsigned cvt_pk_bf16(float lo, float hi) { unsigned r; asm volatile("v_cvt_pk_bf16_f32 %0, %1, %2" : "=v"(r) : "v"(lo), "v"(hi)); return r; }
; __device__ __forceinline__ float bf_lo(unsigned u) { return __uint_as_float(u << 16); }
; __device__ __forceinline__ float bf_hi(unsigned u) { return __uint_as_float(u & 0xffff0000u); }
; #define PG8_STAGE(bufoff, gbase, voff) do { _Pragma("unroll") for (int _i = 0; _i < 2; ++_i) \
;         __builtin_amdgcn_global_load_lds((const unsigned*)((const char*)(gbase) + (voff)[_i]), (PG8_LAS unsigned*)(lds + (bufoff) + ldsw + _i * 8192), 16, 0, 0); } while (0)
;     __device__ __forceinline__ void operator()(const f32x4 (&acc)[2][2][4][2], const Unit& u, int wr, int wc, int fr, int fq) const {
;     ...
;             for (int m = 0; m < 4; ++m) { const size_t r = (size_t)(row0 + ai * HALF + m * 16); bf16_t* rowp = O + r * ldc + col0; const bf16_t* gp = G + r * ldg + col0;
; #pragma unroll
;                 for (int bj = 0; bj < 2; ++bj) { const u32x4 gw = *(const u32x4*)(gp + bj * HALF);
;                     f32x4 v0 = acc[ai][bj][m][0], v1 = acc[ai][bj][m][1];
;                     v0[0] *= bf_lo(gw.x); v0[1] *= bf_hi(gw.x); v0[2] *= bf_lo(gw.y); v0[3] *= bf_hi(gw.y);
;                     v1[0] *= bf_lo(gw.z); v1[1] *= bf_hi(gw.z); v1[2] *= bf_lo(gw.w); v1[3] *= bf_hi(gw.w);
;                     if (ACCUM) { const u32x4 pw = *(const u32x4*)(rowp + bj * HALF);
;                         v0[0] += bf_lo(pw.x); v0[1] += bf_hi(pw.x); v0[2] += bf_lo(pw.y); v0[3] += bf_hi(pw.y);
;                         v1[0] += bf_lo(pw.z); v1[1] += bf_hi(pw.z); v1[2] += bf_lo(pw.w); v1[3] += bf_hi(pw.w); }
;                     u32x4 w; w.x = cvt_pk_bf16(v0[0], v0[1]); w.y = cvt_pk_bf16(v0[2], v0[3]); w.z = cvt_pk_bf16(v1[0], v1[1]); w.w = cvt_pk_bf16(v1[2], v1[3]);
;                     *(u32x4*)(rowp + bj * HALF) = w; } }
; template <class Epi, class Sched>
; __device__ __forceinline__ void gemm_phase(PG8_LAS unsigned char* lds, const Gemm g, const Sched& S, const Epi& E) {
;     ...
;             PG8_BAR; PG8_WAIT_L(0); PG8_MMA(1, 0, At, B0); PG8_BAR; PG8_SCHED;
;             PG8_STAGE(PG8_SB(1, 1), b3 + hstep, voffB);
;             PG8_WAIT_V(6); PG8_BAR; PG8_MMA(1, 1, At, B1); PG8_BAR;
;         }
;         if constexpr (!Epi::AFTER_DRAIN) { E(acc, cur, wr, wc, fr, fq); S.done(cur); }
	s_waitcnt lgkmcnt(0)
	v_mfma_f32_16x16x32_bf16 v[60:63], v[144:147], v[168:171], v[60:63]
	v_mfma_f32_16x16x32_bf16 v[56:59], v[160:163], v[168:171], v[56:59]
	v_mfma_f32_16x16x32_bf16 v[48:51], v[144:147], v[182:185], v[48:51]
	v_mfma_f32_16x16x32_bf16 v[40:43], v[160:163], v[182:185], v[40:43]
	v_mfma_f32_16x16x32_bf16 v[32:35], v[144:147], v[194:197], v[32:35]
	v_mfma_f32_16x16x32_bf16 v[24:27], v[160:163], v[194:197], v[24:27]
	v_mfma_f32_16x16x32_bf16 v[16:19], v[144:147], v[202:205], v[16:19]
	v_mfma_f32_16x16x32_bf16 v[8:11], v[160:163], v[202:205], v[8:11]
	v_mfma_f32_16x16x32_bf16 v[60:63], v[156:159], v[172:175], v[60:63]
	v_mfma_f32_16x16x32_bf16 v[56:59], v[164:167], v[172:175], v[56:59]
	v_mfma_f32_16x16x32_bf16 v[48:51], v[156:159], v[190:193], v[48:51]
	v_mfma_f32_16x16x32_bf16 v[40:43], v[164:167], v[190:193], v[40:43]
	v_mfma_f32_16x16x32_bf16 v[32:35], v[156:159], v[198:201], v[32:35]
	v_mfma_f32_16x16x32_bf16 v[24:27], v[164:167], v[198:201], v[24:27]
	v_mfma_f32_16x16x32_bf16 v[16:19], v[156:159], v[206:209], v[16:19]
	v_mfma_f32_16x16x32_bf16 v[8:11], v[164:167], v[206:209], v[8:11]
	s_barrier
	s_add_u32 s20, s20, 0x40080
	s_addc_u32 s21, s21, 0
	s_add_i32 s22, s22, s29
	v_lshl_add_u64 v[144:145], s[20:21], 0, v[130:131]
	s_mov_b32 m0, s22
	s_nop 0
	global_load_lds_dwordx4 v[144:145], off
	v_lshl_add_u64 v[144:145], s[20:21], 0, v[134:135]
	s_add_i32 m0, s22, 0x2000
	s_nop 0
	global_load_lds_dwordx4 v[144:145], off
	s_waitcnt vmcnt(6)
	s_barrier
	v_mfma_f32_16x16x32_bf16 v[52:55], v[210:213], v[168:171], v[52:55]
	v_mfma_f32_16x16x32_bf16 v[44:47], v[218:221], v[168:171], v[44:47]
	v_mfma_f32_16x16x32_bf16 v[36:39], v[210:213], v[182:185], v[36:39]
	v_mfma_f32_16x16x32_bf16 v[28:31], v[218:221], v[182:185], v[28:31]
	v_mfma_f32_16x16x32_bf16 v[20:23], v[210:213], v[194:197], v[20:23]
	v_mfma_f32_16x16x32_bf16 v[12:15], v[218:221], v[194:197], v[12:15]
	v_mfma_f32_16x16x32_bf16 v[4:7], v[210:213], v[202:205], v[4:7]
	v_mfma_f32_16x16x32_bf16 v[0:3], v[218:221], v[202:205], v[0:3]
	v_mfma_f32_16x16x32_bf16 v[52:55], v[214:217], v[172:175], v[52:55]
	v_mfma_f32_16x16x32_bf16 v[44:47], v[222:225], v[172:175], v[44:47]
	v_mfma_f32_16x16x32_bf16 v[36:39], v[214:217], v[190:193], v[36:39]
	v_mfma_f32_16x16x32_bf16 v[28:31], v[222:225], v[190:193], v[28:31]
	v_mfma_f32_16x16x32_bf16 v[20:23], v[214:217], v[198:201], v[20:23]
	v_mfma_f32_16x16x32_bf16 v[12:15], v[222:225], v[198:201], v[12:15]
	v_mfma_f32_16x16x32_bf16 v[4:7], v[214:217], v[206:209], v[4:7]
	v_mfma_f32_16x16x32_bf16 v[0:3], v[222:225], v[206:209], v[0:3]
	s_barrier
	s_add_i32 s47, s47, 2
	s_add_u32 s18, s18, 0x100
	s_addc_u32 s19, s19, 0
	s_add_u32 s45, s45, 0x100
	s_addc_u32 s46, s46, 0
	s_cmp_gt_u32 s47, 13
	s_cbranch_scc0 .LBB0_991
	v_lshl_or_b32 v144, s42, 8, v152
	v_lshl_add_u32 v146, s16, 8, v150
	v_ashrrev_i32_e32 v145, 31, v144
	v_mov_b64_e32 v[148:149], s[4:5]
	v_lshlrev_b64 v[144:145], 1, v[144:145]
	v_mad_i64_i32 v[156:157], s[18:19], v146, s41, v[148:149]
	v_lshl_add_u64 v[160:161], v[156:157], 0, v[144:145]
	global_load_dwordx4 v[156:159], v[160:161], off offset:3072
	s_and_b64 vcc, exec, s[2:3]
	s_mov_b32 s42, s8
	s_mov_b32 s16, s10
	s_mov_b64 s[20:21], s[14:15]
	s_waitcnt vmcnt(0)
	v_lshlrev_b32_e32 v147, 16, v156
	v_and_b32_e32 v156, 0xffff0000, v156
	v_lshlrev_b32_e32 v162, 16, v157
	v_and_b32_e32 v157, 0xffff0000, v157
	v_lshlrev_b32_e32 v164, 16, v159
	v_and_b32_e32 v159, 0xffff0000, v159
	v_lshlrev_b32_e32 v163, 16, v158
	v_and_b32_e32 v158, 0xffff0000, v158
	v_mul_f32_e32 v124, v124, v147
	v_mul_f32_e32 v125, v125, v156
	v_mul_f32_e32 v126, v126, v162
	v_mul_f32_e32 v127, v127, v157
	v_mul_f32_e32 v123, v123, v159
	v_mul_f32_e32 v147, v120, v163
	v_mul_f32_e32 v156, v121, v158
	v_mul_f32_e32 v157, v122, v164
	v_cvt_pk_bf16_f32 v120, v124, v125
	v_cvt_pk_bf16_f32 v121, v126, v127
	v_cvt_pk_bf16_f32 v122, v147, v156
	v_cvt_pk_bf16_f32 v123, v157, v123
	global_load_dwordx4 v[124:127], v[160:161], off offset:3328
	v_ashrrev_i32_e32 v147, 31, v146
	v_lshlrev_b64 v[158:159], 11, v[146:147]
	v_lshl_add_u64 v[158:159], s[0:1], 0, v[158:159]
	v_or_b32_e32 v156, 16, v146
	v_lshl_add_u64 v[158:159], v[158:159], 0, v[144:145]
	v_mad_i64_i32 v[160:161], s[18:19], v156, s41, v[148:149]
	global_store_dwordx4 v[158:159], v[120:123], off
	v_lshl_add_u64 v[160:161], v[160:161], 0, v[144:145]
	v_ashrrev_i32_e32 v157, 31, v156
	s_waitcnt vmcnt(0)
	v_lshlrev_b32_e32 v120, 16, v124
	v_and_b32_e32 v121, 0xffff0000, v124
	v_lshlrev_b32_e32 v122, 16, v125
	v_and_b32_e32 v123, 0xffff0000, v125
	v_lshlrev_b32_e32 v124, 16, v126
	v_and_b32_e32 v125, 0xffff0000, v126
	v_lshlrev_b32_e32 v126, 16, v127
	v_and_b32_e32 v127, 0xffff0000, v127
	v_mul_f32_e32 v116, v116, v120
	v_mul_f32_e32 v117, v117, v121
	v_mul_f32_e32 v118, v118, v122
	v_mul_f32_e32 v119, v119, v123
	v_mul_f32_e32 v111, v111, v127
	v_mul_f32_e32 v120, v108, v124
	v_mul_f32_e32 v121, v109, v125
	v_mul_f32_e32 v122, v110, v126
	v_cvt_pk_bf16_f32 v108, v116, v117
	v_cvt_pk_bf16_f32 v109, v118, v119
	v_cvt_pk_bf16_f32 v110, v120, v121
	v_cvt_pk_bf16_f32 v111, v122, v111
	global_load_dwordx4 v[116:119], v[160:161], off offset:3072
	s_nop 0
	global_store_dwordx4 v[158:159], v[108:111], off offset:256
	s_waitcnt vmcnt(0)
; __device__ __forceinline__ unsigned cvt_pk_bf16(float lo, float hi) { unsigned r; asm volatile("v_cvt_pk_bf16_f32 %0, %1, %2" : "=v"(r) : "v"(lo), "v"(hi)); return r; }
; __device__ __forceinline__ float bf_lo(unsigned u) { return __uint_as_float(u << 16); }
; __device__ __forceinline__ float bf_hi(unsigned u) { return __uint_as_float(u & 0xffff0000u); }
;     __device__ __forceinline__ void operator()(const f32x4 (&acc)[2][2][4][2], const Unit& u, int wr, int wc, int fr, int fq) const {
;     ...
;             for (int m = 0; m < 4; ++m) { const size_t r = (size_t)(row0 + ai * HALF + m * 16); bf16_t* rowp = O + r * ldc + col0; const bf16_t* gp = G + r * ldg + col0;
; #pragma unroll
;                 for (int bj = 0; bj < 2; ++bj) { const u32x4 gw = *(const u32x4*)(gp + bj * HALF);
;                     f32x4 v0 = acc[ai][bj][m][0], v1 = acc[ai][bj][m][1];
;                     v0[0] *= bf_lo(gw.x); v0[1] *= bf_hi(gw.x); v0[2] *= bf_lo(gw.y); v0[3] *= bf_hi(gw.y);
;                     v1[0] *= bf_lo(gw.z); v1[1] *= bf_hi(gw.z); v1[2] *= bf_lo(gw.w); v1[3] *= bf_hi(gw.w);
;                     if (ACCUM) { const u32x4 pw = *(const u32x4*)(rowp + bj * HALF);
;                         v0[0] += bf_lo(pw.x); v0[1] += bf_hi(pw.x); v0[2] += bf_lo(pw.y); v0[3] += bf_hi(pw.y);
;                         v1[0] += bf_lo(pw.z); v1[1] += bf_hi(pw.z); v1[2] += bf_lo(pw.w); v1[3] += bf_hi(pw.w); }
;                     u32x4 w; w.x = cvt_pk_bf16(v0[0], v0[1]); w.y = cvt_pk_bf16(v0[2], v0[3]); w.z = cvt_pk_bf16(v1[0], v1[1]); w.w = cvt_pk_bf16(v1[2], v1[3]);
;                     *(u32x4*)(rowp + bj * HALF) = w; } }
	s_nop 0
	v_lshlrev_b32_e32 v108, 16, v116
	v_and_b32_e32 v109, 0xffff0000, v116
	v_lshlrev_b32_e32 v110, 16, v117
	v_and_b32_e32 v111, 0xffff0000, v117
	v_lshlrev_b32_e32 v116, 16, v118
	v_and_b32_e32 v117, 0xffff0000, v118
	v_lshlrev_b32_e32 v118, 16, v119
	v_and_b32_e32 v119, 0xffff0000, v119
	v_mul_f32_e32 v108, v112, v108
	v_mul_f32_e32 v109, v113, v109
	v_mul_f32_e32 v110, v114, v110
	v_mul_f32_e32 v111, v115, v111
	v_mul_f32_e32 v107, v107, v119
	v_mul_f32_e32 v112, v104, v116
	v_mul_f32_e32 v113, v105, v117
	v_mul_f32_e32 v114, v106, v118
	v_cvt_pk_bf16_f32 v104, v108, v109
	v_cvt_pk_bf16_f32 v105, v110, v111
	v_cvt_pk_bf16_f32 v106, v112, v113
	v_cvt_pk_bf16_f32 v107, v114, v107
	global_load_dwordx4 v[108:111], v[160:161], off offset:3328
	v_lshlrev_b64 v[116:117], 11, v[156:157]
	v_lshl_add_u64 v[116:117], s[0:1], 0, v[116:117]
	v_or_b32_e32 v112, 32, v146
	v_lshl_add_u64 v[116:117], v[116:117], 0, v[144:145]
	v_mad_i64_i32 v[114:115], s[18:19], v112, s41, v[148:149]
	global_store_dwordx4 v[116:117], v[104:107], off
	v_lshl_add_u64 v[114:115], v[114:115], 0, v[144:145]
	v_ashrrev_i32_e32 v113, 31, v112
	s_waitcnt vmcnt(0)
	v_lshlrev_b32_e32 v104, 16, v108
	v_and_b32_e32 v105, 0xffff0000, v108
	v_lshlrev_b32_e32 v106, 16, v109
	v_and_b32_e32 v107, 0xffff0000, v109
	v_lshlrev_b32_e32 v108, 16, v110
	v_and_b32_e32 v109, 0xffff0000, v110
	v_lshlrev_b32_e32 v110, 16, v111
	v_and_b32_e32 v111, 0xffff0000, v111
	v_mul_f32_e32 v100, v100, v104
	v_mul_f32_e32 v101, v101, v105
	v_mul_f32_e32 v102, v102, v106
	v_mul_f32_e32 v103, v103, v107
	v_mul_f32_e32 v95, v95, v111
	v_mul_f32_e32 v104, v92, v108
	v_mul_f32_e32 v105, v93, v109
	v_mul_f32_e32 v106, v94, v110
	v_cvt_pk_bf16_f32 v92, v100, v101
	v_cvt_pk_bf16_f32 v93, v102, v103
	v_cvt_pk_bf16_f32 v94, v104, v105
	v_cvt_pk_bf16_f32 v95, v106, v95
	global_load_dwordx4 v[100:103], v[114:115], off offset:3072
	s_nop 0
	global_store_dwordx4 v[116:117], v[92:95], off offset:256
	s_waitcnt vmcnt(0)
	s_nop 0
	v_lshlrev_b32_e32 v92, 16, v100
	v_and_b32_e32 v93, 0xffff0000, v100
	v_lshlrev_b32_e32 v94, 16, v101
	v_and_b32_e32 v95, 0xffff0000, v101
	v_lshlrev_b32_e32 v100, 16, v102
	v_and_b32_e32 v101, 0xffff0000, v102
	v_lshlrev_b32_e32 v102, 16, v103
	v_and_b32_e32 v103, 0xffff0000, v103
	v_mul_f32_e32 v92, v96, v92
	v_mul_f32_e32 v93, v97, v93
	v_mul_f32_e32 v94, v98, v94
	v_mul_f32_e32 v95, v99, v95
	v_mul_f32_e32 v91, v91, v103
	v_mul_f32_e32 v96, v88, v100
	v_mul_f32_e32 v97, v89, v101
	v_mul_f32_e32 v98, v90, v102
	v_cvt_pk_bf16_f32 v88, v92, v93
	v_cvt_pk_bf16_f32 v89, v94, v95
	v_cvt_pk_bf16_f32 v90, v96, v97
	v_cvt_pk_bf16_f32 v91, v98, v91
	global_load_dwordx4 v[92:95], v[114:115], off offset:3328
	v_lshlrev_b64 v[100:101], 11, v[112:113]
	v_lshl_add_u64 v[100:101], s[0:1], 0, v[100:101]
	v_or_b32_e32 v96, 48, v146
	v_lshl_add_u64 v[100:101], v[100:101], 0, v[144:145]
	v_mad_i64_i32 v[98:99], s[18:19], v96, s41, v[148:149]
	global_store_dwordx4 v[100:101], v[88:91], off
	v_lshl_add_u64 v[98:99], v[98:99], 0, v[144:145]
	v_ashrrev_i32_e32 v97, 31, v96
	s_waitcnt vmcnt(0)
	v_lshlrev_b32_e32 v88, 16, v92
	v_and_b32_e32 v89, 0xffff0000, v92
	v_lshlrev_b32_e32 v90, 16, v93
	v_and_b32_e32 v91, 0xffff0000, v93
	v_lshlrev_b32_e32 v92, 16, v94
	v_and_b32_e32 v93, 0xffff0000, v94
	v_lshlrev_b32_e32 v94, 16, v95
	v_and_b32_e32 v95, 0xffff0000, v95
	v_mul_f32_e32 v84, v84, v88
	v_mul_f32_e32 v85, v85, v89
	v_mul_f32_e32 v86, v86, v90
	v_mul_f32_e32 v87, v87, v91
	v_mul_f32_e32 v79, v79, v95
	v_mul_f32_e32 v88, v76, v92
	v_mul_f32_e32 v89, v77, v93
	v_mul_f32_e32 v90, v78, v94
	v_cvt_pk_bf16_f32 v76, v84, v85
	v_cvt_pk_bf16_f32 v77, v86, v87
	v_cvt_pk_bf16_f32 v78, v88, v89
	v_cvt_pk_bf16_f32 v79, v90, v79
	global_load_dwordx4 v[84:87], v[98:99], off offset:3072
	s_nop 0
	global_store_dwordx4 v[100:101], v[76:79], off offset:256
	s_waitcnt vmcnt(0)
	s_nop 0
	v_lshlrev_b32_e32 v76, 16, v84
	v_and_b32_e32 v77, 0xffff0000, v84
	v_lshlrev_b32_e32 v78, 16, v85
	v_and_b32_e32 v79, 0xffff0000, v85
	v_lshlrev_b32_e32 v84, 16, v86
	v_and_b32_e32 v85, 0xffff0000, v86
	v_lshlrev_b32_e32 v86, 16, v87
	v_and_b32_e32 v87, 0xffff0000, v87
	v_mul_f32_e32 v76, v80, v76
	v_mul_f32_e32 v77, v81, v77
	v_mul_f32_e32 v78, v82, v78
	v_mul_f32_e32 v79, v83, v79
	v_mul_f32_e32 v75, v75, v87
	v_mul_f32_e32 v80, v72, v84
	v_mul_f32_e32 v81, v73, v85
	v_mul_f32_e32 v82, v74, v86
	v_cvt_pk_bf16_f32 v72, v76, v77
	v_cvt_pk_bf16_f32 v73, v78, v79
	v_cvt_pk_bf16_f32 v74, v80, v81
	v_cvt_pk_bf16_f32 v75, v82, v75
	global_load_dwordx4 v[76:79], v[98:99], off offset:3328
	v_lshlrev_b64 v[84:85], 11, v[96:97]
	v_lshl_add_u64 v[84:85], s[0:1], 0, v[84:85]
	v_add_u32_e32 v80, 0x80, v146
	v_lshl_add_u64 v[84:85], v[84:85], 0, v[144:145]
	v_mad_i64_i32 v[82:83], s[18:19], v80, s41, v[148:149]
	global_store_dwordx4 v[84:85], v[72:75], off
	v_lshl_add_u64 v[82:83], v[82:83], 0, v[144:145]
	v_ashrrev_i32_e32 v81, 31, v80
	s_waitcnt vmcnt(0)
	v_lshlrev_b32_e32 v72, 16, v76
	v_and_b32_e32 v73, 0xffff0000, v76
	v_lshlrev_b32_e32 v74, 16, v77
	v_and_b32_e32 v75, 0xffff0000, v77
	v_lshlrev_b32_e32 v76, 16, v78
	v_and_b32_e32 v77, 0xffff0000, v78
	v_lshlrev_b32_e32 v78, 16, v79
	v_and_b32_e32 v79, 0xffff0000, v79
	v_mul_f32_e32 v68, v68, v72
	v_mul_f32_e32 v69, v69, v73
	v_mul_f32_e32 v70, v70, v74
	v_mul_f32_e32 v71, v71, v75
	v_mul_f32_e32 v67, v67, v79
	v_mul_f32_e32 v72, v64, v76
	v_mul_f32_e32 v73, v65, v77
	v_mul_f32_e32 v74, v66, v78
	v_cvt_pk_bf16_f32 v64, v68, v69
	v_cvt_pk_bf16_f32 v65, v70, v71
	v_cvt_pk_bf16_f32 v66, v72, v73
	v_cvt_pk_bf16_f32 v67, v74, v67
	global_load_dwordx4 v[68:71], v[82:83], off offset:3072
	s_nop 0
	global_store_dwordx4 v[84:85], v[64:67], off offset:256
	s_waitcnt vmcnt(0)
; __device__ __forceinline__ unsigned cvt_pk_bf16(float lo, float hi) { unsigned r; asm volatile("v_cvt_pk_bf16_f32 %0, %1, %2" : "=v"(r) : "v"(lo), "v"(hi)); return r; }
; __device__ __forceinline__ float bf_lo(unsigned u) { return __uint_as_float(u << 16); }
; __device__ __forceinline__ float bf_hi(unsigned u) { return __uint_as_float(u & 0xffff0000u); }
;     __device__ __forceinline__ void operator()(const f32x4 (&acc)[2][2][4][2], const Unit& u, int wr, int wc, int fr, int fq) const {
;     ...
;             for (int m = 0; m < 4; ++m) { const size_t r = (size_t)(row0 + ai * HALF + m * 16); bf16_t* rowp = O + r * ldc + col0; const bf16_t* gp = G + r * ldg + col0;
; #pragma unroll
;                 for (int bj = 0; bj < 2; ++bj) { const u32x4 gw = *(const u32x4*)(gp + bj * HALF);
;                     f32x4 v0 = acc[ai][bj][m][0], v1 = acc[ai][bj][m][1];
;                     v0[0] *= bf_lo(gw.x); v0[1] *= bf_hi(gw.x); v0[2] *= bf_lo(gw.y); v0[3] *= bf_hi(gw.y);
;                     v1[0] *= bf_lo(gw.z); v1[1] *= bf_hi(gw.z); v1[2] *= bf_lo(gw.w); v1[3] *= bf_hi(gw.w);
;                     if (ACCUM) { const u32x4 pw = *(const u32x4*)(rowp + bj * HALF);
;                         v0[0] += bf_lo(pw.x); v0[1] += bf_hi(pw.x); v0[2] += bf_lo(pw.y); v0[3] += bf_hi(pw.y);
;                         v1[0] += bf_lo(pw.z); v1[1] += bf_hi(pw.z); v1[2] += bf_lo(pw.w); v1[3] += bf_hi(pw.w); }
;                     u32x4 w; w.x = cvt_pk_bf16(v0[0], v0[1]); w.y = cvt_pk_bf16(v0[2], v0[3]); w.z = cvt_pk_bf16(v1[0], v1[1]); w.w = cvt_pk_bf16(v1[2], v1[3]);
;                     *(u32x4*)(rowp + bj * HALF) = w; } }
	s_nop 0
	v_lshlrev_b32_e32 v64, 16, v68
	v_and_b32_e32 v65, 0xffff0000, v68
	v_lshlrev_b32_e32 v66, 16, v69
	v_and_b32_e32 v67, 0xffff0000, v69
	v_lshlrev_b32_e32 v68, 16, v70
	v_and_b32_e32 v69, 0xffff0000, v70
	v_lshlrev_b32_e32 v70, 16, v71
	v_and_b32_e32 v71, 0xffff0000, v71
	v_mul_f32_e32 v60, v60, v64
	v_mul_f32_e32 v61, v61, v65
	v_mul_f32_e32 v62, v62, v66
	v_mul_f32_e32 v63, v63, v67
	v_mul_f32_e32 v59, v59, v71
	v_mul_f32_e32 v64, v56, v68
	v_mul_f32_e32 v65, v57, v69
	v_mul_f32_e32 v66, v58, v70
	v_cvt_pk_bf16_f32 v56, v60, v61
	v_cvt_pk_bf16_f32 v57, v62, v63
	v_cvt_pk_bf16_f32 v58, v64, v65
	v_cvt_pk_bf16_f32 v59, v66, v59
	global_load_dwordx4 v[60:63], v[82:83], off offset:3328
	v_lshlrev_b64 v[68:69], 11, v[80:81]
	v_lshl_add_u64 v[68:69], s[0:1], 0, v[68:69]
	v_add_u32_e32 v64, 0x90, v146
	v_lshl_add_u64 v[68:69], v[68:69], 0, v[144:145]
	v_mad_i64_i32 v[66:67], s[18:19], v64, s41, v[148:149]
	global_store_dwordx4 v[68:69], v[56:59], off
	v_lshl_add_u64 v[66:67], v[66:67], 0, v[144:145]
	v_ashrrev_i32_e32 v65, 31, v64
	s_waitcnt vmcnt(0)
	v_lshlrev_b32_e32 v56, 16, v60
	v_and_b32_e32 v57, 0xffff0000, v60
	v_lshlrev_b32_e32 v58, 16, v61
	v_and_b32_e32 v59, 0xffff0000, v61
	v_lshlrev_b32_e32 v60, 16, v62
	v_and_b32_e32 v61, 0xffff0000, v62
	v_lshlrev_b32_e32 v62, 16, v63
	v_and_b32_e32 v63, 0xffff0000, v63
	v_mul_f32_e32 v52, v52, v56
	v_mul_f32_e32 v53, v53, v57
	v_mul_f32_e32 v54, v54, v58
	v_mul_f32_e32 v55, v55, v59
	v_mul_f32_e32 v47, v47, v63
	v_mul_f32_e32 v56, v44, v60
	v_mul_f32_e32 v57, v45, v61
	v_mul_f32_e32 v58, v46, v62
	v_cvt_pk_bf16_f32 v44, v52, v53
	v_cvt_pk_bf16_f32 v45, v54, v55
	v_cvt_pk_bf16_f32 v46, v56, v57
	v_cvt_pk_bf16_f32 v47, v58, v47
	global_load_dwordx4 v[52:55], v[66:67], off offset:3072
	s_nop 0
	global_store_dwordx4 v[68:69], v[44:47], off offset:256
	s_waitcnt vmcnt(0)
	s_nop 0
	v_lshlrev_b32_e32 v44, 16, v52
	v_and_b32_e32 v45, 0xffff0000, v52
	v_lshlrev_b32_e32 v46, 16, v53
	v_and_b32_e32 v47, 0xffff0000, v53
	v_lshlrev_b32_e32 v52, 16, v54
	v_and_b32_e32 v53, 0xffff0000, v54
	v_lshlrev_b32_e32 v54, 16, v55
	v_and_b32_e32 v55, 0xffff0000, v55
	v_mul_f32_e32 v44, v48, v44
	v_mul_f32_e32 v45, v49, v45
	v_mul_f32_e32 v46, v50, v46
	v_mul_f32_e32 v47, v51, v47
	v_mul_f32_e32 v43, v43, v55
	v_mul_f32_e32 v48, v40, v52
	v_mul_f32_e32 v49, v41, v53
	v_mul_f32_e32 v50, v42, v54
	v_cvt_pk_bf16_f32 v40, v44, v45
	v_cvt_pk_bf16_f32 v41, v46, v47
	v_cvt_pk_bf16_f32 v42, v48, v49
	v_cvt_pk_bf16_f32 v43, v50, v43
	global_load_dwordx4 v[44:47], v[66:67], off offset:3328
	v_lshlrev_b64 v[52:53], 11, v[64:65]
	v_lshl_add_u64 v[52:53], s[0:1], 0, v[52:53]
	v_add_u32_e32 v48, 0xa0, v146
	v_lshl_add_u64 v[52:53], v[52:53], 0, v[144:145]
	v_mad_i64_i32 v[50:51], s[18:19], v48, s41, v[148:149]
	global_store_dwordx4 v[52:53], v[40:43], off
	v_lshl_add_u64 v[50:51], v[50:51], 0, v[144:145]
	v_ashrrev_i32_e32 v49, 31, v48
	s_waitcnt vmcnt(0)
	v_lshlrev_b32_e32 v40, 16, v44
	v_and_b32_e32 v41, 0xffff0000, v44
	v_lshlrev_b32_e32 v42, 16, v45
	v_and_b32_e32 v43, 0xffff0000, v45
	v_lshlrev_b32_e32 v44, 16, v46
	v_and_b32_e32 v45, 0xffff0000, v46
	v_lshlrev_b32_e32 v46, 16, v47
	v_and_b32_e32 v47, 0xffff0000, v47
	v_mul_f32_e32 v36, v36, v40
	v_mul_f32_e32 v37, v37, v41
	v_mul_f32_e32 v38, v38, v42
	v_mul_f32_e32 v39, v39, v43
	v_mul_f32_e32 v31, v31, v47
	v_mul_f32_e32 v40, v28, v44
	v_mul_f32_e32 v41, v29, v45
	v_mul_f32_e32 v42, v30, v46
	v_cvt_pk_bf16_f32 v28, v36, v37
	v_cvt_pk_bf16_f32 v29, v38, v39
	v_cvt_pk_bf16_f32 v30, v40, v41
	v_cvt_pk_bf16_f32 v31, v42, v31
	global_load_dwordx4 v[36:39], v[50:51], off offset:3072
	s_nop 0
	global_store_dwordx4 v[52:53], v[28:31], off offset:256
	s_waitcnt vmcnt(0)
; __device__ __forceinline__ unsigned cvt_pk_bf16(float lo, float hi) { unsigned r; asm volatile("v_cvt_pk_bf16_f32 %0, %1, %2" : "=v"(r) : "v"(lo), "v"(hi)); return r; }
; __device__ __forceinline__ float bf_lo(unsigned u) { return __uint_as_float(u << 16); }
; __device__ __forceinline__ float bf_hi(unsigned u) { return __uint_as_float(u & 0xffff0000u); }
; #define PG8_WAIT_V(n) asm volatile("s_waitcnt vmcnt(" #n ")" ::: "memory")
; #define PG8_BAR __builtin_amdgcn_s_barrier()
;     __device__ __forceinline__ void operator()(const f32x4 (&acc)[2][2][4][2], const Unit& u, int wr, int wc, int fr, int fq) const {
;     ...
;             for (int m = 0; m < 4; ++m) { const size_t r = (size_t)(row0 + ai * HALF + m * 16); bf16_t* rowp = O + r * ldc + col0; const bf16_t* gp = G + r * ldg + col0;
; #pragma unroll
;                 for (int bj = 0; bj < 2; ++bj) { const u32x4 gw = *(const u32x4*)(gp + bj * HALF);
;                     f32x4 v0 = acc[ai][bj][m][0], v1 = acc[ai][bj][m][1];
;                     v0[0] *= bf_lo(gw.x); v0[1] *= bf_hi(gw.x); v0[2] *= bf_lo(gw.y); v0[3] *= bf_hi(gw.y);
;                     v1[0] *= bf_lo(gw.z); v1[1] *= bf_hi(gw.z); v1[2] *= bf_lo(gw.w); v1[3] *= bf_hi(gw.w);
;                     if (ACCUM) { const u32x4 pw = *(const u32x4*)(rowp + bj * HALF);
;                         v0[0] += bf_lo(pw.x); v0[1] += bf_hi(pw.x); v0[2] += bf_lo(pw.y); v0[3] += bf_hi(pw.y);
;                         v1[0] += bf_lo(pw.z); v1[1] += bf_hi(pw.z); v1[2] += bf_lo(pw.w); v1[3] += bf_hi(pw.w); }
;                     u32x4 w; w.x = cvt_pk_bf16(v0[0], v0[1]); w.y = cvt_pk_bf16(v0[2], v0[3]); w.z = cvt_pk_bf16(v1[0], v1[1]); w.w = cvt_pk_bf16(v1[2], v1[3]);
;                     *(u32x4*)(rowp + bj * HALF) = w; } }
; template <class Epi, class Sched>
; __device__ __forceinline__ void gemm_phase(PG8_LAS unsigned char* lds, const Gemm g, const Sched& S, const Epi& E) {
;     ...
;     PG8_WAIT_V(0);
;     if (wr == 0) PG8_BAR;
;     PG8_BAR;
	s_nop 0
	v_lshlrev_b32_e32 v28, 16, v36
	v_and_b32_e32 v29, 0xffff0000, v36
	v_lshlrev_b32_e32 v30, 16, v37
	v_and_b32_e32 v31, 0xffff0000, v37
	v_lshlrev_b32_e32 v36, 16, v38
	v_and_b32_e32 v37, 0xffff0000, v38
	v_lshlrev_b32_e32 v38, 16, v39
	v_and_b32_e32 v39, 0xffff0000, v39
	v_mul_f32_e32 v28, v32, v28
	v_mul_f32_e32 v29, v33, v29
	v_mul_f32_e32 v30, v34, v30
	v_mul_f32_e32 v31, v35, v31
	v_mul_f32_e32 v27, v27, v39
	v_mul_f32_e32 v32, v24, v36
	v_mul_f32_e32 v33, v25, v37
	v_mul_f32_e32 v34, v26, v38
	v_cvt_pk_bf16_f32 v24, v28, v29
	v_cvt_pk_bf16_f32 v25, v30, v31
	v_cvt_pk_bf16_f32 v26, v32, v33
	v_cvt_pk_bf16_f32 v27, v34, v27
	global_load_dwordx4 v[28:31], v[50:51], off offset:3328
	v_lshlrev_b64 v[36:37], 11, v[48:49]
	v_lshl_add_u64 v[36:37], s[0:1], 0, v[36:37]
	v_add_u32_e32 v32, 0xb0, v146
	v_lshl_add_u64 v[36:37], v[36:37], 0, v[144:145]
	v_mad_i64_i32 v[34:35], s[18:19], v32, s41, v[148:149]
	global_store_dwordx4 v[36:37], v[24:27], off
	v_lshl_add_u64 v[34:35], v[34:35], 0, v[144:145]
	v_ashrrev_i32_e32 v33, 31, v32
	s_mov_b64 s[18:19], s[12:13]
	s_waitcnt vmcnt(0)
	v_lshlrev_b32_e32 v24, 16, v28
	v_and_b32_e32 v25, 0xffff0000, v28
	v_lshlrev_b32_e32 v26, 16, v29
	v_and_b32_e32 v27, 0xffff0000, v29
	v_lshlrev_b32_e32 v28, 16, v30
	v_and_b32_e32 v29, 0xffff0000, v30
	v_lshlrev_b32_e32 v30, 16, v31
	v_and_b32_e32 v31, 0xffff0000, v31
	v_mul_f32_e32 v20, v20, v24
	v_mul_f32_e32 v21, v21, v25
	v_mul_f32_e32 v22, v22, v26
	v_mul_f32_e32 v23, v23, v27
	v_mul_f32_e32 v15, v15, v31
	v_mul_f32_e32 v24, v12, v28
	v_mul_f32_e32 v25, v13, v29
	v_mul_f32_e32 v26, v14, v30
	v_cvt_pk_bf16_f32 v12, v20, v21
	v_cvt_pk_bf16_f32 v13, v22, v23
	v_cvt_pk_bf16_f32 v14, v24, v25
	v_cvt_pk_bf16_f32 v15, v26, v15
	global_load_dwordx4 v[20:23], v[34:35], off offset:3072
	s_nop 0
	global_store_dwordx4 v[36:37], v[12:15], off offset:256
	s_waitcnt vmcnt(0)
	s_nop 0
	v_lshlrev_b32_e32 v12, 16, v20
	v_and_b32_e32 v13, 0xffff0000, v20
	v_lshlrev_b32_e32 v14, 16, v21
	v_and_b32_e32 v15, 0xffff0000, v21
	v_lshlrev_b32_e32 v20, 16, v22
	v_and_b32_e32 v21, 0xffff0000, v22
	v_lshlrev_b32_e32 v22, 16, v23
	v_and_b32_e32 v23, 0xffff0000, v23
	v_mul_f32_e32 v12, v16, v12
	v_mul_f32_e32 v13, v17, v13
	v_mul_f32_e32 v14, v18, v14
	v_mul_f32_e32 v15, v19, v15
	v_mul_f32_e32 v11, v11, v23
	v_mul_f32_e32 v16, v8, v20
	v_mul_f32_e32 v17, v9, v21
	v_mul_f32_e32 v18, v10, v22
	v_cvt_pk_bf16_f32 v8, v12, v13
	v_cvt_pk_bf16_f32 v9, v14, v15
	v_cvt_pk_bf16_f32 v10, v16, v17
	v_cvt_pk_bf16_f32 v11, v18, v11
	global_load_dwordx4 v[12:15], v[34:35], off offset:3328
	v_lshlrev_b64 v[16:17], 11, v[32:33]
	v_lshl_add_u64 v[16:17], s[0:1], 0, v[16:17]
	v_lshl_add_u64 v[16:17], v[16:17], 0, v[144:145]
	global_store_dwordx4 v[16:17], v[8:11], off
	s_waitcnt vmcnt(0)
	s_nop 0
	v_lshlrev_b32_e32 v8, 16, v12
	v_and_b32_e32 v9, 0xffff0000, v12
	v_lshlrev_b32_e32 v10, 16, v13
	v_and_b32_e32 v11, 0xffff0000, v13
	v_lshlrev_b32_e32 v12, 16, v14
	v_and_b32_e32 v13, 0xffff0000, v14
	v_lshlrev_b32_e32 v14, 16, v15
	v_and_b32_e32 v15, 0xffff0000, v15
	v_mul_f32_e32 v3, v3, v15
	v_mul_f32_e32 v4, v4, v8
	v_mul_f32_e32 v5, v5, v9
	v_mul_f32_e32 v6, v6, v10
	v_mul_f32_e32 v7, v7, v11
	v_mul_f32_e32 v8, v0, v12
	v_mul_f32_e32 v9, v1, v13
	v_mul_f32_e32 v10, v2, v14
	v_cvt_pk_bf16_f32 v0, v4, v5
	v_cvt_pk_bf16_f32 v1, v6, v7
	v_cvt_pk_bf16_f32 v2, v8, v9
	v_cvt_pk_bf16_f32 v3, v10, v3
	global_store_dwordx4 v[16:17], v[0:3], off offset:256
	s_cbranch_vccz .LBB0_984
	s_waitcnt vmcnt(0)
	s_cmpk_gt_u32 s25, 0xff
	s_cbranch_scc1 .LBB0_995
	s_barrier

; #define PG8_STAGE(bufoff, gbase, voff) do { _Pragma("unroll") for (int _i = 0; _i < 2; ++_i) \
;         __builtin_amdgcn_global_load_lds((const unsigned*)((const char*)(gbase) + (voff)[_i]), (PG8_LAS unsigned*)(lds + (bufoff) + ldsw + _i * 8192), 16, 0, 0); } while (0)
; #define PG8_LDA(dst, b, h) do { _Pragma("unroll") for (int m = 0; m < 4; ++m) _Pragma("unroll") for (int k = 0; k < 2; ++k) dst[m][k] = *(const PG8_LAS bf16x8*)(lds + PG8_SA(b, h) + aoff + m * 2048 + k * 1024); } while (0)
; #define PG8_LDB(dst, b, h) do { _Pragma("unroll") for (int n = 0; n < 2; ++n) _Pragma("unroll") for (int k = 0; k < 2; ++k) dst[n][k] = *(const PG8_LAS bf16x8*)(lds + PG8_SB(b, h) + boff + n * 2048 + k * 1024); } while (0)
; #define PG8_MMA(ai, bj, At, Bt) do { __builtin_amdgcn_s_setprio(1); _Pragma("unroll") for (int m = 0; m < 4; ++m) _Pragma("unroll") for (int n = 0; n < 2; ++n) _Pragma("unroll") for (int k = 0; k < 2; ++k) \
;         acc[ai][bj][m][n] = __builtin_amdgcn_mfma_f32_16x16x32_bf16(Bt[n][k], At[m][k], acc[ai][bj][m][n], 0, 0, 0); __builtin_amdgcn_s_setprio(0); } while (0)
; #define PG8_WAIT_V(n) asm volatile("s_waitcnt vmcnt(" #n ")" ::: "memory")
; #define PG8_WAIT_L(n) asm volatile("s_waitcnt lgkmcnt(" #n ")" ::: "memory")
; #define PG8_BAR __builtin_amdgcn_s_barrier()
; #define PG8_SCHED __builtin_amdgcn_sched_barrier(0)
; template <class Epi, class Sched>
; __device__ __forceinline__ void gemm_phase(PG8_LAS unsigned char* lds, const Gemm g, const Sched& S, const Epi& E) {
;     ...
;             PG8_LDB(B0, 0, 0); PG8_SCHED; PG8_LDA(At, 0, 0); PG8_STAGE(PG8_SA(1, 1), a1 + hstep, voffA);
;             PG8_WAIT_L(8); PG8_BAR; PG8_WAIT_L(0); PG8_MMA(0, 0, At, B0); PG8_BAR; PG8_SCHED;
;             PG8_LDB(B1, 0, 1); PG8_STAGE(PG8_SB(0, 0), b2, voffB);
;             PG8_BAR; PG8_WAIT_L(0); PG8_MMA(0, 1, At, B1); PG8_BAR;
;             PG8_LDA(At, 0, 1); PG8_STAGE(PG8_SA(0, 0), a2, voffA);
;             PG8_BAR; PG8_WAIT_L(0); PG8_MMA(1, 0, At, B0); PG8_BAR; PG8_SCHED;
;             PG8_STAGE(PG8_SB(0, 1), b2 + hstep, voffB);
;             PG8_WAIT_V(6); PG8_BAR; PG8_MMA(1, 1, At, B1); PG8_BAR;
.LBB0_1011:
	ds_read_b128 v[144:147], v153
	ds_read_b128 v[156:159], v153 offset:1024
	ds_read_b128 v[160:163], v153 offset:2048
	ds_read_b128 v[164:167], v153 offset:3072
	s_add_u32 s20, s18, 0xfffc0080
	s_addc_u32 s21, s19, -1
	s_cmp_eq_u32 s47, 12
	s_cselect_b32 s23, s11, s21
	s_cselect_b32 s22, s43, s20
	s_cselect_b32 s21, s9, s46
	s_cselect_b32 s20, s44, s45
	v_lshl_add_u64 v[148:149], s[18:19], 0, v[136:137]
	s_add_i32 m0, s17, 0xc000
	ds_read_b128 v[168:171], v154
	ds_read_b128 v[172:175], v154 offset:1024
	ds_read_b128 v[182:185], v154 offset:2048
	ds_read_b128 v[190:193], v154 offset:3072
	ds_read_b128 v[194:197], v154 offset:4096
	ds_read_b128 v[198:201], v154 offset:5120
	ds_read_b128 v[202:205], v154 offset:6144
	ds_read_b128 v[206:209], v154 offset:7168
	global_load_lds_dwordx4 v[148:149], off
	v_lshl_add_u64 v[148:149], s[18:19], 0, v[138:139]
	s_add_i32 m0, s17, 0xe000
	s_nop 0
	global_load_lds_dwordx4 v[148:149], off
	s_waitcnt lgkmcnt(8)
	s_barrier
	s_waitcnt lgkmcnt(0)
	v_mfma_f32_16x16x32_bf16 v[124:127], v[144:147], v[168:171], v[124:127]
	v_mfma_f32_16x16x32_bf16 v[120:123], v[160:163], v[168:171], v[120:123]
	v_mfma_f32_16x16x32_bf16 v[108:111], v[144:147], v[182:185], v[108:111]
	v_mfma_f32_16x16x32_bf16 v[104:107], v[160:163], v[182:185], v[104:107]
	v_mfma_f32_16x16x32_bf16 v[92:95], v[144:147], v[194:197], v[92:95]
	v_mfma_f32_16x16x32_bf16 v[88:91], v[160:163], v[194:197], v[88:91]
	v_mfma_f32_16x16x32_bf16 v[76:79], v[144:147], v[202:205], v[76:79]
	v_mfma_f32_16x16x32_bf16 v[72:75], v[160:163], v[202:205], v[72:75]
	v_mfma_f32_16x16x32_bf16 v[124:127], v[156:159], v[172:175], v[124:127]
	v_mfma_f32_16x16x32_bf16 v[120:123], v[164:167], v[172:175], v[120:123]
	v_mfma_f32_16x16x32_bf16 v[108:111], v[156:159], v[190:193], v[108:111]
	v_mfma_f32_16x16x32_bf16 v[104:107], v[164:167], v[190:193], v[104:107]
	v_mfma_f32_16x16x32_bf16 v[92:95], v[156:159], v[198:201], v[92:95]
	v_mfma_f32_16x16x32_bf16 v[88:91], v[164:167], v[198:201], v[88:91]
	v_mfma_f32_16x16x32_bf16 v[76:79], v[156:159], v[206:209], v[76:79]
	v_mfma_f32_16x16x32_bf16 v[72:75], v[164:167], v[206:209], v[72:75]
	s_barrier
	s_add_i32 s48, s39, s29
	v_lshl_add_u64 v[148:149], s[20:21], 0, v[130:131]
	s_mov_b32 m0, s48
	ds_read_b128 v[210:213], v155
	ds_read_b128 v[214:217], v155 offset:1024
	ds_read_b128 v[218:221], v155 offset:2048
	ds_read_b128 v[222:225], v155 offset:3072
	global_load_lds_dwordx4 v[148:149], off
	v_lshl_add_u64 v[186:187], s[20:21], 0, v[134:135]
	s_add_i32 m0, s48, 0x2000
	s_nop 0
	global_load_lds_dwordx4 v[186:187], off
	s_barrier
	s_waitcnt lgkmcnt(0)
	v_mfma_f32_16x16x32_bf16 v[116:119], v[210:213], v[168:171], v[116:119]
	v_mfma_f32_16x16x32_bf16 v[112:115], v[218:221], v[168:171], v[112:115]
	v_mfma_f32_16x16x32_bf16 v[100:103], v[210:213], v[182:185], v[100:103]
	v_mfma_f32_16x16x32_bf16 v[96:99], v[218:221], v[182:185], v[96:99]
	v_mfma_f32_16x16x32_bf16 v[84:87], v[210:213], v[194:197], v[84:87]
	v_mfma_f32_16x16x32_bf16 v[80:83], v[218:221], v[194:197], v[80:83]
	v_mfma_f32_16x16x32_bf16 v[68:71], v[210:213], v[202:205], v[68:71]
	v_mfma_f32_16x16x32_bf16 v[64:67], v[218:221], v[202:205], v[64:67]
	v_mfma_f32_16x16x32_bf16 v[116:119], v[214:217], v[172:175], v[116:119]
	v_mfma_f32_16x16x32_bf16 v[112:115], v[222:225], v[172:175], v[112:115]
	v_mfma_f32_16x16x32_bf16 v[100:103], v[214:217], v[190:193], v[100:103]
	v_mfma_f32_16x16x32_bf16 v[96:99], v[222:225], v[190:193], v[96:99]
	v_mfma_f32_16x16x32_bf16 v[84:87], v[214:217], v[198:201], v[84:87]
	v_mfma_f32_16x16x32_bf16 v[80:83], v[222:225], v[198:201], v[80:83]
	v_mfma_f32_16x16x32_bf16 v[68:71], v[214:217], v[206:209], v[68:71]
	v_mfma_f32_16x16x32_bf16 v[64:67], v[222:225], v[206:209], v[64:67]
	s_barrier
	s_mov_b32 m0, s17
	v_lshl_add_u64 v[226:227], s[22:23], 0, v[128:129]
	ds_read_b128 v[168:171], v154 offset:16384
	ds_read_b128 v[172:175], v154 offset:17408
	ds_read_b128 v[182:185], v154 offset:18432
	ds_read_b128 v[190:193], v154 offset:19456
	ds_read_b128 v[194:197], v154 offset:20480
	ds_read_b128 v[198:201], v154 offset:21504
	ds_read_b128 v[202:205], v154 offset:22528
	ds_read_b128 v[206:209], v154 offset:23552
	global_load_lds_dwordx4 v[226:227], off
	v_lshl_add_u64 v[228:229], s[22:23], 0, v[132:133]
	s_mov_b32 m0, s30
	s_nop 0
	global_load_lds_dwordx4 v[228:229], off
	s_barrier
	s_waitcnt lgkmcnt(0)
	v_mfma_f32_16x16x32_bf16 v[60:63], v[144:147], v[168:171], v[60:63]
	v_mfma_f32_16x16x32_bf16 v[56:59], v[160:163], v[168:171], v[56:59]
	v_mfma_f32_16x16x32_bf16 v[44:47], v[144:147], v[182:185], v[44:47]
	v_mfma_f32_16x16x32_bf16 v[40:43], v[160:163], v[182:185], v[40:43]
	v_mfma_f32_16x16x32_bf16 v[28:31], v[144:147], v[194:197], v[28:31]
	v_mfma_f32_16x16x32_bf16 v[24:27], v[160:163], v[194:197], v[24:27]
	v_mfma_f32_16x16x32_bf16 v[12:15], v[144:147], v[202:205], v[12:15]
	v_mfma_f32_16x16x32_bf16 v[8:11], v[160:163], v[202:205], v[8:11]
	v_mfma_f32_16x16x32_bf16 v[60:63], v[156:159], v[172:175], v[60:63]
	v_mfma_f32_16x16x32_bf16 v[56:59], v[164:167], v[172:175], v[56:59]
	v_mfma_f32_16x16x32_bf16 v[44:47], v[156:159], v[190:193], v[44:47]
	v_mfma_f32_16x16x32_bf16 v[40:43], v[164:167], v[190:193], v[40:43]
	v_mfma_f32_16x16x32_bf16 v[28:31], v[156:159], v[198:201], v[28:31]
	v_mfma_f32_16x16x32_bf16 v[24:27], v[164:167], v[198:201], v[24:27]
	v_mfma_f32_16x16x32_bf16 v[12:15], v[156:159], v[206:209], v[12:15]
	v_mfma_f32_16x16x32_bf16 v[8:11], v[164:167], v[206:209], v[8:11]
	s_barrier
; #define PG8_STAGE(bufoff, gbase, voff) do { _Pragma("unroll") for (int _i = 0; _i < 2; ++_i) \
;         __builtin_amdgcn_global_load_lds((const unsigned*)((const char*)(gbase) + (voff)[_i]), (PG8_LAS unsigned*)(lds + (bufoff) + ldsw + _i * 8192), 16, 0, 0); } while (0)
; #define PG8_LDA(dst, b, h) do { _Pragma("unroll") for (int m = 0; m < 4; ++m) _Pragma("unroll") for (int k = 0; k < 2; ++k) dst[m][k] = *(const PG8_LAS bf16x8*)(lds + PG8_SA(b, h) + aoff + m * 2048 + k * 1024); } while (0)
; #define PG8_LDB(dst, b, h) do { _Pragma("unroll") for (int n = 0; n < 2; ++n) _Pragma("unroll") for (int k = 0; k < 2; ++k) dst[n][k] = *(const PG8_LAS bf16x8*)(lds + PG8_SB(b, h) + boff + n * 2048 + k * 1024); } while (0)
; #define PG8_MMA(ai, bj, At, Bt) do { __builtin_amdgcn_s_setprio(1); _Pragma("unroll") for (int m = 0; m < 4; ++m) _Pragma("unroll") for (int n = 0; n < 2; ++n) _Pragma("unroll") for (int k = 0; k < 2; ++k) \
;         acc[ai][bj][m][n] = __builtin_amdgcn_mfma_f32_16x16x32_bf16(Bt[n][k], At[m][k], acc[ai][bj][m][n], 0, 0, 0); __builtin_amdgcn_s_setprio(0); } while (0)
; #define PG8_WAIT_V(n) asm volatile("s_waitcnt vmcnt(" #n ")" ::: "memory")
; #define PG8_WAIT_L(n) asm volatile("s_waitcnt lgkmcnt(" #n ")" ::: "memory")
; #define PG8_BAR __builtin_amdgcn_s_barrier()
; #define PG8_SCHED __builtin_amdgcn_sched_barrier(0)
; template <class Epi, class Sched>
; __device__ __forceinline__ void gemm_phase(PG8_LAS unsigned char* lds, const Gemm g, const Sched& S, const Epi& E) {
;     ...
;             PG8_WAIT_V(6); PG8_BAR; PG8_MMA(1, 1, At, B1); PG8_BAR;
;             PG8_LDB(B0, 1, 0); PG8_SCHED; PG8_LDA(At, 1, 0); PG8_STAGE(PG8_SA(0, 1), a2 + hstep, voffA);
;             PG8_WAIT_L(8); PG8_BAR; PG8_WAIT_L(0); PG8_MMA(0, 0, At, B0); PG8_BAR; PG8_SCHED;
;             PG8_LDB(B1, 1, 1); PG8_STAGE(PG8_SB(1, 0), b3, voffB);
;             PG8_BAR; PG8_WAIT_L(0); PG8_MMA(0, 1, At, B1); PG8_BAR;
;             PG8_LDA(At, 1, 1); PG8_STAGE(PG8_SA(1, 0), a3, voffA);
;             PG8_BAR; PG8_WAIT_L(0); PG8_MMA(1, 0, At, B0); PG8_BAR; PG8_SCHED;
;             PG8_STAGE(PG8_SB(1, 1), b3 + hstep, voffB);
	s_add_u32 s48, s20, 0x40000
	s_addc_u32 s49, s21, 0
	s_add_i32 s50, s40, s29
	v_lshl_add_u64 v[144:145], s[48:49], 0, v[130:131]
	s_mov_b32 m0, s50
	s_nop 0
	global_load_lds_dwordx4 v[144:145], off
	v_lshl_add_u64 v[144:145], s[48:49], 0, v[134:135]
	s_add_i32 m0, s50, 0x2000
	s_nop 0
	global_load_lds_dwordx4 v[144:145], off
	s_waitcnt vmcnt(6)
	s_barrier
	v_mfma_f32_16x16x32_bf16 v[52:55], v[210:213], v[168:171], v[52:55]
	v_mfma_f32_16x16x32_bf16 v[48:51], v[218:221], v[168:171], v[48:51]
	v_mfma_f32_16x16x32_bf16 v[36:39], v[210:213], v[182:185], v[36:39]
	v_mfma_f32_16x16x32_bf16 v[32:35], v[218:221], v[182:185], v[32:35]
	v_mfma_f32_16x16x32_bf16 v[20:23], v[210:213], v[194:197], v[20:23]
	v_mfma_f32_16x16x32_bf16 v[16:19], v[218:221], v[194:197], v[16:19]
	v_mfma_f32_16x16x32_bf16 v[4:7], v[210:213], v[202:205], v[4:7]
	v_mfma_f32_16x16x32_bf16 v[0:3], v[218:221], v[202:205], v[0:3]
	v_mfma_f32_16x16x32_bf16 v[52:55], v[214:217], v[172:175], v[52:55]
	v_mfma_f32_16x16x32_bf16 v[48:51], v[222:225], v[172:175], v[48:51]
	v_mfma_f32_16x16x32_bf16 v[36:39], v[214:217], v[190:193], v[36:39]
	v_mfma_f32_16x16x32_bf16 v[32:35], v[222:225], v[190:193], v[32:35]
	v_mfma_f32_16x16x32_bf16 v[20:23], v[214:217], v[198:201], v[20:23]
	v_mfma_f32_16x16x32_bf16 v[16:19], v[222:225], v[198:201], v[16:19]
	v_mfma_f32_16x16x32_bf16 v[4:7], v[214:217], v[206:209], v[4:7]
	v_mfma_f32_16x16x32_bf16 v[0:3], v[222:225], v[206:209], v[0:3]
	s_barrier
	s_add_i32 s48, 0, 0x18000
	v_add_u32_e32 v164, s48, v151
	ds_read_b128 v[144:147], v164
	ds_read_b128 v[156:159], v164 offset:1024
	ds_read_b128 v[160:163], v164 offset:2048
	ds_read_b128 v[164:167], v164 offset:3072
	s_add_u32 s22, s22, 0x40000
	s_addc_u32 s23, s23, 0
	s_mov_b32 m0, s31
	v_lshl_add_u64 v[210:211], s[22:23], 0, v[128:129]
	ds_read_b128 v[168:171], v154 offset:32768
	ds_read_b128 v[172:175], v154 offset:33792
	ds_read_b128 v[182:185], v154 offset:34816
	ds_read_b128 v[190:193], v154 offset:35840
	ds_read_b128 v[194:197], v154 offset:36864
	ds_read_b128 v[198:201], v154 offset:37888
	ds_read_b128 v[202:205], v154 offset:38912
	ds_read_b128 v[206:209], v154 offset:39936
	global_load_lds_dwordx4 v[210:211], off
	v_lshl_add_u64 v[210:211], s[22:23], 0, v[132:133]
	s_mov_b32 m0, s34
	s_nop 0
	global_load_lds_dwordx4 v[210:211], off
	s_waitcnt lgkmcnt(8)
	s_barrier
	s_waitcnt lgkmcnt(0)
	v_mfma_f32_16x16x32_bf16 v[124:127], v[144:147], v[168:171], v[124:127]
	v_mfma_f32_16x16x32_bf16 v[120:123], v[160:163], v[168:171], v[120:123]
	v_mfma_f32_16x16x32_bf16 v[108:111], v[144:147], v[182:185], v[108:111]
	v_mfma_f32_16x16x32_bf16 v[104:107], v[160:163], v[182:185], v[104:107]
	v_mfma_f32_16x16x32_bf16 v[92:95], v[144:147], v[194:197], v[92:95]
	v_mfma_f32_16x16x32_bf16 v[88:91], v[160:163], v[194:197], v[88:91]
	v_mfma_f32_16x16x32_bf16 v[76:79], v[144:147], v[202:205], v[76:79]
	v_mfma_f32_16x16x32_bf16 v[72:75], v[160:163], v[202:205], v[72:75]
	v_mfma_f32_16x16x32_bf16 v[124:127], v[156:159], v[172:175], v[124:127]
	v_mfma_f32_16x16x32_bf16 v[120:123], v[164:167], v[172:175], v[120:123]
	v_mfma_f32_16x16x32_bf16 v[108:111], v[156:159], v[190:193], v[108:111]
	v_mfma_f32_16x16x32_bf16 v[104:107], v[164:167], v[190:193], v[104:107]
	v_mfma_f32_16x16x32_bf16 v[92:95], v[156:159], v[198:201], v[92:95]
	v_mfma_f32_16x16x32_bf16 v[88:91], v[164:167], v[198:201], v[88:91]
	v_mfma_f32_16x16x32_bf16 v[76:79], v[156:159], v[206:209], v[76:79]
	v_mfma_f32_16x16x32_bf16 v[72:75], v[164:167], v[206:209], v[72:75]
	s_barrier
	s_add_i32 s22, 0, 0x1c000
	s_add_i32 s23, s48, s29
	v_add_u32_e32 v179, s22, v151
	v_lshl_add_u64 v[148:149], v[148:149], 0, s[6:7]
	s_mov_b32 m0, s23
	ds_read_b128 v[210:213], v179
	ds_read_b128 v[214:217], v179 offset:1024
	ds_read_b128 v[218:221], v179 offset:2048
	ds_read_b128 v[222:225], v179 offset:3072
	global_load_lds_dwordx4 v[148:149], off
	v_lshl_add_u64 v[148:149], v[186:187], 0, s[6:7]
	s_add_i32 m0, s23, 0x2000
	s_nop 0
	global_load_lds_dwordx4 v[148:149], off
	s_barrier
	s_waitcnt lgkmcnt(0)
	v_mfma_f32_16x16x32_bf16 v[116:119], v[210:213], v[168:171], v[116:119]
	v_mfma_f32_16x16x32_bf16 v[112:115], v[218:221], v[168:171], v[112:115]
	v_mfma_f32_16x16x32_bf16 v[100:103], v[210:213], v[182:185], v[100:103]
	v_mfma_f32_16x16x32_bf16 v[96:99], v[218:221], v[182:185], v[96:99]
	v_mfma_f32_16x16x32_bf16 v[84:87], v[210:213], v[194:197], v[84:87]
	v_mfma_f32_16x16x32_bf16 v[80:83], v[218:221], v[194:197], v[80:83]
	v_mfma_f32_16x16x32_bf16 v[68:71], v[210:213], v[202:205], v[68:71]
	v_mfma_f32_16x16x32_bf16 v[64:67], v[218:221], v[202:205], v[64:67]
	v_mfma_f32_16x16x32_bf16 v[116:119], v[214:217], v[172:175], v[116:119]
	v_mfma_f32_16x16x32_bf16 v[112:115], v[222:225], v[172:175], v[112:115]
	v_mfma_f32_16x16x32_bf16 v[100:103], v[214:217], v[190:193], v[100:103]
	v_mfma_f32_16x16x32_bf16 v[96:99], v[222:225], v[190:193], v[96:99]
	v_mfma_f32_16x16x32_bf16 v[84:87], v[214:217], v[198:201], v[84:87]
	v_mfma_f32_16x16x32_bf16 v[80:83], v[222:225], v[198:201], v[80:83]
	v_mfma_f32_16x16x32_bf16 v[68:71], v[214:217], v[206:209], v[68:71]
	v_mfma_f32_16x16x32_bf16 v[64:67], v[222:225], v[206:209], v[64:67]
	s_barrier
	s_mov_b32 m0, s36
	v_lshl_add_u64 v[148:149], v[226:227], 0, s[6:7]
	ds_read_b128 v[168:171], v154 offset:49152
	ds_read_b128 v[172:175], v154 offset:50176
	ds_read_b128 v[182:185], v154 offset:51200
	ds_read_b128 v[190:193], v154 offset:52224
	ds_read_b128 v[194:197], v154 offset:53248
	ds_read_b128 v[198:201], v154 offset:54272
	ds_read_b128 v[202:205], v154 offset:55296
	ds_read_b128 v[206:209], v154 offset:56320
	global_load_lds_dwordx4 v[148:149], off
	v_lshl_add_u64 v[148:149], v[228:229], 0, s[6:7]
	s_mov_b32 m0, s37
	s_nop 0
	global_load_lds_dwordx4 v[148:149], off
	s_barrier
; __device__ __forceinline__ unsigned cvt_pk_bf16(float lo, float hi) { unsigned r; asm volatile("v_cvt_pk_bf16_f32 %0, %1, %2" : "=v"(r) : "v"(lo), "v"(hi)); return r; }
; __device__ __forceinline__ float bf_lo(unsigned u) { return __uint_as_float(u << 16); }
; __device__ __forceinline__ float bf_hi(unsigned u) { return __uint_as_float(u & 0xffff0000u); }
; #define PG8_STAGE(bufoff, gbase, voff) do { _Pragma("unroll") for (int _i = 0; _i < 2; ++_i) \
;         __builtin_amdgcn_global_load_lds((const unsigned*)((const char*)(gbase) + (voff)[_i]), (PG8_LAS unsigned*)(lds + (bufoff) + ldsw + _i * 8192), 16, 0, 0); } while (0)
;     __device__ __forceinline__ void operator()(const f32x4 (&acc)[2][2][4][2], const Unit& u, int wr, int wc, int fr, int fq) const {
;     ...
;             for (int m = 0; m < 4; ++m) { const size_t r = (size_t)(row0 + ai * HALF + m * 16); bf16_t* rowp = O + r * ldc + col0; const bf16_t* gp = G + r * ldg + col0;
; #pragma unroll
;                 for (int bj = 0; bj < 2; ++bj) { const u32x4 gw = *(const u32x4*)(gp + bj * HALF);
;                     f32x4 v0 = acc[ai][bj][m][0], v1 = acc[ai][bj][m][1];
;                     v0[0] *= bf_lo(gw.x); v0[1] *= bf_hi(gw.x); v0[2] *= bf_lo(gw.y); v0[3] *= bf_hi(gw.y);
;                     v1[0] *= bf_lo(gw.z); v1[1] *= bf_hi(gw.z); v1[2] *= bf_lo(gw.w); v1[3] *= bf_hi(gw.w);
;                     if (ACCUM) { const u32x4 pw = *(const u32x4*)(rowp + bj * HALF);
;                         v0[0] += bf_lo(pw.x); v0[1] += bf_hi(pw.x); v0[2] += bf_lo(pw.y); v0[3] += bf_hi(pw.y);
;                         v1[0] += bf_lo(pw.z); v1[1] += bf_hi(pw.z); v1[2] += bf_lo(pw.w); v1[3] += bf_hi(pw.w); }
;                     u32x4 w; w.x = cvt_pk_bf16(v0[0], v0[1]); w.y = cvt_pk_bf16(v0[2], v0[3]); w.z = cvt_pk_bf16(v1[0], v1[1]); w.w = cvt_pk_bf16(v1[2], v1[3]);
;                     *(u32x4*)(rowp + bj * HALF) = w; } }
; template <class Epi, class Sched>
; __device__ __forceinline__ void gemm_phase(PG8_LAS unsigned char* lds, const Gemm g, const Sched& S, const Epi& E) {
;     ...
;             PG8_BAR; PG8_WAIT_L(0); PG8_MMA(1, 0, At, B0); PG8_BAR; PG8_SCHED;
;             PG8_STAGE(PG8_SB(1, 1), b3 + hstep, voffB);
;             PG8_WAIT_V(6); PG8_BAR; PG8_MMA(1, 1, At, B1); PG8_BAR;
;         }
;         if constexpr (!Epi::AFTER_DRAIN) { E(acc, cur, wr, wc, fr, fq); S.done(cur); }
	s_waitcnt lgkmcnt(0)
	v_mfma_f32_16x16x32_bf16 v[60:63], v[144:147], v[168:171], v[60:63]
	v_mfma_f32_16x16x32_bf16 v[56:59], v[160:163], v[168:171], v[56:59]
	v_mfma_f32_16x16x32_bf16 v[44:47], v[144:147], v[182:185], v[44:47]
	v_mfma_f32_16x16x32_bf16 v[40:43], v[160:163], v[182:185], v[40:43]
	v_mfma_f32_16x16x32_bf16 v[28:31], v[144:147], v[194:197], v[28:31]
	v_mfma_f32_16x16x32_bf16 v[24:27], v[160:163], v[194:197], v[24:27]
	v_mfma_f32_16x16x32_bf16 v[12:15], v[144:147], v[202:205], v[12:15]
	v_mfma_f32_16x16x32_bf16 v[8:11], v[160:163], v[202:205], v[8:11]
	v_mfma_f32_16x16x32_bf16 v[60:63], v[156:159], v[172:175], v[60:63]
	v_mfma_f32_16x16x32_bf16 v[56:59], v[164:167], v[172:175], v[56:59]
	v_mfma_f32_16x16x32_bf16 v[44:47], v[156:159], v[190:193], v[44:47]
	v_mfma_f32_16x16x32_bf16 v[40:43], v[164:167], v[190:193], v[40:43]
	v_mfma_f32_16x16x32_bf16 v[28:31], v[156:159], v[198:201], v[28:31]
	v_mfma_f32_16x16x32_bf16 v[24:27], v[164:167], v[198:201], v[24:27]
	v_mfma_f32_16x16x32_bf16 v[12:15], v[156:159], v[206:209], v[12:15]
	v_mfma_f32_16x16x32_bf16 v[8:11], v[164:167], v[206:209], v[8:11]
	s_barrier
	s_add_u32 s20, s20, 0x40080
	s_addc_u32 s21, s21, 0
	s_add_i32 s22, s22, s29
	v_lshl_add_u64 v[144:145], s[20:21], 0, v[130:131]
	s_mov_b32 m0, s22
	s_nop 0
	global_load_lds_dwordx4 v[144:145], off
	v_lshl_add_u64 v[144:145], s[20:21], 0, v[134:135]
	s_add_i32 m0, s22, 0x2000
	s_nop 0
	global_load_lds_dwordx4 v[144:145], off
	s_waitcnt vmcnt(6)
	s_barrier
	v_mfma_f32_16x16x32_bf16 v[52:55], v[210:213], v[168:171], v[52:55]
	v_mfma_f32_16x16x32_bf16 v[48:51], v[218:221], v[168:171], v[48:51]
	v_mfma_f32_16x16x32_bf16 v[36:39], v[210:213], v[182:185], v[36:39]
	v_mfma_f32_16x16x32_bf16 v[32:35], v[218:221], v[182:185], v[32:35]
	v_mfma_f32_16x16x32_bf16 v[20:23], v[210:213], v[194:197], v[20:23]
	v_mfma_f32_16x16x32_bf16 v[16:19], v[218:221], v[194:197], v[16:19]
	v_mfma_f32_16x16x32_bf16 v[4:7], v[210:213], v[202:205], v[4:7]
	v_mfma_f32_16x16x32_bf16 v[0:3], v[218:221], v[202:205], v[0:3]
	v_mfma_f32_16x16x32_bf16 v[52:55], v[214:217], v[172:175], v[52:55]
	v_mfma_f32_16x16x32_bf16 v[48:51], v[222:225], v[172:175], v[48:51]
	v_mfma_f32_16x16x32_bf16 v[36:39], v[214:217], v[190:193], v[36:39]
	v_mfma_f32_16x16x32_bf16 v[32:35], v[222:225], v[190:193], v[32:35]
	v_mfma_f32_16x16x32_bf16 v[20:23], v[214:217], v[198:201], v[20:23]
	v_mfma_f32_16x16x32_bf16 v[16:19], v[222:225], v[198:201], v[16:19]
	v_mfma_f32_16x16x32_bf16 v[4:7], v[214:217], v[206:209], v[4:7]
	v_mfma_f32_16x16x32_bf16 v[0:3], v[222:225], v[206:209], v[0:3]
	s_barrier
	s_add_i32 s47, s47, 2
	s_add_u32 s18, s18, 0x100
	s_addc_u32 s19, s19, 0
	s_add_u32 s45, s45, 0x100
	s_addc_u32 s46, s46, 0
	s_cmp_gt_u32 s47, 13
	s_cbranch_scc0 .LBB0_1011
	v_lshl_add_u32 v146, s16, 8, v150
	v_lshl_or_b32 v144, s42, 8, v152
	v_ashrrev_i32_e32 v147, 31, v146
	v_ashrrev_i32_e32 v145, 31, v144
	v_mov_b64_e32 v[148:149], s[4:5]
	v_lshlrev_b64 v[160:161], 11, v[146:147]
	v_lshlrev_b64 v[144:145], 1, v[144:145]
	v_mad_i64_i32 v[156:157], s[18:19], v146, s41, v[148:149]
	v_lshl_add_u64 v[160:161], s[0:1], 0, v[160:161]
	v_lshl_add_u64 v[164:165], v[156:157], 0, v[144:145]
	v_lshl_add_u64 v[166:167], v[160:161], 0, v[144:145]
	global_load_dwordx4 v[156:159], v[164:165], off
	global_load_dwordx4 v[160:163], v[166:167], off
	s_and_b64 vcc, exec, s[2:3]
	s_mov_b32 s42, s8
	s_mov_b32 s16, s10
	s_mov_b64 s[20:21], s[14:15]
	s_waitcnt vmcnt(0)
	v_lshlrev_b32_e32 v147, 16, v156
	v_and_b32_e32 v156, 0xffff0000, v156
	v_lshlrev_b32_e32 v168, 16, v157
	v_and_b32_e32 v157, 0xffff0000, v157
	v_lshlrev_b32_e32 v169, 16, v158
	v_and_b32_e32 v158, 0xffff0000, v158
	v_lshlrev_b32_e32 v170, 16, v159
	v_and_b32_e32 v159, 0xffff0000, v159
	v_lshlrev_b32_e32 v171, 16, v160
	v_and_b32_e32 v160, 0xffff0000, v160
	v_lshlrev_b32_e32 v172, 16, v161
	v_and_b32_e32 v161, 0xffff0000, v161
	v_lshlrev_b32_e32 v173, 16, v162
	v_and_b32_e32 v162, 0xffff0000, v162
	v_lshlrev_b32_e32 v174, 16, v163
	v_and_b32_e32 v163, 0xffff0000, v163
	v_fmac_f32_e32 v171, v124, v147
	v_fmac_f32_e32 v160, v125, v156
	v_fmac_f32_e32 v172, v126, v168
	v_fmac_f32_e32 v161, v127, v157
	v_fmac_f32_e32 v173, v120, v169
	v_fmac_f32_e32 v162, v121, v158
	v_fmac_f32_e32 v174, v122, v170
	v_fmac_f32_e32 v163, v123, v159
	v_cvt_pk_bf16_f32 v120, v171, v160
	v_cvt_pk_bf16_f32 v121, v172, v161
	v_cvt_pk_bf16_f32 v122, v173, v162
	v_cvt_pk_bf16_f32 v123, v174, v163
	global_load_dwordx4 v[124:127], v[164:165], off offset:256
	global_load_dwordx4 v[156:159], v[166:167], off offset:256
	v_or_b32_e32 v160, 16, v146
	global_store_dwordx4 v[166:167], v[120:123], off
	v_mad_i64_i32 v[162:163], s[18:19], v160, s41, v[148:149]
	v_lshl_add_u64 v[162:163], v[162:163], 0, v[144:145]
	s_waitcnt vmcnt(0)
	v_lshlrev_b32_e32 v122, 16, v125
	v_lshlrev_b32_e32 v161, 16, v157
	v_lshlrev_b32_e32 v120, 16, v124
	v_and_b32_e32 v121, 0xffff0000, v124
	v_and_b32_e32 v123, 0xffff0000, v125
	v_lshlrev_b32_e32 v124, 16, v126
	v_and_b32_e32 v125, 0xffff0000, v126
	v_lshlrev_b32_e32 v147, 16, v156
	v_and_b32_e32 v156, 0xffff0000, v156
	v_and_b32_e32 v157, 0xffff0000, v157
	v_lshlrev_b32_e32 v164, 16, v158
	v_and_b32_e32 v158, 0xffff0000, v158
	v_fmac_f32_e32 v161, v118, v122
	v_fmac_f32_e32 v147, v116, v120
	v_fmac_f32_e32 v156, v117, v121
	v_fmac_f32_e32 v157, v119, v123
	v_fmac_f32_e32 v164, v112, v124
	v_fmac_f32_e32 v158, v113, v125
	v_cvt_pk_bf16_f32 v112, v147, v156
	v_cvt_pk_bf16_f32 v113, v161, v157
	v_ashrrev_i32_e32 v161, 31, v160
	v_lshlrev_b64 v[120:121], 11, v[160:161]
	v_lshl_add_u64 v[120:121], s[0:1], 0, v[120:121]
	v_lshlrev_b32_e32 v126, 16, v127
	v_and_b32_e32 v127, 0xffff0000, v127
	v_lshlrev_b32_e32 v165, 16, v159
	v_and_b32_e32 v159, 0xffff0000, v159
	v_lshl_add_u64 v[124:125], v[120:121], 0, v[144:145]
	v_fmac_f32_e32 v165, v114, v126
	v_fmac_f32_e32 v159, v115, v127
	v_cvt_pk_bf16_f32 v114, v164, v158
	v_cvt_pk_bf16_f32 v115, v165, v159
	global_load_dwordx4 v[116:119], v[162:163], off
	global_load_dwordx4 v[120:123], v[124:125], off
	s_waitcnt vmcnt(0)
; __device__ __forceinline__ unsigned cvt_pk_bf16(float lo, float hi) { unsigned r; asm volatile("v_cvt_pk_bf16_f32 %0, %1, %2" : "=v"(r) : "v"(lo), "v"(hi)); return r; }
; __device__ __forceinline__ float bf_lo(unsigned u) { return __uint_as_float(u << 16); }
; __device__ __forceinline__ float bf_hi(unsigned u) { return __uint_as_float(u & 0xffff0000u); }
;     __device__ __forceinline__ void operator()(const f32x4 (&acc)[2][2][4][2], const Unit& u, int wr, int wc, int fr, int fq) const {
;     ...
;             for (int m = 0; m < 4; ++m) { const size_t r = (size_t)(row0 + ai * HALF + m * 16); bf16_t* rowp = O + r * ldc + col0; const bf16_t* gp = G + r * ldg + col0;
; #pragma unroll
;                 for (int bj = 0; bj < 2; ++bj) { const u32x4 gw = *(const u32x4*)(gp + bj * HALF);
;                     f32x4 v0 = acc[ai][bj][m][0], v1 = acc[ai][bj][m][1];
;                     v0[0] *= bf_lo(gw.x); v0[1] *= bf_hi(gw.x); v0[2] *= bf_lo(gw.y); v0[3] *= bf_hi(gw.y);
;                     v1[0] *= bf_lo(gw.z); v1[1] *= bf_hi(gw.z); v1[2] *= bf_lo(gw.w); v1[3] *= bf_hi(gw.w);
;                     if (ACCUM) { const u32x4 pw = *(const u32x4*)(rowp + bj * HALF);
;                         v0[0] += bf_lo(pw.x); v0[1] += bf_hi(pw.x); v0[2] += bf_lo(pw.y); v0[3] += bf_hi(pw.y);
;                         v1[0] += bf_lo(pw.z); v1[1] += bf_hi(pw.z); v1[2] += bf_lo(pw.w); v1[3] += bf_hi(pw.w); }
;                     u32x4 w; w.x = cvt_pk_bf16(v0[0], v0[1]); w.y = cvt_pk_bf16(v0[2], v0[3]); w.z = cvt_pk_bf16(v1[0], v1[1]); w.w = cvt_pk_bf16(v1[2], v1[3]);
;                     *(u32x4*)(rowp + bj * HALF) = w; } }
	v_lshlrev_b32_e32 v126, 16, v120
	global_store_dwordx4 v[166:167], v[112:115], off offset:256
	v_and_b32_e32 v120, 0xffff0000, v120
	v_lshlrev_b32_e32 v127, 16, v121
	v_lshlrev_b32_e32 v112, 16, v116
	v_and_b32_e32 v113, 0xffff0000, v116
	v_lshlrev_b32_e32 v114, 16, v117
	v_and_b32_e32 v115, 0xffff0000, v117
	v_lshlrev_b32_e32 v116, 16, v118
	v_and_b32_e32 v117, 0xffff0000, v118
	v_lshlrev_b32_e32 v118, 16, v119
	v_and_b32_e32 v119, 0xffff0000, v119
	v_and_b32_e32 v121, 0xffff0000, v121
	v_lshlrev_b32_e32 v147, 16, v122
	v_and_b32_e32 v122, 0xffff0000, v122
	v_lshlrev_b32_e32 v156, 16, v123
	v_and_b32_e32 v123, 0xffff0000, v123
	v_fmac_f32_e32 v126, v108, v112
	v_fmac_f32_e32 v120, v109, v113
	v_fmac_f32_e32 v127, v110, v114
	v_fmac_f32_e32 v121, v111, v115
	v_fmac_f32_e32 v147, v104, v116
	v_fmac_f32_e32 v122, v105, v117
	v_fmac_f32_e32 v156, v106, v118
	v_fmac_f32_e32 v123, v107, v119
	v_cvt_pk_bf16_f32 v104, v126, v120
	v_cvt_pk_bf16_f32 v105, v127, v121
	v_cvt_pk_bf16_f32 v106, v147, v122
	v_cvt_pk_bf16_f32 v107, v156, v123
	global_load_dwordx4 v[108:111], v[162:163], off offset:256
	global_load_dwordx4 v[112:115], v[124:125], off offset:256
	v_or_b32_e32 v116, 32, v146
	global_store_dwordx4 v[124:125], v[104:107], off
	v_mad_i64_i32 v[118:119], s[18:19], v116, s41, v[148:149]
	v_lshl_add_u64 v[118:119], v[118:119], 0, v[144:145]
	s_waitcnt vmcnt(0)
	v_lshlrev_b32_e32 v104, 16, v108
	v_lshlrev_b32_e32 v117, 16, v112
	v_and_b32_e32 v105, 0xffff0000, v108
	v_lshlrev_b32_e32 v108, 16, v110
	v_and_b32_e32 v112, 0xffff0000, v112
	v_lshlrev_b32_e32 v121, 16, v114
	v_fmac_f32_e32 v117, v100, v104
	v_fmac_f32_e32 v112, v101, v105
	v_fmac_f32_e32 v121, v96, v108
	v_cvt_pk_bf16_f32 v96, v117, v112
	v_ashrrev_i32_e32 v117, 31, v116
	v_lshlrev_b64 v[104:105], 11, v[116:117]
	v_lshlrev_b32_e32 v106, 16, v109
	v_and_b32_e32 v107, 0xffff0000, v109
	v_and_b32_e32 v109, 0xffff0000, v110
	v_and_b32_e32 v114, 0xffff0000, v114
	v_lshl_add_u64 v[104:105], s[0:1], 0, v[104:105]
	v_lshlrev_b32_e32 v110, 16, v111
	v_and_b32_e32 v111, 0xffff0000, v111
	v_lshlrev_b32_e32 v120, 16, v113
	v_and_b32_e32 v113, 0xffff0000, v113
	v_lshlrev_b32_e32 v122, 16, v115
	v_and_b32_e32 v115, 0xffff0000, v115
	v_fmac_f32_e32 v114, v97, v109
	v_lshl_add_u64 v[108:109], v[104:105], 0, v[144:145]
	v_fmac_f32_e32 v120, v102, v106
	v_fmac_f32_e32 v113, v103, v107
	v_fmac_f32_e32 v122, v98, v110
	v_fmac_f32_e32 v115, v99, v111
	v_cvt_pk_bf16_f32 v97, v120, v113
	v_cvt_pk_bf16_f32 v98, v121, v114
	v_cvt_pk_bf16_f32 v99, v122, v115
	global_load_dwordx4 v[100:103], v[118:119], off
	global_load_dwordx4 v[104:107], v[108:109], off
	s_waitcnt vmcnt(0)
	v_lshlrev_b32_e32 v110, 16, v104
	global_store_dwordx4 v[124:125], v[96:99], off offset:256
	v_and_b32_e32 v104, 0xffff0000, v104
	v_lshlrev_b32_e32 v111, 16, v105
	v_lshlrev_b32_e32 v96, 16, v100
	v_and_b32_e32 v97, 0xffff0000, v100
	v_lshlrev_b32_e32 v98, 16, v101
	v_and_b32_e32 v99, 0xffff0000, v101
	v_lshlrev_b32_e32 v100, 16, v102
	v_and_b32_e32 v101, 0xffff0000, v102
	v_lshlrev_b32_e32 v102, 16, v103
	v_and_b32_e32 v103, 0xffff0000, v103
	v_and_b32_e32 v105, 0xffff0000, v105
	v_lshlrev_b32_e32 v112, 16, v106
	v_and_b32_e32 v106, 0xffff0000, v106
	v_lshlrev_b32_e32 v113, 16, v107
	v_and_b32_e32 v107, 0xffff0000, v107
	v_fmac_f32_e32 v110, v92, v96
	v_fmac_f32_e32 v104, v93, v97
	v_fmac_f32_e32 v111, v94, v98
	v_fmac_f32_e32 v105, v95, v99
	v_fmac_f32_e32 v112, v88, v100
	v_fmac_f32_e32 v106, v89, v101
	v_fmac_f32_e32 v113, v90, v102
	v_fmac_f32_e32 v107, v91, v103
	v_cvt_pk_bf16_f32 v88, v110, v104
	v_cvt_pk_bf16_f32 v89, v111, v105
	v_cvt_pk_bf16_f32 v90, v112, v106
	v_cvt_pk_bf16_f32 v91, v113, v107
	global_load_dwordx4 v[92:95], v[118:119], off offset:256
	global_load_dwordx4 v[96:99], v[108:109], off offset:256
	v_or_b32_e32 v100, 48, v146
	global_store_dwordx4 v[108:109], v[88:91], off
	v_mad_i64_i32 v[102:103], s[18:19], v100, s41, v[148:149]
	v_lshl_add_u64 v[102:103], v[102:103], 0, v[144:145]
	s_waitcnt vmcnt(0)
	v_lshlrev_b32_e32 v88, 16, v92
	v_lshlrev_b32_e32 v101, 16, v96
	v_and_b32_e32 v89, 0xffff0000, v92
	v_lshlrev_b32_e32 v92, 16, v94
	v_and_b32_e32 v96, 0xffff0000, v96
	v_lshlrev_b32_e32 v105, 16, v98
	v_fmac_f32_e32 v101, v84, v88
	v_fmac_f32_e32 v96, v85, v89
	v_fmac_f32_e32 v105, v80, v92
	v_cvt_pk_bf16_f32 v80, v101, v96
	v_ashrrev_i32_e32 v101, 31, v100
	v_lshlrev_b64 v[88:89], 11, v[100:101]
	v_lshlrev_b32_e32 v90, 16, v93
	v_and_b32_e32 v91, 0xffff0000, v93
	v_and_b32_e32 v93, 0xffff0000, v94
	v_and_b32_e32 v98, 0xffff0000, v98
	v_lshl_add_u64 v[88:89], s[0:1], 0, v[88:89]
	v_lshlrev_b32_e32 v94, 16, v95
	v_and_b32_e32 v95, 0xffff0000, v95
	v_lshlrev_b32_e32 v104, 16, v97
	v_and_b32_e32 v97, 0xffff0000, v97
	v_lshlrev_b32_e32 v106, 16, v99
	v_and_b32_e32 v99, 0xffff0000, v99
	v_fmac_f32_e32 v98, v81, v93
	v_lshl_add_u64 v[92:93], v[88:89], 0, v[144:145]
	v_fmac_f32_e32 v104, v86, v90
	v_fmac_f32_e32 v97, v87, v91
	v_fmac_f32_e32 v106, v82, v94
	v_fmac_f32_e32 v99, v83, v95
	v_cvt_pk_bf16_f32 v81, v104, v97
	v_cvt_pk_bf16_f32 v82, v105, v98
	v_cvt_pk_bf16_f32 v83, v106, v99
	global_load_dwordx4 v[84:87], v[102:103], off
	global_load_dwordx4 v[88:91], v[92:93], off
	s_waitcnt vmcnt(0)
; __device__ __forceinline__ unsigned cvt_pk_bf16(float lo, float hi) { unsigned r; asm volatile("v_cvt_pk_bf16_f32 %0, %1, %2" : "=v"(r) : "v"(lo), "v"(hi)); return r; }
; __device__ __forceinline__ float bf_lo(unsigned u) { return __uint_as_float(u << 16); }
; __device__ __forceinline__ float bf_hi(unsigned u) { return __uint_as_float(u & 0xffff0000u); }
;     __device__ __forceinline__ void operator()(const f32x4 (&acc)[2][2][4][2], const Unit& u, int wr, int wc, int fr, int fq) const {
;     ...
;             for (int m = 0; m < 4; ++m) { const size_t r = (size_t)(row0 + ai * HALF + m * 16); bf16_t* rowp = O + r * ldc + col0; const bf16_t* gp = G + r * ldg + col0;
; #pragma unroll
;                 for (int bj = 0; bj < 2; ++bj) { const u32x4 gw = *(const u32x4*)(gp + bj * HALF);
;                     f32x4 v0 = acc[ai][bj][m][0], v1 = acc[ai][bj][m][1];
;                     v0[0] *= bf_lo(gw.x); v0[1] *= bf_hi(gw.x); v0[2] *= bf_lo(gw.y); v0[3] *= bf_hi(gw.y);
;                     v1[0] *= bf_lo(gw.z); v1[1] *= bf_hi(gw.z); v1[2] *= bf_lo(gw.w); v1[3] *= bf_hi(gw.w);
;                     if (ACCUM) { const u32x4 pw = *(const u32x4*)(rowp + bj * HALF);
;                         v0[0] += bf_lo(pw.x); v0[1] += bf_hi(pw.x); v0[2] += bf_lo(pw.y); v0[3] += bf_hi(pw.y);
;                         v1[0] += bf_lo(pw.z); v1[1] += bf_hi(pw.z); v1[2] += bf_lo(pw.w); v1[3] += bf_hi(pw.w); }
;                     u32x4 w; w.x = cvt_pk_bf16(v0[0], v0[1]); w.y = cvt_pk_bf16(v0[2], v0[3]); w.z = cvt_pk_bf16(v1[0], v1[1]); w.w = cvt_pk_bf16(v1[2], v1[3]);
;                     *(u32x4*)(rowp + bj * HALF) = w; } }
	v_lshlrev_b32_e32 v94, 16, v88
	global_store_dwordx4 v[108:109], v[80:83], off offset:256
	v_and_b32_e32 v88, 0xffff0000, v88
	v_lshlrev_b32_e32 v95, 16, v89
	v_lshlrev_b32_e32 v80, 16, v84
	v_and_b32_e32 v81, 0xffff0000, v84
	v_lshlrev_b32_e32 v82, 16, v85
	v_and_b32_e32 v83, 0xffff0000, v85
	v_lshlrev_b32_e32 v84, 16, v86
	v_and_b32_e32 v85, 0xffff0000, v86
	v_lshlrev_b32_e32 v86, 16, v87
	v_and_b32_e32 v87, 0xffff0000, v87
	v_and_b32_e32 v89, 0xffff0000, v89
	v_lshlrev_b32_e32 v96, 16, v90
	v_and_b32_e32 v90, 0xffff0000, v90
	v_lshlrev_b32_e32 v97, 16, v91
	v_and_b32_e32 v91, 0xffff0000, v91
	v_fmac_f32_e32 v94, v76, v80
	v_fmac_f32_e32 v88, v77, v81
	v_fmac_f32_e32 v95, v78, v82
	v_fmac_f32_e32 v89, v79, v83
	v_fmac_f32_e32 v96, v72, v84
	v_fmac_f32_e32 v90, v73, v85
	v_fmac_f32_e32 v97, v74, v86
	v_fmac_f32_e32 v91, v75, v87
	v_cvt_pk_bf16_f32 v72, v94, v88
	v_cvt_pk_bf16_f32 v73, v95, v89
	v_cvt_pk_bf16_f32 v74, v96, v90
	v_cvt_pk_bf16_f32 v75, v97, v91
	global_load_dwordx4 v[76:79], v[102:103], off offset:256
	global_load_dwordx4 v[80:83], v[92:93], off offset:256
	v_add_u32_e32 v84, 0x80, v146
	global_store_dwordx4 v[92:93], v[72:75], off
	v_mad_i64_i32 v[86:87], s[18:19], v84, s41, v[148:149]
	v_lshl_add_u64 v[86:87], v[86:87], 0, v[144:145]
	s_waitcnt vmcnt(0)
	v_lshlrev_b32_e32 v72, 16, v76
	v_lshlrev_b32_e32 v85, 16, v80
	v_and_b32_e32 v73, 0xffff0000, v76
	v_lshlrev_b32_e32 v76, 16, v78
	v_and_b32_e32 v80, 0xffff0000, v80
	v_lshlrev_b32_e32 v89, 16, v82
	v_fmac_f32_e32 v85, v68, v72
	v_fmac_f32_e32 v80, v69, v73
	v_fmac_f32_e32 v89, v64, v76
	v_cvt_pk_bf16_f32 v64, v85, v80
	v_ashrrev_i32_e32 v85, 31, v84
	v_lshlrev_b64 v[72:73], 11, v[84:85]
	v_lshlrev_b32_e32 v74, 16, v77
	v_and_b32_e32 v75, 0xffff0000, v77
	v_and_b32_e32 v77, 0xffff0000, v78
	v_and_b32_e32 v82, 0xffff0000, v82
	v_lshl_add_u64 v[72:73], s[0:1], 0, v[72:73]
	v_lshlrev_b32_e32 v78, 16, v79
	v_and_b32_e32 v79, 0xffff0000, v79
	v_lshlrev_b32_e32 v88, 16, v81
	v_and_b32_e32 v81, 0xffff0000, v81
	v_lshlrev_b32_e32 v90, 16, v83
	v_and_b32_e32 v83, 0xffff0000, v83
	v_fmac_f32_e32 v82, v65, v77
	v_lshl_add_u64 v[76:77], v[72:73], 0, v[144:145]
	v_fmac_f32_e32 v88, v70, v74
	v_fmac_f32_e32 v81, v71, v75
	v_fmac_f32_e32 v90, v66, v78
	v_fmac_f32_e32 v83, v67, v79
	v_cvt_pk_bf16_f32 v65, v88, v81
	v_cvt_pk_bf16_f32 v66, v89, v82
	v_cvt_pk_bf16_f32 v67, v90, v83
	global_load_dwordx4 v[68:71], v[86:87], off
	global_load_dwordx4 v[72:75], v[76:77], off
	s_waitcnt vmcnt(0)
	v_lshlrev_b32_e32 v78, 16, v72
	global_store_dwordx4 v[92:93], v[64:67], off offset:256
	v_and_b32_e32 v72, 0xffff0000, v72
	v_lshlrev_b32_e32 v79, 16, v73
	v_lshlrev_b32_e32 v64, 16, v68
	v_and_b32_e32 v65, 0xffff0000, v68
	v_lshlrev_b32_e32 v66, 16, v69
	v_and_b32_e32 v67, 0xffff0000, v69
	v_lshlrev_b32_e32 v68, 16, v70
	v_and_b32_e32 v69, 0xffff0000, v70
	v_lshlrev_b32_e32 v70, 16, v71
	v_and_b32_e32 v71, 0xffff0000, v71
	v_and_b32_e32 v73, 0xffff0000, v73
	v_lshlrev_b32_e32 v80, 16, v74
	v_and_b32_e32 v74, 0xffff0000, v74
	v_lshlrev_b32_e32 v81, 16, v75
	v_and_b32_e32 v75, 0xffff0000, v75
	v_fmac_f32_e32 v78, v60, v64
	v_fmac_f32_e32 v72, v61, v65
	v_fmac_f32_e32 v79, v62, v66
	v_fmac_f32_e32 v73, v63, v67
	v_fmac_f32_e32 v80, v56, v68
	v_fmac_f32_e32 v74, v57, v69
	v_fmac_f32_e32 v81, v58, v70
	v_fmac_f32_e32 v75, v59, v71
	v_cvt_pk_bf16_f32 v56, v78, v72
	v_cvt_pk_bf16_f32 v57, v79, v73
	v_cvt_pk_bf16_f32 v58, v80, v74
	v_cvt_pk_bf16_f32 v59, v81, v75
	global_load_dwordx4 v[60:63], v[86:87], off offset:256
	global_load_dwordx4 v[64:67], v[76:77], off offset:256
	v_add_u32_e32 v68, 0x90, v146
	global_store_dwordx4 v[76:77], v[56:59], off
	v_mad_i64_i32 v[70:71], s[18:19], v68, s41, v[148:149]
	v_lshl_add_u64 v[70:71], v[70:71], 0, v[144:145]
	s_waitcnt vmcnt(0)
	v_lshlrev_b32_e32 v56, 16, v60
	v_lshlrev_b32_e32 v69, 16, v64
	v_and_b32_e32 v57, 0xffff0000, v60
	v_lshlrev_b32_e32 v60, 16, v62
	v_and_b32_e32 v64, 0xffff0000, v64
	v_lshlrev_b32_e32 v73, 16, v66
	v_fmac_f32_e32 v69, v52, v56
	v_fmac_f32_e32 v64, v53, v57
	v_fmac_f32_e32 v73, v48, v60
	v_cvt_pk_bf16_f32 v48, v69, v64
	v_ashrrev_i32_e32 v69, 31, v68
	v_lshlrev_b64 v[56:57], 11, v[68:69]
	v_lshlrev_b32_e32 v58, 16, v61
	v_and_b32_e32 v59, 0xffff0000, v61
	v_and_b32_e32 v61, 0xffff0000, v62
	v_and_b32_e32 v66, 0xffff0000, v66
	v_lshl_add_u64 v[56:57], s[0:1], 0, v[56:57]
	v_lshlrev_b32_e32 v62, 16, v63
	v_and_b32_e32 v63, 0xffff0000, v63
	v_lshlrev_b32_e32 v72, 16, v65
	v_and_b32_e32 v65, 0xffff0000, v65
	v_lshlrev_b32_e32 v74, 16, v67
	v_and_b32_e32 v67, 0xffff0000, v67
	v_fmac_f32_e32 v66, v49, v61
	v_lshl_add_u64 v[60:61], v[56:57], 0, v[144:145]
	v_fmac_f32_e32 v72, v54, v58
	v_fmac_f32_e32 v65, v55, v59
	v_fmac_f32_e32 v74, v50, v62
	v_fmac_f32_e32 v67, v51, v63
	v_cvt_pk_bf16_f32 v49, v72, v65
	v_cvt_pk_bf16_f32 v50, v73, v66
	v_cvt_pk_bf16_f32 v51, v74, v67
	global_load_dwordx4 v[52:55], v[70:71], off
	global_load_dwordx4 v[56:59], v[60:61], off
	s_waitcnt vmcnt(0)
	v_lshlrev_b32_e32 v62, 16, v56
	global_store_dwordx4 v[76:77], v[48:51], off offset:256
	v_and_b32_e32 v56, 0xffff0000, v56
	v_lshlrev_b32_e32 v63, 16, v57
	v_lshlrev_b32_e32 v48, 16, v52
	v_and_b32_e32 v49, 0xffff0000, v52
	v_lshlrev_b32_e32 v50, 16, v53
	v_and_b32_e32 v51, 0xffff0000, v53
	v_lshlrev_b32_e32 v52, 16, v54
	v_and_b32_e32 v53, 0xffff0000, v54
	v_lshlrev_b32_e32 v54, 16, v55
	v_and_b32_e32 v55, 0xffff0000, v55
	v_and_b32_e32 v57, 0xffff0000, v57
	v_lshlrev_b32_e32 v64, 16, v58
	v_and_b32_e32 v58, 0xffff0000, v58
	v_lshlrev_b32_e32 v65, 16, v59
	v_and_b32_e32 v59, 0xffff0000, v59
	v_fmac_f32_e32 v62, v44, v48
	v_fmac_f32_e32 v56, v45, v49
	v_fmac_f32_e32 v63, v46, v50
	v_fmac_f32_e32 v57, v47, v51
	v_fmac_f32_e32 v64, v40, v52
	v_fmac_f32_e32 v58, v41, v53
	v_fmac_f32_e32 v65, v42, v54
	v_fmac_f32_e32 v59, v43, v55
	v_cvt_pk_bf16_f32 v40, v62, v56
	v_cvt_pk_bf16_f32 v41, v63, v57
	v_cvt_pk_bf16_f32 v42, v64, v58
	v_cvt_pk_bf16_f32 v43, v65, v59
	global_load_dwordx4 v[44:47], v[70:71], off offset:256
	global_load_dwordx4 v[48:51], v[60:61], off offset:256
	v_add_u32_e32 v52, 0xa0, v146
	global_store_dwordx4 v[60:61], v[40:43], off
	v_mad_i64_i32 v[54:55], s[18:19], v52, s41, v[148:149]
	v_lshl_add_u64 v[54:55], v[54:55], 0, v[144:145]
	s_waitcnt vmcnt(0)
; __device__ __forceinline__ unsigned cvt_pk_bf16(float lo, float hi) { unsigned r; asm volatile("v_cvt_pk_bf16_f32 %0, %1, %2" : "=v"(r) : "v"(lo), "v"(hi)); return r; }
; __device__ __forceinline__ float bf_lo(unsigned u) { return __uint_as_float(u << 16); }
; __device__ __forceinline__ float bf_hi(unsigned u) { return __uint_as_float(u & 0xffff0000u); }
; #define PG8_WAIT_V(n) asm volatile("s_waitcnt vmcnt(" #n ")" ::: "memory")
; #define PG8_BAR __builtin_amdgcn_s_barrier()
;     __device__ __forceinline__ void operator()(const f32x4 (&acc)[2][2][4][2], const Unit& u, int wr, int wc, int fr, int fq) const {
;     ...
;             for (int m = 0; m < 4; ++m) { const size_t r = (size_t)(row0 + ai * HALF + m * 16); bf16_t* rowp = O + r * ldc + col0; const bf16_t* gp = G + r * ldg + col0;
; #pragma unroll
;                 for (int bj = 0; bj < 2; ++bj) { const u32x4 gw = *(const u32x4*)(gp + bj * HALF);
;                     f32x4 v0 = acc[ai][bj][m][0], v1 = acc[ai][bj][m][1];
;                     v0[0] *= bf_lo(gw.x); v0[1] *= bf_hi(gw.x); v0[2] *= bf_lo(gw.y); v0[3] *= bf_hi(gw.y);
;                     v1[0] *= bf_lo(gw.z); v1[1] *= bf_hi(gw.z); v1[2] *= bf_lo(gw.w); v1[3] *= bf_hi(gw.w);
;                     if (ACCUM) { const u32x4 pw = *(const u32x4*)(rowp + bj * HALF);
;                         v0[0] += bf_lo(pw.x); v0[1] += bf_hi(pw.x); v0[2] += bf_lo(pw.y); v0[3] += bf_hi(pw.y);
;                         v1[0] += bf_lo(pw.z); v1[1] += bf_hi(pw.z); v1[2] += bf_lo(pw.w); v1[3] += bf_hi(pw.w); }
;                     u32x4 w; w.x = cvt_pk_bf16(v0[0], v0[1]); w.y = cvt_pk_bf16(v0[2], v0[3]); w.z = cvt_pk_bf16(v1[0], v1[1]); w.w = cvt_pk_bf16(v1[2], v1[3]);
;                     *(u32x4*)(rowp + bj * HALF) = w; } }
; template <class Epi, class Sched>
; __device__ __forceinline__ void gemm_phase(PG8_LAS unsigned char* lds, const Gemm g, const Sched& S, const Epi& E) {
;     ...
;     PG8_WAIT_V(0);
;     if (wr == 0) PG8_BAR;
;     PG8_BAR;
	v_lshlrev_b32_e32 v40, 16, v44
	v_lshlrev_b32_e32 v53, 16, v48
	v_and_b32_e32 v41, 0xffff0000, v44
	v_lshlrev_b32_e32 v44, 16, v46
	v_and_b32_e32 v48, 0xffff0000, v48
	v_lshlrev_b32_e32 v57, 16, v50
	v_fmac_f32_e32 v53, v36, v40
	v_fmac_f32_e32 v48, v37, v41
	v_fmac_f32_e32 v57, v32, v44
	v_cvt_pk_bf16_f32 v32, v53, v48
	v_ashrrev_i32_e32 v53, 31, v52
	v_lshlrev_b64 v[40:41], 11, v[52:53]
	v_lshlrev_b32_e32 v42, 16, v45
	v_and_b32_e32 v43, 0xffff0000, v45
	v_and_b32_e32 v45, 0xffff0000, v46
	v_and_b32_e32 v50, 0xffff0000, v50
	v_lshl_add_u64 v[40:41], s[0:1], 0, v[40:41]
	v_lshlrev_b32_e32 v46, 16, v47
	v_and_b32_e32 v47, 0xffff0000, v47
	v_lshlrev_b32_e32 v56, 16, v49
	v_and_b32_e32 v49, 0xffff0000, v49
	v_lshlrev_b32_e32 v58, 16, v51
	v_and_b32_e32 v51, 0xffff0000, v51
	v_fmac_f32_e32 v50, v33, v45
	v_lshl_add_u64 v[44:45], v[40:41], 0, v[144:145]
	v_fmac_f32_e32 v56, v38, v42
	v_fmac_f32_e32 v49, v39, v43
	v_fmac_f32_e32 v58, v34, v46
	v_fmac_f32_e32 v51, v35, v47
	v_cvt_pk_bf16_f32 v33, v56, v49
	v_cvt_pk_bf16_f32 v34, v57, v50
	v_cvt_pk_bf16_f32 v35, v58, v51
	global_load_dwordx4 v[36:39], v[54:55], off
	global_load_dwordx4 v[40:43], v[44:45], off
	s_waitcnt vmcnt(0)
	v_lshlrev_b32_e32 v46, 16, v40
	global_store_dwordx4 v[60:61], v[32:35], off offset:256
	v_and_b32_e32 v40, 0xffff0000, v40
	v_lshlrev_b32_e32 v47, 16, v41
	v_lshlrev_b32_e32 v32, 16, v36
	v_and_b32_e32 v33, 0xffff0000, v36
	v_lshlrev_b32_e32 v34, 16, v37
	v_and_b32_e32 v35, 0xffff0000, v37
	v_lshlrev_b32_e32 v36, 16, v38
	v_and_b32_e32 v37, 0xffff0000, v38
	v_lshlrev_b32_e32 v38, 16, v39
	v_and_b32_e32 v39, 0xffff0000, v39
	v_and_b32_e32 v41, 0xffff0000, v41
	v_lshlrev_b32_e32 v48, 16, v42
	v_and_b32_e32 v42, 0xffff0000, v42
	v_lshlrev_b32_e32 v49, 16, v43
	v_and_b32_e32 v43, 0xffff0000, v43
	v_fmac_f32_e32 v46, v28, v32
	v_fmac_f32_e32 v40, v29, v33
	v_fmac_f32_e32 v47, v30, v34
	v_fmac_f32_e32 v41, v31, v35
	v_fmac_f32_e32 v48, v24, v36
	v_fmac_f32_e32 v42, v25, v37
	v_fmac_f32_e32 v49, v26, v38
	v_fmac_f32_e32 v43, v27, v39
	v_cvt_pk_bf16_f32 v24, v46, v40
	v_cvt_pk_bf16_f32 v25, v47, v41
	v_cvt_pk_bf16_f32 v26, v48, v42
	v_cvt_pk_bf16_f32 v27, v49, v43
	global_load_dwordx4 v[28:31], v[54:55], off offset:256
	global_load_dwordx4 v[32:35], v[44:45], off offset:256
	v_add_u32_e32 v36, 0xb0, v146
	global_store_dwordx4 v[44:45], v[24:27], off
	v_mad_i64_i32 v[38:39], s[18:19], v36, s41, v[148:149]
	v_lshl_add_u64 v[38:39], v[38:39], 0, v[144:145]
	s_mov_b64 s[18:19], s[12:13]
	s_waitcnt vmcnt(0)
	v_lshlrev_b32_e32 v24, 16, v28
	v_lshlrev_b32_e32 v37, 16, v32
	v_and_b32_e32 v25, 0xffff0000, v28
	v_lshlrev_b32_e32 v28, 16, v30
	v_and_b32_e32 v32, 0xffff0000, v32
	v_lshlrev_b32_e32 v41, 16, v34
	v_fmac_f32_e32 v37, v20, v24
	v_fmac_f32_e32 v32, v21, v25
	v_fmac_f32_e32 v41, v16, v28
	v_cvt_pk_bf16_f32 v16, v37, v32
	v_ashrrev_i32_e32 v37, 31, v36
	v_lshlrev_b64 v[24:25], 11, v[36:37]
	v_lshlrev_b32_e32 v26, 16, v29
	v_and_b32_e32 v27, 0xffff0000, v29
	v_and_b32_e32 v29, 0xffff0000, v30
	v_and_b32_e32 v34, 0xffff0000, v34
	v_lshl_add_u64 v[24:25], s[0:1], 0, v[24:25]
	v_lshlrev_b32_e32 v30, 16, v31
	v_and_b32_e32 v31, 0xffff0000, v31
	v_lshlrev_b32_e32 v40, 16, v33
	v_and_b32_e32 v33, 0xffff0000, v33
	v_lshlrev_b32_e32 v42, 16, v35
	v_and_b32_e32 v35, 0xffff0000, v35
	v_fmac_f32_e32 v34, v17, v29
	v_lshl_add_u64 v[28:29], v[24:25], 0, v[144:145]
	v_fmac_f32_e32 v40, v22, v26
	v_fmac_f32_e32 v33, v23, v27
	v_fmac_f32_e32 v42, v18, v30
	v_fmac_f32_e32 v35, v19, v31
	v_cvt_pk_bf16_f32 v17, v40, v33
	v_cvt_pk_bf16_f32 v18, v41, v34
	v_cvt_pk_bf16_f32 v19, v42, v35
	global_load_dwordx4 v[20:23], v[38:39], off
	global_load_dwordx4 v[24:27], v[28:29], off
	s_waitcnt vmcnt(0)
	v_lshlrev_b32_e32 v30, 16, v24
	global_store_dwordx4 v[44:45], v[16:19], off offset:256
	v_and_b32_e32 v24, 0xffff0000, v24
	v_lshlrev_b32_e32 v31, 16, v25
	v_lshlrev_b32_e32 v16, 16, v20
	v_and_b32_e32 v17, 0xffff0000, v20
	v_lshlrev_b32_e32 v18, 16, v21
	v_and_b32_e32 v19, 0xffff0000, v21
	v_lshlrev_b32_e32 v20, 16, v22
	v_and_b32_e32 v21, 0xffff0000, v22
	v_lshlrev_b32_e32 v22, 16, v23
	v_and_b32_e32 v23, 0xffff0000, v23
	v_and_b32_e32 v25, 0xffff0000, v25
	v_lshlrev_b32_e32 v32, 16, v26
	v_and_b32_e32 v26, 0xffff0000, v26
	v_lshlrev_b32_e32 v33, 16, v27
	v_and_b32_e32 v27, 0xffff0000, v27
	v_fmac_f32_e32 v30, v12, v16
	v_fmac_f32_e32 v24, v13, v17
	v_fmac_f32_e32 v31, v14, v18
	v_fmac_f32_e32 v25, v15, v19
	v_fmac_f32_e32 v32, v8, v20
	v_fmac_f32_e32 v26, v9, v21
	v_fmac_f32_e32 v33, v10, v22
	v_fmac_f32_e32 v27, v11, v23
	v_cvt_pk_bf16_f32 v8, v30, v24
	v_cvt_pk_bf16_f32 v9, v31, v25
	v_cvt_pk_bf16_f32 v10, v32, v26
	v_cvt_pk_bf16_f32 v11, v33, v27
	global_load_dwordx4 v[12:15], v[38:39], off offset:256
	global_load_dwordx4 v[16:19], v[28:29], off offset:256
	s_waitcnt vmcnt(0)
	v_lshlrev_b32_e32 v20, 16, v16
	global_store_dwordx4 v[28:29], v[8:11], off
	v_and_b32_e32 v16, 0xffff0000, v16
	v_lshlrev_b32_e32 v21, 16, v17
	v_lshlrev_b32_e32 v8, 16, v12
	v_and_b32_e32 v9, 0xffff0000, v12
	v_lshlrev_b32_e32 v10, 16, v13
	v_and_b32_e32 v11, 0xffff0000, v13
	v_lshlrev_b32_e32 v12, 16, v14
	v_and_b32_e32 v13, 0xffff0000, v14
	v_lshlrev_b32_e32 v14, 16, v15
	v_and_b32_e32 v15, 0xffff0000, v15
	v_and_b32_e32 v17, 0xffff0000, v17
	v_lshlrev_b32_e32 v22, 16, v18
	v_and_b32_e32 v18, 0xffff0000, v18
	v_lshlrev_b32_e32 v23, 16, v19
	v_and_b32_e32 v19, 0xffff0000, v19
	v_fmac_f32_e32 v20, v4, v8
	v_fmac_f32_e32 v16, v5, v9
	v_fmac_f32_e32 v21, v6, v10
	v_fmac_f32_e32 v17, v7, v11
	v_fmac_f32_e32 v22, v0, v12
	v_fmac_f32_e32 v18, v1, v13
	v_fmac_f32_e32 v23, v2, v14
	v_fmac_f32_e32 v19, v3, v15
	v_cvt_pk_bf16_f32 v0, v20, v16
	v_cvt_pk_bf16_f32 v1, v21, v17
	v_cvt_pk_bf16_f32 v2, v22, v18
	v_cvt_pk_bf16_f32 v3, v23, v19
	global_store_dwordx4 v[28:29], v[0:3], off offset:256
	s_cbranch_vccz .LBB0_1004
	s_waitcnt vmcnt(0)
	s_cmpk_gt_u32 s25, 0xff
	s_cbranch_scc1 .LBB0_1015
	s_barrier

; #define PG8_STAGE(bufoff, gbase, voff) do { _Pragma("unroll") for (int _i = 0; _i < 2; ++_i) \
;         __builtin_amdgcn_global_load_lds((const unsigned*)((const char*)(gbase) + (voff)[_i]), (PG8_LAS unsigned*)(lds + (bufoff) + ldsw + _i * 8192), 16, 0, 0); } while (0)
; #define PG8_LDA(dst, b, h) do { _Pragma("unroll") for (int m = 0; m < 4; ++m) _Pragma("unroll") for (int k = 0; k < 2; ++k) dst[m][k] = *(const PG8_LAS bf16x8*)(lds + PG8_SA(b, h) + aoff + m * 2048 + k * 1024); } while (0)
; #define PG8_LDB(dst, b, h) do { _Pragma("unroll") for (int n = 0; n < 2; ++n) _Pragma("unroll") for (int k = 0; k < 2; ++k) dst[n][k] = *(const PG8_LAS bf16x8*)(lds + PG8_SB(b, h) + boff + n * 2048 + k * 1024); } while (0)
; #define PG8_MMA(ai, bj, At, Bt) do { __builtin_amdgcn_s_setprio(1); _Pragma("unroll") for (int m = 0; m < 4; ++m) _Pragma("unroll") for (int n = 0; n < 2; ++n) _Pragma("unroll") for (int k = 0; k < 2; ++k) \
;         acc[ai][bj][m][n] = __builtin_amdgcn_mfma_f32_16x16x32_bf16(Bt[n][k], At[m][k], acc[ai][bj][m][n], 0, 0, 0); __builtin_amdgcn_s_setprio(0); } while (0)
; #define PG8_WAIT_V(n) asm volatile("s_waitcnt vmcnt(" #n ")" ::: "memory")
; #define PG8_WAIT_L(n) asm volatile("s_waitcnt lgkmcnt(" #n ")" ::: "memory")
; #define PG8_BAR __builtin_amdgcn_s_barrier()
; #define PG8_SCHED __builtin_amdgcn_sched_barrier(0)
; template <class Epi, class Sched>
; __device__ __forceinline__ void gemm_phase(PG8_LAS unsigned char* lds, const Gemm g, const Sched& S, const Epi& E) {
;     ...
;             PG8_LDB(B0, 0, 0); PG8_SCHED; PG8_LDA(At, 0, 0); PG8_STAGE(PG8_SA(1, 1), a1 + hstep, voffA);
;             PG8_WAIT_L(8); PG8_BAR; PG8_WAIT_L(0); PG8_MMA(0, 0, At, B0); PG8_BAR; PG8_SCHED;
;             PG8_LDB(B1, 0, 1); PG8_STAGE(PG8_SB(0, 0), b2, voffB);
;             PG8_BAR; PG8_WAIT_L(0); PG8_MMA(0, 1, At, B1); PG8_BAR;
;             PG8_LDA(At, 0, 1); PG8_STAGE(PG8_SA(0, 0), a2, voffA);
;             PG8_BAR; PG8_WAIT_L(0); PG8_MMA(1, 0, At, B0); PG8_BAR; PG8_SCHED;
;             PG8_STAGE(PG8_SB(0, 1), b2 + hstep, voffB);
;             PG8_WAIT_V(6); PG8_BAR; PG8_MMA(1, 1, At, B1); PG8_BAR;
.LBB0_1083:
	ds_read_b128 v[152:155], v149
	ds_read_b128 v[156:159], v149 offset:1024
	ds_read_b128 v[160:163], v149 offset:2048
	ds_read_b128 v[164:167], v149 offset:3072
	s_add_u32 s26, s24, 0xfffc0080
	s_addc_u32 s27, s25, -1
	s_cmp_eq_u32 s56, 12
	s_cselect_b32 s29, s17, s27
	s_cselect_b32 s28, s52, s26
	s_cselect_b32 s27, s15, s55
	s_cselect_b32 s26, s53, s54
	v_lshl_add_u64 v[144:145], s[24:25], 0, v[136:137]
	s_add_i32 m0, s23, 0xc000
	ds_read_b128 v[168:171], v150
	ds_read_b128 v[172:175], v150 offset:1024
	ds_read_b128 v[182:185], v150 offset:2048
	ds_read_b128 v[190:193], v150 offset:3072
	ds_read_b128 v[194:197], v150 offset:4096
	ds_read_b128 v[198:201], v150 offset:5120
	ds_read_b128 v[202:205], v150 offset:6144
	ds_read_b128 v[206:209], v150 offset:7168
	global_load_lds_dwordx4 v[144:145], off
	v_lshl_add_u64 v[144:145], s[24:25], 0, v[138:139]
	s_add_i32 m0, s23, 0xe000
	s_nop 0
	global_load_lds_dwordx4 v[144:145], off
	s_waitcnt lgkmcnt(8)
	s_barrier
	s_waitcnt lgkmcnt(0)
	v_mfma_f32_16x16x32_bf16 v[124:127], v[152:155], v[168:171], v[124:127]
	v_mfma_f32_16x16x32_bf16 v[120:123], v[160:163], v[168:171], v[120:123]
	v_mfma_f32_16x16x32_bf16 v[108:111], v[152:155], v[182:185], v[108:111]
	v_mfma_f32_16x16x32_bf16 v[104:107], v[160:163], v[182:185], v[104:107]
	v_mfma_f32_16x16x32_bf16 v[92:95], v[152:155], v[194:197], v[92:95]
	v_mfma_f32_16x16x32_bf16 v[88:91], v[160:163], v[194:197], v[88:91]
	v_mfma_f32_16x16x32_bf16 v[76:79], v[152:155], v[202:205], v[76:79]
	v_mfma_f32_16x16x32_bf16 v[72:75], v[160:163], v[202:205], v[72:75]
	v_mfma_f32_16x16x32_bf16 v[124:127], v[156:159], v[172:175], v[124:127]
	v_mfma_f32_16x16x32_bf16 v[120:123], v[164:167], v[172:175], v[120:123]
	v_mfma_f32_16x16x32_bf16 v[108:111], v[156:159], v[190:193], v[108:111]
	v_mfma_f32_16x16x32_bf16 v[104:107], v[164:167], v[190:193], v[104:107]
	v_mfma_f32_16x16x32_bf16 v[92:95], v[156:159], v[198:201], v[92:95]
	v_mfma_f32_16x16x32_bf16 v[88:91], v[164:167], v[198:201], v[88:91]
	v_mfma_f32_16x16x32_bf16 v[76:79], v[156:159], v[206:209], v[76:79]
	v_mfma_f32_16x16x32_bf16 v[72:75], v[164:167], v[206:209], v[72:75]
	s_barrier
	s_add_i32 s57, s45, s37
	v_lshl_add_u64 v[144:145], s[26:27], 0, v[130:131]
	s_mov_b32 m0, s57
	ds_read_b128 v[210:213], v151
	ds_read_b128 v[214:217], v151 offset:1024
	ds_read_b128 v[218:221], v151 offset:2048
	ds_read_b128 v[222:225], v151 offset:3072
	global_load_lds_dwordx4 v[144:145], off
	v_lshl_add_u64 v[186:187], s[26:27], 0, v[134:135]
	s_add_i32 m0, s57, 0x2000
	s_nop 0
	global_load_lds_dwordx4 v[186:187], off
	s_barrier
	s_waitcnt lgkmcnt(0)
	v_mfma_f32_16x16x32_bf16 v[116:119], v[210:213], v[168:171], v[116:119]
	v_mfma_f32_16x16x32_bf16 v[112:115], v[218:221], v[168:171], v[112:115]
	v_mfma_f32_16x16x32_bf16 v[100:103], v[210:213], v[182:185], v[100:103]
	v_mfma_f32_16x16x32_bf16 v[96:99], v[218:221], v[182:185], v[96:99]
	v_mfma_f32_16x16x32_bf16 v[84:87], v[210:213], v[194:197], v[84:87]
	v_mfma_f32_16x16x32_bf16 v[80:83], v[218:221], v[194:197], v[80:83]
	v_mfma_f32_16x16x32_bf16 v[68:71], v[210:213], v[202:205], v[68:71]
	v_mfma_f32_16x16x32_bf16 v[64:67], v[218:221], v[202:205], v[64:67]
	v_mfma_f32_16x16x32_bf16 v[116:119], v[214:217], v[172:175], v[116:119]
	v_mfma_f32_16x16x32_bf16 v[112:115], v[222:225], v[172:175], v[112:115]
	v_mfma_f32_16x16x32_bf16 v[100:103], v[214:217], v[190:193], v[100:103]
	v_mfma_f32_16x16x32_bf16 v[96:99], v[222:225], v[190:193], v[96:99]
	v_mfma_f32_16x16x32_bf16 v[84:87], v[214:217], v[198:201], v[84:87]
	v_mfma_f32_16x16x32_bf16 v[80:83], v[222:225], v[198:201], v[80:83]
	v_mfma_f32_16x16x32_bf16 v[68:71], v[214:217], v[206:209], v[68:71]
	v_mfma_f32_16x16x32_bf16 v[64:67], v[222:225], v[206:209], v[64:67]
	s_barrier
	s_mov_b32 m0, s23
	v_lshl_add_u64 v[226:227], s[28:29], 0, v[128:129]
	ds_read_b128 v[168:171], v150 offset:16384
	ds_read_b128 v[172:175], v150 offset:17408
	ds_read_b128 v[182:185], v150 offset:18432
	ds_read_b128 v[190:193], v150 offset:19456
	ds_read_b128 v[194:197], v150 offset:20480
	ds_read_b128 v[198:201], v150 offset:21504
	ds_read_b128 v[202:205], v150 offset:22528
	ds_read_b128 v[206:209], v150 offset:23552
	global_load_lds_dwordx4 v[226:227], off
	v_lshl_add_u64 v[228:229], s[28:29], 0, v[132:133]
	s_mov_b32 m0, s38
	s_nop 0
	global_load_lds_dwordx4 v[228:229], off
	s_barrier
	s_waitcnt lgkmcnt(0)
	v_mfma_f32_16x16x32_bf16 v[60:63], v[152:155], v[168:171], v[60:63]
	v_mfma_f32_16x16x32_bf16 v[56:59], v[160:163], v[168:171], v[56:59]
	v_mfma_f32_16x16x32_bf16 v[48:51], v[152:155], v[182:185], v[48:51]
	v_mfma_f32_16x16x32_bf16 v[40:43], v[160:163], v[182:185], v[40:43]
	v_mfma_f32_16x16x32_bf16 v[32:35], v[152:155], v[194:197], v[32:35]
	v_mfma_f32_16x16x32_bf16 v[24:27], v[160:163], v[194:197], v[24:27]
	v_mfma_f32_16x16x32_bf16 v[16:19], v[152:155], v[202:205], v[16:19]
	v_mfma_f32_16x16x32_bf16 v[8:11], v[160:163], v[202:205], v[8:11]
	v_mfma_f32_16x16x32_bf16 v[60:63], v[156:159], v[172:175], v[60:63]
	v_mfma_f32_16x16x32_bf16 v[56:59], v[164:167], v[172:175], v[56:59]
	v_mfma_f32_16x16x32_bf16 v[48:51], v[156:159], v[190:193], v[48:51]
	v_mfma_f32_16x16x32_bf16 v[40:43], v[164:167], v[190:193], v[40:43]
	v_mfma_f32_16x16x32_bf16 v[32:35], v[156:159], v[198:201], v[32:35]
	v_mfma_f32_16x16x32_bf16 v[24:27], v[164:167], v[198:201], v[24:27]
	v_mfma_f32_16x16x32_bf16 v[16:19], v[156:159], v[206:209], v[16:19]
	v_mfma_f32_16x16x32_bf16 v[8:11], v[164:167], v[206:209], v[8:11]
	s_barrier
; #define PG8_STAGE(bufoff, gbase, voff) do { _Pragma("unroll") for (int _i = 0; _i < 2; ++_i) \
;         __builtin_amdgcn_global_load_lds((const unsigned*)((const char*)(gbase) + (voff)[_i]), (PG8_LAS unsigned*)(lds + (bufoff) + ldsw + _i * 8192), 16, 0, 0); } while (0)
; #define PG8_LDA(dst, b, h) do { _Pragma("unroll") for (int m = 0; m < 4; ++m) _Pragma("unroll") for (int k = 0; k < 2; ++k) dst[m][k] = *(const PG8_LAS bf16x8*)(lds + PG8_SA(b, h) + aoff + m * 2048 + k * 1024); } while (0)
; #define PG8_LDB(dst, b, h) do { _Pragma("unroll") for (int n = 0; n < 2; ++n) _Pragma("unroll") for (int k = 0; k < 2; ++k) dst[n][k] = *(const PG8_LAS bf16x8*)(lds + PG8_SB(b, h) + boff + n * 2048 + k * 1024); } while (0)
; #define PG8_MMA(ai, bj, At, Bt) do { __builtin_amdgcn_s_setprio(1); _Pragma("unroll") for (int m = 0; m < 4; ++m) _Pragma("unroll") for (int n = 0; n < 2; ++n) _Pragma("unroll") for (int k = 0; k < 2; ++k) \
;         acc[ai][bj][m][n] = __builtin_amdgcn_mfma_f32_16x16x32_bf16(Bt[n][k], At[m][k], acc[ai][bj][m][n], 0, 0, 0); __builtin_amdgcn_s_setprio(0); } while (0)
; #define PG8_WAIT_V(n) asm volatile("s_waitcnt vmcnt(" #n ")" ::: "memory")
; #define PG8_WAIT_L(n) asm volatile("s_waitcnt lgkmcnt(" #n ")" ::: "memory")
; #define PG8_BAR __builtin_amdgcn_s_barrier()
; #define PG8_SCHED __builtin_amdgcn_sched_barrier(0)
; template <class Epi, class Sched>
; __device__ __forceinline__ void gemm_phase(PG8_LAS unsigned char* lds, const Gemm g, const Sched& S, const Epi& E) {
;     ...
;             PG8_WAIT_V(6); PG8_BAR; PG8_MMA(1, 1, At, B1); PG8_BAR;
;             PG8_LDB(B0, 1, 0); PG8_SCHED; PG8_LDA(At, 1, 0); PG8_STAGE(PG8_SA(0, 1), a2 + hstep, voffA);
;             PG8_WAIT_L(8); PG8_BAR; PG8_WAIT_L(0); PG8_MMA(0, 0, At, B0); PG8_BAR; PG8_SCHED;
;             PG8_LDB(B1, 1, 1); PG8_STAGE(PG8_SB(1, 0), b3, voffB);
;             PG8_BAR; PG8_WAIT_L(0); PG8_MMA(0, 1, At, B1); PG8_BAR;
;             PG8_LDA(At, 1, 1); PG8_STAGE(PG8_SA(1, 0), a3, voffA);
;             PG8_BAR; PG8_WAIT_L(0); PG8_MMA(1, 0, At, B0); PG8_BAR; PG8_SCHED;
;             PG8_STAGE(PG8_SB(1, 1), b3 + hstep, voffB);
	s_add_u32 s58, s26, 0x40000
	s_addc_u32 s59, s27, 0
	s_add_i32 s57, s46, s37
	v_lshl_add_u64 v[152:153], s[58:59], 0, v[130:131]
	s_mov_b32 m0, s57
	s_nop 0
	global_load_lds_dwordx4 v[152:153], off
	v_lshl_add_u64 v[152:153], s[58:59], 0, v[134:135]
	s_add_i32 m0, s57, 0x2000
	s_nop 0
	global_load_lds_dwordx4 v[152:153], off
	s_waitcnt vmcnt(6)
	s_barrier
	v_mfma_f32_16x16x32_bf16 v[52:55], v[210:213], v[168:171], v[52:55]
	v_mfma_f32_16x16x32_bf16 v[44:47], v[218:221], v[168:171], v[44:47]
	v_mfma_f32_16x16x32_bf16 v[36:39], v[210:213], v[182:185], v[36:39]
	v_mfma_f32_16x16x32_bf16 v[28:31], v[218:221], v[182:185], v[28:31]
	v_mfma_f32_16x16x32_bf16 v[20:23], v[210:213], v[194:197], v[20:23]
	v_mfma_f32_16x16x32_bf16 v[12:15], v[218:221], v[194:197], v[12:15]
	v_mfma_f32_16x16x32_bf16 v[4:7], v[210:213], v[202:205], v[4:7]
	v_mfma_f32_16x16x32_bf16 v[0:3], v[218:221], v[202:205], v[0:3]
	v_mfma_f32_16x16x32_bf16 v[52:55], v[214:217], v[172:175], v[52:55]
	v_mfma_f32_16x16x32_bf16 v[44:47], v[222:225], v[172:175], v[44:47]
	v_mfma_f32_16x16x32_bf16 v[36:39], v[214:217], v[190:193], v[36:39]
	v_mfma_f32_16x16x32_bf16 v[28:31], v[222:225], v[190:193], v[28:31]
	v_mfma_f32_16x16x32_bf16 v[20:23], v[214:217], v[198:201], v[20:23]
	v_mfma_f32_16x16x32_bf16 v[12:15], v[222:225], v[198:201], v[12:15]
	v_mfma_f32_16x16x32_bf16 v[4:7], v[214:217], v[206:209], v[4:7]
	v_mfma_f32_16x16x32_bf16 v[0:3], v[222:225], v[206:209], v[0:3]
	s_barrier
	s_add_i32 s57, 0, 0x18000
	v_add_u32_e32 v164, s57, v147
	ds_read_b128 v[152:155], v164
	ds_read_b128 v[156:159], v164 offset:1024
	ds_read_b128 v[160:163], v164 offset:2048
	ds_read_b128 v[164:167], v164 offset:3072
	s_add_u32 s28, s28, 0x40000
	s_addc_u32 s29, s29, 0
	s_mov_b32 m0, s39
	v_lshl_add_u64 v[210:211], s[28:29], 0, v[128:129]
	ds_read_b128 v[168:171], v150 offset:32768
	ds_read_b128 v[172:175], v150 offset:33792
	ds_read_b128 v[182:185], v150 offset:34816
	ds_read_b128 v[190:193], v150 offset:35840
	ds_read_b128 v[194:197], v150 offset:36864
	ds_read_b128 v[198:201], v150 offset:37888
	ds_read_b128 v[202:205], v150 offset:38912
	ds_read_b128 v[206:209], v150 offset:39936
	global_load_lds_dwordx4 v[210:211], off
	v_lshl_add_u64 v[210:211], s[28:29], 0, v[132:133]
	s_mov_b32 m0, s40
	s_nop 0
	global_load_lds_dwordx4 v[210:211], off
	s_waitcnt lgkmcnt(8)
	s_barrier
	s_waitcnt lgkmcnt(0)
	v_mfma_f32_16x16x32_bf16 v[124:127], v[152:155], v[168:171], v[124:127]
	v_mfma_f32_16x16x32_bf16 v[120:123], v[160:163], v[168:171], v[120:123]
	v_mfma_f32_16x16x32_bf16 v[108:111], v[152:155], v[182:185], v[108:111]
	v_mfma_f32_16x16x32_bf16 v[104:107], v[160:163], v[182:185], v[104:107]
	v_mfma_f32_16x16x32_bf16 v[92:95], v[152:155], v[194:197], v[92:95]
	v_mfma_f32_16x16x32_bf16 v[88:91], v[160:163], v[194:197], v[88:91]
	v_mfma_f32_16x16x32_bf16 v[76:79], v[152:155], v[202:205], v[76:79]
	v_mfma_f32_16x16x32_bf16 v[72:75], v[160:163], v[202:205], v[72:75]
	v_mfma_f32_16x16x32_bf16 v[124:127], v[156:159], v[172:175], v[124:127]
	v_mfma_f32_16x16x32_bf16 v[120:123], v[164:167], v[172:175], v[120:123]
	v_mfma_f32_16x16x32_bf16 v[108:111], v[156:159], v[190:193], v[108:111]
	v_mfma_f32_16x16x32_bf16 v[104:107], v[164:167], v[190:193], v[104:107]
	v_mfma_f32_16x16x32_bf16 v[92:95], v[156:159], v[198:201], v[92:95]
	v_mfma_f32_16x16x32_bf16 v[88:91], v[164:167], v[198:201], v[88:91]
	v_mfma_f32_16x16x32_bf16 v[76:79], v[156:159], v[206:209], v[76:79]
	v_mfma_f32_16x16x32_bf16 v[72:75], v[164:167], v[206:209], v[72:75]
	s_barrier
	s_add_i32 s28, 0, 0x1c000
	s_add_i32 s29, s57, s37
	v_add_u32_e32 v179, s28, v147
	v_lshl_add_u64 v[144:145], v[144:145], 0, s[6:7]
	s_mov_b32 m0, s29
	ds_read_b128 v[210:213], v179
	ds_read_b128 v[214:217], v179 offset:1024
	ds_read_b128 v[218:221], v179 offset:2048
	ds_read_b128 v[222:225], v179 offset:3072
	global_load_lds_dwordx4 v[144:145], off
	v_lshl_add_u64 v[144:145], v[186:187], 0, s[6:7]
	s_add_i32 m0, s29, 0x2000
	s_nop 0
	global_load_lds_dwordx4 v[144:145], off
	s_barrier
	s_waitcnt lgkmcnt(0)
	v_mfma_f32_16x16x32_bf16 v[116:119], v[210:213], v[168:171], v[116:119]
	v_mfma_f32_16x16x32_bf16 v[112:115], v[218:221], v[168:171], v[112:115]
	v_mfma_f32_16x16x32_bf16 v[100:103], v[210:213], v[182:185], v[100:103]
	v_mfma_f32_16x16x32_bf16 v[96:99], v[218:221], v[182:185], v[96:99]
	v_mfma_f32_16x16x32_bf16 v[84:87], v[210:213], v[194:197], v[84:87]
	v_mfma_f32_16x16x32_bf16 v[80:83], v[218:221], v[194:197], v[80:83]
	v_mfma_f32_16x16x32_bf16 v[68:71], v[210:213], v[202:205], v[68:71]
	v_mfma_f32_16x16x32_bf16 v[64:67], v[218:221], v[202:205], v[64:67]
	v_mfma_f32_16x16x32_bf16 v[116:119], v[214:217], v[172:175], v[116:119]
	v_mfma_f32_16x16x32_bf16 v[112:115], v[222:225], v[172:175], v[112:115]
	v_mfma_f32_16x16x32_bf16 v[100:103], v[214:217], v[190:193], v[100:103]
	v_mfma_f32_16x16x32_bf16 v[96:99], v[222:225], v[190:193], v[96:99]
	v_mfma_f32_16x16x32_bf16 v[84:87], v[214:217], v[198:201], v[84:87]
	v_mfma_f32_16x16x32_bf16 v[80:83], v[222:225], v[198:201], v[80:83]
	v_mfma_f32_16x16x32_bf16 v[68:71], v[214:217], v[206:209], v[68:71]
	v_mfma_f32_16x16x32_bf16 v[64:67], v[222:225], v[206:209], v[64:67]
	s_barrier
	s_mov_b32 m0, s42
	v_lshl_add_u64 v[144:145], v[226:227], 0, s[6:7]
	ds_read_b128 v[168:171], v150 offset:49152
	ds_read_b128 v[172:175], v150 offset:50176
	ds_read_b128 v[182:185], v150 offset:51200
	ds_read_b128 v[190:193], v150 offset:52224
	ds_read_b128 v[194:197], v150 offset:53248
	ds_read_b128 v[198:201], v150 offset:54272
	ds_read_b128 v[202:205], v150 offset:55296
	ds_read_b128 v[206:209], v150 offset:56320
	global_load_lds_dwordx4 v[144:145], off
	v_lshl_add_u64 v[144:145], v[228:229], 0, s[6:7]
	s_mov_b32 m0, s43
	s_nop 0
	global_load_lds_dwordx4 v[144:145], off
	s_barrier
; __device__ __forceinline__ unsigned cvt_pk_bf16(float lo, float hi) { unsigned r; asm volatile("v_cvt_pk_bf16_f32 %0, %1, %2" : "=v"(r) : "v"(lo), "v"(hi)); return r; }
; __device__ __forceinline__ float flogsig16(float x) { return (fminf(x, 0.f) - __logf(1.0f + __expf(-fabsf(x)))) * 0.0625f; }
; #define PG8_WAIT_V(n) asm volatile("s_waitcnt vmcnt(" #n ")" ::: "memory")
;     __device__ __forceinline__ void operator()(const f32x4 (&acc)[2][2][4][2], const Unit& u, int wr, int wc, int fr, int fq) const {
;     ...
;         const int row0 = u.pm * BM + wr * 64 + fr, col0 = u.pn * BM + wc * 32 + 8 * fq, bcol0 = wc * 32 + 8 * fq;
;         f32x4 bv[2][2];
; #pragma unroll
;         for (int bj = 0; bj < 2; ++bj)
; #pragma unroll
;             for (int n = 0; n < 2; ++n) bv[bj][n] = bias ? *(const f32x4*)(bias + bcol0 + bj * HALF + 4 * n) : (f32x4){0.f, 0.f, 0.f, 0.f};
; #pragma unroll
;         for (int ai = 0; ai < 2; ++ai)
; #pragma unroll
;             for (int m = 0; m < 4; ++m) { bf16_t* rowp = O + (size_t)(row0 + ai * HALF + m * 16) * ldc + col0;
; #pragma unroll
;                 for (int bj = 0; bj < 2; ++bj) { f32x4 v0 = acc[ai][bj][m][0] + bv[bj][0], v1 = acc[ai][bj][m][1] + bv[bj][1];
;                     if (act == 1) {
; #pragma unroll
;                         for (int j = 0; j < 1; ++j) { v0 = v0 * sigmoid4(v0); v1 = v1 * sigmoid4(v1); } }
;                     else if (act == 2) {
; #pragma unroll
;                         for (int j = 0; j < 1; ++j) { v0 = sigmoid4(v0); v1 = sigmoid4(v1); } }
;                     else if (act == 3) {
; #pragma unroll
;                         for (int j = 0; j < 4; ++j) { v0[j] = flogsig16(v0[j]); v1[j] = flogsig16(v1[j]); } }
;                     u32x4 w; w.x = cvt_pk_bf16(v0[0], v0[1]); w.y = cvt_pk_bf16(v0[2], v0[3]); w.z = cvt_pk_bf16(v1[0], v1[1]); w.w = cvt_pk_bf16(v1[2], v1[3]);
;                     *(u32x4*)(rowp + bj * HALF) = w; } }
; template <class Epi, class Sched>
; __device__ __forceinline__ void gemm_phase(PG8_LAS unsigned char* lds, const Gemm g, const Sched& S, const Epi& E) {
;     ...
;             PG8_BAR; PG8_WAIT_L(0); PG8_MMA(1, 0, At, B0); PG8_BAR; PG8_SCHED;
;             PG8_STAGE(PG8_SB(1, 1), b3 + hstep, voffB);
;             PG8_WAIT_V(6); PG8_BAR; PG8_MMA(1, 1, At, B1); PG8_BAR;
;         }
;         if constexpr (!Epi::AFTER_DRAIN) { E(acc, cur, wr, wc, fr, fq); S.done(cur); }
	s_waitcnt lgkmcnt(0)
	v_mfma_f32_16x16x32_bf16 v[60:63], v[152:155], v[168:171], v[60:63]
	v_mfma_f32_16x16x32_bf16 v[56:59], v[160:163], v[168:171], v[56:59]
	v_mfma_f32_16x16x32_bf16 v[48:51], v[152:155], v[182:185], v[48:51]
	v_mfma_f32_16x16x32_bf16 v[40:43], v[160:163], v[182:185], v[40:43]
	v_mfma_f32_16x16x32_bf16 v[32:35], v[152:155], v[194:197], v[32:35]
	v_mfma_f32_16x16x32_bf16 v[24:27], v[160:163], v[194:197], v[24:27]
	v_mfma_f32_16x16x32_bf16 v[16:19], v[152:155], v[202:205], v[16:19]
	v_mfma_f32_16x16x32_bf16 v[8:11], v[160:163], v[202:205], v[8:11]
	v_mfma_f32_16x16x32_bf16 v[60:63], v[156:159], v[172:175], v[60:63]
	v_mfma_f32_16x16x32_bf16 v[56:59], v[164:167], v[172:175], v[56:59]
	v_mfma_f32_16x16x32_bf16 v[48:51], v[156:159], v[190:193], v[48:51]
	v_mfma_f32_16x16x32_bf16 v[40:43], v[164:167], v[190:193], v[40:43]
	v_mfma_f32_16x16x32_bf16 v[32:35], v[156:159], v[198:201], v[32:35]
	v_mfma_f32_16x16x32_bf16 v[24:27], v[164:167], v[198:201], v[24:27]
	v_mfma_f32_16x16x32_bf16 v[16:19], v[156:159], v[206:209], v[16:19]
	v_mfma_f32_16x16x32_bf16 v[8:11], v[164:167], v[206:209], v[8:11]
	s_barrier
	s_add_u32 s26, s26, 0x40080
	s_addc_u32 s27, s27, 0
	s_add_i32 s28, s28, s37
	v_lshl_add_u64 v[144:145], s[26:27], 0, v[130:131]
	s_mov_b32 m0, s28
	s_nop 0
	global_load_lds_dwordx4 v[144:145], off
	v_lshl_add_u64 v[144:145], s[26:27], 0, v[134:135]
	s_add_i32 m0, s28, 0x2000
	s_nop 0
	global_load_lds_dwordx4 v[144:145], off
	s_waitcnt vmcnt(6)
	s_barrier
	v_mfma_f32_16x16x32_bf16 v[52:55], v[210:213], v[168:171], v[52:55]
	v_mfma_f32_16x16x32_bf16 v[44:47], v[218:221], v[168:171], v[44:47]
	v_mfma_f32_16x16x32_bf16 v[36:39], v[210:213], v[182:185], v[36:39]
	v_mfma_f32_16x16x32_bf16 v[28:31], v[218:221], v[182:185], v[28:31]
	v_mfma_f32_16x16x32_bf16 v[20:23], v[210:213], v[194:197], v[20:23]
	v_mfma_f32_16x16x32_bf16 v[12:15], v[218:221], v[194:197], v[12:15]
	v_mfma_f32_16x16x32_bf16 v[4:7], v[210:213], v[202:205], v[4:7]
	v_mfma_f32_16x16x32_bf16 v[0:3], v[218:221], v[202:205], v[0:3]
	v_mfma_f32_16x16x32_bf16 v[52:55], v[214:217], v[172:175], v[52:55]
	v_mfma_f32_16x16x32_bf16 v[44:47], v[222:225], v[172:175], v[44:47]
	v_mfma_f32_16x16x32_bf16 v[36:39], v[214:217], v[190:193], v[36:39]
	v_mfma_f32_16x16x32_bf16 v[28:31], v[222:225], v[190:193], v[28:31]
	v_mfma_f32_16x16x32_bf16 v[20:23], v[214:217], v[198:201], v[20:23]
	v_mfma_f32_16x16x32_bf16 v[12:15], v[222:225], v[198:201], v[12:15]
	v_mfma_f32_16x16x32_bf16 v[4:7], v[214:217], v[206:209], v[4:7]
	v_mfma_f32_16x16x32_bf16 v[0:3], v[222:225], v[206:209], v[0:3]
	s_barrier
	s_add_i32 s56, s56, 2
	s_add_u32 s24, s24, 0x100
	s_addc_u32 s25, s25, 0
	s_add_u32 s54, s54, 0x100
	s_addc_u32 s55, s55, 0
	s_cmp_gt_u32 s56, 13
	s_cbranch_scc0 .LBB0_1083
	v_lshl_add_u32 v152, s22, 8, v146
	v_lshl_or_b32 v144, s51, 8, v148
	v_ashrrev_i32_e32 v153, 31, v152
	v_ashrrev_i32_e32 v145, 31, v144
	v_lshlrev_b64 v[154:155], 11, v[152:153]
	v_lshl_add_u64 v[154:155], s[4:5], 0, v[154:155]
	v_lshlrev_b64 v[156:157], 1, v[144:145]
	v_lshl_add_u64 v[144:145], v[154:155], 0, v[156:157]
	v_pk_add_f32 v[126:127], v[126:127], 0 op_sel_hi:[1,0]
	v_pk_add_f32 v[124:125], v[124:125], 0 op_sel_hi:[1,0]
	v_pk_add_f32 v[154:155], v[122:123], 0 op_sel_hi:[1,0]
	v_pk_add_f32 v[122:123], v[120:121], 0 op_sel_hi:[1,0]
	v_cvt_pk_bf16_f32 v120, v124, v125
	v_cvt_pk_bf16_f32 v121, v126, v127
	v_pk_add_f32 v[116:117], v[116:117], 0 op_sel_hi:[1,0]
	v_cvt_pk_bf16_f32 v122, v122, v123
	v_cvt_pk_bf16_f32 v123, v154, v155
	global_store_dwordx4 v[144:145], v[120:123], off
	v_pk_add_f32 v[118:119], v[118:119], 0 op_sel_hi:[1,0]
	v_pk_add_f32 v[110:111], v[110:111], 0 op_sel_hi:[1,0]
	v_pk_add_f32 v[120:121], v[114:115], 0 op_sel_hi:[1,0]
	v_pk_add_f32 v[114:115], v[112:113], 0 op_sel_hi:[1,0]
	v_cvt_pk_bf16_f32 v112, v116, v117
	v_cvt_pk_bf16_f32 v113, v118, v119
	v_pk_add_f32 v[108:109], v[108:109], 0 op_sel_hi:[1,0]
	v_cvt_pk_bf16_f32 v114, v114, v115
	v_cvt_pk_bf16_f32 v115, v120, v121
	global_store_dwordx4 v[144:145], v[112:115], off offset:256
	v_pk_add_f32 v[100:101], v[100:101], 0 op_sel_hi:[1,0]
	v_pk_add_f32 v[102:103], v[102:103], 0 op_sel_hi:[1,0]
	v_or_b32_e32 v112, 16, v152
	v_ashrrev_i32_e32 v113, 31, v112
	v_lshlrev_b64 v[112:113], 11, v[112:113]
	v_lshl_add_u64 v[112:113], s[4:5], 0, v[112:113]
	v_lshl_add_u64 v[112:113], v[112:113], 0, v[156:157]
	v_pk_add_f32 v[114:115], v[106:107], 0 op_sel_hi:[1,0]
	v_pk_add_f32 v[106:107], v[104:105], 0 op_sel_hi:[1,0]
	v_cvt_pk_bf16_f32 v104, v108, v109
	v_cvt_pk_bf16_f32 v105, v110, v111
	v_pk_add_f32 v[94:95], v[94:95], 0 op_sel_hi:[1,0]
	v_cvt_pk_bf16_f32 v106, v106, v107
	v_cvt_pk_bf16_f32 v107, v114, v115
	global_store_dwordx4 v[112:113], v[104:107], off
	v_pk_add_f32 v[92:93], v[92:93], 0 op_sel_hi:[1,0]
	v_pk_add_f32 v[84:85], v[84:85], 0 op_sel_hi:[1,0]
	v_pk_add_f32 v[104:105], v[98:99], 0 op_sel_hi:[1,0]
	v_pk_add_f32 v[98:99], v[96:97], 0 op_sel_hi:[1,0]
	v_cvt_pk_bf16_f32 v96, v100, v101
	v_cvt_pk_bf16_f32 v97, v102, v103
	v_pk_add_f32 v[86:87], v[86:87], 0 op_sel_hi:[1,0]
	v_cvt_pk_bf16_f32 v98, v98, v99
	v_cvt_pk_bf16_f32 v99, v104, v105
	global_store_dwordx4 v[112:113], v[96:99], off offset:256
	v_pk_add_f32 v[78:79], v[78:79], 0 op_sel_hi:[1,0]
	v_pk_add_f32 v[76:77], v[76:77], 0 op_sel_hi:[1,0]
	v_or_b32_e32 v96, 32, v152
	v_ashrrev_i32_e32 v97, 31, v96
	v_lshlrev_b64 v[96:97], 11, v[96:97]
	v_lshl_add_u64 v[96:97], s[4:5], 0, v[96:97]
; __device__ __forceinline__ unsigned cvt_pk_bf16(float lo, float hi) { unsigned r; asm volatile("v_cvt_pk_bf16_f32 %0, %1, %2" : "=v"(r) : "v"(lo), "v"(hi)); return r; }
; __device__ __forceinline__ float flogsig16(float x) { return (fminf(x, 0.f) - __logf(1.0f + __expf(-fabsf(x)))) * 0.0625f; }
; #define PG8_WAIT_V(n) asm volatile("s_waitcnt vmcnt(" #n ")" ::: "memory")
; #define PG8_BAR __builtin_amdgcn_s_barrier()
;     __device__ __forceinline__ void operator()(const f32x4 (&acc)[2][2][4][2], const Unit& u, int wr, int wc, int fr, int fq) const {
;     ...
;         const int row0 = u.pm * BM + wr * 64 + fr, col0 = u.pn * BM + wc * 32 + 8 * fq, bcol0 = wc * 32 + 8 * fq;
;         f32x4 bv[2][2];
; #pragma unroll
;         for (int bj = 0; bj < 2; ++bj)
; #pragma unroll
;             for (int n = 0; n < 2; ++n) bv[bj][n] = bias ? *(const f32x4*)(bias + bcol0 + bj * HALF + 4 * n) : (f32x4){0.f, 0.f, 0.f, 0.f};
; #pragma unroll
;         for (int ai = 0; ai < 2; ++ai)
; #pragma unroll
;             for (int m = 0; m < 4; ++m) { bf16_t* rowp = O + (size_t)(row0 + ai * HALF + m * 16) * ldc + col0;
; #pragma unroll
;                 for (int bj = 0; bj < 2; ++bj) { f32x4 v0 = acc[ai][bj][m][0] + bv[bj][0], v1 = acc[ai][bj][m][1] + bv[bj][1];
;                     if (act == 1) {
; #pragma unroll
;                         for (int j = 0; j < 1; ++j) { v0 = v0 * sigmoid4(v0); v1 = v1 * sigmoid4(v1); } }
;                     else if (act == 2) {
; #pragma unroll
;                         for (int j = 0; j < 1; ++j) { v0 = sigmoid4(v0); v1 = sigmoid4(v1); } }
;                     else if (act == 3) {
; #pragma unroll
;                         for (int j = 0; j < 4; ++j) { v0[j] = flogsig16(v0[j]); v1[j] = flogsig16(v1[j]); } }
;                     u32x4 w; w.x = cvt_pk_bf16(v0[0], v0[1]); w.y = cvt_pk_bf16(v0[2], v0[3]); w.z = cvt_pk_bf16(v1[0], v1[1]); w.w = cvt_pk_bf16(v1[2], v1[3]);
;                     *(u32x4*)(rowp + bj * HALF) = w; } }
; template <class Epi, class Sched>
; __device__ __forceinline__ void gemm_phase(PG8_LAS unsigned char* lds, const Gemm g, const Sched& S, const Epi& E) {
;     ...
;     PG8_WAIT_V(0);
;     if (wr == 0) PG8_BAR;
;     PG8_BAR;
	v_lshl_add_u64 v[96:97], v[96:97], 0, v[156:157]
	v_pk_add_f32 v[98:99], v[90:91], 0 op_sel_hi:[1,0]
	v_pk_add_f32 v[90:91], v[88:89], 0 op_sel_hi:[1,0]
	v_cvt_pk_bf16_f32 v88, v92, v93
	v_cvt_pk_bf16_f32 v89, v94, v95
	v_pk_add_f32 v[70:71], v[70:71], 0 op_sel_hi:[1,0]
	v_cvt_pk_bf16_f32 v90, v90, v91
	v_cvt_pk_bf16_f32 v91, v98, v99
	global_store_dwordx4 v[96:97], v[88:91], off
	v_pk_add_f32 v[68:69], v[68:69], 0 op_sel_hi:[1,0]
	v_pk_add_f32 v[60:61], v[60:61], 0 op_sel_hi:[1,0]
	v_pk_add_f32 v[88:89], v[82:83], 0 op_sel_hi:[1,0]
	v_pk_add_f32 v[82:83], v[80:81], 0 op_sel_hi:[1,0]
	v_cvt_pk_bf16_f32 v80, v84, v85
	v_cvt_pk_bf16_f32 v81, v86, v87
	v_pk_add_f32 v[62:63], v[62:63], 0 op_sel_hi:[1,0]
	v_cvt_pk_bf16_f32 v82, v82, v83
	v_cvt_pk_bf16_f32 v83, v88, v89
	global_store_dwordx4 v[96:97], v[80:83], off offset:256
	v_pk_add_f32 v[54:55], v[54:55], 0 op_sel_hi:[1,0]
	v_pk_add_f32 v[52:53], v[52:53], 0 op_sel_hi:[1,0]
	v_or_b32_e32 v80, 48, v152
	v_ashrrev_i32_e32 v81, 31, v80
	v_lshlrev_b64 v[80:81], 11, v[80:81]
	v_lshl_add_u64 v[80:81], s[4:5], 0, v[80:81]
	v_lshl_add_u64 v[80:81], v[80:81], 0, v[156:157]
	v_pk_add_f32 v[82:83], v[74:75], 0 op_sel_hi:[1,0]
	v_pk_add_f32 v[74:75], v[72:73], 0 op_sel_hi:[1,0]
	v_cvt_pk_bf16_f32 v72, v76, v77
	v_cvt_pk_bf16_f32 v73, v78, v79
	v_pk_add_f32 v[48:49], v[48:49], 0 op_sel_hi:[1,0]
	v_cvt_pk_bf16_f32 v74, v74, v75
	v_cvt_pk_bf16_f32 v75, v82, v83
	global_store_dwordx4 v[80:81], v[72:75], off
	v_pk_add_f32 v[38:39], v[38:39], 0 op_sel_hi:[1,0]
	v_pk_add_f32 v[36:37], v[36:37], 0 op_sel_hi:[1,0]
	v_pk_add_f32 v[72:73], v[66:67], 0 op_sel_hi:[1,0]
	v_pk_add_f32 v[66:67], v[64:65], 0 op_sel_hi:[1,0]
	v_cvt_pk_bf16_f32 v64, v68, v69
	v_cvt_pk_bf16_f32 v65, v70, v71
	v_pk_add_f32 v[32:33], v[32:33], 0 op_sel_hi:[1,0]
	v_cvt_pk_bf16_f32 v66, v66, v67
	v_cvt_pk_bf16_f32 v67, v72, v73
	global_store_dwordx4 v[80:81], v[64:67], off offset:256
	v_pk_add_f32 v[22:23], v[22:23], 0 op_sel_hi:[1,0]
	v_pk_add_f32 v[20:21], v[20:21], 0 op_sel_hi:[1,0]
	v_pk_add_f32 v[66:67], v[58:59], 0 op_sel_hi:[1,0]
	v_pk_add_f32 v[58:59], v[56:57], 0 op_sel_hi:[1,0]
	v_cvt_pk_bf16_f32 v56, v60, v61
	v_add_co_u32_e32 v60, vcc, s47, v144
	v_cvt_pk_bf16_f32 v57, v62, v63
	v_cvt_pk_bf16_f32 v58, v58, v59
	v_cvt_pk_bf16_f32 v59, v66, v67
	v_lshl_add_u64 v[64:65], v[144:145], 0, s[0:1]
	s_nop 0
	v_addc_co_u32_e32 v61, vcc, 0, v145, vcc
	global_store_dwordx4 v[60:61], v[56:59], off
	v_pk_add_f32 v[16:17], v[16:17], 0 op_sel_hi:[1,0]
	s_mov_b32 s51, s14
	v_pk_add_f32 v[56:57], v[46:47], 0 op_sel_hi:[1,0]
	v_pk_add_f32 v[46:47], v[44:45], 0 op_sel_hi:[1,0]
	v_cvt_pk_bf16_f32 v44, v52, v53
	v_cvt_pk_bf16_f32 v45, v54, v55
	s_mov_b32 s22, s16
	v_cvt_pk_bf16_f32 v46, v46, v47
	v_cvt_pk_bf16_f32 v47, v56, v57
	global_store_dwordx4 v[64:65], v[44:47], off offset:256
	s_mov_b64 s[26:27], s[20:21]
	s_mov_b64 s[24:25], s[18:19]
	v_pk_add_f32 v[46:47], v[50:51], 0 op_sel_hi:[1,0]
	v_pk_add_f32 v[50:51], v[42:43], 0 op_sel_hi:[1,0]
	v_pk_add_f32 v[42:43], v[40:41], 0 op_sel_hi:[1,0]
	v_cvt_pk_bf16_f32 v40, v48, v49
	v_cvt_pk_bf16_f32 v41, v46, v47
	v_add_co_u32_e32 v46, vcc, s48, v144
	v_cvt_pk_bf16_f32 v42, v42, v43
	v_cvt_pk_bf16_f32 v43, v50, v51
	v_lshl_add_u64 v[44:45], v[144:145], 0, s[8:9]
	s_nop 0
	v_addc_co_u32_e32 v47, vcc, 0, v145, vcc
	global_store_dwordx4 v[46:47], v[40:43], off
	v_pk_add_f32 v[6:7], v[6:7], 0 op_sel_hi:[1,0]
	v_pk_add_f32 v[4:5], v[4:5], 0 op_sel_hi:[1,0]
	v_pk_add_f32 v[40:41], v[30:31], 0 op_sel_hi:[1,0]
	v_pk_add_f32 v[30:31], v[28:29], 0 op_sel_hi:[1,0]
	v_cvt_pk_bf16_f32 v28, v36, v37
	v_cvt_pk_bf16_f32 v29, v38, v39
	s_nop 0
	v_cvt_pk_bf16_f32 v30, v30, v31
	v_cvt_pk_bf16_f32 v31, v40, v41
	global_store_dwordx4 v[44:45], v[28:31], off offset:256
	s_nop 1
	v_pk_add_f32 v[30:31], v[34:35], 0 op_sel_hi:[1,0]
	v_pk_add_f32 v[34:35], v[26:27], 0 op_sel_hi:[1,0]
	v_pk_add_f32 v[26:27], v[24:25], 0 op_sel_hi:[1,0]
	v_cvt_pk_bf16_f32 v24, v32, v33
	v_cvt_pk_bf16_f32 v25, v30, v31
	v_add_co_u32_e32 v30, vcc, s49, v144
	v_cvt_pk_bf16_f32 v26, v26, v27
	v_cvt_pk_bf16_f32 v27, v34, v35
	v_lshl_add_u64 v[28:29], v[144:145], 0, s[10:11]
	s_nop 0
	v_addc_co_u32_e32 v31, vcc, 0, v145, vcc
	global_store_dwordx4 v[30:31], v[24:27], off
	s_nop 1
	v_pk_add_f32 v[24:25], v[14:15], 0 op_sel_hi:[1,0]
	v_pk_add_f32 v[14:15], v[12:13], 0 op_sel_hi:[1,0]
	v_cvt_pk_bf16_f32 v12, v20, v21
	v_cvt_pk_bf16_f32 v13, v22, v23
	s_nop 0
	v_cvt_pk_bf16_f32 v14, v14, v15
	v_cvt_pk_bf16_f32 v15, v24, v25
	global_store_dwordx4 v[28:29], v[12:15], off offset:256
	s_nop 1
	v_pk_add_f32 v[14:15], v[18:19], 0 op_sel_hi:[1,0]
	v_pk_add_f32 v[18:19], v[10:11], 0 op_sel_hi:[1,0]
	v_pk_add_f32 v[10:11], v[8:9], 0 op_sel_hi:[1,0]
	v_cvt_pk_bf16_f32 v8, v16, v17
	v_cvt_pk_bf16_f32 v9, v14, v15
	v_add_co_u32_e32 v14, vcc, s50, v144
	v_lshl_add_u64 v[12:13], v[144:145], 0, s[12:13]
	s_nop 0
	v_addc_co_u32_e32 v15, vcc, 0, v145, vcc
	v_cvt_pk_bf16_f32 v10, v10, v11
	v_cvt_pk_bf16_f32 v11, v18, v19
	global_store_dwordx4 v[14:15], v[8:11], off
	s_and_b64 vcc, exec, s[2:3]
	s_nop 0
	v_pk_add_f32 v[8:9], v[2:3], 0 op_sel_hi:[1,0]
	v_pk_add_f32 v[2:3], v[0:1], 0 op_sel_hi:[1,0]
	v_cvt_pk_bf16_f32 v0, v4, v5
	v_cvt_pk_bf16_f32 v1, v6, v7
	s_nop 0
	v_cvt_pk_bf16_f32 v2, v2, v3
	v_cvt_pk_bf16_f32 v3, v8, v9
	global_store_dwordx4 v[12:13], v[0:3], off offset:256
	s_cbranch_vccz .LBB0_1076
	s_waitcnt vmcnt(0)
	s_cmpk_gt_u32 s31, 0xff
	s_cbranch_scc1 .LBB0_1087
	s_barrier

; #define PG8_STAGE(bufoff, gbase, voff) do { _Pragma("unroll") for (int _i = 0; _i < 2; ++_i) \
;         __builtin_amdgcn_global_load_lds((const unsigned*)((const char*)(gbase) + (voff)[_i]), (PG8_LAS unsigned*)(lds + (bufoff) + ldsw + _i * 8192), 16, 0, 0); } while (0)
; #define PG8_LDA(dst, b, h) do { _Pragma("unroll") for (int m = 0; m < 4; ++m) _Pragma("unroll") for (int k = 0; k < 2; ++k) dst[m][k] = *(const PG8_LAS bf16x8*)(lds + PG8_SA(b, h) + aoff + m * 2048 + k * 1024); } while (0)
; #define PG8_LDB(dst, b, h) do { _Pragma("unroll") for (int n = 0; n < 2; ++n) _Pragma("unroll") for (int k = 0; k < 2; ++k) dst[n][k] = *(const PG8_LAS bf16x8*)(lds + PG8_SB(b, h) + boff + n * 2048 + k * 1024); } while (0)
; #define PG8_MMA(ai, bj, At, Bt) do { __builtin_amdgcn_s_setprio(1); _Pragma("unroll") for (int m = 0; m < 4; ++m) _Pragma("unroll") for (int n = 0; n < 2; ++n) _Pragma("unroll") for (int k = 0; k < 2; ++k) \
;         acc[ai][bj][m][n] = __builtin_amdgcn_mfma_f32_16x16x32_bf16(Bt[n][k], At[m][k], acc[ai][bj][m][n], 0, 0, 0); __builtin_amdgcn_s_setprio(0); } while (0)
; #define PG8_WAIT_V(n) asm volatile("s_waitcnt vmcnt(" #n ")" ::: "memory")
; #define PG8_WAIT_L(n) asm volatile("s_waitcnt lgkmcnt(" #n ")" ::: "memory")
; #define PG8_BAR __builtin_amdgcn_s_barrier()
; #define PG8_SCHED __builtin_amdgcn_sched_barrier(0)
; template <class Epi, class Sched>
; __device__ __forceinline__ void gemm_phase(PG8_LAS unsigned char* lds, const Gemm g, const Sched& S, const Epi& E) {
;     ...
;             PG8_LDB(B0, 0, 0); PG8_SCHED; PG8_LDA(At, 0, 0); PG8_STAGE(PG8_SA(1, 1), a1 + hstep, voffA);
;             PG8_WAIT_L(8); PG8_BAR; PG8_WAIT_L(0); PG8_MMA(0, 0, At, B0); PG8_BAR; PG8_SCHED;
;             PG8_LDB(B1, 0, 1); PG8_STAGE(PG8_SB(0, 0), b2, voffB);
;             PG8_BAR; PG8_WAIT_L(0); PG8_MMA(0, 1, At, B1); PG8_BAR;
;             PG8_LDA(At, 0, 1); PG8_STAGE(PG8_SA(0, 0), a2, voffA);
;             PG8_BAR; PG8_WAIT_L(0); PG8_MMA(1, 0, At, B0); PG8_BAR; PG8_SCHED;
;             PG8_STAGE(PG8_SB(0, 1), b2 + hstep, voffB);
;             PG8_WAIT_V(6); PG8_BAR; PG8_MMA(1, 1, At, B1); PG8_BAR;
.LBB0_1202:
	ds_read_b128 v[144:147], v151
	ds_read_b128 v[154:157], v151 offset:1024
	ds_read_b128 v[158:161], v151 offset:2048
	ds_read_b128 v[162:165], v151 offset:3072
	s_add_u32 s18, s16, 0xfffc0080
	s_addc_u32 s19, s17, -1
	s_cmp_eq_u32 s46, 12
	s_cselect_b32 s21, s9, s19
	s_cselect_b32 s20, s42, s18
	s_cselect_b32 s19, s7, s45
	s_cselect_b32 s18, s43, s44
	v_lshl_add_u64 v[174:175], s[16:17], 0, v[136:137]
	s_add_i32 m0, s15, 0xc000
	ds_read_b128 v[166:169], v152
	ds_read_b128 v[170:173], v152 offset:1024
	ds_read_b128 v[182:185], v152 offset:2048
	ds_read_b128 v[190:193], v152 offset:3072
	ds_read_b128 v[194:197], v152 offset:4096
	ds_read_b128 v[198:201], v152 offset:5120
	ds_read_b128 v[202:205], v152 offset:6144
	ds_read_b128 v[206:209], v152 offset:7168
	global_load_lds_dwordx4 v[174:175], off
	v_lshl_add_u64 v[174:175], s[16:17], 0, v[138:139]
	s_add_i32 m0, s15, 0xe000
	s_nop 0
	global_load_lds_dwordx4 v[174:175], off
	s_waitcnt lgkmcnt(8)
	s_barrier
	s_waitcnt lgkmcnt(0)
	v_mfma_f32_16x16x32_bf16 v[124:127], v[144:147], v[166:169], v[124:127]
	v_mfma_f32_16x16x32_bf16 v[120:123], v[158:161], v[166:169], v[120:123]
	v_mfma_f32_16x16x32_bf16 v[108:111], v[144:147], v[182:185], v[108:111]
	v_mfma_f32_16x16x32_bf16 v[104:107], v[158:161], v[182:185], v[104:107]
	v_mfma_f32_16x16x32_bf16 v[92:95], v[144:147], v[194:197], v[92:95]
	v_mfma_f32_16x16x32_bf16 v[88:91], v[158:161], v[194:197], v[88:91]
	v_mfma_f32_16x16x32_bf16 v[76:79], v[144:147], v[202:205], v[76:79]
	v_mfma_f32_16x16x32_bf16 v[72:75], v[158:161], v[202:205], v[72:75]
	v_mfma_f32_16x16x32_bf16 v[124:127], v[154:157], v[170:173], v[124:127]
	v_mfma_f32_16x16x32_bf16 v[120:123], v[162:165], v[170:173], v[120:123]
	v_mfma_f32_16x16x32_bf16 v[108:111], v[154:157], v[190:193], v[108:111]
	v_mfma_f32_16x16x32_bf16 v[104:107], v[162:165], v[190:193], v[104:107]
	v_mfma_f32_16x16x32_bf16 v[92:95], v[154:157], v[198:201], v[92:95]
	v_mfma_f32_16x16x32_bf16 v[88:91], v[162:165], v[198:201], v[88:91]
	v_mfma_f32_16x16x32_bf16 v[76:79], v[154:157], v[206:209], v[76:79]
	v_mfma_f32_16x16x32_bf16 v[72:75], v[162:165], v[206:209], v[72:75]
	s_barrier
	s_add_i32 s47, s38, s26
	v_lshl_add_u64 v[174:175], s[18:19], 0, v[132:133]
	s_mov_b32 m0, s47
	ds_read_b128 v[210:213], v153
	ds_read_b128 v[214:217], v153 offset:1024
	ds_read_b128 v[218:221], v153 offset:2048
	ds_read_b128 v[222:225], v153 offset:3072
	global_load_lds_dwordx4 v[174:175], off
	v_lshl_add_u64 v[186:187], s[18:19], 0, v[128:129]
	s_add_i32 m0, s47, 0x2000
	s_nop 0
	global_load_lds_dwordx4 v[186:187], off
	s_barrier
	s_waitcnt lgkmcnt(0)
	v_mfma_f32_16x16x32_bf16 v[116:119], v[210:213], v[166:169], v[116:119]
	v_mfma_f32_16x16x32_bf16 v[112:115], v[218:221], v[166:169], v[112:115]
	v_mfma_f32_16x16x32_bf16 v[100:103], v[210:213], v[182:185], v[100:103]
	v_mfma_f32_16x16x32_bf16 v[96:99], v[218:221], v[182:185], v[96:99]
	v_mfma_f32_16x16x32_bf16 v[84:87], v[210:213], v[194:197], v[84:87]
	v_mfma_f32_16x16x32_bf16 v[80:83], v[218:221], v[194:197], v[80:83]
	v_mfma_f32_16x16x32_bf16 v[68:71], v[210:213], v[202:205], v[68:71]
	v_mfma_f32_16x16x32_bf16 v[64:67], v[218:221], v[202:205], v[64:67]
	v_mfma_f32_16x16x32_bf16 v[116:119], v[214:217], v[170:173], v[116:119]
	v_mfma_f32_16x16x32_bf16 v[112:115], v[222:225], v[170:173], v[112:115]
	v_mfma_f32_16x16x32_bf16 v[100:103], v[214:217], v[190:193], v[100:103]
	v_mfma_f32_16x16x32_bf16 v[96:99], v[222:225], v[190:193], v[96:99]
	v_mfma_f32_16x16x32_bf16 v[84:87], v[214:217], v[198:201], v[84:87]
	v_mfma_f32_16x16x32_bf16 v[80:83], v[222:225], v[198:201], v[80:83]
	v_mfma_f32_16x16x32_bf16 v[68:71], v[214:217], v[206:209], v[68:71]
	v_mfma_f32_16x16x32_bf16 v[64:67], v[222:225], v[206:209], v[64:67]
	s_barrier
	s_mov_b32 m0, s15
	v_lshl_add_u64 v[226:227], s[20:21], 0, v[134:135]
	ds_read_b128 v[166:169], v152 offset:16384
	ds_read_b128 v[170:173], v152 offset:17408
	ds_read_b128 v[182:185], v152 offset:18432
	ds_read_b128 v[190:193], v152 offset:19456
	ds_read_b128 v[194:197], v152 offset:20480
	ds_read_b128 v[198:201], v152 offset:21504
	ds_read_b128 v[202:205], v152 offset:22528
	ds_read_b128 v[206:209], v152 offset:23552
	global_load_lds_dwordx4 v[226:227], off
	v_lshl_add_u64 v[228:229], s[20:21], 0, v[130:131]
	s_mov_b32 m0, s29
	s_nop 0
	global_load_lds_dwordx4 v[228:229], off
	s_barrier
	s_waitcnt lgkmcnt(0)
	v_mfma_f32_16x16x32_bf16 v[60:63], v[144:147], v[166:169], v[60:63]
	v_mfma_f32_16x16x32_bf16 v[56:59], v[158:161], v[166:169], v[56:59]
	v_mfma_f32_16x16x32_bf16 v[44:47], v[144:147], v[182:185], v[44:47]
	v_mfma_f32_16x16x32_bf16 v[40:43], v[158:161], v[182:185], v[40:43]
	v_mfma_f32_16x16x32_bf16 v[28:31], v[144:147], v[194:197], v[28:31]
	v_mfma_f32_16x16x32_bf16 v[24:27], v[158:161], v[194:197], v[24:27]
	v_mfma_f32_16x16x32_bf16 v[12:15], v[144:147], v[202:205], v[12:15]
	v_mfma_f32_16x16x32_bf16 v[8:11], v[158:161], v[202:205], v[8:11]
	v_mfma_f32_16x16x32_bf16 v[60:63], v[154:157], v[170:173], v[60:63]
	v_mfma_f32_16x16x32_bf16 v[56:59], v[162:165], v[170:173], v[56:59]
	v_mfma_f32_16x16x32_bf16 v[44:47], v[154:157], v[190:193], v[44:47]
	v_mfma_f32_16x16x32_bf16 v[40:43], v[162:165], v[190:193], v[40:43]
	v_mfma_f32_16x16x32_bf16 v[28:31], v[154:157], v[198:201], v[28:31]
	v_mfma_f32_16x16x32_bf16 v[24:27], v[162:165], v[198:201], v[24:27]
	v_mfma_f32_16x16x32_bf16 v[12:15], v[154:157], v[206:209], v[12:15]
	v_mfma_f32_16x16x32_bf16 v[8:11], v[162:165], v[206:209], v[8:11]
	s_barrier
; #define PG8_STAGE(bufoff, gbase, voff) do { _Pragma("unroll") for (int _i = 0; _i < 2; ++_i) \
;         __builtin_amdgcn_global_load_lds((const unsigned*)((const char*)(gbase) + (voff)[_i]), (PG8_LAS unsigned*)(lds + (bufoff) + ldsw + _i * 8192), 16, 0, 0); } while (0)
; #define PG8_LDA(dst, b, h) do { _Pragma("unroll") for (int m = 0; m < 4; ++m) _Pragma("unroll") for (int k = 0; k < 2; ++k) dst[m][k] = *(const PG8_LAS bf16x8*)(lds + PG8_SA(b, h) + aoff + m * 2048 + k * 1024); } while (0)
; #define PG8_LDB(dst, b, h) do { _Pragma("unroll") for (int n = 0; n < 2; ++n) _Pragma("unroll") for (int k = 0; k < 2; ++k) dst[n][k] = *(const PG8_LAS bf16x8*)(lds + PG8_SB(b, h) + boff + n * 2048 + k * 1024); } while (0)
; #define PG8_MMA(ai, bj, At, Bt) do { __builtin_amdgcn_s_setprio(1); _Pragma("unroll") for (int m = 0; m < 4; ++m) _Pragma("unroll") for (int n = 0; n < 2; ++n) _Pragma("unroll") for (int k = 0; k < 2; ++k) \
;         acc[ai][bj][m][n] = __builtin_amdgcn_mfma_f32_16x16x32_bf16(Bt[n][k], At[m][k], acc[ai][bj][m][n], 0, 0, 0); __builtin_amdgcn_s_setprio(0); } while (0)
; #define PG8_WAIT_V(n) asm volatile("s_waitcnt vmcnt(" #n ")" ::: "memory")
; #define PG8_WAIT_L(n) asm volatile("s_waitcnt lgkmcnt(" #n ")" ::: "memory")
; #define PG8_BAR __builtin_amdgcn_s_barrier()
; #define PG8_SCHED __builtin_amdgcn_sched_barrier(0)
; template <class Epi, class Sched>
; __device__ __forceinline__ void gemm_phase(PG8_LAS unsigned char* lds, const Gemm g, const Sched& S, const Epi& E) {
;     ...
;             PG8_WAIT_V(6); PG8_BAR; PG8_MMA(1, 1, At, B1); PG8_BAR;
;             PG8_LDB(B0, 1, 0); PG8_SCHED; PG8_LDA(At, 1, 0); PG8_STAGE(PG8_SA(0, 1), a2 + hstep, voffA);
;             PG8_WAIT_L(8); PG8_BAR; PG8_WAIT_L(0); PG8_MMA(0, 0, At, B0); PG8_BAR; PG8_SCHED;
;             PG8_LDB(B1, 1, 1); PG8_STAGE(PG8_SB(1, 0), b3, voffB);
;             PG8_BAR; PG8_WAIT_L(0); PG8_MMA(0, 1, At, B1); PG8_BAR;
;             PG8_LDA(At, 1, 1); PG8_STAGE(PG8_SA(1, 0), a3, voffA);
;             PG8_BAR; PG8_WAIT_L(0); PG8_MMA(1, 0, At, B0); PG8_BAR; PG8_SCHED;
;             PG8_STAGE(PG8_SB(1, 1), b3 + hstep, voffB);
	s_add_u32 s48, s18, 0x40000
	s_addc_u32 s49, s19, 0
	s_add_i32 s47, s39, s26
	v_lshl_add_u64 v[144:145], s[48:49], 0, v[132:133]
	s_mov_b32 m0, s47
	s_nop 0
	global_load_lds_dwordx4 v[144:145], off
	v_lshl_add_u64 v[144:145], s[48:49], 0, v[128:129]
	s_add_i32 m0, s47, 0x2000
	s_nop 0
	global_load_lds_dwordx4 v[144:145], off
	s_waitcnt vmcnt(6)
	s_barrier
	v_mfma_f32_16x16x32_bf16 v[52:55], v[210:213], v[166:169], v[52:55]
	v_mfma_f32_16x16x32_bf16 v[48:51], v[218:221], v[166:169], v[48:51]
	v_mfma_f32_16x16x32_bf16 v[36:39], v[210:213], v[182:185], v[36:39]
	v_mfma_f32_16x16x32_bf16 v[32:35], v[218:221], v[182:185], v[32:35]
	v_mfma_f32_16x16x32_bf16 v[20:23], v[210:213], v[194:197], v[20:23]
	v_mfma_f32_16x16x32_bf16 v[16:19], v[218:221], v[194:197], v[16:19]
	v_mfma_f32_16x16x32_bf16 v[4:7], v[210:213], v[202:205], v[4:7]
	v_mfma_f32_16x16x32_bf16 v[0:3], v[218:221], v[202:205], v[0:3]
	v_mfma_f32_16x16x32_bf16 v[52:55], v[214:217], v[170:173], v[52:55]
	v_mfma_f32_16x16x32_bf16 v[48:51], v[222:225], v[170:173], v[48:51]
	v_mfma_f32_16x16x32_bf16 v[36:39], v[214:217], v[190:193], v[36:39]
	v_mfma_f32_16x16x32_bf16 v[32:35], v[222:225], v[190:193], v[32:35]
	v_mfma_f32_16x16x32_bf16 v[20:23], v[214:217], v[198:201], v[20:23]
	v_mfma_f32_16x16x32_bf16 v[16:19], v[222:225], v[198:201], v[16:19]
	v_mfma_f32_16x16x32_bf16 v[4:7], v[214:217], v[206:209], v[4:7]
	v_mfma_f32_16x16x32_bf16 v[0:3], v[222:225], v[206:209], v[0:3]
	s_barrier
	s_add_i32 s47, 0, 0x18000
	v_add_u32_e32 v162, s47, v149
	ds_read_b128 v[144:147], v162
	ds_read_b128 v[154:157], v162 offset:1024
	ds_read_b128 v[158:161], v162 offset:2048
	ds_read_b128 v[162:165], v162 offset:3072
	s_add_u32 s20, s20, 0x40000
	s_addc_u32 s21, s21, 0
	s_mov_b32 m0, s30
	v_lshl_add_u64 v[210:211], s[20:21], 0, v[134:135]
	ds_read_b128 v[166:169], v152 offset:32768
	ds_read_b128 v[170:173], v152 offset:33792
	ds_read_b128 v[182:185], v152 offset:34816
	ds_read_b128 v[190:193], v152 offset:35840
	ds_read_b128 v[194:197], v152 offset:36864
	ds_read_b128 v[198:201], v152 offset:37888
	ds_read_b128 v[202:205], v152 offset:38912
	ds_read_b128 v[206:209], v152 offset:39936
	global_load_lds_dwordx4 v[210:211], off
	v_lshl_add_u64 v[210:211], s[20:21], 0, v[130:131]
	s_mov_b32 m0, s31
	s_nop 0
	global_load_lds_dwordx4 v[210:211], off
	s_waitcnt lgkmcnt(8)
	s_barrier
	s_waitcnt lgkmcnt(0)
	v_mfma_f32_16x16x32_bf16 v[124:127], v[144:147], v[166:169], v[124:127]
	v_mfma_f32_16x16x32_bf16 v[120:123], v[158:161], v[166:169], v[120:123]
	v_mfma_f32_16x16x32_bf16 v[108:111], v[144:147], v[182:185], v[108:111]
	v_mfma_f32_16x16x32_bf16 v[104:107], v[158:161], v[182:185], v[104:107]
	v_mfma_f32_16x16x32_bf16 v[92:95], v[144:147], v[194:197], v[92:95]
	v_mfma_f32_16x16x32_bf16 v[88:91], v[158:161], v[194:197], v[88:91]
	v_mfma_f32_16x16x32_bf16 v[76:79], v[144:147], v[202:205], v[76:79]
	v_mfma_f32_16x16x32_bf16 v[72:75], v[158:161], v[202:205], v[72:75]
	v_mfma_f32_16x16x32_bf16 v[124:127], v[154:157], v[170:173], v[124:127]
	v_mfma_f32_16x16x32_bf16 v[120:123], v[162:165], v[170:173], v[120:123]
	v_mfma_f32_16x16x32_bf16 v[108:111], v[154:157], v[190:193], v[108:111]
	v_mfma_f32_16x16x32_bf16 v[104:107], v[162:165], v[190:193], v[104:107]
	v_mfma_f32_16x16x32_bf16 v[92:95], v[154:157], v[198:201], v[92:95]
	v_mfma_f32_16x16x32_bf16 v[88:91], v[162:165], v[198:201], v[88:91]
	v_mfma_f32_16x16x32_bf16 v[76:79], v[154:157], v[206:209], v[76:79]
	v_mfma_f32_16x16x32_bf16 v[72:75], v[162:165], v[206:209], v[72:75]
	s_barrier
	s_add_i32 s20, 0, 0x1c000
	s_add_i32 s21, s47, s26
	v_add_u32_e32 v179, s20, v149
	v_lshl_add_u64 v[174:175], v[174:175], 0, s[4:5]
	s_mov_b32 m0, s21
	ds_read_b128 v[210:213], v179
	ds_read_b128 v[214:217], v179 offset:1024
	ds_read_b128 v[218:221], v179 offset:2048
	ds_read_b128 v[222:225], v179 offset:3072
	global_load_lds_dwordx4 v[174:175], off
	v_lshl_add_u64 v[174:175], v[186:187], 0, s[4:5]
	s_add_i32 m0, s21, 0x2000
	s_nop 0
	global_load_lds_dwordx4 v[174:175], off
	s_barrier
	s_waitcnt lgkmcnt(0)
	v_mfma_f32_16x16x32_bf16 v[116:119], v[210:213], v[166:169], v[116:119]
	v_mfma_f32_16x16x32_bf16 v[112:115], v[218:221], v[166:169], v[112:115]
	v_mfma_f32_16x16x32_bf16 v[100:103], v[210:213], v[182:185], v[100:103]
	v_mfma_f32_16x16x32_bf16 v[96:99], v[218:221], v[182:185], v[96:99]
	v_mfma_f32_16x16x32_bf16 v[84:87], v[210:213], v[194:197], v[84:87]
	v_mfma_f32_16x16x32_bf16 v[80:83], v[218:221], v[194:197], v[80:83]
	v_mfma_f32_16x16x32_bf16 v[68:71], v[210:213], v[202:205], v[68:71]
	v_mfma_f32_16x16x32_bf16 v[64:67], v[218:221], v[202:205], v[64:67]
	v_mfma_f32_16x16x32_bf16 v[116:119], v[214:217], v[170:173], v[116:119]
	v_mfma_f32_16x16x32_bf16 v[112:115], v[222:225], v[170:173], v[112:115]
	v_mfma_f32_16x16x32_bf16 v[100:103], v[214:217], v[190:193], v[100:103]
	v_mfma_f32_16x16x32_bf16 v[96:99], v[222:225], v[190:193], v[96:99]
	v_mfma_f32_16x16x32_bf16 v[84:87], v[214:217], v[198:201], v[84:87]
	v_mfma_f32_16x16x32_bf16 v[80:83], v[222:225], v[198:201], v[80:83]
	v_mfma_f32_16x16x32_bf16 v[68:71], v[214:217], v[206:209], v[68:71]
	v_mfma_f32_16x16x32_bf16 v[64:67], v[222:225], v[206:209], v[64:67]
	s_barrier
	s_mov_b32 m0, s35
	v_lshl_add_u64 v[174:175], v[226:227], 0, s[4:5]
	ds_read_b128 v[166:169], v152 offset:49152
	ds_read_b128 v[170:173], v152 offset:50176
	ds_read_b128 v[182:185], v152 offset:51200
	ds_read_b128 v[190:193], v152 offset:52224
	ds_read_b128 v[194:197], v152 offset:53248
	ds_read_b128 v[198:201], v152 offset:54272
	ds_read_b128 v[202:205], v152 offset:55296
	ds_read_b128 v[206:209], v152 offset:56320
	global_load_lds_dwordx4 v[174:175], off
	v_lshl_add_u64 v[174:175], v[228:229], 0, s[4:5]
	s_mov_b32 m0, s36
	s_nop 0
	global_load_lds_dwordx4 v[174:175], off
	s_barrier
; __device__ __forceinline__ unsigned cvt_pk_bf16(float lo, float hi) { unsigned r; asm volatile("v_cvt_pk_bf16_f32 %0, %1, %2" : "=v"(r) : "v"(lo), "v"(hi)); return r; }
; #define PG8_STAGE(bufoff, gbase, voff) do { _Pragma("unroll") for (int _i = 0; _i < 2; ++_i) \
;         __builtin_amdgcn_global_load_lds((const unsigned*)((const char*)(gbase) + (voff)[_i]), (PG8_LAS unsigned*)(lds + (bufoff) + ldsw + _i * 8192), 16, 0, 0); } while (0)
; #define PG8_MMA(ai, bj, At, Bt) do { __builtin_amdgcn_s_setprio(1); _Pragma("unroll") for (int m = 0; m < 4; ++m) _Pragma("unroll") for (int n = 0; n < 2; ++n) _Pragma("unroll") for (int k = 0; k < 2; ++k) \
;         acc[ai][bj][m][n] = __builtin_amdgcn_mfma_f32_16x16x32_bf16(Bt[n][k], At[m][k], acc[ai][bj][m][n], 0, 0, 0); __builtin_amdgcn_s_setprio(0); } while (0)
; #define PG8_WAIT_V(n) asm volatile("s_waitcnt vmcnt(" #n ")" ::: "memory")
; #define PG8_WAIT_L(n) asm volatile("s_waitcnt lgkmcnt(" #n ")" ::: "memory")
; #define PG8_BAR __builtin_amdgcn_s_barrier()
; #define PG8_SCHED __builtin_amdgcn_sched_barrier(0)
;     __device__ __forceinline__ void operator()(const f32x4 (&acc)[2][2][4][2], const Unit& u, int wr, int wc, int fr, int fq) const {
;         const int row0 = u.pm * BM + wr * 64 + fr, col0 = u.pn * HALF + wc * 32 + 8 * fq;
; #pragma unroll
;         for (int ai = 0; ai < 2; ++ai)
; #pragma unroll
;             for (int m = 0; m < 4; ++m) { bf16_t* rowp = O + (size_t)(row0 + ai * HALF + m * 16) * ldc + col0;
;                 f32x4 v0, v1;
; #pragma unroll
;                 for (int j = 0; j < 1; ++j) { v0 = acc[ai][0][m][0] * sigmoid4(acc[ai][0][m][0]) * acc[ai][1][m][0]; v1 = acc[ai][0][m][1] * sigmoid4(acc[ai][0][m][1]) * acc[ai][1][m][1]; }
;                 u32x4 w; w.x = cvt_pk_bf16(v0[0], v0[1]); w.y = cvt_pk_bf16(v0[2], v0[3]); w.z = cvt_pk_bf16(v1[0], v1[1]); w.w = cvt_pk_bf16(v1[2], v1[3]);
;                 *(u32x4*)rowp = w; }
; template <class Epi, class Sched>
; __device__ __forceinline__ void gemm_phase(PG8_LAS unsigned char* lds, const Gemm g, const Sched& S, const Epi& E) {
;     ...
;             PG8_BAR; PG8_WAIT_L(0); PG8_MMA(1, 0, At, B0); PG8_BAR; PG8_SCHED;
;             PG8_STAGE(PG8_SB(1, 1), b3 + hstep, voffB);
;             PG8_WAIT_V(6); PG8_BAR; PG8_MMA(1, 1, At, B1); PG8_BAR;
;         }
;         if constexpr (!Epi::AFTER_DRAIN) { E(acc, cur, wr, wc, fr, fq); S.done(cur); }
	s_waitcnt lgkmcnt(0)
	v_mfma_f32_16x16x32_bf16 v[60:63], v[144:147], v[166:169], v[60:63]
	v_mfma_f32_16x16x32_bf16 v[56:59], v[158:161], v[166:169], v[56:59]
	v_mfma_f32_16x16x32_bf16 v[44:47], v[144:147], v[182:185], v[44:47]
	v_mfma_f32_16x16x32_bf16 v[40:43], v[158:161], v[182:185], v[40:43]
	v_mfma_f32_16x16x32_bf16 v[28:31], v[144:147], v[194:197], v[28:31]
	v_mfma_f32_16x16x32_bf16 v[24:27], v[158:161], v[194:197], v[24:27]
	v_mfma_f32_16x16x32_bf16 v[12:15], v[144:147], v[202:205], v[12:15]
	v_mfma_f32_16x16x32_bf16 v[8:11], v[158:161], v[202:205], v[8:11]
	v_mfma_f32_16x16x32_bf16 v[60:63], v[154:157], v[170:173], v[60:63]
	v_mfma_f32_16x16x32_bf16 v[56:59], v[162:165], v[170:173], v[56:59]
	v_mfma_f32_16x16x32_bf16 v[44:47], v[154:157], v[190:193], v[44:47]
	v_mfma_f32_16x16x32_bf16 v[40:43], v[162:165], v[190:193], v[40:43]
	v_mfma_f32_16x16x32_bf16 v[28:31], v[154:157], v[198:201], v[28:31]
	v_mfma_f32_16x16x32_bf16 v[24:27], v[162:165], v[198:201], v[24:27]
	v_mfma_f32_16x16x32_bf16 v[12:15], v[154:157], v[206:209], v[12:15]
	v_mfma_f32_16x16x32_bf16 v[8:11], v[162:165], v[206:209], v[8:11]
	s_barrier
	s_add_u32 s18, s18, 0x40080
	s_addc_u32 s19, s19, 0
	s_add_i32 s20, s20, s26
	v_lshl_add_u64 v[144:145], s[18:19], 0, v[132:133]
	s_mov_b32 m0, s20
	s_nop 0
	global_load_lds_dwordx4 v[144:145], off
	v_lshl_add_u64 v[144:145], s[18:19], 0, v[128:129]
	s_add_i32 m0, s20, 0x2000
	s_nop 0
	global_load_lds_dwordx4 v[144:145], off
	s_waitcnt vmcnt(6)
	s_barrier
	v_mfma_f32_16x16x32_bf16 v[52:55], v[210:213], v[166:169], v[52:55]
	v_mfma_f32_16x16x32_bf16 v[48:51], v[218:221], v[166:169], v[48:51]
	v_mfma_f32_16x16x32_bf16 v[36:39], v[210:213], v[182:185], v[36:39]
	v_mfma_f32_16x16x32_bf16 v[32:35], v[218:221], v[182:185], v[32:35]
	v_mfma_f32_16x16x32_bf16 v[20:23], v[210:213], v[194:197], v[20:23]
	v_mfma_f32_16x16x32_bf16 v[16:19], v[218:221], v[194:197], v[16:19]
	v_mfma_f32_16x16x32_bf16 v[4:7], v[210:213], v[202:205], v[4:7]
	v_mfma_f32_16x16x32_bf16 v[0:3], v[218:221], v[202:205], v[0:3]
	v_mfma_f32_16x16x32_bf16 v[52:55], v[214:217], v[170:173], v[52:55]
	v_mfma_f32_16x16x32_bf16 v[48:51], v[222:225], v[170:173], v[48:51]
	v_mfma_f32_16x16x32_bf16 v[36:39], v[214:217], v[190:193], v[36:39]
	v_mfma_f32_16x16x32_bf16 v[32:35], v[222:225], v[190:193], v[32:35]
	v_mfma_f32_16x16x32_bf16 v[20:23], v[214:217], v[198:201], v[20:23]
	v_mfma_f32_16x16x32_bf16 v[16:19], v[222:225], v[198:201], v[16:19]
	v_mfma_f32_16x16x32_bf16 v[4:7], v[214:217], v[206:209], v[4:7]
	v_mfma_f32_16x16x32_bf16 v[0:3], v[222:225], v[206:209], v[0:3]
	s_barrier
	s_add_i32 s46, s46, 2
	s_add_u32 s16, s16, 0x100
	s_addc_u32 s17, s17, 0
	s_add_u32 s44, s44, 0x100
	s_addc_u32 s45, s45, 0
	s_cmp_gt_u32 s46, 13
	s_cbranch_scc0 .LBB0_1202
	v_max_f32_e32 v144, v124, v124
	v_max_f32_e32 v144, 0xc1a00000, v144
	v_mul_f32_e32 v144, 0xbfb8aa3b, v144
	v_exp_f32_e32 v157, v144
	v_max_f32_e32 v144, v125, v125
	v_max_f32_e32 v144, 0xc1a00000, v144
	v_mul_f32_e32 v144, 0xbfb8aa3b, v144
	v_exp_f32_e32 v156, v144
	v_max_f32_e32 v144, v126, v126
	v_max_f32_e32 v144, 0xc1a00000, v144
	v_mul_f32_e32 v144, 0xbfb8aa3b, v144
	v_exp_f32_e32 v159, v144
	v_max_f32_e32 v144, v127, v127
	v_max_f32_e32 v144, 0xc1a00000, v144
	v_mul_f32_e32 v144, 0xbfb8aa3b, v144
	v_exp_f32_e32 v158, v144
	v_pk_add_f32 v[156:157], v[156:157], 1.0 op_sel_hi:[1,0]
	v_lshl_or_b32 v146, s41, 7, v150
	v_mov_b32_e32 v160, v157
	v_pk_add_f32 v[158:159], v[158:159], 1.0 op_sel_hi:[1,0]
	v_mov_b32_e32 v162, v156
	v_mov_b32_e32 v161, v159
	v_mov_b32_e32 v163, v158
	v_pk_mul_f32 v[160:161], v[160:161], v[162:163]
	v_lshl_add_u32 v154, s14, 8, v148
	v_mul_f32_e32 v155, v160, v161
	v_rcp_f32_e32 v155, v155
	v_ashrrev_i32_e32 v147, 31, v146
	v_mov_b64_e32 v[144:145], s[0:1]
	v_mad_i64_i32 v[162:163], s[16:17], v154, s40, v[144:145]
	v_mul_f32_e32 v164, v161, v155
	v_mul_f32_e32 v160, v160, v155
	v_max_f32_e32 v155, v120, v120
	v_max_f32_e32 v155, 0xc1a00000, v155
	v_mul_f32_e32 v155, 0xbfb8aa3b, v155
	v_pk_mul_f32 v[158:159], v[158:159], v[160:161] op_sel_hi:[1,0]
	v_exp_f32_e32 v161, v155
	v_max_f32_e32 v155, v121, v121
	v_max_f32_e32 v155, 0xc1a00000, v155
	v_mul_f32_e32 v155, 0xbfb8aa3b, v155
	v_exp_f32_e32 v160, v155
	v_max_f32_e32 v155, v122, v122
	v_max_f32_e32 v155, 0xc1a00000, v155
	v_mul_f32_e32 v155, 0xbfb8aa3b, v155
	v_exp_f32_e32 v167, v155
	v_max_f32_e32 v155, v123, v123
	v_max_f32_e32 v155, 0xc1a00000, v155
	v_mul_f32_e32 v155, 0xbfb8aa3b, v155
	v_exp_f32_e32 v166, v155
	v_pk_mul_f32 v[156:157], v[156:157], v[164:165] op_sel_hi:[1,0]
	v_pk_mul_f32 v[126:127], v[126:127], v[158:159]
	v_pk_mul_f32 v[124:125], v[124:125], v[156:157]
	v_pk_add_f32 v[156:157], v[160:161], 1.0 op_sel_hi:[1,0]
	v_pk_add_f32 v[160:161], v[166:167], 1.0 op_sel_hi:[1,0]
	v_mov_b32_e32 v164, v157
	v_mov_b32_e32 v165, v161
	v_mov_b32_e32 v166, v156
	v_mov_b32_e32 v167, v160
	v_pk_mul_f32 v[164:165], v[164:165], v[166:167]
	v_pk_mul_f32 v[118:119], v[126:127], v[118:119]
	v_mul_f32_e32 v155, v164, v165
	v_rcp_f32_e32 v155, v155
	v_pk_mul_f32 v[116:117], v[124:125], v[116:117]
	v_lshlrev_b64 v[146:147], 1, v[146:147]
	v_lshl_add_u64 v[162:163], v[162:163], 0, v[146:147]
	v_mul_f32_e32 v124, v165, v155
	v_mul_f32_e32 v126, v164, v155
	v_pk_mul_f32 v[126:127], v[160:161], v[126:127] op_sel_hi:[1,0]
	v_pk_mul_f32 v[124:125], v[156:157], v[124:125] op_sel_hi:[1,0]
	v_pk_mul_f32 v[122:123], v[122:123], v[126:127]
	v_pk_mul_f32 v[120:121], v[120:121], v[124:125]
	v_pk_mul_f32 v[122:123], v[122:123], v[114:115]
	v_pk_mul_f32 v[114:115], v[120:121], v[112:113]
	v_cvt_pk_bf16_f32 v112, v116, v117
	v_cvt_pk_bf16_f32 v113, v118, v119
; __device__ __forceinline__ unsigned cvt_pk_bf16(float lo, float hi) { unsigned r; asm volatile("v_cvt_pk_bf16_f32 %0, %1, %2" : "=v"(r) : "v"(lo), "v"(hi)); return r; }
;     __device__ __forceinline__ void operator()(const f32x4 (&acc)[2][2][4][2], const Unit& u, int wr, int wc, int fr, int fq) const {
;         const int row0 = u.pm * BM + wr * 64 + fr, col0 = u.pn * HALF + wc * 32 + 8 * fq;
; #pragma unroll
;         for (int ai = 0; ai < 2; ++ai)
; #pragma unroll
;             for (int m = 0; m < 4; ++m) { bf16_t* rowp = O + (size_t)(row0 + ai * HALF + m * 16) * ldc + col0;
;                 f32x4 v0, v1;
; #pragma unroll
;                 for (int j = 0; j < 1; ++j) { v0 = acc[ai][0][m][0] * sigmoid4(acc[ai][0][m][0]) * acc[ai][1][m][0]; v1 = acc[ai][0][m][1] * sigmoid4(acc[ai][0][m][1]) * acc[ai][1][m][1]; }
;                 u32x4 w; w.x = cvt_pk_bf16(v0[0], v0[1]); w.y = cvt_pk_bf16(v0[2], v0[3]); w.z = cvt_pk_bf16(v1[0], v1[1]); w.w = cvt_pk_bf16(v1[2], v1[3]);
;                 *(u32x4*)rowp = w; }
	v_max_f32_e32 v116, v108, v108
	v_max_f32_e32 v118, v110, v110
	v_max_f32_e32 v116, 0xc1a00000, v116
	v_max_f32_e32 v118, 0xc1a00000, v118
	v_mul_f32_e32 v116, 0xbfb8aa3b, v116
	v_mul_f32_e32 v118, 0xbfb8aa3b, v118
	v_exp_f32_e32 v117, v116
	v_max_f32_e32 v116, v109, v109
	v_exp_f32_e32 v119, v118
	v_max_f32_e32 v118, v111, v111
	v_max_f32_e32 v116, 0xc1a00000, v116
	v_max_f32_e32 v118, 0xc1a00000, v118
	v_mul_f32_e32 v116, 0xbfb8aa3b, v116
	v_mul_f32_e32 v118, 0xbfb8aa3b, v118
	v_exp_f32_e32 v116, v116
	v_exp_f32_e32 v118, v118
	v_cvt_pk_bf16_f32 v114, v114, v115
	v_cvt_pk_bf16_f32 v115, v122, v123
	global_store_dwordx4 v[162:163], v[112:115], off
	v_or_b32_e32 v120, 16, v154
	s_and_b64 vcc, exec, s[2:3]
	v_pk_add_f32 v[112:113], v[116:117], 1.0 op_sel_hi:[1,0]
	v_pk_add_f32 v[114:115], v[118:119], 1.0 op_sel_hi:[1,0]
	v_mov_b32_e32 v116, v113
	v_mov_b32_e32 v117, v115
	v_mov_b32_e32 v118, v112
	v_mov_b32_e32 v119, v114
	v_pk_mul_f32 v[116:117], v[116:117], v[118:119]
	s_mov_b32 s41, s6
	v_mul_f32_e32 v118, v116, v117
	v_rcp_f32_e32 v121, v118
	v_mad_i64_i32 v[118:119], s[16:17], v120, s40, v[144:145]
	v_lshl_add_u64 v[118:119], v[118:119], 0, v[146:147]
	v_mul_f32_e32 v116, v116, v121
	v_mul_f32_e32 v120, v117, v121
	v_pk_mul_f32 v[114:115], v[114:115], v[116:117] op_sel_hi:[1,0]
	v_max_f32_e32 v116, v104, v104
	v_max_f32_e32 v121, v106, v106
	v_max_f32_e32 v116, 0xc1a00000, v116
	v_max_f32_e32 v121, 0xc1a00000, v121
	v_mul_f32_e32 v116, 0xbfb8aa3b, v116
	v_mul_f32_e32 v121, 0xbfb8aa3b, v121
	v_exp_f32_e32 v117, v116
	v_max_f32_e32 v116, v105, v105
	v_exp_f32_e32 v123, v121
	v_max_f32_e32 v121, v107, v107
	v_max_f32_e32 v116, 0xc1a00000, v116
	v_max_f32_e32 v121, 0xc1a00000, v121
	v_mul_f32_e32 v116, 0xbfb8aa3b, v116
	v_mul_f32_e32 v121, 0xbfb8aa3b, v121
	v_exp_f32_e32 v116, v116
	v_exp_f32_e32 v122, v121
	v_pk_mul_f32 v[112:113], v[112:113], v[120:121] op_sel_hi:[1,0]
	v_pk_mul_f32 v[110:111], v[110:111], v[114:115]
	v_pk_mul_f32 v[108:109], v[108:109], v[112:113]
	v_pk_add_f32 v[112:113], v[116:117], 1.0 op_sel_hi:[1,0]
	v_pk_add_f32 v[116:117], v[122:123], 1.0 op_sel_hi:[1,0]
	v_mov_b32_e32 v120, v113
	v_mov_b32_e32 v121, v117
	v_mov_b32_e32 v122, v112
	v_mov_b32_e32 v123, v116
	v_pk_mul_f32 v[120:121], v[120:121], v[122:123]
	v_pk_mul_f32 v[102:103], v[110:111], v[102:103]
	v_mul_f32_e32 v122, v120, v121
	v_rcp_f32_e32 v122, v122
	v_pk_mul_f32 v[100:101], v[108:109], v[100:101]
	s_mov_b32 s14, s8
	s_mov_b64 s[18:19], s[12:13]
	v_mul_f32_e32 v108, v121, v122
	v_mul_f32_e32 v110, v120, v122
	v_pk_mul_f32 v[110:111], v[116:117], v[110:111] op_sel_hi:[1,0]
	v_pk_mul_f32 v[108:109], v[112:113], v[108:109] op_sel_hi:[1,0]
	v_pk_mul_f32 v[106:107], v[106:107], v[110:111]
	v_pk_mul_f32 v[104:105], v[104:105], v[108:109]
	v_pk_mul_f32 v[106:107], v[106:107], v[98:99]
	v_pk_mul_f32 v[98:99], v[104:105], v[96:97]
	v_cvt_pk_bf16_f32 v96, v100, v101
	v_cvt_pk_bf16_f32 v97, v102, v103
	v_max_f32_e32 v100, v92, v92
	v_max_f32_e32 v102, v94, v94
	v_max_f32_e32 v100, 0xc1a00000, v100
	v_max_f32_e32 v102, 0xc1a00000, v102
	v_mul_f32_e32 v100, 0xbfb8aa3b, v100
	v_mul_f32_e32 v102, 0xbfb8aa3b, v102
	v_exp_f32_e32 v101, v100
	v_max_f32_e32 v100, v93, v93
	v_exp_f32_e32 v103, v102
	v_max_f32_e32 v102, v95, v95
	v_max_f32_e32 v100, 0xc1a00000, v100
	v_max_f32_e32 v102, 0xc1a00000, v102
	v_mul_f32_e32 v100, 0xbfb8aa3b, v100
	v_mul_f32_e32 v102, 0xbfb8aa3b, v102
	v_exp_f32_e32 v100, v100
	v_exp_f32_e32 v102, v102
	v_cvt_pk_bf16_f32 v98, v98, v99
	v_cvt_pk_bf16_f32 v99, v106, v107
	global_store_dwordx4 v[118:119], v[96:99], off
	v_or_b32_e32 v104, 32, v154
	s_nop 0
	v_pk_add_f32 v[96:97], v[100:101], 1.0 op_sel_hi:[1,0]
	v_pk_add_f32 v[98:99], v[102:103], 1.0 op_sel_hi:[1,0]
	v_mov_b32_e32 v100, v97
	v_mov_b32_e32 v101, v99
	v_mov_b32_e32 v102, v96
	v_mov_b32_e32 v103, v98
	v_pk_mul_f32 v[100:101], v[100:101], v[102:103]
	s_nop 0
	v_mul_f32_e32 v102, v100, v101
	v_rcp_f32_e32 v105, v102
	v_mad_i64_i32 v[102:103], s[16:17], v104, s40, v[144:145]
	v_lshl_add_u64 v[102:103], v[102:103], 0, v[146:147]
	v_mul_f32_e32 v100, v100, v105
	v_mul_f32_e32 v104, v101, v105
	v_pk_mul_f32 v[98:99], v[98:99], v[100:101] op_sel_hi:[1,0]
	v_max_f32_e32 v100, v88, v88
	v_max_f32_e32 v105, v90, v90
	v_max_f32_e32 v100, 0xc1a00000, v100
	v_max_f32_e32 v105, 0xc1a00000, v105
	v_mul_f32_e32 v100, 0xbfb8aa3b, v100
	v_mul_f32_e32 v105, 0xbfb8aa3b, v105
	v_exp_f32_e32 v101, v100
	v_max_f32_e32 v100, v89, v89
	v_exp_f32_e32 v107, v105
	v_max_f32_e32 v105, v91, v91
	v_max_f32_e32 v100, 0xc1a00000, v100
	v_max_f32_e32 v105, 0xc1a00000, v105
	v_mul_f32_e32 v100, 0xbfb8aa3b, v100
	v_mul_f32_e32 v105, 0xbfb8aa3b, v105
	v_exp_f32_e32 v100, v100
	v_exp_f32_e32 v106, v105
	v_pk_mul_f32 v[96:97], v[96:97], v[104:105] op_sel_hi:[1,0]
	v_pk_mul_f32 v[94:95], v[94:95], v[98:99]
	v_pk_mul_f32 v[92:93], v[92:93], v[96:97]
	v_pk_add_f32 v[96:97], v[100:101], 1.0 op_sel_hi:[1,0]
	v_pk_add_f32 v[100:101], v[106:107], 1.0 op_sel_hi:[1,0]
	v_mov_b32_e32 v104, v97
	v_mov_b32_e32 v105, v101
	v_mov_b32_e32 v106, v96
	v_mov_b32_e32 v107, v100
	v_pk_mul_f32 v[104:105], v[104:105], v[106:107]
	v_pk_mul_f32 v[86:87], v[94:95], v[86:87]
	v_mul_f32_e32 v106, v104, v105
	v_rcp_f32_e32 v106, v106
	v_pk_mul_f32 v[84:85], v[92:93], v[84:85]
	v_mul_f32_e32 v92, v105, v106
	v_mul_f32_e32 v94, v104, v106
	v_pk_mul_f32 v[94:95], v[100:101], v[94:95] op_sel_hi:[1,0]
	v_pk_mul_f32 v[92:93], v[96:97], v[92:93] op_sel_hi:[1,0]
	v_pk_mul_f32 v[90:91], v[90:91], v[94:95]
	v_pk_mul_f32 v[88:89], v[88:89], v[92:93]
	v_pk_mul_f32 v[90:91], v[90:91], v[82:83]
	v_pk_mul_f32 v[82:83], v[88:89], v[80:81]
	v_cvt_pk_bf16_f32 v80, v84, v85
; __device__ __forceinline__ unsigned cvt_pk_bf16(float lo, float hi) { unsigned r; asm volatile("v_cvt_pk_bf16_f32 %0, %1, %2" : "=v"(r) : "v"(lo), "v"(hi)); return r; }
;     __device__ __forceinline__ void operator()(const f32x4 (&acc)[2][2][4][2], const Unit& u, int wr, int wc, int fr, int fq) const {
;         const int row0 = u.pm * BM + wr * 64 + fr, col0 = u.pn * HALF + wc * 32 + 8 * fq;
; #pragma unroll
;         for (int ai = 0; ai < 2; ++ai)
; #pragma unroll
;             for (int m = 0; m < 4; ++m) { bf16_t* rowp = O + (size_t)(row0 + ai * HALF + m * 16) * ldc + col0;
;                 f32x4 v0, v1;
; #pragma unroll
;                 for (int j = 0; j < 1; ++j) { v0 = acc[ai][0][m][0] * sigmoid4(acc[ai][0][m][0]) * acc[ai][1][m][0]; v1 = acc[ai][0][m][1] * sigmoid4(acc[ai][0][m][1]) * acc[ai][1][m][1]; }
;                 u32x4 w; w.x = cvt_pk_bf16(v0[0], v0[1]); w.y = cvt_pk_bf16(v0[2], v0[3]); w.z = cvt_pk_bf16(v1[0], v1[1]); w.w = cvt_pk_bf16(v1[2], v1[3]);
;                 *(u32x4*)rowp = w; }
	v_cvt_pk_bf16_f32 v81, v86, v87
	v_max_f32_e32 v84, v76, v76
	v_max_f32_e32 v86, v78, v78
	v_max_f32_e32 v84, 0xc1a00000, v84
	v_max_f32_e32 v86, 0xc1a00000, v86
	v_mul_f32_e32 v84, 0xbfb8aa3b, v84
	v_mul_f32_e32 v86, 0xbfb8aa3b, v86
	v_exp_f32_e32 v85, v84
	v_max_f32_e32 v84, v77, v77
	v_exp_f32_e32 v87, v86
	v_max_f32_e32 v86, v79, v79
	v_max_f32_e32 v84, 0xc1a00000, v84
	v_max_f32_e32 v86, 0xc1a00000, v86
	v_mul_f32_e32 v84, 0xbfb8aa3b, v84
	v_mul_f32_e32 v86, 0xbfb8aa3b, v86
	v_exp_f32_e32 v84, v84
	v_exp_f32_e32 v86, v86
	v_cvt_pk_bf16_f32 v82, v82, v83
	v_cvt_pk_bf16_f32 v83, v90, v91
	global_store_dwordx4 v[102:103], v[80:83], off
	v_or_b32_e32 v88, 48, v154
	s_nop 0
	v_pk_add_f32 v[80:81], v[84:85], 1.0 op_sel_hi:[1,0]
	v_pk_add_f32 v[82:83], v[86:87], 1.0 op_sel_hi:[1,0]
	v_mov_b32_e32 v84, v81
	v_mov_b32_e32 v85, v83
	v_mov_b32_e32 v86, v80
	v_mov_b32_e32 v87, v82
	v_pk_mul_f32 v[84:85], v[84:85], v[86:87]
	s_nop 0
	v_mul_f32_e32 v86, v84, v85
	v_rcp_f32_e32 v89, v86
	v_mad_i64_i32 v[86:87], s[16:17], v88, s40, v[144:145]
	v_lshl_add_u64 v[86:87], v[86:87], 0, v[146:147]
	v_mul_f32_e32 v84, v84, v89
	v_mul_f32_e32 v88, v85, v89
	v_pk_mul_f32 v[82:83], v[82:83], v[84:85] op_sel_hi:[1,0]
	v_max_f32_e32 v84, v72, v72
	v_max_f32_e32 v89, v74, v74
	v_max_f32_e32 v84, 0xc1a00000, v84
	v_max_f32_e32 v89, 0xc1a00000, v89
	v_mul_f32_e32 v84, 0xbfb8aa3b, v84
	v_mul_f32_e32 v89, 0xbfb8aa3b, v89
	v_exp_f32_e32 v85, v84
	v_max_f32_e32 v84, v73, v73
	v_exp_f32_e32 v91, v89
	v_max_f32_e32 v89, v75, v75
	v_max_f32_e32 v84, 0xc1a00000, v84
	v_max_f32_e32 v89, 0xc1a00000, v89
	v_mul_f32_e32 v84, 0xbfb8aa3b, v84
	v_mul_f32_e32 v89, 0xbfb8aa3b, v89
	v_exp_f32_e32 v84, v84
	v_exp_f32_e32 v90, v89
	v_pk_mul_f32 v[80:81], v[80:81], v[88:89] op_sel_hi:[1,0]
	v_pk_mul_f32 v[78:79], v[78:79], v[82:83]
	v_pk_mul_f32 v[76:77], v[76:77], v[80:81]
	v_pk_add_f32 v[80:81], v[84:85], 1.0 op_sel_hi:[1,0]
	v_pk_add_f32 v[84:85], v[90:91], 1.0 op_sel_hi:[1,0]
	v_mov_b32_e32 v88, v81
	v_mov_b32_e32 v89, v85
	v_mov_b32_e32 v90, v80
	v_mov_b32_e32 v91, v84
	v_pk_mul_f32 v[88:89], v[88:89], v[90:91]
	v_pk_mul_f32 v[70:71], v[78:79], v[70:71]
	v_mul_f32_e32 v90, v88, v89
	v_rcp_f32_e32 v90, v90
	v_pk_mul_f32 v[68:69], v[76:77], v[68:69]
	v_mul_f32_e32 v76, v89, v90
	v_mul_f32_e32 v78, v88, v90
	v_pk_mul_f32 v[78:79], v[84:85], v[78:79] op_sel_hi:[1,0]
	v_pk_mul_f32 v[76:77], v[80:81], v[76:77] op_sel_hi:[1,0]
	v_pk_mul_f32 v[74:75], v[74:75], v[78:79]
	v_pk_mul_f32 v[72:73], v[72:73], v[76:77]
	v_pk_mul_f32 v[74:75], v[74:75], v[66:67]
	v_pk_mul_f32 v[66:67], v[72:73], v[64:65]
	v_cvt_pk_bf16_f32 v64, v68, v69
	v_cvt_pk_bf16_f32 v65, v70, v71
	v_max_f32_e32 v68, v60, v60
	v_max_f32_e32 v70, v62, v62
	v_max_f32_e32 v68, 0xc1a00000, v68
	v_max_f32_e32 v70, 0xc1a00000, v70
	v_mul_f32_e32 v68, 0xbfb8aa3b, v68
	v_mul_f32_e32 v70, 0xbfb8aa3b, v70
	v_exp_f32_e32 v69, v68
	v_max_f32_e32 v68, v61, v61
	v_exp_f32_e32 v71, v70
	v_max_f32_e32 v70, v63, v63
	v_max_f32_e32 v68, 0xc1a00000, v68
	v_max_f32_e32 v70, 0xc1a00000, v70
	v_mul_f32_e32 v68, 0xbfb8aa3b, v68
	v_mul_f32_e32 v70, 0xbfb8aa3b, v70
	v_exp_f32_e32 v68, v68
	v_exp_f32_e32 v70, v70
	v_cvt_pk_bf16_f32 v66, v66, v67
	v_cvt_pk_bf16_f32 v67, v74, v75
	global_store_dwordx4 v[86:87], v[64:67], off
	v_add_u32_e32 v72, 0x80, v154
	s_nop 0
	v_pk_add_f32 v[64:65], v[68:69], 1.0 op_sel_hi:[1,0]
	v_pk_add_f32 v[66:67], v[70:71], 1.0 op_sel_hi:[1,0]
	v_mov_b32_e32 v68, v65
	v_mov_b32_e32 v69, v67
	v_mov_b32_e32 v70, v64
	v_mov_b32_e32 v71, v66
	v_pk_mul_f32 v[68:69], v[68:69], v[70:71]
	s_nop 0
	v_mul_f32_e32 v70, v68, v69
	v_rcp_f32_e32 v73, v70
	v_mad_i64_i32 v[70:71], s[16:17], v72, s40, v[144:145]
	v_lshl_add_u64 v[70:71], v[70:71], 0, v[146:147]
	v_mul_f32_e32 v68, v68, v73
	v_mul_f32_e32 v72, v69, v73
	v_pk_mul_f32 v[66:67], v[66:67], v[68:69] op_sel_hi:[1,0]
	v_max_f32_e32 v68, v56, v56
	v_max_f32_e32 v73, v58, v58
	v_max_f32_e32 v68, 0xc1a00000, v68
	v_max_f32_e32 v73, 0xc1a00000, v73
	v_mul_f32_e32 v68, 0xbfb8aa3b, v68
	v_mul_f32_e32 v73, 0xbfb8aa3b, v73
	v_exp_f32_e32 v69, v68
	v_max_f32_e32 v68, v57, v57
	v_exp_f32_e32 v75, v73
	v_max_f32_e32 v73, v59, v59
	v_max_f32_e32 v68, 0xc1a00000, v68
	v_max_f32_e32 v73, 0xc1a00000, v73
	v_mul_f32_e32 v68, 0xbfb8aa3b, v68
	v_mul_f32_e32 v73, 0xbfb8aa3b, v73
	v_exp_f32_e32 v68, v68
	v_exp_f32_e32 v74, v73
	v_pk_mul_f32 v[64:65], v[64:65], v[72:73] op_sel_hi:[1,0]
	v_pk_mul_f32 v[62:63], v[62:63], v[66:67]
	v_pk_mul_f32 v[60:61], v[60:61], v[64:65]
	v_pk_add_f32 v[64:65], v[68:69], 1.0 op_sel_hi:[1,0]
	v_pk_add_f32 v[68:69], v[74:75], 1.0 op_sel_hi:[1,0]
	v_mov_b32_e32 v72, v65
	v_mov_b32_e32 v73, v69
	v_mov_b32_e32 v74, v64
	v_mov_b32_e32 v75, v68
	v_pk_mul_f32 v[72:73], v[72:73], v[74:75]
	v_pk_mul_f32 v[54:55], v[62:63], v[54:55]
	v_mul_f32_e32 v74, v72, v73
	v_rcp_f32_e32 v74, v74
	v_pk_mul_f32 v[52:53], v[60:61], v[52:53]
	v_mul_f32_e32 v60, v73, v74
	v_mul_f32_e32 v62, v72, v74
	v_pk_mul_f32 v[62:63], v[68:69], v[62:63] op_sel_hi:[1,0]
	v_pk_mul_f32 v[60:61], v[64:65], v[60:61] op_sel_hi:[1,0]
	v_pk_mul_f32 v[58:59], v[58:59], v[62:63]
	v_pk_mul_f32 v[56:57], v[56:57], v[60:61]
	v_pk_mul_f32 v[58:59], v[58:59], v[50:51]
	v_pk_mul_f32 v[50:51], v[56:57], v[48:49]
	v_cvt_pk_bf16_f32 v48, v52, v53
	v_cvt_pk_bf16_f32 v49, v54, v55
	v_max_f32_e32 v52, v44, v44
	v_max_f32_e32 v54, v46, v46
	v_max_f32_e32 v52, 0xc1a00000, v52
	v_max_f32_e32 v54, 0xc1a00000, v54
	v_mul_f32_e32 v52, 0xbfb8aa3b, v52
	v_mul_f32_e32 v54, 0xbfb8aa3b, v54
	v_exp_f32_e32 v53, v52
	v_max_f32_e32 v52, v45, v45
	v_exp_f32_e32 v55, v54
	v_max_f32_e32 v54, v47, v47
	v_max_f32_e32 v52, 0xc1a00000, v52
; __device__ __forceinline__ unsigned cvt_pk_bf16(float lo, float hi) { unsigned r; asm volatile("v_cvt_pk_bf16_f32 %0, %1, %2" : "=v"(r) : "v"(lo), "v"(hi)); return r; }
;     __device__ __forceinline__ void operator()(const f32x4 (&acc)[2][2][4][2], const Unit& u, int wr, int wc, int fr, int fq) const {
;         const int row0 = u.pm * BM + wr * 64 + fr, col0 = u.pn * HALF + wc * 32 + 8 * fq;
; #pragma unroll
;         for (int ai = 0; ai < 2; ++ai)
; #pragma unroll
;             for (int m = 0; m < 4; ++m) { bf16_t* rowp = O + (size_t)(row0 + ai * HALF + m * 16) * ldc + col0;
;                 f32x4 v0, v1;
; #pragma unroll
;                 for (int j = 0; j < 1; ++j) { v0 = acc[ai][0][m][0] * sigmoid4(acc[ai][0][m][0]) * acc[ai][1][m][0]; v1 = acc[ai][0][m][1] * sigmoid4(acc[ai][0][m][1]) * acc[ai][1][m][1]; }
;                 u32x4 w; w.x = cvt_pk_bf16(v0[0], v0[1]); w.y = cvt_pk_bf16(v0[2], v0[3]); w.z = cvt_pk_bf16(v1[0], v1[1]); w.w = cvt_pk_bf16(v1[2], v1[3]);
;                 *(u32x4*)rowp = w; }
	v_max_f32_e32 v54, 0xc1a00000, v54
	v_mul_f32_e32 v52, 0xbfb8aa3b, v52
	v_mul_f32_e32 v54, 0xbfb8aa3b, v54
	v_exp_f32_e32 v52, v52
	v_exp_f32_e32 v54, v54
	v_cvt_pk_bf16_f32 v50, v50, v51
	v_cvt_pk_bf16_f32 v51, v58, v59
	global_store_dwordx4 v[70:71], v[48:51], off
	v_add_u32_e32 v56, 0x90, v154
	s_nop 0
	v_pk_add_f32 v[48:49], v[52:53], 1.0 op_sel_hi:[1,0]
	v_pk_add_f32 v[50:51], v[54:55], 1.0 op_sel_hi:[1,0]
	v_mov_b32_e32 v52, v49
	v_mov_b32_e32 v53, v51
	v_mov_b32_e32 v54, v48
	v_mov_b32_e32 v55, v50
	v_pk_mul_f32 v[52:53], v[52:53], v[54:55]
	s_nop 0
	v_mul_f32_e32 v54, v52, v53
	v_rcp_f32_e32 v57, v54
	v_mad_i64_i32 v[54:55], s[16:17], v56, s40, v[144:145]
	v_lshl_add_u64 v[54:55], v[54:55], 0, v[146:147]
	v_mul_f32_e32 v52, v52, v57
	v_mul_f32_e32 v56, v53, v57
	v_pk_mul_f32 v[50:51], v[50:51], v[52:53] op_sel_hi:[1,0]
	v_max_f32_e32 v52, v40, v40
	v_max_f32_e32 v57, v42, v42
	v_max_f32_e32 v52, 0xc1a00000, v52
	v_max_f32_e32 v57, 0xc1a00000, v57
	v_mul_f32_e32 v52, 0xbfb8aa3b, v52
	v_mul_f32_e32 v57, 0xbfb8aa3b, v57
	v_exp_f32_e32 v53, v52
	v_max_f32_e32 v52, v41, v41
	v_exp_f32_e32 v59, v57
	v_max_f32_e32 v57, v43, v43
	v_max_f32_e32 v52, 0xc1a00000, v52
	v_max_f32_e32 v57, 0xc1a00000, v57
	v_mul_f32_e32 v52, 0xbfb8aa3b, v52
	v_mul_f32_e32 v57, 0xbfb8aa3b, v57
	v_exp_f32_e32 v52, v52
	v_exp_f32_e32 v58, v57
	v_pk_mul_f32 v[48:49], v[48:49], v[56:57] op_sel_hi:[1,0]
	v_pk_mul_f32 v[46:47], v[46:47], v[50:51]
	v_pk_mul_f32 v[44:45], v[44:45], v[48:49]
	v_pk_add_f32 v[48:49], v[52:53], 1.0 op_sel_hi:[1,0]
	v_pk_add_f32 v[52:53], v[58:59], 1.0 op_sel_hi:[1,0]
	v_mov_b32_e32 v56, v49
	v_mov_b32_e32 v57, v53
	v_mov_b32_e32 v58, v48
	v_mov_b32_e32 v59, v52
	v_pk_mul_f32 v[56:57], v[56:57], v[58:59]
	v_pk_mul_f32 v[38:39], v[46:47], v[38:39]
	v_mul_f32_e32 v58, v56, v57
	v_rcp_f32_e32 v58, v58
	v_pk_mul_f32 v[36:37], v[44:45], v[36:37]
	v_mul_f32_e32 v44, v57, v58
	v_mul_f32_e32 v46, v56, v58
	v_pk_mul_f32 v[46:47], v[52:53], v[46:47] op_sel_hi:[1,0]
	v_pk_mul_f32 v[44:45], v[48:49], v[44:45] op_sel_hi:[1,0]
	v_pk_mul_f32 v[42:43], v[42:43], v[46:47]
	v_pk_mul_f32 v[40:41], v[40:41], v[44:45]
	v_pk_mul_f32 v[42:43], v[42:43], v[34:35]
	v_pk_mul_f32 v[34:35], v[40:41], v[32:33]
	v_cvt_pk_bf16_f32 v32, v36, v37
	v_cvt_pk_bf16_f32 v33, v38, v39
	v_max_f32_e32 v36, v28, v28
	v_max_f32_e32 v38, v30, v30
	v_max_f32_e32 v36, 0xc1a00000, v36
	v_max_f32_e32 v38, 0xc1a00000, v38
	v_mul_f32_e32 v36, 0xbfb8aa3b, v36
	v_mul_f32_e32 v38, 0xbfb8aa3b, v38
	v_exp_f32_e32 v37, v36
	v_max_f32_e32 v36, v29, v29
	v_exp_f32_e32 v39, v38
	v_max_f32_e32 v38, v31, v31
	v_max_f32_e32 v36, 0xc1a00000, v36
	v_max_f32_e32 v38, 0xc1a00000, v38
	v_mul_f32_e32 v36, 0xbfb8aa3b, v36
	v_mul_f32_e32 v38, 0xbfb8aa3b, v38
	v_exp_f32_e32 v36, v36
	v_exp_f32_e32 v38, v38
	v_cvt_pk_bf16_f32 v34, v34, v35
	v_cvt_pk_bf16_f32 v35, v42, v43
	global_store_dwordx4 v[54:55], v[32:35], off
	v_add_u32_e32 v40, 0xa0, v154
	s_nop 0
	v_pk_add_f32 v[32:33], v[36:37], 1.0 op_sel_hi:[1,0]
	v_pk_add_f32 v[34:35], v[38:39], 1.0 op_sel_hi:[1,0]
	v_mov_b32_e32 v36, v33
	v_mov_b32_e32 v37, v35
	v_mov_b32_e32 v38, v32
	v_mov_b32_e32 v39, v34
	v_pk_mul_f32 v[36:37], v[36:37], v[38:39]
	s_nop 0
	v_mul_f32_e32 v38, v36, v37
	v_rcp_f32_e32 v41, v38
	v_mad_i64_i32 v[38:39], s[16:17], v40, s40, v[144:145]
	v_lshl_add_u64 v[38:39], v[38:39], 0, v[146:147]
	v_mul_f32_e32 v36, v36, v41
	v_mul_f32_e32 v40, v37, v41
	v_pk_mul_f32 v[34:35], v[34:35], v[36:37] op_sel_hi:[1,0]
	v_max_f32_e32 v36, v24, v24
	v_max_f32_e32 v41, v26, v26
	v_max_f32_e32 v36, 0xc1a00000, v36
	v_max_f32_e32 v41, 0xc1a00000, v41
	v_mul_f32_e32 v36, 0xbfb8aa3b, v36
	v_mul_f32_e32 v41, 0xbfb8aa3b, v41
	v_exp_f32_e32 v37, v36
	v_max_f32_e32 v36, v25, v25
	v_exp_f32_e32 v43, v41
	v_max_f32_e32 v41, v27, v27
	v_max_f32_e32 v36, 0xc1a00000, v36
	v_max_f32_e32 v41, 0xc1a00000, v41
	v_mul_f32_e32 v36, 0xbfb8aa3b, v36
; __device__ __forceinline__ unsigned cvt_pk_bf16(float lo, float hi) { unsigned r; asm volatile("v_cvt_pk_bf16_f32 %0, %1, %2" : "=v"(r) : "v"(lo), "v"(hi)); return r; }
; #define PG8_WAIT_V(n) asm volatile("s_waitcnt vmcnt(" #n ")" ::: "memory")
; #define PG8_BAR __builtin_amdgcn_s_barrier()
;     __device__ __forceinline__ void operator()(const f32x4 (&acc)[2][2][4][2], const Unit& u, int wr, int wc, int fr, int fq) const {
;         const int row0 = u.pm * BM + wr * 64 + fr, col0 = u.pn * HALF + wc * 32 + 8 * fq;
; #pragma unroll
;         for (int ai = 0; ai < 2; ++ai)
; #pragma unroll
;             for (int m = 0; m < 4; ++m) { bf16_t* rowp = O + (size_t)(row0 + ai * HALF + m * 16) * ldc + col0;
;                 f32x4 v0, v1;
; #pragma unroll
;                 for (int j = 0; j < 1; ++j) { v0 = acc[ai][0][m][0] * sigmoid4(acc[ai][0][m][0]) * acc[ai][1][m][0]; v1 = acc[ai][0][m][1] * sigmoid4(acc[ai][0][m][1]) * acc[ai][1][m][1]; }
;                 u32x4 w; w.x = cvt_pk_bf16(v0[0], v0[1]); w.y = cvt_pk_bf16(v0[2], v0[3]); w.z = cvt_pk_bf16(v1[0], v1[1]); w.w = cvt_pk_bf16(v1[2], v1[3]);
;                 *(u32x4*)rowp = w; }
; template <class Epi, class Sched>
; __device__ __forceinline__ void gemm_phase(PG8_LAS unsigned char* lds, const Gemm g, const Sched& S, const Epi& E) {
;     ...
;     PG8_WAIT_V(0);
;     if (wr == 0) PG8_BAR;
;     PG8_BAR;
	v_mul_f32_e32 v41, 0xbfb8aa3b, v41
	v_exp_f32_e32 v36, v36
	v_exp_f32_e32 v42, v41
	v_pk_mul_f32 v[32:33], v[32:33], v[40:41] op_sel_hi:[1,0]
	v_pk_mul_f32 v[30:31], v[30:31], v[34:35]
	v_pk_mul_f32 v[28:29], v[28:29], v[32:33]
	v_pk_add_f32 v[32:33], v[36:37], 1.0 op_sel_hi:[1,0]
	v_pk_add_f32 v[36:37], v[42:43], 1.0 op_sel_hi:[1,0]
	v_mov_b32_e32 v40, v33
	v_mov_b32_e32 v41, v37
	v_mov_b32_e32 v42, v32
	v_mov_b32_e32 v43, v36
	v_pk_mul_f32 v[40:41], v[40:41], v[42:43]
	v_pk_mul_f32 v[22:23], v[30:31], v[22:23]
	v_mul_f32_e32 v42, v40, v41
	v_rcp_f32_e32 v42, v42
	v_pk_mul_f32 v[20:21], v[28:29], v[20:21]
	v_mul_f32_e32 v28, v41, v42
	v_mul_f32_e32 v30, v40, v42
	v_pk_mul_f32 v[30:31], v[36:37], v[30:31] op_sel_hi:[1,0]
	v_pk_mul_f32 v[28:29], v[32:33], v[28:29] op_sel_hi:[1,0]
	v_pk_mul_f32 v[26:27], v[26:27], v[30:31]
	v_pk_mul_f32 v[24:25], v[24:25], v[28:29]
	v_pk_mul_f32 v[26:27], v[26:27], v[18:19]
	v_pk_mul_f32 v[18:19], v[24:25], v[16:17]
	v_cvt_pk_bf16_f32 v16, v20, v21
	v_cvt_pk_bf16_f32 v17, v22, v23
	v_max_f32_e32 v20, v12, v12
	v_max_f32_e32 v22, v14, v14
	v_max_f32_e32 v20, 0xc1a00000, v20
	v_max_f32_e32 v22, 0xc1a00000, v22
	v_mul_f32_e32 v20, 0xbfb8aa3b, v20
	v_mul_f32_e32 v22, 0xbfb8aa3b, v22
	v_exp_f32_e32 v21, v20
	v_max_f32_e32 v20, v13, v13
	v_exp_f32_e32 v23, v22
	v_max_f32_e32 v22, v15, v15
	v_max_f32_e32 v20, 0xc1a00000, v20
	v_max_f32_e32 v22, 0xc1a00000, v22
	v_mul_f32_e32 v20, 0xbfb8aa3b, v20
	v_mul_f32_e32 v22, 0xbfb8aa3b, v22
	v_exp_f32_e32 v20, v20
	v_exp_f32_e32 v22, v22
	v_cvt_pk_bf16_f32 v18, v18, v19
	v_cvt_pk_bf16_f32 v19, v26, v27
	global_store_dwordx4 v[38:39], v[16:19], off
	v_add_u32_e32 v24, 0xb0, v154
	s_nop 0
	v_pk_add_f32 v[16:17], v[20:21], 1.0 op_sel_hi:[1,0]
	v_pk_add_f32 v[18:19], v[22:23], 1.0 op_sel_hi:[1,0]
	v_mov_b32_e32 v20, v17
	v_mov_b32_e32 v21, v19
	v_mov_b32_e32 v22, v16
	v_mov_b32_e32 v23, v18
	v_pk_mul_f32 v[20:21], v[20:21], v[22:23]
	s_nop 0
	v_mul_f32_e32 v22, v20, v21
	v_rcp_f32_e32 v25, v22
	v_mad_i64_i32 v[22:23], s[16:17], v24, s40, v[144:145]
	v_lshl_add_u64 v[22:23], v[22:23], 0, v[146:147]
	v_mul_f32_e32 v20, v20, v25
	v_mul_f32_e32 v24, v21, v25
	v_pk_mul_f32 v[18:19], v[18:19], v[20:21] op_sel_hi:[1,0]
	v_max_f32_e32 v20, v8, v8
	v_max_f32_e32 v25, v10, v10
	v_max_f32_e32 v20, 0xc1a00000, v20
	v_max_f32_e32 v25, 0xc1a00000, v25
	v_mul_f32_e32 v20, 0xbfb8aa3b, v20
	v_mul_f32_e32 v25, 0xbfb8aa3b, v25
	v_exp_f32_e32 v21, v20
	v_max_f32_e32 v20, v9, v9
	v_exp_f32_e32 v27, v25
	v_max_f32_e32 v25, v11, v11
	v_max_f32_e32 v20, 0xc1a00000, v20
	v_max_f32_e32 v25, 0xc1a00000, v25
	v_mul_f32_e32 v20, 0xbfb8aa3b, v20
	v_mul_f32_e32 v25, 0xbfb8aa3b, v25
	v_exp_f32_e32 v20, v20
	v_exp_f32_e32 v26, v25
	v_pk_mul_f32 v[16:17], v[16:17], v[24:25] op_sel_hi:[1,0]
	v_pk_mul_f32 v[14:15], v[14:15], v[18:19]
	v_pk_mul_f32 v[12:13], v[12:13], v[16:17]
	v_pk_add_f32 v[16:17], v[20:21], 1.0 op_sel_hi:[1,0]
	v_pk_add_f32 v[20:21], v[26:27], 1.0 op_sel_hi:[1,0]
	v_mov_b32_e32 v24, v17
	v_mov_b32_e32 v25, v21
	v_mov_b32_e32 v26, v16
	v_mov_b32_e32 v27, v20
	v_pk_mul_f32 v[24:25], v[24:25], v[26:27]
	v_pk_mul_f32 v[6:7], v[14:15], v[6:7]
	v_mul_f32_e32 v26, v24, v25
	v_rcp_f32_e32 v26, v26
	v_pk_mul_f32 v[4:5], v[12:13], v[4:5]
	s_mov_b64 s[16:17], s[10:11]
	v_mul_f32_e32 v12, v25, v26
	v_mul_f32_e32 v14, v24, v26
	v_pk_mul_f32 v[14:15], v[20:21], v[14:15] op_sel_hi:[1,0]
	v_pk_mul_f32 v[12:13], v[16:17], v[12:13] op_sel_hi:[1,0]
	v_pk_mul_f32 v[10:11], v[10:11], v[14:15]
	v_pk_mul_f32 v[8:9], v[8:9], v[12:13]
	v_pk_mul_f32 v[10:11], v[10:11], v[2:3]
	v_pk_mul_f32 v[2:3], v[8:9], v[0:1]
	v_cvt_pk_bf16_f32 v0, v4, v5
	v_cvt_pk_bf16_f32 v1, v6, v7
	s_nop 0
	v_cvt_pk_bf16_f32 v2, v2, v3
	v_cvt_pk_bf16_f32 v3, v10, v11
	global_store_dwordx4 v[22:23], v[0:3], off
	s_cbranch_vccz .LBB0_1199
	s_waitcnt vmcnt(0)
	s_cmpk_gt_u32 s23, 0xff
	s_cbranch_scc1 .LBB0_1206
	s_barrier

; #define PG8_STAGE(bufoff, gbase, voff) do { _Pragma("unroll") for (int _i = 0; _i < 2; ++_i) \
;         __builtin_amdgcn_global_load_lds((const unsigned*)((const char*)(gbase) + (voff)[_i]), (PG8_LAS unsigned*)(lds + (bufoff) + ldsw + _i * 8192), 16, 0, 0); } while (0)
; #define PG8_LDA(dst, b, h) do { _Pragma("unroll") for (int m = 0; m < 4; ++m) _Pragma("unroll") for (int k = 0; k < 2; ++k) dst[m][k] = *(const PG8_LAS bf16x8*)(lds + PG8_SA(b, h) + aoff + m * 2048 + k * 1024); } while (0)
; #define PG8_LDB(dst, b, h) do { _Pragma("unroll") for (int n = 0; n < 2; ++n) _Pragma("unroll") for (int k = 0; k < 2; ++k) dst[n][k] = *(const PG8_LAS bf16x8*)(lds + PG8_SB(b, h) + boff + n * 2048 + k * 1024); } while (0)
; #define PG8_MMA(ai, bj, At, Bt) do { __builtin_amdgcn_s_setprio(1); _Pragma("unroll") for (int m = 0; m < 4; ++m) _Pragma("unroll") for (int n = 0; n < 2; ++n) _Pragma("unroll") for (int k = 0; k < 2; ++k) \
;         acc[ai][bj][m][n] = __builtin_amdgcn_mfma_f32_16x16x32_bf16(Bt[n][k], At[m][k], acc[ai][bj][m][n], 0, 0, 0); __builtin_amdgcn_s_setprio(0); } while (0)
; #define PG8_WAIT_L(n) asm volatile("s_waitcnt lgkmcnt(" #n ")" ::: "memory")
; #define PG8_BAR __builtin_amdgcn_s_barrier()
; #define PG8_SCHED __builtin_amdgcn_sched_barrier(0)
; template <class Epi, class Sched>
; __device__ __forceinline__ void gemm_phase(PG8_LAS unsigned char* lds, const Gemm g, const Sched& S, const Epi& E) {
;     ...
;             PG8_LDB(B0, 0, 0); PG8_SCHED; PG8_LDA(At, 0, 0); PG8_STAGE(PG8_SA(1, 1), a1 + hstep, voffA);
;             PG8_WAIT_L(8); PG8_BAR; PG8_WAIT_L(0); PG8_MMA(0, 0, At, B0); PG8_BAR; PG8_SCHED;
;             PG8_LDB(B1, 0, 1); PG8_STAGE(PG8_SB(0, 0), b2, voffB);
;             PG8_BAR; PG8_WAIT_L(0); PG8_MMA(0, 1, At, B1); PG8_BAR;
;             PG8_LDA(At, 0, 1); PG8_STAGE(PG8_SA(0, 0), a2, voffA);
;             PG8_BAR; PG8_WAIT_L(0); PG8_MMA(1, 0, At, B0); PG8_BAR; PG8_SCHED;
.LBB0_1278:
	ds_read_b128 v[152:155], v149
	ds_read_b128 v[156:159], v149 offset:1024
	ds_read_b128 v[160:163], v149 offset:2048
	ds_read_b128 v[164:167], v149 offset:3072
	s_add_u32 s20, s18, 0x100
	s_addc_u32 s21, s19, 0
	s_cmp_eq_u32 s54, 40
	s_cselect_b32 s25, s1, s21
	s_cselect_b32 s24, s0, s20
	s_cselect_b32 s23, s5, s53
	s_cselect_b32 s22, s4, s52
	v_lshl_add_u64 v[144:145], s[18:19], 0, v[136:137]
	s_add_i32 m0, s34, 0xc000
	ds_read_b128 v[168:171], v150
	ds_read_b128 v[172:175], v150 offset:1024
	ds_read_b128 v[182:185], v150 offset:2048
	ds_read_b128 v[190:193], v150 offset:3072
	ds_read_b128 v[194:197], v150 offset:4096
	ds_read_b128 v[198:201], v150 offset:5120
	ds_read_b128 v[202:205], v150 offset:6144
	ds_read_b128 v[206:209], v150 offset:7168
	global_load_lds_dwordx4 v[144:145], off
	v_lshl_add_u64 v[144:145], s[18:19], 0, v[138:139]
	s_add_i32 m0, s34, 0xe000
	s_nop 0
	global_load_lds_dwordx4 v[144:145], off
	s_waitcnt lgkmcnt(8)
	s_barrier
	s_waitcnt lgkmcnt(0)
	v_mfma_f32_16x16x32_bf16 v[124:127], v[152:155], v[168:171], v[124:127]
	v_mfma_f32_16x16x32_bf16 v[120:123], v[160:163], v[168:171], v[120:123]
	v_mfma_f32_16x16x32_bf16 v[108:111], v[152:155], v[182:185], v[108:111]
	v_mfma_f32_16x16x32_bf16 v[104:107], v[160:163], v[182:185], v[104:107]
	v_mfma_f32_16x16x32_bf16 v[92:95], v[152:155], v[194:197], v[92:95]
	v_mfma_f32_16x16x32_bf16 v[88:91], v[160:163], v[194:197], v[88:91]
	v_mfma_f32_16x16x32_bf16 v[76:79], v[152:155], v[202:205], v[76:79]
	v_mfma_f32_16x16x32_bf16 v[72:75], v[160:163], v[202:205], v[72:75]
	v_mfma_f32_16x16x32_bf16 v[124:127], v[156:159], v[172:175], v[124:127]
	v_mfma_f32_16x16x32_bf16 v[120:123], v[164:167], v[172:175], v[120:123]
	v_mfma_f32_16x16x32_bf16 v[108:111], v[156:159], v[190:193], v[108:111]
	v_mfma_f32_16x16x32_bf16 v[104:107], v[164:167], v[190:193], v[104:107]
	v_mfma_f32_16x16x32_bf16 v[92:95], v[156:159], v[198:201], v[92:95]
	v_mfma_f32_16x16x32_bf16 v[88:91], v[164:167], v[198:201], v[88:91]
	v_mfma_f32_16x16x32_bf16 v[76:79], v[156:159], v[206:209], v[76:79]
	v_mfma_f32_16x16x32_bf16 v[72:75], v[164:167], v[206:209], v[72:75]
	s_barrier
	s_add_i32 s18, s42, s31
	v_lshl_add_u64 v[144:145], s[22:23], 0, v[130:131]
	s_mov_b32 m0, s18
	ds_read_b128 v[210:213], v151
	ds_read_b128 v[214:217], v151 offset:1024
	ds_read_b128 v[218:221], v151 offset:2048
	ds_read_b128 v[222:225], v151 offset:3072
	global_load_lds_dwordx4 v[144:145], off
	v_lshl_add_u64 v[186:187], s[22:23], 0, v[134:135]
	s_add_i32 m0, s18, 0x2000
	s_nop 0
	global_load_lds_dwordx4 v[186:187], off
	s_barrier
	s_waitcnt lgkmcnt(0)
	v_mfma_f32_16x16x32_bf16 v[116:119], v[210:213], v[168:171], v[116:119]
	v_mfma_f32_16x16x32_bf16 v[112:115], v[218:221], v[168:171], v[112:115]
	v_mfma_f32_16x16x32_bf16 v[100:103], v[210:213], v[182:185], v[100:103]
	v_mfma_f32_16x16x32_bf16 v[96:99], v[218:221], v[182:185], v[96:99]
	v_mfma_f32_16x16x32_bf16 v[84:87], v[210:213], v[194:197], v[84:87]
	v_mfma_f32_16x16x32_bf16 v[80:83], v[218:221], v[194:197], v[80:83]
	v_mfma_f32_16x16x32_bf16 v[68:71], v[210:213], v[202:205], v[68:71]
	v_mfma_f32_16x16x32_bf16 v[64:67], v[218:221], v[202:205], v[64:67]
	v_mfma_f32_16x16x32_bf16 v[116:119], v[214:217], v[172:175], v[116:119]
	v_mfma_f32_16x16x32_bf16 v[112:115], v[222:225], v[172:175], v[112:115]
	v_mfma_f32_16x16x32_bf16 v[100:103], v[214:217], v[190:193], v[100:103]
	v_mfma_f32_16x16x32_bf16 v[96:99], v[222:225], v[190:193], v[96:99]
	v_mfma_f32_16x16x32_bf16 v[84:87], v[214:217], v[198:201], v[84:87]
	v_mfma_f32_16x16x32_bf16 v[80:83], v[222:225], v[198:201], v[80:83]
	v_mfma_f32_16x16x32_bf16 v[68:71], v[214:217], v[206:209], v[68:71]
	v_mfma_f32_16x16x32_bf16 v[64:67], v[222:225], v[206:209], v[64:67]
	s_barrier
	s_mov_b32 m0, s34
	v_lshl_add_u64 v[226:227], s[24:25], 0, v[128:129]
	ds_read_b128 v[168:171], v150 offset:16384
	ds_read_b128 v[172:175], v150 offset:17408
	ds_read_b128 v[182:185], v150 offset:18432
	ds_read_b128 v[190:193], v150 offset:19456
	ds_read_b128 v[194:197], v150 offset:20480
	ds_read_b128 v[198:201], v150 offset:21504
	ds_read_b128 v[202:205], v150 offset:22528
	ds_read_b128 v[206:209], v150 offset:23552
	global_load_lds_dwordx4 v[226:227], off
	v_lshl_add_u64 v[228:229], s[24:25], 0, v[132:133]
	s_mov_b32 m0, s35
	s_nop 0
	global_load_lds_dwordx4 v[228:229], off
	s_barrier
	s_waitcnt lgkmcnt(0)
	v_mfma_f32_16x16x32_bf16 v[60:63], v[152:155], v[168:171], v[60:63]
	v_mfma_f32_16x16x32_bf16 v[56:59], v[160:163], v[168:171], v[56:59]
	v_mfma_f32_16x16x32_bf16 v[48:51], v[152:155], v[182:185], v[48:51]
	v_mfma_f32_16x16x32_bf16 v[40:43], v[160:163], v[182:185], v[40:43]
	v_mfma_f32_16x16x32_bf16 v[32:35], v[152:155], v[194:197], v[32:35]
	v_mfma_f32_16x16x32_bf16 v[24:27], v[160:163], v[194:197], v[24:27]
	v_mfma_f32_16x16x32_bf16 v[16:19], v[152:155], v[202:205], v[16:19]
	v_mfma_f32_16x16x32_bf16 v[8:11], v[160:163], v[202:205], v[8:11]
	v_mfma_f32_16x16x32_bf16 v[60:63], v[156:159], v[172:175], v[60:63]
	v_mfma_f32_16x16x32_bf16 v[56:59], v[164:167], v[172:175], v[56:59]
	v_mfma_f32_16x16x32_bf16 v[48:51], v[156:159], v[190:193], v[48:51]
	v_mfma_f32_16x16x32_bf16 v[40:43], v[164:167], v[190:193], v[40:43]
	v_mfma_f32_16x16x32_bf16 v[32:35], v[156:159], v[198:201], v[32:35]
	v_mfma_f32_16x16x32_bf16 v[24:27], v[164:167], v[198:201], v[24:27]
	v_mfma_f32_16x16x32_bf16 v[16:19], v[156:159], v[206:209], v[16:19]
	v_mfma_f32_16x16x32_bf16 v[8:11], v[164:167], v[206:209], v[8:11]
	s_barrier
; #define PG8_STAGE(bufoff, gbase, voff) do { _Pragma("unroll") for (int _i = 0; _i < 2; ++_i) \
;         __builtin_amdgcn_global_load_lds((const unsigned*)((const char*)(gbase) + (voff)[_i]), (PG8_LAS unsigned*)(lds + (bufoff) + ldsw + _i * 8192), 16, 0, 0); } while (0)
; #define PG8_LDA(dst, b, h) do { _Pragma("unroll") for (int m = 0; m < 4; ++m) _Pragma("unroll") for (int k = 0; k < 2; ++k) dst[m][k] = *(const PG8_LAS bf16x8*)(lds + PG8_SA(b, h) + aoff + m * 2048 + k * 1024); } while (0)
; #define PG8_LDB(dst, b, h) do { _Pragma("unroll") for (int n = 0; n < 2; ++n) _Pragma("unroll") for (int k = 0; k < 2; ++k) dst[n][k] = *(const PG8_LAS bf16x8*)(lds + PG8_SB(b, h) + boff + n * 2048 + k * 1024); } while (0)
; #define PG8_MMA(ai, bj, At, Bt) do { __builtin_amdgcn_s_setprio(1); _Pragma("unroll") for (int m = 0; m < 4; ++m) _Pragma("unroll") for (int n = 0; n < 2; ++n) _Pragma("unroll") for (int k = 0; k < 2; ++k) \
;         acc[ai][bj][m][n] = __builtin_amdgcn_mfma_f32_16x16x32_bf16(Bt[n][k], At[m][k], acc[ai][bj][m][n], 0, 0, 0); __builtin_amdgcn_s_setprio(0); } while (0)
; #define PG8_WAIT_V(n) asm volatile("s_waitcnt vmcnt(" #n ")" ::: "memory")
; #define PG8_WAIT_L(n) asm volatile("s_waitcnt lgkmcnt(" #n ")" ::: "memory")
; #define PG8_BAR __builtin_amdgcn_s_barrier()
; #define PG8_SCHED __builtin_amdgcn_sched_barrier(0)
; template <class Epi, class Sched>
; __device__ __forceinline__ void gemm_phase(PG8_LAS unsigned char* lds, const Gemm g, const Sched& S, const Epi& E) {
;     ...
;             PG8_STAGE(PG8_SB(0, 1), b2 + hstep, voffB);
;             PG8_WAIT_V(6); PG8_BAR; PG8_MMA(1, 1, At, B1); PG8_BAR;
;             PG8_LDB(B0, 1, 0); PG8_SCHED; PG8_LDA(At, 1, 0); PG8_STAGE(PG8_SA(0, 1), a2 + hstep, voffA);
;             PG8_WAIT_L(8); PG8_BAR; PG8_WAIT_L(0); PG8_MMA(0, 0, At, B0); PG8_BAR; PG8_SCHED;
;             PG8_LDB(B1, 1, 1); PG8_STAGE(PG8_SB(1, 0), b3, voffB);
;             PG8_BAR; PG8_WAIT_L(0); PG8_MMA(0, 1, At, B1); PG8_BAR;
;             PG8_LDA(At, 1, 1); PG8_STAGE(PG8_SA(1, 0), a3, voffA);
;             PG8_BAR; PG8_WAIT_L(0); PG8_MMA(1, 0, At, B0); PG8_BAR; PG8_SCHED;
	s_add_u32 s18, s22, 0xb0000
	s_addc_u32 s19, s23, 0
	s_add_i32 s55, s43, s31
	v_lshl_add_u64 v[152:153], s[18:19], 0, v[130:131]
	s_mov_b32 m0, s55
	s_nop 0
	global_load_lds_dwordx4 v[152:153], off
	v_lshl_add_u64 v[152:153], s[18:19], 0, v[134:135]
	s_add_i32 m0, s55, 0x2000
	s_nop 0
	global_load_lds_dwordx4 v[152:153], off
	s_waitcnt vmcnt(6)
	s_barrier
	v_mfma_f32_16x16x32_bf16 v[52:55], v[210:213], v[168:171], v[52:55]
	v_mfma_f32_16x16x32_bf16 v[44:47], v[218:221], v[168:171], v[44:47]
	v_mfma_f32_16x16x32_bf16 v[36:39], v[210:213], v[182:185], v[36:39]
	v_mfma_f32_16x16x32_bf16 v[28:31], v[218:221], v[182:185], v[28:31]
	v_mfma_f32_16x16x32_bf16 v[20:23], v[210:213], v[194:197], v[20:23]
	v_mfma_f32_16x16x32_bf16 v[12:15], v[218:221], v[194:197], v[12:15]
	v_mfma_f32_16x16x32_bf16 v[4:7], v[210:213], v[202:205], v[4:7]
	v_mfma_f32_16x16x32_bf16 v[0:3], v[218:221], v[202:205], v[0:3]
	v_mfma_f32_16x16x32_bf16 v[52:55], v[214:217], v[172:175], v[52:55]
	v_mfma_f32_16x16x32_bf16 v[44:47], v[222:225], v[172:175], v[44:47]
	v_mfma_f32_16x16x32_bf16 v[36:39], v[214:217], v[190:193], v[36:39]
	v_mfma_f32_16x16x32_bf16 v[28:31], v[222:225], v[190:193], v[28:31]
	v_mfma_f32_16x16x32_bf16 v[20:23], v[214:217], v[198:201], v[20:23]
	v_mfma_f32_16x16x32_bf16 v[12:15], v[222:225], v[198:201], v[12:15]
	v_mfma_f32_16x16x32_bf16 v[4:7], v[214:217], v[206:209], v[4:7]
	v_mfma_f32_16x16x32_bf16 v[0:3], v[222:225], v[206:209], v[0:3]
	s_barrier
	s_add_i32 s55, 0, 0x18000
	v_add_u32_e32 v164, s55, v147
	ds_read_b128 v[152:155], v164
	ds_read_b128 v[156:159], v164 offset:1024
	ds_read_b128 v[160:163], v164 offset:2048
	ds_read_b128 v[164:167], v164 offset:3072
	s_add_u32 s18, s24, 0xb0000
	s_addc_u32 s19, s25, 0
	s_mov_b32 m0, s36
	v_lshl_add_u64 v[210:211], s[18:19], 0, v[128:129]
	ds_read_b128 v[168:171], v150 offset:32768
	ds_read_b128 v[172:175], v150 offset:33792
	ds_read_b128 v[182:185], v150 offset:34816
	ds_read_b128 v[190:193], v150 offset:35840
	ds_read_b128 v[194:197], v150 offset:36864
	ds_read_b128 v[198:201], v150 offset:37888
	ds_read_b128 v[202:205], v150 offset:38912
	ds_read_b128 v[206:209], v150 offset:39936
	global_load_lds_dwordx4 v[210:211], off
	v_lshl_add_u64 v[210:211], s[18:19], 0, v[132:133]
	s_mov_b32 m0, s37
	s_nop 0
	global_load_lds_dwordx4 v[210:211], off
	s_waitcnt lgkmcnt(8)
	s_barrier
	s_waitcnt lgkmcnt(0)
	v_mfma_f32_16x16x32_bf16 v[124:127], v[152:155], v[168:171], v[124:127]
	v_mfma_f32_16x16x32_bf16 v[120:123], v[160:163], v[168:171], v[120:123]
	v_mfma_f32_16x16x32_bf16 v[108:111], v[152:155], v[182:185], v[108:111]
	v_mfma_f32_16x16x32_bf16 v[104:107], v[160:163], v[182:185], v[104:107]
	v_mfma_f32_16x16x32_bf16 v[92:95], v[152:155], v[194:197], v[92:95]
	v_mfma_f32_16x16x32_bf16 v[88:91], v[160:163], v[194:197], v[88:91]
	v_mfma_f32_16x16x32_bf16 v[76:79], v[152:155], v[202:205], v[76:79]
	v_mfma_f32_16x16x32_bf16 v[72:75], v[160:163], v[202:205], v[72:75]
	v_mfma_f32_16x16x32_bf16 v[124:127], v[156:159], v[172:175], v[124:127]
	v_mfma_f32_16x16x32_bf16 v[120:123], v[164:167], v[172:175], v[120:123]
	v_mfma_f32_16x16x32_bf16 v[108:111], v[156:159], v[190:193], v[108:111]
	v_mfma_f32_16x16x32_bf16 v[104:107], v[164:167], v[190:193], v[104:107]
	v_mfma_f32_16x16x32_bf16 v[92:95], v[156:159], v[198:201], v[92:95]
	v_mfma_f32_16x16x32_bf16 v[88:91], v[164:167], v[198:201], v[88:91]
	v_mfma_f32_16x16x32_bf16 v[76:79], v[156:159], v[206:209], v[76:79]
	v_mfma_f32_16x16x32_bf16 v[72:75], v[164:167], v[206:209], v[72:75]
	s_barrier
	s_add_i32 s24, 0, 0x1c000
	s_add_i32 s18, s55, s31
	v_add_u32_e32 v179, s24, v147
	v_lshl_add_u64 v[144:145], v[144:145], 0, s[8:9]
	s_mov_b32 m0, s18
	ds_read_b128 v[210:213], v179
	ds_read_b128 v[214:217], v179 offset:1024
	ds_read_b128 v[218:221], v179 offset:2048
	ds_read_b128 v[222:225], v179 offset:3072
	global_load_lds_dwordx4 v[144:145], off
	v_lshl_add_u64 v[144:145], v[186:187], 0, s[8:9]
	s_add_i32 m0, s18, 0x2000
	s_nop 0
	global_load_lds_dwordx4 v[144:145], off
	s_barrier
	s_waitcnt lgkmcnt(0)
	v_mfma_f32_16x16x32_bf16 v[116:119], v[210:213], v[168:171], v[116:119]
	v_mfma_f32_16x16x32_bf16 v[112:115], v[218:221], v[168:171], v[112:115]
	v_mfma_f32_16x16x32_bf16 v[100:103], v[210:213], v[182:185], v[100:103]
	v_mfma_f32_16x16x32_bf16 v[96:99], v[218:221], v[182:185], v[96:99]
	v_mfma_f32_16x16x32_bf16 v[84:87], v[210:213], v[194:197], v[84:87]
	v_mfma_f32_16x16x32_bf16 v[80:83], v[218:221], v[194:197], v[80:83]
	v_mfma_f32_16x16x32_bf16 v[68:71], v[210:213], v[202:205], v[68:71]
	v_mfma_f32_16x16x32_bf16 v[64:67], v[218:221], v[202:205], v[64:67]
	v_mfma_f32_16x16x32_bf16 v[116:119], v[214:217], v[172:175], v[116:119]
	v_mfma_f32_16x16x32_bf16 v[112:115], v[222:225], v[172:175], v[112:115]
	v_mfma_f32_16x16x32_bf16 v[100:103], v[214:217], v[190:193], v[100:103]
	v_mfma_f32_16x16x32_bf16 v[96:99], v[222:225], v[190:193], v[96:99]
	v_mfma_f32_16x16x32_bf16 v[84:87], v[214:217], v[198:201], v[84:87]
	v_mfma_f32_16x16x32_bf16 v[80:83], v[222:225], v[198:201], v[80:83]
	v_mfma_f32_16x16x32_bf16 v[68:71], v[214:217], v[206:209], v[68:71]
	v_mfma_f32_16x16x32_bf16 v[64:67], v[222:225], v[206:209], v[64:67]
	s_barrier
	s_mov_b32 m0, s39
	v_lshl_add_u64 v[144:145], v[226:227], 0, s[8:9]
	ds_read_b128 v[168:171], v150 offset:49152
	ds_read_b128 v[172:175], v150 offset:50176
	ds_read_b128 v[182:185], v150 offset:51200
	ds_read_b128 v[190:193], v150 offset:52224
	ds_read_b128 v[194:197], v150 offset:53248
	ds_read_b128 v[198:201], v150 offset:54272
	ds_read_b128 v[202:205], v150 offset:55296
	ds_read_b128 v[206:209], v150 offset:56320
	global_load_lds_dwordx4 v[144:145], off
	v_lshl_add_u64 v[144:145], v[228:229], 0, s[8:9]
	s_mov_b32 m0, s40
	s_nop 0
	global_load_lds_dwordx4 v[144:145], off
	s_barrier
; __device__ __forceinline__ unsigned cvt_pk_bf16(float lo, float hi) { unsigned r; asm volatile("v_cvt_pk_bf16_f32 %0, %1, %2" : "=v"(r) : "v"(lo), "v"(hi)); return r; }
; __device__ __forceinline__ float flogsig16(float x) { return (fminf(x, 0.f) - __logf(1.0f + __expf(-fabsf(x)))) * 0.0625f; }
; #define PG8_BAR __builtin_amdgcn_s_barrier()
;     __device__ __forceinline__ void operator()(const f32x4 (&acc)[2][2][4][2], const Unit& u, int wr, int wc, int fr, int fq) const {
;     ...
;         const int row0 = u.pm * BM + wr * 64 + fr, col0 = u.pn * BM + wc * 32 + 8 * fq, bcol0 = wc * 32 + 8 * fq;
;         f32x4 bv[2][2];
; #pragma unroll
;         for (int bj = 0; bj < 2; ++bj)
; #pragma unroll
;             for (int n = 0; n < 2; ++n) bv[bj][n] = bias ? *(const f32x4*)(bias + bcol0 + bj * HALF + 4 * n) : (f32x4){0.f, 0.f, 0.f, 0.f};
; #pragma unroll
;         for (int ai = 0; ai < 2; ++ai)
; #pragma unroll
;             for (int m = 0; m < 4; ++m) { bf16_t* rowp = O + (size_t)(row0 + ai * HALF + m * 16) * ldc + col0;
; #pragma unroll
;                 for (int bj = 0; bj < 2; ++bj) { f32x4 v0 = acc[ai][bj][m][0] + bv[bj][0], v1 = acc[ai][bj][m][1] + bv[bj][1];
;                     if (act == 1) {
; #pragma unroll
;                         for (int j = 0; j < 1; ++j) { v0 = v0 * sigmoid4(v0); v1 = v1 * sigmoid4(v1); } }
;                     else if (act == 2) {
; #pragma unroll
;                         for (int j = 0; j < 1; ++j) { v0 = sigmoid4(v0); v1 = sigmoid4(v1); } }
;                     else if (act == 3) {
; #pragma unroll
;                         for (int j = 0; j < 4; ++j) { v0[j] = flogsig16(v0[j]); v1[j] = flogsig16(v1[j]); } }
;                     u32x4 w; w.x = cvt_pk_bf16(v0[0], v0[1]); w.y = cvt_pk_bf16(v0[2], v0[3]); w.z = cvt_pk_bf16(v1[0], v1[1]); w.w = cvt_pk_bf16(v1[2], v1[3]);
;                     *(u32x4*)(rowp + bj * HALF) = w; } }
; template <class Epi, class Sched>
; __device__ __forceinline__ void gemm_phase(PG8_LAS unsigned char* lds, const Gemm g, const Sched& S, const Epi& E) {
;     ...
;             PG8_BAR; PG8_WAIT_L(0); PG8_MMA(0, 1, At, B1); PG8_BAR;
;             PG8_LDA(At, 1, 1); PG8_STAGE(PG8_SA(1, 0), a3, voffA);
;             PG8_BAR; PG8_WAIT_L(0); PG8_MMA(1, 0, At, B0); PG8_BAR; PG8_SCHED;
;             PG8_STAGE(PG8_SB(1, 1), b3 + hstep, voffB);
;             PG8_WAIT_V(6); PG8_BAR; PG8_MMA(1, 1, At, B1); PG8_BAR;
	s_waitcnt lgkmcnt(0)
	v_mfma_f32_16x16x32_bf16 v[60:63], v[152:155], v[168:171], v[60:63]
	v_mfma_f32_16x16x32_bf16 v[56:59], v[160:163], v[168:171], v[56:59]
	v_mfma_f32_16x16x32_bf16 v[48:51], v[152:155], v[182:185], v[48:51]
	v_mfma_f32_16x16x32_bf16 v[40:43], v[160:163], v[182:185], v[40:43]
	v_mfma_f32_16x16x32_bf16 v[32:35], v[152:155], v[194:197], v[32:35]
	v_mfma_f32_16x16x32_bf16 v[24:27], v[160:163], v[194:197], v[24:27]
	v_mfma_f32_16x16x32_bf16 v[16:19], v[152:155], v[202:205], v[16:19]
	v_mfma_f32_16x16x32_bf16 v[8:11], v[160:163], v[202:205], v[8:11]
	v_mfma_f32_16x16x32_bf16 v[60:63], v[156:159], v[172:175], v[60:63]
	v_mfma_f32_16x16x32_bf16 v[56:59], v[164:167], v[172:175], v[56:59]
	v_mfma_f32_16x16x32_bf16 v[48:51], v[156:159], v[190:193], v[48:51]
	v_mfma_f32_16x16x32_bf16 v[40:43], v[164:167], v[190:193], v[40:43]
	v_mfma_f32_16x16x32_bf16 v[32:35], v[156:159], v[198:201], v[32:35]
	v_mfma_f32_16x16x32_bf16 v[24:27], v[164:167], v[198:201], v[24:27]
	v_mfma_f32_16x16x32_bf16 v[16:19], v[156:159], v[206:209], v[16:19]
	v_mfma_f32_16x16x32_bf16 v[8:11], v[164:167], v[206:209], v[8:11]
	s_barrier
	s_add_u32 s18, s22, 0xb0080
	s_addc_u32 s19, s23, 0
	s_add_i32 s22, s24, s31
	v_lshl_add_u64 v[144:145], s[18:19], 0, v[130:131]
	s_mov_b32 m0, s22
	s_nop 0
	global_load_lds_dwordx4 v[144:145], off
	v_lshl_add_u64 v[144:145], s[18:19], 0, v[134:135]
	s_add_i32 m0, s22, 0x2000
	s_nop 0
	global_load_lds_dwordx4 v[144:145], off
	s_waitcnt vmcnt(6)
	s_barrier
	v_mfma_f32_16x16x32_bf16 v[52:55], v[210:213], v[168:171], v[52:55]
	v_mfma_f32_16x16x32_bf16 v[44:47], v[218:221], v[168:171], v[44:47]
	v_mfma_f32_16x16x32_bf16 v[36:39], v[210:213], v[182:185], v[36:39]
	v_mfma_f32_16x16x32_bf16 v[28:31], v[218:221], v[182:185], v[28:31]
	v_mfma_f32_16x16x32_bf16 v[20:23], v[210:213], v[194:197], v[20:23]
	v_mfma_f32_16x16x32_bf16 v[12:15], v[218:221], v[194:197], v[12:15]
	v_mfma_f32_16x16x32_bf16 v[4:7], v[210:213], v[202:205], v[4:7]
	v_mfma_f32_16x16x32_bf16 v[0:3], v[218:221], v[202:205], v[0:3]
	v_mfma_f32_16x16x32_bf16 v[52:55], v[214:217], v[172:175], v[52:55]
	v_mfma_f32_16x16x32_bf16 v[44:47], v[222:225], v[172:175], v[44:47]
	v_mfma_f32_16x16x32_bf16 v[36:39], v[214:217], v[190:193], v[36:39]
	v_mfma_f32_16x16x32_bf16 v[28:31], v[222:225], v[190:193], v[28:31]
	v_mfma_f32_16x16x32_bf16 v[20:23], v[214:217], v[198:201], v[20:23]
	v_mfma_f32_16x16x32_bf16 v[12:15], v[222:225], v[198:201], v[12:15]
	v_mfma_f32_16x16x32_bf16 v[4:7], v[214:217], v[206:209], v[4:7]
	v_mfma_f32_16x16x32_bf16 v[0:3], v[222:225], v[206:209], v[0:3]
	s_add_i32 s54, s54, 2
	s_add_u32 s52, s52, 0x100
	s_addc_u32 s53, s53, 0
	s_cmp_gt_u32 s54, 41
	s_mov_b64 s[18:19], s[20:21]
	s_barrier
	s_cbranch_scc0 .LBB0_1278
	v_lshl_add_u32 v152, s50, 8, v146
	v_lshl_or_b32 v144, s51, 8, v148
	v_ashrrev_i32_e32 v153, 31, v152
	v_ashrrev_i32_e32 v145, 31, v144
	v_lshlrev_b64 v[154:155], 11, v[152:153]
	v_lshl_add_u64 v[154:155], s[6:7], 0, v[154:155]
	v_lshlrev_b64 v[156:157], 1, v[144:145]
	v_lshl_add_u64 v[144:145], v[154:155], 0, v[156:157]
	v_pk_add_f32 v[126:127], v[126:127], 0 op_sel_hi:[1,0]
	v_pk_add_f32 v[124:125], v[124:125], 0 op_sel_hi:[1,0]
	v_pk_add_f32 v[154:155], v[122:123], 0 op_sel_hi:[1,0]
	v_pk_add_f32 v[122:123], v[120:121], 0 op_sel_hi:[1,0]
	v_cvt_pk_bf16_f32 v120, v124, v125
	v_cvt_pk_bf16_f32 v121, v126, v127
	v_pk_add_f32 v[116:117], v[116:117], 0 op_sel_hi:[1,0]
	v_cvt_pk_bf16_f32 v122, v122, v123
	v_cvt_pk_bf16_f32 v123, v154, v155
	global_store_dwordx4 v[144:145], v[120:123], off
	v_pk_add_f32 v[118:119], v[118:119], 0 op_sel_hi:[1,0]
	v_pk_add_f32 v[110:111], v[110:111], 0 op_sel_hi:[1,0]
	v_pk_add_f32 v[120:121], v[114:115], 0 op_sel_hi:[1,0]
	v_pk_add_f32 v[114:115], v[112:113], 0 op_sel_hi:[1,0]
	v_cvt_pk_bf16_f32 v112, v116, v117
	v_cvt_pk_bf16_f32 v113, v118, v119
	v_pk_add_f32 v[108:109], v[108:109], 0 op_sel_hi:[1,0]
	v_cvt_pk_bf16_f32 v114, v114, v115
	v_cvt_pk_bf16_f32 v115, v120, v121
	global_store_dwordx4 v[144:145], v[112:115], off offset:256
	v_pk_add_f32 v[100:101], v[100:101], 0 op_sel_hi:[1,0]
	v_pk_add_f32 v[102:103], v[102:103], 0 op_sel_hi:[1,0]
	v_or_b32_e32 v112, 16, v152
	v_ashrrev_i32_e32 v113, 31, v112
	v_lshlrev_b64 v[112:113], 11, v[112:113]
	v_lshl_add_u64 v[112:113], s[6:7], 0, v[112:113]
	v_lshl_add_u64 v[112:113], v[112:113], 0, v[156:157]
	v_pk_add_f32 v[114:115], v[106:107], 0 op_sel_hi:[1,0]
	v_pk_add_f32 v[106:107], v[104:105], 0 op_sel_hi:[1,0]
	v_cvt_pk_bf16_f32 v104, v108, v109
	v_cvt_pk_bf16_f32 v105, v110, v111
	v_pk_add_f32 v[94:95], v[94:95], 0 op_sel_hi:[1,0]
	v_cvt_pk_bf16_f32 v106, v106, v107
	v_cvt_pk_bf16_f32 v107, v114, v115
	global_store_dwordx4 v[112:113], v[104:107], off
	v_pk_add_f32 v[92:93], v[92:93], 0 op_sel_hi:[1,0]
	v_pk_add_f32 v[84:85], v[84:85], 0 op_sel_hi:[1,0]
	v_pk_add_f32 v[104:105], v[98:99], 0 op_sel_hi:[1,0]
	v_pk_add_f32 v[98:99], v[96:97], 0 op_sel_hi:[1,0]
	v_cvt_pk_bf16_f32 v96, v100, v101
	v_cvt_pk_bf16_f32 v97, v102, v103
	v_pk_add_f32 v[86:87], v[86:87], 0 op_sel_hi:[1,0]
	v_cvt_pk_bf16_f32 v98, v98, v99
	v_cvt_pk_bf16_f32 v99, v104, v105
	global_store_dwordx4 v[112:113], v[96:99], off offset:256
	v_pk_add_f32 v[78:79], v[78:79], 0 op_sel_hi:[1,0]
	v_pk_add_f32 v[76:77], v[76:77], 0 op_sel_hi:[1,0]
	v_or_b32_e32 v96, 32, v152
	v_ashrrev_i32_e32 v97, 31, v96
	v_lshlrev_b64 v[96:97], 11, v[96:97]
	v_lshl_add_u64 v[96:97], s[6:7], 0, v[96:97]
; __device__ __forceinline__ unsigned cvt_pk_bf16(float lo, float hi) { unsigned r; asm volatile("v_cvt_pk_bf16_f32 %0, %1, %2" : "=v"(r) : "v"(lo), "v"(hi)); return r; }
; __device__ __forceinline__ float flogsig16(float x) { return (fminf(x, 0.f) - __logf(1.0f + __expf(-fabsf(x)))) * 0.0625f; }
; #define PG8_WAIT_V(n) asm volatile("s_waitcnt vmcnt(" #n ")" ::: "memory")
; #define PG8_BAR __builtin_amdgcn_s_barrier()
;     __device__ __forceinline__ void operator()(const f32x4 (&acc)[2][2][4][2], const Unit& u, int wr, int wc, int fr, int fq) const {
;     ...
;             for (int m = 0; m < 4; ++m) { bf16_t* rowp = O + (size_t)(row0 + ai * HALF + m * 16) * ldc + col0;
; #pragma unroll
;                 for (int bj = 0; bj < 2; ++bj) { f32x4 v0 = acc[ai][bj][m][0] + bv[bj][0], v1 = acc[ai][bj][m][1] + bv[bj][1];
;                     if (act == 1) {
; #pragma unroll
;                         for (int j = 0; j < 1; ++j) { v0 = v0 * sigmoid4(v0); v1 = v1 * sigmoid4(v1); } }
;                     else if (act == 2) {
; #pragma unroll
;                         for (int j = 0; j < 1; ++j) { v0 = sigmoid4(v0); v1 = sigmoid4(v1); } }
;                     else if (act == 3) {
; #pragma unroll
;                         for (int j = 0; j < 4; ++j) { v0[j] = flogsig16(v0[j]); v1[j] = flogsig16(v1[j]); } }
;                     u32x4 w; w.x = cvt_pk_bf16(v0[0], v0[1]); w.y = cvt_pk_bf16(v0[2], v0[3]); w.z = cvt_pk_bf16(v1[0], v1[1]); w.w = cvt_pk_bf16(v1[2], v1[3]);
;                     *(u32x4*)(rowp + bj * HALF) = w; } }
; template <class Epi, class Sched>
; __device__ __forceinline__ void gemm_phase(PG8_LAS unsigned char* lds, const Gemm g, const Sched& S, const Epi& E) {
;     ...
;     PG8_WAIT_V(0);
;     if (wr == 0) PG8_BAR;
;     PG8_BAR;
	v_lshl_add_u64 v[96:97], v[96:97], 0, v[156:157]
	v_pk_add_f32 v[98:99], v[90:91], 0 op_sel_hi:[1,0]
	v_pk_add_f32 v[90:91], v[88:89], 0 op_sel_hi:[1,0]
	v_cvt_pk_bf16_f32 v88, v92, v93
	v_cvt_pk_bf16_f32 v89, v94, v95
	v_pk_add_f32 v[70:71], v[70:71], 0 op_sel_hi:[1,0]
	v_cvt_pk_bf16_f32 v90, v90, v91
	v_cvt_pk_bf16_f32 v91, v98, v99
	global_store_dwordx4 v[96:97], v[88:91], off
	v_pk_add_f32 v[68:69], v[68:69], 0 op_sel_hi:[1,0]
	v_pk_add_f32 v[60:61], v[60:61], 0 op_sel_hi:[1,0]
	v_pk_add_f32 v[88:89], v[82:83], 0 op_sel_hi:[1,0]
	v_pk_add_f32 v[82:83], v[80:81], 0 op_sel_hi:[1,0]
	v_cvt_pk_bf16_f32 v80, v84, v85
	v_cvt_pk_bf16_f32 v81, v86, v87
	v_pk_add_f32 v[62:63], v[62:63], 0 op_sel_hi:[1,0]
	v_cvt_pk_bf16_f32 v82, v82, v83
	v_cvt_pk_bf16_f32 v83, v88, v89
	global_store_dwordx4 v[96:97], v[80:83], off offset:256
	v_pk_add_f32 v[54:55], v[54:55], 0 op_sel_hi:[1,0]
	v_pk_add_f32 v[52:53], v[52:53], 0 op_sel_hi:[1,0]
	v_or_b32_e32 v80, 48, v152
	v_ashrrev_i32_e32 v81, 31, v80
	v_lshlrev_b64 v[80:81], 11, v[80:81]
	v_lshl_add_u64 v[80:81], s[6:7], 0, v[80:81]
	v_lshl_add_u64 v[80:81], v[80:81], 0, v[156:157]
	v_pk_add_f32 v[82:83], v[74:75], 0 op_sel_hi:[1,0]
	v_pk_add_f32 v[74:75], v[72:73], 0 op_sel_hi:[1,0]
	v_cvt_pk_bf16_f32 v72, v76, v77
	v_cvt_pk_bf16_f32 v73, v78, v79
	v_pk_add_f32 v[48:49], v[48:49], 0 op_sel_hi:[1,0]
	v_cvt_pk_bf16_f32 v74, v74, v75
	v_cvt_pk_bf16_f32 v75, v82, v83
	global_store_dwordx4 v[80:81], v[72:75], off
	v_pk_add_f32 v[38:39], v[38:39], 0 op_sel_hi:[1,0]
	v_pk_add_f32 v[36:37], v[36:37], 0 op_sel_hi:[1,0]
	v_pk_add_f32 v[72:73], v[66:67], 0 op_sel_hi:[1,0]
	v_pk_add_f32 v[66:67], v[64:65], 0 op_sel_hi:[1,0]
	v_cvt_pk_bf16_f32 v64, v68, v69
	v_cvt_pk_bf16_f32 v65, v70, v71
	v_pk_add_f32 v[32:33], v[32:33], 0 op_sel_hi:[1,0]
	v_cvt_pk_bf16_f32 v66, v66, v67
	v_cvt_pk_bf16_f32 v67, v72, v73
	global_store_dwordx4 v[80:81], v[64:67], off offset:256
	v_pk_add_f32 v[22:23], v[22:23], 0 op_sel_hi:[1,0]
	v_pk_add_f32 v[20:21], v[20:21], 0 op_sel_hi:[1,0]
	v_pk_add_f32 v[66:67], v[58:59], 0 op_sel_hi:[1,0]
	v_pk_add_f32 v[58:59], v[56:57], 0 op_sel_hi:[1,0]
	v_cvt_pk_bf16_f32 v56, v60, v61
	v_add_co_u32_e32 v60, vcc, s44, v144
	v_cvt_pk_bf16_f32 v57, v62, v63
	v_cvt_pk_bf16_f32 v58, v58, v59
	v_cvt_pk_bf16_f32 v59, v66, v67
	v_lshl_add_u64 v[64:65], v[144:145], 0, s[10:11]
	s_nop 0
	v_addc_co_u32_e32 v61, vcc, 0, v145, vcc
	global_store_dwordx4 v[60:61], v[56:59], off
	v_pk_add_f32 v[16:17], v[16:17], 0 op_sel_hi:[1,0]
	s_mov_b32 s51, s48
	v_pk_add_f32 v[56:57], v[46:47], 0 op_sel_hi:[1,0]
	v_pk_add_f32 v[46:47], v[44:45], 0 op_sel_hi:[1,0]
	v_cvt_pk_bf16_f32 v44, v52, v53
	v_cvt_pk_bf16_f32 v45, v54, v55
	s_mov_b32 s50, s49
	v_cvt_pk_bf16_f32 v46, v46, v47
	v_cvt_pk_bf16_f32 v47, v56, v57
	global_store_dwordx4 v[64:65], v[44:47], off offset:256
	s_mov_b64 s[20:21], s[4:5]
	s_mov_b64 s[18:19], s[0:1]
	v_pk_add_f32 v[46:47], v[50:51], 0 op_sel_hi:[1,0]
	v_pk_add_f32 v[50:51], v[42:43], 0 op_sel_hi:[1,0]
	v_pk_add_f32 v[42:43], v[40:41], 0 op_sel_hi:[1,0]
	v_cvt_pk_bf16_f32 v40, v48, v49
	v_cvt_pk_bf16_f32 v41, v46, v47
	v_add_co_u32_e32 v46, vcc, s45, v144
	v_cvt_pk_bf16_f32 v42, v42, v43
	v_cvt_pk_bf16_f32 v43, v50, v51
	v_lshl_add_u64 v[44:45], v[144:145], 0, s[12:13]
	s_nop 0
	v_addc_co_u32_e32 v47, vcc, 0, v145, vcc
	global_store_dwordx4 v[46:47], v[40:43], off
	v_pk_add_f32 v[6:7], v[6:7], 0 op_sel_hi:[1,0]
	v_pk_add_f32 v[4:5], v[4:5], 0 op_sel_hi:[1,0]
	v_pk_add_f32 v[40:41], v[30:31], 0 op_sel_hi:[1,0]
	v_pk_add_f32 v[30:31], v[28:29], 0 op_sel_hi:[1,0]
	v_cvt_pk_bf16_f32 v28, v36, v37
	v_cvt_pk_bf16_f32 v29, v38, v39
	s_nop 0
	v_cvt_pk_bf16_f32 v30, v30, v31
	v_cvt_pk_bf16_f32 v31, v40, v41
	global_store_dwordx4 v[44:45], v[28:31], off offset:256
	s_nop 1
	v_pk_add_f32 v[30:31], v[34:35], 0 op_sel_hi:[1,0]
	v_pk_add_f32 v[34:35], v[26:27], 0 op_sel_hi:[1,0]
	v_pk_add_f32 v[26:27], v[24:25], 0 op_sel_hi:[1,0]
	v_cvt_pk_bf16_f32 v24, v32, v33
	v_cvt_pk_bf16_f32 v25, v30, v31
	v_add_co_u32_e32 v30, vcc, s46, v144
	v_cvt_pk_bf16_f32 v26, v26, v27
	v_cvt_pk_bf16_f32 v27, v34, v35
	v_lshl_add_u64 v[28:29], v[144:145], 0, s[14:15]
	s_nop 0
	v_addc_co_u32_e32 v31, vcc, 0, v145, vcc
	global_store_dwordx4 v[30:31], v[24:27], off
	s_nop 1
	v_pk_add_f32 v[24:25], v[14:15], 0 op_sel_hi:[1,0]
	v_pk_add_f32 v[14:15], v[12:13], 0 op_sel_hi:[1,0]
	v_cvt_pk_bf16_f32 v12, v20, v21
	v_cvt_pk_bf16_f32 v13, v22, v23
	s_nop 0
	v_cvt_pk_bf16_f32 v14, v14, v15
	v_cvt_pk_bf16_f32 v15, v24, v25
	global_store_dwordx4 v[28:29], v[12:15], off offset:256
	s_nop 1
	v_pk_add_f32 v[14:15], v[18:19], 0 op_sel_hi:[1,0]
	v_pk_add_f32 v[18:19], v[10:11], 0 op_sel_hi:[1,0]
	v_pk_add_f32 v[10:11], v[8:9], 0 op_sel_hi:[1,0]
	v_cvt_pk_bf16_f32 v8, v16, v17
	v_cvt_pk_bf16_f32 v9, v14, v15
	v_add_co_u32_e32 v14, vcc, s47, v144
	v_lshl_add_u64 v[12:13], v[144:145], 0, s[16:17]
	s_nop 0
	v_addc_co_u32_e32 v15, vcc, 0, v145, vcc
	v_cvt_pk_bf16_f32 v10, v10, v11
	v_cvt_pk_bf16_f32 v11, v18, v19
	global_store_dwordx4 v[14:15], v[8:11], off
	s_and_b64 vcc, exec, s[2:3]
	s_nop 0
	v_pk_add_f32 v[8:9], v[2:3], 0 op_sel_hi:[1,0]
	v_pk_add_f32 v[2:3], v[0:1], 0 op_sel_hi:[1,0]
	v_cvt_pk_bf16_f32 v0, v4, v5
	v_cvt_pk_bf16_f32 v1, v6, v7
	s_nop 0
	v_cvt_pk_bf16_f32 v2, v2, v3
	v_cvt_pk_bf16_f32 v3, v8, v9
	global_store_dwordx4 v[12:13], v[0:3], off offset:256
	s_cbranch_vccz .LBB0_1267
	s_waitcnt vmcnt(0)
	s_cmpk_gt_u32 s27, 0xff
	s_cbranch_scc1 .LBB0_1282
	s_barrier
